# write-through (sc1) 16-byte stores for all inter-phase activations (P1..P10) to shorten the L2 writeback at each grid barrier
# speedup vs baseline: 1.0691x; 1.0056x over previous
.LBB0_223:
	v_lshl_add_u32 v164, s10, 8, v170
	v_ashrrev_i32_e32 v165, 31, v164
	v_or_b32_e32 v162, 16, v164
	v_lshlrev_b64 v[148:149], 6, v[164:165]
	v_ashrrev_i32_e32 v163, 31, v162
	v_or_b32_e32 v160, 32, v164
	v_lshl_add_u64 v[148:149], v[138:139], 0, v[148:149]
	v_lshlrev_b64 v[150:151], 6, v[162:163]
	v_ashrrev_i32_e32 v161, 31, v160
	v_or_b32_e32 v158, 48, v164
	v_lshl_add_u64 v[150:151], v[138:139], 0, v[150:151]
	global_load_dwordx4 v[166:169], v[148:149], off
	global_load_dwordx4 v[182:185], v[150:151], off
	v_lshlrev_b64 v[148:149], 6, v[160:161]
	v_ashrrev_i32_e32 v159, 31, v158
	v_lshl_add_u64 v[148:149], v[138:139], 0, v[148:149]
	v_lshlrev_b64 v[150:151], 6, v[158:159]
	v_lshl_add_u64 v[150:151], v[138:139], 0, v[150:151]
	global_load_dwordx4 v[186:189], v[148:149], off
	global_load_dwordx4 v[190:193], v[150:151], off
	v_add_u32_e32 v156, 0x80, v164
	v_ashrrev_i32_e32 v157, 31, v156
	v_lshlrev_b64 v[148:149], 6, v[156:157]
	v_add_u32_e32 v154, 0x90, v164
	v_lshl_add_u64 v[148:149], v[138:139], 0, v[148:149]
	v_ashrrev_i32_e32 v155, 31, v154
	global_load_dwordx4 v[194:197], v[148:149], off
	v_lshlrev_b64 v[148:149], 6, v[154:155]
	v_lshl_add_u64 v[148:149], v[138:139], 0, v[148:149]
	global_load_dwordx4 v[198:201], v[148:149], off
	v_and_b32_e32 v148, 64, v176
	v_xor_b32_e32 v137, 16, v176
	v_add_u32_e32 v151, 64, v148
	v_xor_b32_e32 v149, 32, v176
	v_add_u32_e32 v150, 0xa0, v164
	v_cmp_lt_i32_e32 vcc, v137, v151
	v_add_u32_e32 v148, 0xb0, v164
	s_cmp_gt_i32 s8, 7
	v_cndmask_b32_e32 v137, v176, v137, vcc
	v_cmp_lt_i32_e32 vcc, v149, v151
	v_ashrrev_i32_e32 v151, 31, v150
	v_lshlrev_b64 v[152:153], 6, v[150:151]
	v_lshl_add_u64 v[152:153], v[138:139], 0, v[152:153]
	global_load_dwordx4 v[204:207], v[152:153], off
	v_cndmask_b32_e32 v179, v176, v149, vcc
	v_ashrrev_i32_e32 v149, 31, v148
	v_lshlrev_b64 v[152:153], 6, v[148:149]
	v_lshl_add_u64 v[152:153], v[138:139], 0, v[152:153]
	global_load_dwordx4 v[208:211], v[152:153], off
	v_lshlrev_b32_e32 v180, 2, v137
	v_lshlrev_b32_e32 v179, 2, v179
	s_cselect_b64 s[10:11], -1, 0
	s_and_b64 s[50:51], s[10:11], exec
	s_cselect_b32 s20, -8, 0
	s_cselect_b32 s9, 0x8000000, 0
	s_add_i32 s20, s20, s8
	s_add_u32 s50, s58, s9
	s_addc_u32 s51, s59, 0
	s_cmp_lt_i32 s8, 8
	s_waitcnt vmcnt(0)
	v_mov_b32_e32 v152, v167
	v_mov_b32_e32 v153, v168
	v_mov_b32_e32 v167, v169
	v_pk_add_f32 v[152:153], v[152:153], v[166:167]
	v_add_f32_e32 v137, v182, v183
	v_add_f32_e32 v152, v152, v153
	v_add_f32_e32 v167, v186, v187
	v_add_f32_e32 v168, v188, v189
	v_add_f32_e32 v153, v167, v168
	ds_bpermute_b32 v168, v180, v152
	v_add_f32_e32 v166, v184, v185
	v_add_f32_e32 v169, v190, v191
	v_add_f32_e32 v181, v192, v193
	v_add_f32_e32 v137, v137, v166
	s_waitcnt lgkmcnt(0)
	v_add_f32_e32 v152, v152, v168
	v_add_f32_e32 v166, v169, v181
	ds_bpermute_b32 v181, v180, v137
	ds_bpermute_b32 v168, v179, v152
	v_add_f32_e32 v182, v194, v195
	v_add_f32_e32 v183, v196, v197
	v_add_f32_e32 v184, v198, v199
	s_waitcnt lgkmcnt(1)
	v_add_f32_e32 v193, v137, v181
	s_waitcnt lgkmcnt(0)
	v_add_f32_e32 v137, v152, v168
	v_fmamk_f32 v137, v137, 0x3a800000, v177
	v_mul_f32_e32 v152, 0x4f800000, v137
	v_cmp_gt_f32_e32 vcc, s65, v137
	v_add_f32_e32 v185, v200, v201
	v_add_f32_e32 v167, v182, v183
	ds_bpermute_b32 v182, v180, v153
	v_cndmask_b32_e32 v137, v137, v152, vcc
	v_add_f32_e32 v169, v184, v185
	ds_bpermute_b32 v183, v180, v166
	ds_bpermute_b32 v184, v180, v167
	v_sqrt_f32_e32 v152, v137
	s_waitcnt lgkmcnt(2)
	v_add_f32_e32 v191, v153, v182
	v_mov_b64_e32 v[198:199], s[30:31]
	s_waitcnt lgkmcnt(1)
	v_add_f32_e32 v189, v166, v183
	v_add_u32_e32 v153, -1, v152
	s_waitcnt lgkmcnt(0)
	v_add_f32_e32 v187, v167, v184
	v_add_u32_e32 v166, 1, v152
	v_fma_f32 v167, -v153, v152, v137
	v_fma_f32 v168, -v166, v152, v137
	v_cmp_ge_f32_e64 s[8:9], 0, v167
	ds_bpermute_b32 v194, v179, v193
	ds_bpermute_b32 v192, v179, v191
	v_cndmask_b32_e64 v152, v152, v153, s[8:9]
	v_cmp_lt_f32_e64 s[8:9], 0, v168
	ds_bpermute_b32 v190, v179, v189
	ds_bpermute_b32 v188, v179, v187
	v_cndmask_b32_e64 v152, v152, v166, s[8:9]
	v_mul_f32_e32 v153, 0x37800000, v152
	v_cndmask_b32_e32 v152, v152, v153, vcc
	v_cmp_class_f32_e32 vcc, v137, v178
	s_nop 1
	v_cndmask_b32_e32 v137, v152, v137, vcc
	v_div_scale_f32 v152, s[8:9], v137, v137, 1.0
	v_rcp_f32_e32 v153, v152
	v_div_scale_f32 v166, vcc, 1.0, v137, 1.0
	v_fma_f32 v167, -v152, v153, 1.0
	v_fmac_f32_e32 v153, v167, v153
	v_mul_f32_e32 v167, v166, v153
	v_fma_f32 v168, -v152, v167, v166
	v_fmac_f32_e32 v167, v168, v153
	v_fma_f32 v152, -v152, v167, v166
	v_div_fmas_f32 v152, v152, v153, v167
	v_div_fixup_f32 v168, v152, v137, 1.0
	v_pk_mul_f32 v[124:125], v[124:125], v[168:169] op_sel_hi:[1,0]
	v_add_f32_e32 v152, v204, v205
	v_and_b32_e32 v197, 0x7fffffff, v125
	v_and_b32_e32 v196, 0x7fffffff, v124
	v_pk_fma_f32 v[196:197], v[196:197], s[26:27], 1.0 op_sel_hi:[1,0,0]
	v_pk_mul_f32 v[204:205], v[124:125], v[124:125]
	v_rcp_f32_e32 v196, v196
	v_rcp_f32_e32 v197, v197
	v_pk_mul_f32 v[204:205], v[204:205], s[40:41] op_sel_hi:[1,0]
	v_pk_mul_f32 v[126:127], v[126:127], v[168:169] op_sel_hi:[1,0]
	v_exp_f32_e32 v204, v204
	v_pk_fma_f32 v[200:201], v[196:197], s[28:29], v[198:199] op_sel_hi:[1,0,0]
	v_exp_f32_e32 v205, v205
	v_pk_fma_f32 v[200:201], v[196:197], v[200:201], s[34:35] op_sel_hi:[1,1,0]
	ds_bpermute_b32 v137, v180, v169
	v_add_f32_e32 v153, v206, v207
	v_pk_fma_f32 v[200:201], v[196:197], v[200:201], s[36:37] op_sel_hi:[1,1,0]
	v_and_b32_e32 v207, 0x7fffffff, v127
	v_and_b32_e32 v206, 0x7fffffff, v126
	v_pk_fma_f32 v[200:201], v[196:197], v[200:201], s[38:39] op_sel_hi:[1,1,0]
	v_pk_fma_f32 v[206:207], v[206:207], s[26:27], 1.0 op_sel_hi:[1,0,0]
	v_pk_mul_f32 v[196:197], v[196:197], v[200:201]
	v_rcp_f32_e32 v206, v206
	v_rcp_f32_e32 v207, v207
	v_pk_mul_f32 v[196:197], v[204:205], v[196:197]
	v_cmp_gt_f32_e32 vcc, 0, v124
	v_pk_mul_f32 v[204:205], v[124:125], v[196:197]
	v_pk_fma_f32 v[196:197], v[124:125], v[196:197], v[124:125] neg_lo:[1,0,0] neg_hi:[1,0,0]
	s_waitcnt lgkmcnt(0)
	v_add_f32_e32 v185, v169, v137
	v_pk_mul_f32 v[200:201], v[126:127], v[126:127]
	v_cndmask_b32_e32 v137, v196, v204, vcc
	v_cmp_gt_f32_e32 vcc, 0, v125
	v_pk_mul_f32 v[122:123], v[122:123], v[168:169] op_sel_hi:[1,0]
	v_pk_mul_f32 v[120:121], v[120:121], v[168:169] op_sel_hi:[1,0]
	v_cndmask_b32_e32 v169, v197, v205, vcc
	v_pk_fma_f32 v[124:125], v[206:207], s[28:29], v[198:199] op_sel_hi:[1,0,0]
	v_pk_mul_f32 v[196:197], v[200:201], s[40:41] op_sel_hi:[1,0]
	v_pk_fma_f32 v[124:125], v[206:207], v[124:125], s[34:35] op_sel_hi:[1,1,0]
	v_exp_f32_e32 v196, v196
	v_exp_f32_e32 v197, v197
	v_pk_fma_f32 v[124:125], v[206:207], v[124:125], s[36:37] op_sel_hi:[1,1,0]
	v_and_b32_e32 v201, 0x7fffffff, v121
	v_and_b32_e32 v200, 0x7fffffff, v120
	v_pk_fma_f32 v[124:125], v[206:207], v[124:125], s[38:39] op_sel_hi:[1,1,0]
	v_pk_fma_f32 v[200:201], v[200:201], s[26:27], 1.0 op_sel_hi:[1,0,0]
	v_pk_mul_f32 v[124:125], v[206:207], v[124:125]
	v_rcp_f32_e32 v200, v200
	v_rcp_f32_e32 v201, v201
	v_pk_mul_f32 v[124:125], v[196:197], v[124:125]
	v_cmp_gt_f32_e32 vcc, 0, v126
	v_pk_mul_f32 v[196:197], v[126:127], v[124:125]
	v_pk_fma_f32 v[124:125], v[126:127], v[124:125], v[126:127] neg_lo:[1,0,0] neg_hi:[1,0,0]
	v_add_f32_e32 v166, v208, v209
	v_cndmask_b32_e32 v195, v124, v196, vcc
	v_cmp_gt_f32_e32 vcc, 0, v127
	v_pk_mul_f32 v[126:127], v[120:121], v[120:121]
	v_add_f32_e32 v167, v210, v211
	v_cndmask_b32_e32 v204, v125, v197, vcc
	v_pk_fma_f32 v[124:125], v[200:201], s[28:29], v[198:199] op_sel_hi:[1,0,0]
	v_pk_mul_f32 v[126:127], v[126:127], s[40:41] op_sel_hi:[1,0]
	v_pk_fma_f32 v[124:125], v[200:201], v[124:125], s[34:35] op_sel_hi:[1,1,0]
	v_exp_f32_e32 v126, v126
	v_pk_fma_f32 v[124:125], v[200:201], v[124:125], s[36:37] op_sel_hi:[1,1,0]
	v_exp_f32_e32 v127, v127
	v_pk_fma_f32 v[124:125], v[200:201], v[124:125], s[38:39] op_sel_hi:[1,1,0]
	v_add_f32_e32 v152, v152, v153
	v_pk_mul_f32 v[124:125], v[200:201], v[124:125]
	v_and_b32_e32 v201, 0x7fffffff, v123
	v_and_b32_e32 v200, 0x7fffffff, v122
	v_pk_fma_f32 v[200:201], v[200:201], s[26:27], 1.0 op_sel_hi:[1,0,0]
	v_pk_mul_f32 v[124:125], v[126:127], v[124:125]
	v_rcp_f32_e32 v200, v200
	v_rcp_f32_e32 v201, v201
	v_add_f32_e32 v166, v166, v167
	v_pk_mul_f32 v[126:127], v[120:121], v[124:125]
	v_pk_fma_f32 v[124:125], v[120:121], v[124:125], v[120:121] neg_lo:[1,0,0] neg_hi:[1,0,0]
	v_cmp_gt_f32_e32 vcc, 0, v120
	ds_bpermute_b32 v153, v180, v152
	ds_bpermute_b32 v167, v180, v166
	v_pk_mul_f32 v[196:197], v[122:123], v[122:123]
	v_cndmask_b32_e32 v126, v124, v126, vcc
	v_cmp_gt_f32_e32 vcc, 0, v121
	v_pk_fma_f32 v[120:121], v[200:201], s[28:29], v[198:199] op_sel_hi:[1,0,0]
	s_waitcnt lgkmcnt(1)
	v_add_f32_e32 v183, v152, v153
	v_cndmask_b32_e32 v127, v125, v127, vcc
	v_pk_mul_f32 v[124:125], v[196:197], s[40:41] op_sel_hi:[1,0]
	v_pk_fma_f32 v[120:121], v[200:201], v[120:121], s[34:35] op_sel_hi:[1,1,0]
	v_exp_f32_e32 v124, v124
	v_exp_f32_e32 v125, v125
	v_pk_fma_f32 v[120:121], v[200:201], v[120:121], s[36:37] op_sel_hi:[1,1,0]
	s_waitcnt lgkmcnt(0)
	v_add_f32_e32 v181, v166, v167
	v_pk_fma_f32 v[120:121], v[200:201], v[120:121], s[38:39] op_sel_hi:[1,1,0]
	ds_bpermute_b32 v186, v179, v185
	v_pk_mul_f32 v[120:121], v[200:201], v[120:121]
	ds_bpermute_b32 v184, v179, v183
	ds_bpermute_b32 v182, v179, v181
	v_pk_mul_f32 v[120:121], v[124:125], v[120:121]
	v_lshl_or_b32 v152, s20, 8, v172
	v_pk_mul_f32 v[124:125], v[122:123], v[120:121]
	v_pk_fma_f32 v[120:121], v[122:123], v[120:121], v[122:123] neg_lo:[1,0,0] neg_hi:[1,0,0]
	v_cmp_gt_f32_e32 vcc, 0, v122
	v_ashrrev_i32_e32 v153, 31, v152
	v_lshl_add_u64 v[152:153], v[152:153], 1, s[50:51]
	v_cndmask_b32_e32 v124, v120, v124, vcc
	v_cmp_gt_f32_e32 vcc, 0, v123
	v_lshlrev_b64 v[166:167], 12, v[164:165]
	v_lshl_add_u64 v[166:167], v[152:153], 0, v[166:167]
	v_cndmask_b32_e32 v123, v121, v125, vcc
	v_cvt_pk_bf16_f32 v120, v137, v169
	v_cvt_pk_bf16_f32 v121, v195, v204
	v_cvt_pk_bf16_f32 v122, v126, v127
	v_cvt_pk_bf16_f32 v123, v124, v123
	v_mov_b32_e32 v124, 0
	v_mov_b32_e32 v125, 0
	global_store_dwordx4 v[166:167], v[120:123], off sc1
	s_cbranch_scc1 .LBB0_225
	v_and_b32_e32 v125, 16, v120
	v_and_b32_e32 v124, 0xffff0000, v120
	v_lshlrev_b32_e32 v197, 16, v121
	v_lshlrev_b32_e32 v196, 16, v122
	v_and_b32_e32 v126, 0xffff0000, v121
	v_mov_b32_e32 v127, v124
	v_pk_mov_b32 v[204:205], v[196:197], v[124:125] op_sel:[1,0]
	v_lshlrev_b32_e32 v120, 16, v120
	v_and_b32_e32 v198, 0xffff0000, v123
	v_mov_b32_e32 v199, v126
	v_and_b32_e32 v122, 0xffff0000, v122
	v_lshlrev_b32_e32 v200, 16, v123
	v_mov_b32_e32 v123, v197
	v_mov_b32_e32 v121, v126
	v_mov_b32_e32 v201, v126
	v_pk_add_f32 v[206:207], v[126:127], v[204:205]
	v_pk_mul_f32 v[126:127], v[126:127], v[204:205]
	v_pk_add_f32 v[124:125], v[120:121], v[124:125] op_sel_hi:[0,1]
	v_mov_b32_e32 v207, v127
	v_pk_add_f32 v[126:127], v[196:197], v[122:123]
	v_pk_mul_f32 v[204:205], v[196:197], v[196:197]
	v_mov_b32_e32 v123, v198
	v_mul_f32_e32 v125, v120, v120
	v_mov_b32_e32 v127, v205
	v_pk_add_f32 v[204:205], v[198:199], v[200:201]
	v_pk_mul_f32 v[120:121], v[198:199], v[120:121]
	v_mov_b32_e32 v197, v200
	v_pk_mul_f32 v[122:123], v[122:123], v[122:123]
	v_mov_b32_e32 v205, v121
	v_pk_fma_f32 v[122:123], v[196:197], v[196:197], v[122:123]
	v_pk_add_f32 v[124:125], v[124:125], v[206:207]
	v_pk_add_f32 v[120:121], v[126:127], v[204:205]
	v_pk_add_f32 v[122:123], v[122:123], v[122:123] op_sel_hi:[0,1]
	v_pk_add_f32 v[120:121], v[124:125], v[120:121]
	v_mov_b32_e32 v137, v123
	v_pk_add_f32 v[124:125], v[120:121], v[136:137]
.LBB0_225:
	v_mov_b32_e32 v169, v168
	v_pk_mul_f32 v[116:117], v[116:117], v[168:169]
	v_mov_b32_e32 v120, v168
	v_and_b32_e32 v123, 0x7fffffff, v117
	v_and_b32_e32 v122, 0x7fffffff, v116
	v_pk_fma_f32 v[122:123], v[122:123], s[26:27], 1.0 op_sel_hi:[1,0,0]
	v_mov_b32_e32 v121, v168
	v_rcp_f32_e32 v122, v122
	v_rcp_f32_e32 v123, v123
	v_pk_mul_f32 v[118:119], v[118:119], v[120:121]
	v_pk_mul_f32 v[114:115], v[114:115], v[120:121]
	v_pk_mul_f32 v[112:113], v[112:113], v[168:169]
	v_mov_b64_e32 v[120:121], s[30:31]
	v_pk_mul_f32 v[168:169], v[116:117], v[116:117]
	v_pk_fma_f32 v[126:127], v[122:123], s[28:29], v[120:121] op_sel_hi:[1,0,0]
	v_pk_mul_f32 v[168:169], v[168:169], s[40:41] op_sel_hi:[1,0]
	v_pk_fma_f32 v[126:127], v[122:123], v[126:127], s[34:35] op_sel_hi:[1,1,0]
	v_exp_f32_e32 v168, v168
	v_exp_f32_e32 v169, v169
	v_pk_fma_f32 v[126:127], v[122:123], v[126:127], s[36:37] op_sel_hi:[1,1,0]
	v_and_b32_e32 v197, 0x7fffffff, v119
	v_and_b32_e32 v196, 0x7fffffff, v118
	v_pk_fma_f32 v[126:127], v[122:123], v[126:127], s[38:39] op_sel_hi:[1,1,0]
	v_pk_fma_f32 v[196:197], v[196:197], s[26:27], 1.0 op_sel_hi:[1,0,0]
	v_pk_mul_f32 v[122:123], v[122:123], v[126:127]
	v_rcp_f32_e32 v196, v196
	v_rcp_f32_e32 v197, v197
	v_pk_mul_f32 v[122:123], v[168:169], v[122:123]
	v_cmp_gt_f32_e32 vcc, 0, v116
	v_pk_mul_f32 v[168:169], v[116:117], v[122:123]
	v_pk_fma_f32 v[122:123], v[116:117], v[122:123], v[116:117] neg_lo:[1,0,0] neg_hi:[1,0,0]
	v_pk_mul_f32 v[126:127], v[118:119], v[118:119]
	v_cndmask_b32_e32 v137, v122, v168, vcc
	v_cmp_gt_f32_e32 vcc, 0, v117
	v_pk_fma_f32 v[116:117], v[196:197], s[28:29], v[120:121] op_sel_hi:[1,0,0]
	s_lshl_b32 s8, s20, 3
	v_cndmask_b32_e32 v168, v123, v169, vcc
	v_pk_mul_f32 v[122:123], v[126:127], s[40:41] op_sel_hi:[1,0]
	v_pk_fma_f32 v[116:117], v[196:197], v[116:117], s[34:35] op_sel_hi:[1,1,0]
	v_exp_f32_e32 v122, v122
	v_exp_f32_e32 v123, v123
	v_pk_fma_f32 v[116:117], v[196:197], v[116:117], s[36:37] op_sel_hi:[1,1,0]
	v_and_b32_e32 v127, 0x7fffffff, v113
	v_and_b32_e32 v126, 0x7fffffff, v112
	v_pk_fma_f32 v[116:117], v[196:197], v[116:117], s[38:39] op_sel_hi:[1,1,0]
	v_pk_fma_f32 v[126:127], v[126:127], s[26:27], 1.0 op_sel_hi:[1,0,0]
	v_pk_mul_f32 v[116:117], v[196:197], v[116:117]
	v_rcp_f32_e32 v126, v126
	v_rcp_f32_e32 v127, v127
	v_pk_mul_f32 v[116:117], v[122:123], v[116:117]
	v_cmp_gt_f32_e32 vcc, 0, v118
	v_pk_mul_f32 v[122:123], v[118:119], v[116:117]
	v_pk_fma_f32 v[116:117], v[118:119], v[116:117], v[118:119] neg_lo:[1,0,0] neg_hi:[1,0,0]
	s_or_b32 s50, s8, s62
	v_cndmask_b32_e32 v169, v116, v122, vcc
	v_cmp_gt_f32_e32 vcc, 0, v119
	v_pk_mul_f32 v[118:119], v[112:113], v[112:113]
	s_ashr_i32 s51, s50, 31
	v_cndmask_b32_e32 v195, v117, v123, vcc
	v_pk_fma_f32 v[116:117], v[126:127], s[28:29], v[120:121] op_sel_hi:[1,0,0]
	v_pk_mul_f32 v[118:119], v[118:119], s[40:41] op_sel_hi:[1,0]
	v_pk_fma_f32 v[116:117], v[126:127], v[116:117], s[34:35] op_sel_hi:[1,1,0]
	v_exp_f32_e32 v118, v118
	v_pk_fma_f32 v[116:117], v[126:127], v[116:117], s[36:37] op_sel_hi:[1,1,0]
	v_exp_f32_e32 v119, v119
	v_pk_fma_f32 v[116:117], v[126:127], v[116:117], s[38:39] op_sel_hi:[1,1,0]
	v_cmp_gt_f32_e32 vcc, 0, v112
	v_pk_mul_f32 v[116:117], v[126:127], v[116:117]
	v_and_b32_e32 v127, 0x7fffffff, v115
	v_and_b32_e32 v126, 0x7fffffff, v114
	v_pk_fma_f32 v[126:127], v[126:127], s[26:27], 1.0 op_sel_hi:[1,0,0]
	v_pk_mul_f32 v[116:117], v[118:119], v[116:117]
	v_rcp_f32_e32 v126, v126
	v_rcp_f32_e32 v127, v127
	v_pk_mul_f32 v[118:119], v[112:113], v[116:117]
	v_pk_fma_f32 v[116:117], v[112:113], v[116:117], v[112:113] neg_lo:[1,0,0] neg_hi:[1,0,0]
	v_pk_mul_f32 v[122:123], v[114:115], v[114:115]
	v_cndmask_b32_e32 v118, v116, v118, vcc
	v_cmp_gt_f32_e32 vcc, 0, v113
	v_pk_fma_f32 v[112:113], v[126:127], s[28:29], v[120:121] op_sel_hi:[1,0,0]
	s_nop 0
	v_cndmask_b32_e32 v119, v117, v119, vcc
	v_pk_mul_f32 v[116:117], v[122:123], s[40:41] op_sel_hi:[1,0]
	v_pk_fma_f32 v[112:113], v[126:127], v[112:113], s[34:35] op_sel_hi:[1,1,0]
	v_exp_f32_e32 v116, v116
	v_exp_f32_e32 v117, v117
	v_pk_fma_f32 v[112:113], v[126:127], v[112:113], s[36:37] op_sel_hi:[1,1,0]
	v_cmp_gt_f32_e32 vcc, 0, v114
	v_pk_fma_f32 v[112:113], v[126:127], v[112:113], s[38:39] op_sel_hi:[1,1,0]
	s_nop 0
	v_pk_mul_f32 v[112:113], v[126:127], v[112:113]
	s_nop 0
	v_pk_mul_f32 v[112:113], v[116:117], v[112:113]
	s_nop 0
	v_pk_mul_f32 v[116:117], v[114:115], v[112:113]
	v_pk_fma_f32 v[112:113], v[114:115], v[112:113], v[114:115] neg_lo:[1,0,0] neg_hi:[1,0,0]
	s_nop 0
	v_cndmask_b32_e32 v116, v112, v116, vcc
	v_cmp_gt_f32_e32 vcc, 0, v115
	v_cvt_pk_bf16_f32 v112, v137, v168
	s_nop 1
	v_cndmask_b32_e32 v115, v113, v117, vcc
	v_cvt_pk_bf16_f32 v113, v169, v195
	v_cvt_pk_bf16_f32 v114, v118, v119
	v_cvt_pk_bf16_f32 v115, v116, v115
	v_cndmask_b32_e64 v116, 0, 1, s[10:11]
	v_cmp_ne_u32_e64 s[8:9], 1, v116
	s_andn2_b64 vcc, exec, s[10:11]
	global_store_dwordx4 v[166:167], v[112:115], off offset:256 sc1
	s_cbranch_vccnz .LBB0_229
	v_lshlrev_b32_e32 v116, 16, v112
	v_and_b32_e32 v112, 0xffff0000, v112
	v_lshlrev_b32_e32 v118, 16, v113
	v_and_b32_e32 v120, 0xffff0000, v113
	v_lshlrev_b32_e32 v122, 16, v114
	v_and_b32_e32 v114, 0xffff0000, v114
	v_lshlrev_b32_e32 v126, 16, v115
	v_and_b32_e32 v166, 0xffff0000, v115
	v_mul_f32_e32 v117, v116, v116
	v_mul_f32_e32 v113, v112, v112
	v_mul_f32_e32 v119, v118, v118
	v_mul_f32_e32 v121, v120, v120
	v_mul_f32_e32 v123, v122, v122
	v_mul_f32_e32 v115, v114, v114
	v_mul_f32_e32 v127, v126, v126
	v_mul_f32_e32 v167, v166, v166
	v_pk_add_f32 v[112:113], v[116:117], v[112:113]
	v_pk_add_f32 v[116:117], v[118:119], v[120:121]
	v_pk_add_f32 v[114:115], v[122:123], v[114:115]
	v_pk_add_f32 v[112:113], v[112:113], v[116:117]
	v_pk_add_f32 v[116:117], v[126:127], v[166:167]
	s_nop 0
	v_pk_add_f32 v[114:115], v[114:115], v[116:117]
	s_nop 0
	v_pk_add_f32 v[112:113], v[112:113], v[114:115]
	s_nop 0
	v_pk_add_f32 v[112:113], v[124:125], v[112:113]
	ds_bpermute_b32 v114, v180, v112
	ds_bpermute_b32 v115, v180, v113
	s_waitcnt lgkmcnt(0)
	v_pk_add_f32 v[112:113], v[112:113], v[114:115]
	ds_bpermute_b32 v114, v179, v112
	ds_bpermute_b32 v115, v179, v113
	s_and_saveexec_b64 s[10:11], s[4:5]
	s_cbranch_execz .LBB0_228
	v_lshlrev_b64 v[116:117], 8, v[164:165]
	v_lshl_add_u64 v[116:117], s[16:17], 0, v[116:117]
	v_lshl_add_u64 v[116:117], s[50:51], 2, v[116:117]
	s_waitcnt lgkmcnt(0)
	v_pk_add_f32 v[112:113], v[112:113], v[114:115]
	global_store_dwordx2 v[116:117], v[112:113], off

.LBB0_229:
	s_nop 0
	v_add_f32_e32 v112, v193, v194
	v_fmamk_f32 v112, v112, 0x3a800000, v177
	v_mul_f32_e32 v113, 0x4f800000, v112
	v_cmp_gt_f32_e32 vcc, s65, v112
	v_mov_b64_e32 v[118:119], s[30:31]
	s_nop 0
	v_cndmask_b32_e32 v112, v112, v113, vcc
	v_sqrt_f32_e32 v113, v112
	s_waitcnt lgkmcnt(1)
	v_add_u32_e32 v114, -1, v113
	v_fma_f32 v116, -v114, v113, v112
	s_waitcnt lgkmcnt(0)
	v_add_u32_e32 v115, 1, v113
	v_cmp_ge_f32_e64 s[10:11], 0, v116
	s_nop 1
	v_cndmask_b32_e64 v114, v113, v114, s[10:11]
	v_fma_f32 v113, -v115, v113, v112
	v_cmp_lt_f32_e64 s[10:11], 0, v113
	s_nop 1
	v_cndmask_b32_e64 v113, v114, v115, s[10:11]
	v_mul_f32_e32 v114, 0x37800000, v113
	v_cndmask_b32_e32 v113, v113, v114, vcc
	v_cmp_class_f32_e32 vcc, v112, v178
	s_nop 1
	v_cndmask_b32_e32 v112, v113, v112, vcc
	v_div_scale_f32 v113, s[10:11], v112, v112, 1.0
	v_rcp_f32_e32 v114, v113
	s_nop 0
	v_fma_f32 v115, -v113, v114, 1.0
	v_fmac_f32_e32 v114, v115, v114
	v_div_scale_f32 v115, vcc, 1.0, v112, 1.0
	v_mul_f32_e32 v116, v115, v114
	v_fma_f32 v117, -v113, v116, v115
	v_fmac_f32_e32 v116, v117, v114
	v_fma_f32 v113, -v113, v116, v115
	v_div_fmas_f32 v113, v113, v114, v116
	v_div_fixup_f32 v114, v113, v112, 1.0
	v_pk_mul_f32 v[108:109], v[108:109], v[114:115] op_sel_hi:[1,0]
	v_pk_mul_f32 v[110:111], v[110:111], v[114:115] op_sel_hi:[1,0]
	v_and_b32_e32 v117, 0x7fffffff, v109
	v_and_b32_e32 v116, 0x7fffffff, v108
	v_pk_fma_f32 v[116:117], v[116:117], s[26:27], 1.0 op_sel_hi:[1,0,0]
	v_pk_mul_f32 v[122:123], v[108:109], v[108:109]
	v_rcp_f32_e32 v116, v116
	v_rcp_f32_e32 v117, v117
	v_pk_mul_f32 v[122:123], v[122:123], s[40:41] op_sel_hi:[1,0]
	v_and_b32_e32 v125, 0x7fffffff, v111
	v_exp_f32_e32 v122, v122
	v_pk_fma_f32 v[120:121], v[116:117], s[28:29], v[118:119] op_sel_hi:[1,0,0]
	v_exp_f32_e32 v123, v123
	v_pk_fma_f32 v[120:121], v[116:117], v[120:121], s[34:35] op_sel_hi:[1,1,0]
	v_and_b32_e32 v124, 0x7fffffff, v110
	v_pk_fma_f32 v[120:121], v[116:117], v[120:121], s[36:37] op_sel_hi:[1,1,0]
	v_pk_fma_f32 v[124:125], v[124:125], s[26:27], 1.0 op_sel_hi:[1,0,0]
	v_pk_fma_f32 v[120:121], v[116:117], v[120:121], s[38:39] op_sel_hi:[1,1,0]
	v_rcp_f32_e32 v124, v124
	v_pk_mul_f32 v[116:117], v[116:117], v[120:121]
	v_rcp_f32_e32 v125, v125
	v_pk_mul_f32 v[116:117], v[122:123], v[116:117]
	v_cmp_gt_f32_e32 vcc, 0, v108
	v_pk_mul_f32 v[122:123], v[108:109], v[116:117]
	v_pk_fma_f32 v[116:117], v[108:109], v[116:117], v[108:109] neg_lo:[1,0,0] neg_hi:[1,0,0]
	v_pk_mul_f32 v[106:107], v[106:107], v[114:115] op_sel_hi:[1,0]
	v_pk_mul_f32 v[104:105], v[104:105], v[114:115] op_sel_hi:[1,0]
	v_pk_mul_f32 v[120:121], v[110:111], v[110:111]
	v_cndmask_b32_e32 v115, v116, v122, vcc
	v_cmp_gt_f32_e32 vcc, 0, v109
	v_pk_fma_f32 v[108:109], v[124:125], s[28:29], v[118:119] op_sel_hi:[1,0,0]
	v_lshlrev_b64 v[112:113], 12, v[162:163]
	v_cndmask_b32_e32 v122, v117, v123, vcc
	v_pk_mul_f32 v[116:117], v[120:121], s[40:41] op_sel_hi:[1,0]
	v_pk_fma_f32 v[108:109], v[124:125], v[108:109], s[34:35] op_sel_hi:[1,1,0]
	v_exp_f32_e32 v116, v116
	v_exp_f32_e32 v117, v117
	v_pk_fma_f32 v[108:109], v[124:125], v[108:109], s[36:37] op_sel_hi:[1,1,0]
	v_and_b32_e32 v121, 0x7fffffff, v105
	v_and_b32_e32 v120, 0x7fffffff, v104
	v_pk_fma_f32 v[108:109], v[124:125], v[108:109], s[38:39] op_sel_hi:[1,1,0]
	v_pk_fma_f32 v[120:121], v[120:121], s[26:27], 1.0 op_sel_hi:[1,0,0]
	v_pk_mul_f32 v[108:109], v[124:125], v[108:109]
	v_rcp_f32_e32 v120, v120
	v_rcp_f32_e32 v121, v121
	v_pk_mul_f32 v[108:109], v[116:117], v[108:109]
	v_cmp_gt_f32_e32 vcc, 0, v110
	v_pk_mul_f32 v[116:117], v[110:111], v[108:109]
	v_pk_fma_f32 v[108:109], v[110:111], v[108:109], v[110:111] neg_lo:[1,0,0] neg_hi:[1,0,0]
	v_lshl_add_u64 v[112:113], v[152:153], 0, v[112:113]
	v_cndmask_b32_e32 v123, v108, v116, vcc
	v_cmp_gt_f32_e32 vcc, 0, v111
	v_pk_mul_f32 v[110:111], v[104:105], v[104:105]
	s_nop 0
	v_cndmask_b32_e32 v124, v109, v117, vcc
	v_pk_fma_f32 v[108:109], v[120:121], s[28:29], v[118:119] op_sel_hi:[1,0,0]
	v_pk_mul_f32 v[110:111], v[110:111], s[40:41] op_sel_hi:[1,0]
	v_pk_fma_f32 v[108:109], v[120:121], v[108:109], s[34:35] op_sel_hi:[1,1,0]
	v_exp_f32_e32 v110, v110
	v_pk_fma_f32 v[108:109], v[120:121], v[108:109], s[36:37] op_sel_hi:[1,1,0]
	v_exp_f32_e32 v111, v111
	v_pk_fma_f32 v[108:109], v[120:121], v[108:109], s[38:39] op_sel_hi:[1,1,0]
	v_cmp_gt_f32_e32 vcc, 0, v104
	v_pk_mul_f32 v[108:109], v[120:121], v[108:109]
	v_and_b32_e32 v121, 0x7fffffff, v107
	v_and_b32_e32 v120, 0x7fffffff, v106
	v_pk_fma_f32 v[120:121], v[120:121], s[26:27], 1.0 op_sel_hi:[1,0,0]
	v_pk_mul_f32 v[108:109], v[110:111], v[108:109]
	v_rcp_f32_e32 v120, v120
	v_rcp_f32_e32 v121, v121
	v_pk_mul_f32 v[110:111], v[104:105], v[108:109]
	v_pk_fma_f32 v[108:109], v[104:105], v[108:109], v[104:105] neg_lo:[1,0,0] neg_hi:[1,0,0]
	v_pk_mul_f32 v[116:117], v[106:107], v[106:107]
	v_cndmask_b32_e32 v110, v108, v110, vcc
	v_cmp_gt_f32_e32 vcc, 0, v105
	v_pk_fma_f32 v[104:105], v[120:121], s[28:29], v[118:119] op_sel_hi:[1,0,0]
	s_nop 0
	v_cndmask_b32_e32 v111, v109, v111, vcc
	v_pk_mul_f32 v[108:109], v[116:117], s[40:41] op_sel_hi:[1,0]
	v_pk_fma_f32 v[104:105], v[120:121], v[104:105], s[34:35] op_sel_hi:[1,1,0]
	v_exp_f32_e32 v108, v108
	v_exp_f32_e32 v109, v109
	v_pk_fma_f32 v[104:105], v[120:121], v[104:105], s[36:37] op_sel_hi:[1,1,0]
	v_cmp_gt_f32_e32 vcc, 0, v106
	v_pk_fma_f32 v[104:105], v[120:121], v[104:105], s[38:39] op_sel_hi:[1,1,0]
	s_nop 0
	v_pk_mul_f32 v[104:105], v[120:121], v[104:105]
	s_nop 0
	v_pk_mul_f32 v[104:105], v[108:109], v[104:105]
	s_nop 0
	v_pk_mul_f32 v[108:109], v[106:107], v[104:105]
	v_pk_fma_f32 v[104:105], v[106:107], v[104:105], v[106:107] neg_lo:[1,0,0] neg_hi:[1,0,0]
	s_nop 0
	v_cndmask_b32_e32 v108, v104, v108, vcc
	v_cmp_gt_f32_e32 vcc, 0, v107
	v_cvt_pk_bf16_f32 v104, v115, v122
	s_nop 1
	v_cndmask_b32_e32 v107, v105, v109, vcc
	v_cvt_pk_bf16_f32 v105, v123, v124
	v_cvt_pk_bf16_f32 v106, v110, v111
	v_cvt_pk_bf16_f32 v107, v108, v107
	v_mov_b32_e32 v108, 0
	s_and_b64 vcc, exec, s[8:9]
	v_mov_b32_e32 v109, 0
	global_store_dwordx4 v[112:113], v[104:107], off sc1
	s_cbranch_vccnz .LBB0_231
	v_and_b32_e32 v109, 16, v104
	v_and_b32_e32 v108, 0xffff0000, v104
	v_lshlrev_b32_e32 v117, 16, v105
	v_lshlrev_b32_e32 v116, 16, v106
	v_and_b32_e32 v110, 0xffff0000, v105
	v_mov_b32_e32 v111, v108
	v_pk_mov_b32 v[122:123], v[116:117], v[108:109] op_sel:[1,0]
	v_lshlrev_b32_e32 v104, 16, v104
	v_and_b32_e32 v118, 0xffff0000, v107
	v_mov_b32_e32 v119, v110
	v_and_b32_e32 v106, 0xffff0000, v106
	v_lshlrev_b32_e32 v120, 16, v107
	v_mov_b32_e32 v107, v117
	v_mov_b32_e32 v105, v110
	v_mov_b32_e32 v121, v110
	v_pk_add_f32 v[124:125], v[110:111], v[122:123]
	v_pk_mul_f32 v[110:111], v[110:111], v[122:123]
	v_pk_add_f32 v[108:109], v[104:105], v[108:109] op_sel_hi:[0,1]
	v_mov_b32_e32 v125, v111
	v_pk_add_f32 v[110:111], v[116:117], v[106:107]
	v_pk_mul_f32 v[122:123], v[116:117], v[116:117]
	v_mov_b32_e32 v107, v118
	v_mul_f32_e32 v109, v104, v104
	v_mov_b32_e32 v111, v123
	v_pk_add_f32 v[122:123], v[118:119], v[120:121]
	v_pk_mul_f32 v[104:105], v[118:119], v[104:105]
	v_mov_b32_e32 v117, v120
	v_pk_mul_f32 v[106:107], v[106:107], v[106:107]
	v_mov_b32_e32 v123, v105
	v_pk_fma_f32 v[106:107], v[116:117], v[116:117], v[106:107]
	v_pk_add_f32 v[108:109], v[108:109], v[124:125]
	v_pk_add_f32 v[104:105], v[110:111], v[122:123]
	v_pk_add_f32 v[106:107], v[106:107], v[106:107] op_sel_hi:[0,1]
	v_pk_add_f32 v[104:105], v[108:109], v[104:105]
	v_mov_b32_e32 v137, v107
	v_pk_add_f32 v[108:109], v[104:105], v[136:137]
.LBB0_231:
	v_mov_b32_e32 v115, v114
	v_pk_mul_f32 v[100:101], v[100:101], v[114:115]
	v_mov_b32_e32 v104, v114
	v_and_b32_e32 v107, 0x7fffffff, v101
	v_and_b32_e32 v106, 0x7fffffff, v100
	v_pk_fma_f32 v[106:107], v[106:107], s[26:27], 1.0 op_sel_hi:[1,0,0]
	v_mov_b32_e32 v105, v114
	v_rcp_f32_e32 v106, v106
	v_rcp_f32_e32 v107, v107
	v_pk_mul_f32 v[102:103], v[102:103], v[104:105]
	v_pk_mul_f32 v[98:99], v[98:99], v[104:105]
	v_pk_mul_f32 v[96:97], v[96:97], v[114:115]
	v_mov_b64_e32 v[104:105], s[30:31]
	v_pk_mul_f32 v[114:115], v[100:101], v[100:101]
	v_pk_fma_f32 v[110:111], v[106:107], s[28:29], v[104:105] op_sel_hi:[1,0,0]
	v_pk_mul_f32 v[114:115], v[114:115], s[40:41] op_sel_hi:[1,0]
	v_pk_fma_f32 v[110:111], v[106:107], v[110:111], s[34:35] op_sel_hi:[1,1,0]
	v_exp_f32_e32 v114, v114
	v_exp_f32_e32 v115, v115
	v_pk_fma_f32 v[110:111], v[106:107], v[110:111], s[36:37] op_sel_hi:[1,1,0]
	v_and_b32_e32 v117, 0x7fffffff, v103
	v_and_b32_e32 v116, 0x7fffffff, v102
	v_pk_fma_f32 v[110:111], v[106:107], v[110:111], s[38:39] op_sel_hi:[1,1,0]
	v_pk_fma_f32 v[116:117], v[116:117], s[26:27], 1.0 op_sel_hi:[1,0,0]
	v_pk_mul_f32 v[106:107], v[106:107], v[110:111]
	v_rcp_f32_e32 v116, v116
	v_rcp_f32_e32 v117, v117
	v_pk_mul_f32 v[106:107], v[114:115], v[106:107]
	v_cmp_gt_f32_e32 vcc, 0, v100
	v_pk_mul_f32 v[114:115], v[100:101], v[106:107]
	v_pk_fma_f32 v[106:107], v[100:101], v[106:107], v[100:101] neg_lo:[1,0,0] neg_hi:[1,0,0]
	v_pk_mul_f32 v[110:111], v[102:103], v[102:103]
	v_cndmask_b32_e32 v114, v106, v114, vcc
	v_cmp_gt_f32_e32 vcc, 0, v101
	v_pk_fma_f32 v[100:101], v[116:117], s[28:29], v[104:105] op_sel_hi:[1,0,0]
	s_nop 0
	v_cndmask_b32_e32 v115, v107, v115, vcc
	v_pk_mul_f32 v[106:107], v[110:111], s[40:41] op_sel_hi:[1,0]
	v_pk_fma_f32 v[100:101], v[116:117], v[100:101], s[34:35] op_sel_hi:[1,1,0]
	v_exp_f32_e32 v106, v106
	v_exp_f32_e32 v107, v107
	v_pk_fma_f32 v[100:101], v[116:117], v[100:101], s[36:37] op_sel_hi:[1,1,0]
	v_and_b32_e32 v111, 0x7fffffff, v97
	v_and_b32_e32 v110, 0x7fffffff, v96
	v_pk_fma_f32 v[100:101], v[116:117], v[100:101], s[38:39] op_sel_hi:[1,1,0]
	v_pk_fma_f32 v[110:111], v[110:111], s[26:27], 1.0 op_sel_hi:[1,0,0]
	v_pk_mul_f32 v[100:101], v[116:117], v[100:101]
	v_rcp_f32_e32 v110, v110
	v_rcp_f32_e32 v111, v111
	v_pk_mul_f32 v[100:101], v[106:107], v[100:101]
	v_cmp_gt_f32_e32 vcc, 0, v102
	v_pk_mul_f32 v[106:107], v[102:103], v[100:101]
	v_pk_fma_f32 v[100:101], v[102:103], v[100:101], v[102:103] neg_lo:[1,0,0] neg_hi:[1,0,0]
	s_nop 0
	v_cndmask_b32_e32 v116, v100, v106, vcc
	v_cmp_gt_f32_e32 vcc, 0, v103
	v_pk_mul_f32 v[102:103], v[96:97], v[96:97]
	s_nop 0
	v_cndmask_b32_e32 v117, v101, v107, vcc
	v_pk_fma_f32 v[100:101], v[110:111], s[28:29], v[104:105] op_sel_hi:[1,0,0]
	v_pk_mul_f32 v[102:103], v[102:103], s[40:41] op_sel_hi:[1,0]
	v_pk_fma_f32 v[100:101], v[110:111], v[100:101], s[34:35] op_sel_hi:[1,1,0]
	v_exp_f32_e32 v102, v102
	v_pk_fma_f32 v[100:101], v[110:111], v[100:101], s[36:37] op_sel_hi:[1,1,0]
	v_exp_f32_e32 v103, v103
	v_pk_fma_f32 v[100:101], v[110:111], v[100:101], s[38:39] op_sel_hi:[1,1,0]
	v_cmp_gt_f32_e32 vcc, 0, v96
	v_pk_mul_f32 v[100:101], v[110:111], v[100:101]
	v_and_b32_e32 v111, 0x7fffffff, v99
	v_and_b32_e32 v110, 0x7fffffff, v98
	v_pk_fma_f32 v[110:111], v[110:111], s[26:27], 1.0 op_sel_hi:[1,0,0]
	v_pk_mul_f32 v[100:101], v[102:103], v[100:101]
	v_rcp_f32_e32 v110, v110
	v_rcp_f32_e32 v111, v111
	v_pk_mul_f32 v[102:103], v[96:97], v[100:101]
	v_pk_fma_f32 v[100:101], v[96:97], v[100:101], v[96:97] neg_lo:[1,0,0] neg_hi:[1,0,0]
	v_pk_mul_f32 v[106:107], v[98:99], v[98:99]
	v_cndmask_b32_e32 v102, v100, v102, vcc
	v_cmp_gt_f32_e32 vcc, 0, v97
	v_pk_fma_f32 v[96:97], v[110:111], s[28:29], v[104:105] op_sel_hi:[1,0,0]
	s_nop 0
	v_cndmask_b32_e32 v103, v101, v103, vcc
	v_pk_mul_f32 v[100:101], v[106:107], s[40:41] op_sel_hi:[1,0]
	v_pk_fma_f32 v[96:97], v[110:111], v[96:97], s[34:35] op_sel_hi:[1,1,0]
	v_exp_f32_e32 v100, v100
	v_exp_f32_e32 v101, v101
	v_pk_fma_f32 v[96:97], v[110:111], v[96:97], s[36:37] op_sel_hi:[1,1,0]
	v_cmp_gt_f32_e32 vcc, 0, v98
	v_pk_fma_f32 v[96:97], v[110:111], v[96:97], s[38:39] op_sel_hi:[1,1,0]
	s_nop 0
	v_pk_mul_f32 v[96:97], v[110:111], v[96:97]
	s_nop 0
	v_pk_mul_f32 v[96:97], v[100:101], v[96:97]
	s_nop 0
	v_pk_mul_f32 v[100:101], v[98:99], v[96:97]
	v_pk_fma_f32 v[96:97], v[98:99], v[96:97], v[98:99] neg_lo:[1,0,0] neg_hi:[1,0,0]
	s_nop 0
	v_cndmask_b32_e32 v100, v96, v100, vcc
	v_cmp_gt_f32_e32 vcc, 0, v99
	v_cvt_pk_bf16_f32 v96, v114, v115
	s_nop 1
	v_cndmask_b32_e32 v99, v97, v101, vcc
	s_and_b64 vcc, exec, s[8:9]
	v_cvt_pk_bf16_f32 v97, v116, v117
	v_cvt_pk_bf16_f32 v98, v102, v103
	v_cvt_pk_bf16_f32 v99, v100, v99
	global_store_dwordx4 v[112:113], v[96:99], off offset:256 sc1
	s_cbranch_vccnz .LBB0_235
	v_lshlrev_b32_e32 v100, 16, v96
	v_and_b32_e32 v96, 0xffff0000, v96
	v_lshlrev_b32_e32 v102, 16, v97
	v_and_b32_e32 v104, 0xffff0000, v97
	v_lshlrev_b32_e32 v106, 16, v98
	v_and_b32_e32 v98, 0xffff0000, v98
	v_lshlrev_b32_e32 v110, 16, v99
	v_and_b32_e32 v112, 0xffff0000, v99
	v_mul_f32_e32 v101, v100, v100
	v_mul_f32_e32 v97, v96, v96
	v_mul_f32_e32 v103, v102, v102
	v_mul_f32_e32 v105, v104, v104
	v_mul_f32_e32 v107, v106, v106
	v_mul_f32_e32 v99, v98, v98
	v_mul_f32_e32 v111, v110, v110
	v_mul_f32_e32 v113, v112, v112
	v_pk_add_f32 v[96:97], v[100:101], v[96:97]
	v_pk_add_f32 v[100:101], v[102:103], v[104:105]
	v_pk_add_f32 v[98:99], v[106:107], v[98:99]
	v_pk_add_f32 v[96:97], v[96:97], v[100:101]
	v_pk_add_f32 v[100:101], v[110:111], v[112:113]
	s_nop 0
	v_pk_add_f32 v[98:99], v[98:99], v[100:101]
	s_nop 0
	v_pk_add_f32 v[96:97], v[96:97], v[98:99]
	s_nop 0
	v_pk_add_f32 v[96:97], v[108:109], v[96:97]
	ds_bpermute_b32 v98, v180, v96
	ds_bpermute_b32 v99, v180, v97
	s_waitcnt lgkmcnt(0)
	v_pk_add_f32 v[96:97], v[96:97], v[98:99]
	ds_bpermute_b32 v98, v179, v96
	ds_bpermute_b32 v99, v179, v97
	s_and_saveexec_b64 s[10:11], s[4:5]
	s_cbranch_execz .LBB0_234
	v_lshlrev_b64 v[100:101], 8, v[162:163]
	v_lshl_add_u64 v[100:101], s[16:17], 0, v[100:101]
	v_lshl_add_u64 v[100:101], s[50:51], 2, v[100:101]
	s_waitcnt lgkmcnt(0)
	v_pk_add_f32 v[96:97], v[96:97], v[98:99]
	global_store_dwordx2 v[100:101], v[96:97], off

.LBB0_235:
	s_nop 0
	v_add_f32_e32 v96, v191, v192
	v_fmamk_f32 v96, v96, 0x3a800000, v177
	v_mul_f32_e32 v97, 0x4f800000, v96
	v_cmp_gt_f32_e32 vcc, s65, v96
	v_mov_b64_e32 v[102:103], s[30:31]
	s_nop 0
	v_cndmask_b32_e32 v96, v96, v97, vcc
	v_sqrt_f32_e32 v97, v96
	s_waitcnt lgkmcnt(1)
	v_add_u32_e32 v98, -1, v97
	v_fma_f32 v100, -v98, v97, v96
	s_waitcnt lgkmcnt(0)
	v_add_u32_e32 v99, 1, v97
	v_cmp_ge_f32_e64 s[10:11], 0, v100
	s_nop 1
	v_cndmask_b32_e64 v98, v97, v98, s[10:11]
	v_fma_f32 v97, -v99, v97, v96
	v_cmp_lt_f32_e64 s[10:11], 0, v97
	s_nop 1
	v_cndmask_b32_e64 v97, v98, v99, s[10:11]
	v_mul_f32_e32 v98, 0x37800000, v97
	v_cndmask_b32_e32 v97, v97, v98, vcc
	v_cmp_class_f32_e32 vcc, v96, v178
	s_nop 1
	v_cndmask_b32_e32 v96, v97, v96, vcc
	v_div_scale_f32 v97, s[10:11], v96, v96, 1.0
	v_rcp_f32_e32 v98, v97
	s_nop 0
	v_fma_f32 v99, -v97, v98, 1.0
	v_fmac_f32_e32 v98, v99, v98
	v_div_scale_f32 v99, vcc, 1.0, v96, 1.0
	v_mul_f32_e32 v100, v99, v98
	v_fma_f32 v101, -v97, v100, v99
	v_fmac_f32_e32 v100, v101, v98
	v_fma_f32 v97, -v97, v100, v99
	v_div_fmas_f32 v97, v97, v98, v100
	v_div_fixup_f32 v98, v97, v96, 1.0
	v_pk_mul_f32 v[92:93], v[92:93], v[98:99] op_sel_hi:[1,0]
	v_pk_mul_f32 v[94:95], v[94:95], v[98:99] op_sel_hi:[1,0]
	v_and_b32_e32 v101, 0x7fffffff, v93
	v_and_b32_e32 v100, 0x7fffffff, v92
	v_pk_fma_f32 v[100:101], v[100:101], s[26:27], 1.0 op_sel_hi:[1,0,0]
	v_pk_mul_f32 v[106:107], v[92:93], v[92:93]
	v_rcp_f32_e32 v100, v100
	v_rcp_f32_e32 v101, v101
	v_pk_mul_f32 v[106:107], v[106:107], s[40:41] op_sel_hi:[1,0]
	v_and_b32_e32 v109, 0x7fffffff, v95
	v_exp_f32_e32 v106, v106
	v_pk_fma_f32 v[104:105], v[100:101], s[28:29], v[102:103] op_sel_hi:[1,0,0]
	v_exp_f32_e32 v107, v107
	v_pk_fma_f32 v[104:105], v[100:101], v[104:105], s[34:35] op_sel_hi:[1,1,0]
	v_and_b32_e32 v108, 0x7fffffff, v94
	v_pk_fma_f32 v[104:105], v[100:101], v[104:105], s[36:37] op_sel_hi:[1,1,0]
	v_pk_fma_f32 v[108:109], v[108:109], s[26:27], 1.0 op_sel_hi:[1,0,0]
	v_pk_fma_f32 v[104:105], v[100:101], v[104:105], s[38:39] op_sel_hi:[1,1,0]
	v_rcp_f32_e32 v108, v108
	v_pk_mul_f32 v[100:101], v[100:101], v[104:105]
	v_rcp_f32_e32 v109, v109
	v_pk_mul_f32 v[100:101], v[106:107], v[100:101]
	v_cmp_gt_f32_e32 vcc, 0, v92
	v_pk_mul_f32 v[106:107], v[92:93], v[100:101]
	v_pk_fma_f32 v[100:101], v[92:93], v[100:101], v[92:93] neg_lo:[1,0,0] neg_hi:[1,0,0]
	v_pk_mul_f32 v[90:91], v[90:91], v[98:99] op_sel_hi:[1,0]
	v_pk_mul_f32 v[88:89], v[88:89], v[98:99] op_sel_hi:[1,0]
	v_pk_mul_f32 v[104:105], v[94:95], v[94:95]
	v_cndmask_b32_e32 v99, v100, v106, vcc
	v_cmp_gt_f32_e32 vcc, 0, v93
	v_pk_fma_f32 v[92:93], v[108:109], s[28:29], v[102:103] op_sel_hi:[1,0,0]
	v_lshlrev_b64 v[96:97], 12, v[160:161]
	v_cndmask_b32_e32 v106, v101, v107, vcc
	v_pk_mul_f32 v[100:101], v[104:105], s[40:41] op_sel_hi:[1,0]
	v_pk_fma_f32 v[92:93], v[108:109], v[92:93], s[34:35] op_sel_hi:[1,1,0]
	v_exp_f32_e32 v100, v100
	v_exp_f32_e32 v101, v101
	v_pk_fma_f32 v[92:93], v[108:109], v[92:93], s[36:37] op_sel_hi:[1,1,0]
	v_and_b32_e32 v105, 0x7fffffff, v89
	v_and_b32_e32 v104, 0x7fffffff, v88
	v_pk_fma_f32 v[92:93], v[108:109], v[92:93], s[38:39] op_sel_hi:[1,1,0]
	v_pk_fma_f32 v[104:105], v[104:105], s[26:27], 1.0 op_sel_hi:[1,0,0]
	v_pk_mul_f32 v[92:93], v[108:109], v[92:93]
	v_rcp_f32_e32 v104, v104
	v_rcp_f32_e32 v105, v105
	v_pk_mul_f32 v[92:93], v[100:101], v[92:93]
	v_cmp_gt_f32_e32 vcc, 0, v94
	v_pk_mul_f32 v[100:101], v[94:95], v[92:93]
	v_pk_fma_f32 v[92:93], v[94:95], v[92:93], v[94:95] neg_lo:[1,0,0] neg_hi:[1,0,0]
	v_lshl_add_u64 v[96:97], v[152:153], 0, v[96:97]
	v_cndmask_b32_e32 v107, v92, v100, vcc
	v_cmp_gt_f32_e32 vcc, 0, v95
	v_pk_mul_f32 v[94:95], v[88:89], v[88:89]
	s_nop 0
	v_cndmask_b32_e32 v108, v93, v101, vcc
	v_pk_fma_f32 v[92:93], v[104:105], s[28:29], v[102:103] op_sel_hi:[1,0,0]
	v_pk_mul_f32 v[94:95], v[94:95], s[40:41] op_sel_hi:[1,0]
	v_pk_fma_f32 v[92:93], v[104:105], v[92:93], s[34:35] op_sel_hi:[1,1,0]
	v_exp_f32_e32 v94, v94
	v_pk_fma_f32 v[92:93], v[104:105], v[92:93], s[36:37] op_sel_hi:[1,1,0]
	v_exp_f32_e32 v95, v95
	v_pk_fma_f32 v[92:93], v[104:105], v[92:93], s[38:39] op_sel_hi:[1,1,0]
	v_cmp_gt_f32_e32 vcc, 0, v88
	v_pk_mul_f32 v[92:93], v[104:105], v[92:93]
	v_and_b32_e32 v105, 0x7fffffff, v91
	v_and_b32_e32 v104, 0x7fffffff, v90
	v_pk_fma_f32 v[104:105], v[104:105], s[26:27], 1.0 op_sel_hi:[1,0,0]
	v_pk_mul_f32 v[92:93], v[94:95], v[92:93]
	v_rcp_f32_e32 v104, v104
	v_rcp_f32_e32 v105, v105
	v_pk_mul_f32 v[94:95], v[88:89], v[92:93]
	v_pk_fma_f32 v[92:93], v[88:89], v[92:93], v[88:89] neg_lo:[1,0,0] neg_hi:[1,0,0]
	v_pk_mul_f32 v[100:101], v[90:91], v[90:91]
	v_cndmask_b32_e32 v94, v92, v94, vcc
	v_cmp_gt_f32_e32 vcc, 0, v89
	v_pk_fma_f32 v[88:89], v[104:105], s[28:29], v[102:103] op_sel_hi:[1,0,0]
	s_nop 0
	v_cndmask_b32_e32 v95, v93, v95, vcc
	v_pk_mul_f32 v[92:93], v[100:101], s[40:41] op_sel_hi:[1,0]
	v_pk_fma_f32 v[88:89], v[104:105], v[88:89], s[34:35] op_sel_hi:[1,1,0]
	v_exp_f32_e32 v92, v92
	v_exp_f32_e32 v93, v93
	v_pk_fma_f32 v[88:89], v[104:105], v[88:89], s[36:37] op_sel_hi:[1,1,0]
	v_cmp_gt_f32_e32 vcc, 0, v90
	v_pk_fma_f32 v[88:89], v[104:105], v[88:89], s[38:39] op_sel_hi:[1,1,0]
	s_nop 0
	v_pk_mul_f32 v[88:89], v[104:105], v[88:89]
	s_nop 0
	v_pk_mul_f32 v[88:89], v[92:93], v[88:89]
	s_nop 0
	v_pk_mul_f32 v[92:93], v[90:91], v[88:89]
	v_pk_fma_f32 v[88:89], v[90:91], v[88:89], v[90:91] neg_lo:[1,0,0] neg_hi:[1,0,0]
	s_nop 0
	v_cndmask_b32_e32 v92, v88, v92, vcc
	v_cmp_gt_f32_e32 vcc, 0, v91
	v_cvt_pk_bf16_f32 v88, v99, v106
	s_nop 1
	v_cndmask_b32_e32 v91, v89, v93, vcc
	v_cvt_pk_bf16_f32 v89, v107, v108
	v_cvt_pk_bf16_f32 v90, v94, v95
	v_cvt_pk_bf16_f32 v91, v92, v91
	v_mov_b32_e32 v92, 0
	s_and_b64 vcc, exec, s[8:9]
	v_mov_b32_e32 v93, 0
	global_store_dwordx4 v[96:97], v[88:91], off sc1
	s_cbranch_vccnz .LBB0_237
	v_and_b32_e32 v93, 16, v88
	v_and_b32_e32 v92, 0xffff0000, v88
	v_lshlrev_b32_e32 v101, 16, v89
	v_lshlrev_b32_e32 v100, 16, v90
	v_and_b32_e32 v94, 0xffff0000, v89
	v_mov_b32_e32 v95, v92
	v_pk_mov_b32 v[106:107], v[100:101], v[92:93] op_sel:[1,0]
	v_lshlrev_b32_e32 v88, 16, v88
	v_and_b32_e32 v102, 0xffff0000, v91
	v_mov_b32_e32 v103, v94
	v_and_b32_e32 v90, 0xffff0000, v90
	v_lshlrev_b32_e32 v104, 16, v91
	v_mov_b32_e32 v91, v101
	v_mov_b32_e32 v89, v94
	v_mov_b32_e32 v105, v94
	v_pk_add_f32 v[108:109], v[94:95], v[106:107]
	v_pk_mul_f32 v[94:95], v[94:95], v[106:107]
	v_pk_add_f32 v[92:93], v[88:89], v[92:93] op_sel_hi:[0,1]
	v_mov_b32_e32 v109, v95
	v_pk_add_f32 v[94:95], v[100:101], v[90:91]
	v_pk_mul_f32 v[106:107], v[100:101], v[100:101]
	v_mov_b32_e32 v91, v102
	v_mul_f32_e32 v93, v88, v88
	v_mov_b32_e32 v95, v107
	v_pk_add_f32 v[106:107], v[102:103], v[104:105]
	v_pk_mul_f32 v[88:89], v[102:103], v[88:89]
	v_mov_b32_e32 v101, v104
	v_pk_mul_f32 v[90:91], v[90:91], v[90:91]
	v_mov_b32_e32 v107, v89
	v_pk_fma_f32 v[90:91], v[100:101], v[100:101], v[90:91]
	v_pk_add_f32 v[92:93], v[92:93], v[108:109]
	v_pk_add_f32 v[88:89], v[94:95], v[106:107]
	v_pk_add_f32 v[90:91], v[90:91], v[90:91] op_sel_hi:[0,1]
	v_pk_add_f32 v[88:89], v[92:93], v[88:89]
	v_mov_b32_e32 v137, v91
	v_pk_add_f32 v[92:93], v[88:89], v[136:137]
.LBB0_237:
	v_mov_b32_e32 v99, v98
	v_pk_mul_f32 v[84:85], v[84:85], v[98:99]
	v_mov_b32_e32 v88, v98
	v_and_b32_e32 v91, 0x7fffffff, v85
	v_and_b32_e32 v90, 0x7fffffff, v84
	v_pk_fma_f32 v[90:91], v[90:91], s[26:27], 1.0 op_sel_hi:[1,0,0]
	v_mov_b32_e32 v89, v98
	v_rcp_f32_e32 v90, v90
	v_rcp_f32_e32 v91, v91
	v_pk_mul_f32 v[86:87], v[86:87], v[88:89]
	v_pk_mul_f32 v[82:83], v[82:83], v[88:89]
	v_pk_mul_f32 v[80:81], v[80:81], v[98:99]
	v_mov_b64_e32 v[88:89], s[30:31]
	v_pk_mul_f32 v[98:99], v[84:85], v[84:85]
	v_pk_fma_f32 v[94:95], v[90:91], s[28:29], v[88:89] op_sel_hi:[1,0,0]
	v_pk_mul_f32 v[98:99], v[98:99], s[40:41] op_sel_hi:[1,0]
	v_pk_fma_f32 v[94:95], v[90:91], v[94:95], s[34:35] op_sel_hi:[1,1,0]
	v_exp_f32_e32 v98, v98
	v_exp_f32_e32 v99, v99
	v_pk_fma_f32 v[94:95], v[90:91], v[94:95], s[36:37] op_sel_hi:[1,1,0]
	v_and_b32_e32 v101, 0x7fffffff, v87
	v_and_b32_e32 v100, 0x7fffffff, v86
	v_pk_fma_f32 v[94:95], v[90:91], v[94:95], s[38:39] op_sel_hi:[1,1,0]
	v_pk_fma_f32 v[100:101], v[100:101], s[26:27], 1.0 op_sel_hi:[1,0,0]
	v_pk_mul_f32 v[90:91], v[90:91], v[94:95]
	v_rcp_f32_e32 v100, v100
	v_rcp_f32_e32 v101, v101
	v_pk_mul_f32 v[90:91], v[98:99], v[90:91]
	v_cmp_gt_f32_e32 vcc, 0, v84
	v_pk_mul_f32 v[98:99], v[84:85], v[90:91]
	v_pk_fma_f32 v[90:91], v[84:85], v[90:91], v[84:85] neg_lo:[1,0,0] neg_hi:[1,0,0]
	v_pk_mul_f32 v[94:95], v[86:87], v[86:87]
	v_cndmask_b32_e32 v98, v90, v98, vcc
	v_cmp_gt_f32_e32 vcc, 0, v85
	v_pk_fma_f32 v[84:85], v[100:101], s[28:29], v[88:89] op_sel_hi:[1,0,0]
	s_nop 0
	v_cndmask_b32_e32 v99, v91, v99, vcc
	v_pk_mul_f32 v[90:91], v[94:95], s[40:41] op_sel_hi:[1,0]
	v_pk_fma_f32 v[84:85], v[100:101], v[84:85], s[34:35] op_sel_hi:[1,1,0]
	v_exp_f32_e32 v90, v90
	v_exp_f32_e32 v91, v91
	v_pk_fma_f32 v[84:85], v[100:101], v[84:85], s[36:37] op_sel_hi:[1,1,0]
	v_and_b32_e32 v95, 0x7fffffff, v81
	v_and_b32_e32 v94, 0x7fffffff, v80
	v_pk_fma_f32 v[84:85], v[100:101], v[84:85], s[38:39] op_sel_hi:[1,1,0]
	v_pk_fma_f32 v[94:95], v[94:95], s[26:27], 1.0 op_sel_hi:[1,0,0]
	v_pk_mul_f32 v[84:85], v[100:101], v[84:85]
	v_rcp_f32_e32 v94, v94
	v_rcp_f32_e32 v95, v95
	v_pk_mul_f32 v[84:85], v[90:91], v[84:85]
	v_cmp_gt_f32_e32 vcc, 0, v86
	v_pk_mul_f32 v[90:91], v[86:87], v[84:85]
	v_pk_fma_f32 v[84:85], v[86:87], v[84:85], v[86:87] neg_lo:[1,0,0] neg_hi:[1,0,0]
	s_nop 0
	v_cndmask_b32_e32 v100, v84, v90, vcc
	v_cmp_gt_f32_e32 vcc, 0, v87
	v_pk_mul_f32 v[86:87], v[80:81], v[80:81]
	s_nop 0
	v_cndmask_b32_e32 v101, v85, v91, vcc
	v_pk_fma_f32 v[84:85], v[94:95], s[28:29], v[88:89] op_sel_hi:[1,0,0]
	v_pk_mul_f32 v[86:87], v[86:87], s[40:41] op_sel_hi:[1,0]
	v_pk_fma_f32 v[84:85], v[94:95], v[84:85], s[34:35] op_sel_hi:[1,1,0]
	v_exp_f32_e32 v86, v86
	v_pk_fma_f32 v[84:85], v[94:95], v[84:85], s[36:37] op_sel_hi:[1,1,0]
	v_exp_f32_e32 v87, v87
	v_pk_fma_f32 v[84:85], v[94:95], v[84:85], s[38:39] op_sel_hi:[1,1,0]
	v_cmp_gt_f32_e32 vcc, 0, v80
	v_pk_mul_f32 v[84:85], v[94:95], v[84:85]
	v_and_b32_e32 v95, 0x7fffffff, v83
	v_and_b32_e32 v94, 0x7fffffff, v82
	v_pk_fma_f32 v[94:95], v[94:95], s[26:27], 1.0 op_sel_hi:[1,0,0]
	v_pk_mul_f32 v[84:85], v[86:87], v[84:85]
	v_rcp_f32_e32 v94, v94
	v_rcp_f32_e32 v95, v95
	v_pk_mul_f32 v[86:87], v[80:81], v[84:85]
	v_pk_fma_f32 v[84:85], v[80:81], v[84:85], v[80:81] neg_lo:[1,0,0] neg_hi:[1,0,0]
	v_pk_mul_f32 v[90:91], v[82:83], v[82:83]
	v_cndmask_b32_e32 v86, v84, v86, vcc
	v_cmp_gt_f32_e32 vcc, 0, v81
	v_pk_fma_f32 v[80:81], v[94:95], s[28:29], v[88:89] op_sel_hi:[1,0,0]
	s_nop 0
	v_cndmask_b32_e32 v87, v85, v87, vcc
	v_pk_mul_f32 v[84:85], v[90:91], s[40:41] op_sel_hi:[1,0]
	v_pk_fma_f32 v[80:81], v[94:95], v[80:81], s[34:35] op_sel_hi:[1,1,0]
	v_exp_f32_e32 v84, v84
	v_exp_f32_e32 v85, v85
	v_pk_fma_f32 v[80:81], v[94:95], v[80:81], s[36:37] op_sel_hi:[1,1,0]
	v_cmp_gt_f32_e32 vcc, 0, v82
	v_pk_fma_f32 v[80:81], v[94:95], v[80:81], s[38:39] op_sel_hi:[1,1,0]
	s_nop 0
	v_pk_mul_f32 v[80:81], v[94:95], v[80:81]
	s_nop 0
	v_pk_mul_f32 v[80:81], v[84:85], v[80:81]
	s_nop 0
	v_pk_mul_f32 v[84:85], v[82:83], v[80:81]
	v_pk_fma_f32 v[80:81], v[82:83], v[80:81], v[82:83] neg_lo:[1,0,0] neg_hi:[1,0,0]
	s_nop 0
	v_cndmask_b32_e32 v84, v80, v84, vcc
	v_cmp_gt_f32_e32 vcc, 0, v83
	v_cvt_pk_bf16_f32 v80, v98, v99
	s_nop 1
	v_cndmask_b32_e32 v83, v81, v85, vcc
	s_and_b64 vcc, exec, s[8:9]
	v_cvt_pk_bf16_f32 v81, v100, v101
	v_cvt_pk_bf16_f32 v82, v86, v87
	v_cvt_pk_bf16_f32 v83, v84, v83
	global_store_dwordx4 v[96:97], v[80:83], off offset:256 sc1
	s_cbranch_vccnz .LBB0_241
	v_lshlrev_b32_e32 v84, 16, v80
	v_and_b32_e32 v80, 0xffff0000, v80
	v_lshlrev_b32_e32 v86, 16, v81
	v_and_b32_e32 v88, 0xffff0000, v81
	v_lshlrev_b32_e32 v90, 16, v82
	v_and_b32_e32 v82, 0xffff0000, v82
	v_lshlrev_b32_e32 v94, 16, v83
	v_and_b32_e32 v96, 0xffff0000, v83
	v_mul_f32_e32 v85, v84, v84
	v_mul_f32_e32 v81, v80, v80
	v_mul_f32_e32 v87, v86, v86
	v_mul_f32_e32 v89, v88, v88
	v_mul_f32_e32 v91, v90, v90
	v_mul_f32_e32 v83, v82, v82
	v_mul_f32_e32 v95, v94, v94
	v_mul_f32_e32 v97, v96, v96
	v_pk_add_f32 v[80:81], v[84:85], v[80:81]
	v_pk_add_f32 v[84:85], v[86:87], v[88:89]
	v_pk_add_f32 v[82:83], v[90:91], v[82:83]
	v_pk_add_f32 v[80:81], v[80:81], v[84:85]
	v_pk_add_f32 v[84:85], v[94:95], v[96:97]
	s_nop 0
	v_pk_add_f32 v[82:83], v[82:83], v[84:85]
	s_nop 0
	v_pk_add_f32 v[80:81], v[80:81], v[82:83]
	s_nop 0
	v_pk_add_f32 v[80:81], v[92:93], v[80:81]
	ds_bpermute_b32 v82, v180, v80
	ds_bpermute_b32 v83, v180, v81
	s_waitcnt lgkmcnt(0)
	v_pk_add_f32 v[80:81], v[80:81], v[82:83]
	ds_bpermute_b32 v82, v179, v80
	ds_bpermute_b32 v83, v179, v81
	s_and_saveexec_b64 s[10:11], s[4:5]
	s_cbranch_execz .LBB0_240
	v_lshlrev_b64 v[84:85], 8, v[160:161]
	v_lshl_add_u64 v[84:85], s[16:17], 0, v[84:85]
	v_lshl_add_u64 v[84:85], s[50:51], 2, v[84:85]
	s_waitcnt lgkmcnt(0)
	v_pk_add_f32 v[80:81], v[80:81], v[82:83]
	global_store_dwordx2 v[84:85], v[80:81], off

.LBB0_241:
	s_nop 0
	v_add_f32_e32 v80, v189, v190
	v_fmamk_f32 v80, v80, 0x3a800000, v177
	v_mul_f32_e32 v81, 0x4f800000, v80
	v_cmp_gt_f32_e32 vcc, s65, v80
	v_mov_b64_e32 v[86:87], s[30:31]
	s_nop 0
	v_cndmask_b32_e32 v80, v80, v81, vcc
	v_sqrt_f32_e32 v81, v80
	s_waitcnt lgkmcnt(1)
	v_add_u32_e32 v82, -1, v81
	v_fma_f32 v84, -v82, v81, v80
	s_waitcnt lgkmcnt(0)
	v_add_u32_e32 v83, 1, v81
	v_cmp_ge_f32_e64 s[10:11], 0, v84
	s_nop 1
	v_cndmask_b32_e64 v82, v81, v82, s[10:11]
	v_fma_f32 v81, -v83, v81, v80
	v_cmp_lt_f32_e64 s[10:11], 0, v81
	s_nop 1
	v_cndmask_b32_e64 v81, v82, v83, s[10:11]
	v_mul_f32_e32 v82, 0x37800000, v81
	v_cndmask_b32_e32 v81, v81, v82, vcc
	v_cmp_class_f32_e32 vcc, v80, v178
	s_nop 1
	v_cndmask_b32_e32 v80, v81, v80, vcc
	v_div_scale_f32 v81, s[10:11], v80, v80, 1.0
	v_rcp_f32_e32 v82, v81
	s_nop 0
	v_fma_f32 v83, -v81, v82, 1.0
	v_fmac_f32_e32 v82, v83, v82
	v_div_scale_f32 v83, vcc, 1.0, v80, 1.0
	v_mul_f32_e32 v84, v83, v82
	v_fma_f32 v85, -v81, v84, v83
	v_fmac_f32_e32 v84, v85, v82
	v_fma_f32 v81, -v81, v84, v83
	v_div_fmas_f32 v81, v81, v82, v84
	v_div_fixup_f32 v82, v81, v80, 1.0
	v_pk_mul_f32 v[76:77], v[76:77], v[82:83] op_sel_hi:[1,0]
	v_pk_mul_f32 v[78:79], v[78:79], v[82:83] op_sel_hi:[1,0]
	v_and_b32_e32 v85, 0x7fffffff, v77
	v_and_b32_e32 v84, 0x7fffffff, v76
	v_pk_fma_f32 v[84:85], v[84:85], s[26:27], 1.0 op_sel_hi:[1,0,0]
	v_pk_mul_f32 v[90:91], v[76:77], v[76:77]
	v_rcp_f32_e32 v84, v84
	v_rcp_f32_e32 v85, v85
	v_pk_mul_f32 v[90:91], v[90:91], s[40:41] op_sel_hi:[1,0]
	v_and_b32_e32 v93, 0x7fffffff, v79
	v_exp_f32_e32 v90, v90
	v_pk_fma_f32 v[88:89], v[84:85], s[28:29], v[86:87] op_sel_hi:[1,0,0]
	v_exp_f32_e32 v91, v91
	v_pk_fma_f32 v[88:89], v[84:85], v[88:89], s[34:35] op_sel_hi:[1,1,0]
	v_and_b32_e32 v92, 0x7fffffff, v78
	v_pk_fma_f32 v[88:89], v[84:85], v[88:89], s[36:37] op_sel_hi:[1,1,0]
	v_pk_fma_f32 v[92:93], v[92:93], s[26:27], 1.0 op_sel_hi:[1,0,0]
	v_pk_fma_f32 v[88:89], v[84:85], v[88:89], s[38:39] op_sel_hi:[1,1,0]
	v_rcp_f32_e32 v92, v92
	v_pk_mul_f32 v[84:85], v[84:85], v[88:89]
	v_rcp_f32_e32 v93, v93
	v_pk_mul_f32 v[84:85], v[90:91], v[84:85]
	v_cmp_gt_f32_e32 vcc, 0, v76
	v_pk_mul_f32 v[90:91], v[76:77], v[84:85]
	v_pk_fma_f32 v[84:85], v[76:77], v[84:85], v[76:77] neg_lo:[1,0,0] neg_hi:[1,0,0]
	v_pk_mul_f32 v[74:75], v[74:75], v[82:83] op_sel_hi:[1,0]
	v_pk_mul_f32 v[72:73], v[72:73], v[82:83] op_sel_hi:[1,0]
	v_pk_mul_f32 v[88:89], v[78:79], v[78:79]
	v_cndmask_b32_e32 v83, v84, v90, vcc
	v_cmp_gt_f32_e32 vcc, 0, v77
	v_pk_fma_f32 v[76:77], v[92:93], s[28:29], v[86:87] op_sel_hi:[1,0,0]
	v_lshlrev_b64 v[80:81], 12, v[158:159]
	v_cndmask_b32_e32 v90, v85, v91, vcc
	v_pk_mul_f32 v[84:85], v[88:89], s[40:41] op_sel_hi:[1,0]
	v_pk_fma_f32 v[76:77], v[92:93], v[76:77], s[34:35] op_sel_hi:[1,1,0]
	v_exp_f32_e32 v84, v84
	v_exp_f32_e32 v85, v85
	v_pk_fma_f32 v[76:77], v[92:93], v[76:77], s[36:37] op_sel_hi:[1,1,0]
	v_and_b32_e32 v89, 0x7fffffff, v73
	v_and_b32_e32 v88, 0x7fffffff, v72
	v_pk_fma_f32 v[76:77], v[92:93], v[76:77], s[38:39] op_sel_hi:[1,1,0]
	v_pk_fma_f32 v[88:89], v[88:89], s[26:27], 1.0 op_sel_hi:[1,0,0]
	v_pk_mul_f32 v[76:77], v[92:93], v[76:77]
	v_rcp_f32_e32 v88, v88
	v_rcp_f32_e32 v89, v89
	v_pk_mul_f32 v[76:77], v[84:85], v[76:77]
	v_cmp_gt_f32_e32 vcc, 0, v78
	v_pk_mul_f32 v[84:85], v[78:79], v[76:77]
	v_pk_fma_f32 v[76:77], v[78:79], v[76:77], v[78:79] neg_lo:[1,0,0] neg_hi:[1,0,0]
	v_lshl_add_u64 v[80:81], v[152:153], 0, v[80:81]
	v_cndmask_b32_e32 v91, v76, v84, vcc
	v_cmp_gt_f32_e32 vcc, 0, v79
	v_pk_mul_f32 v[78:79], v[72:73], v[72:73]
	s_nop 0
	v_cndmask_b32_e32 v92, v77, v85, vcc
	v_pk_fma_f32 v[76:77], v[88:89], s[28:29], v[86:87] op_sel_hi:[1,0,0]
	v_pk_mul_f32 v[78:79], v[78:79], s[40:41] op_sel_hi:[1,0]
	v_pk_fma_f32 v[76:77], v[88:89], v[76:77], s[34:35] op_sel_hi:[1,1,0]
	v_exp_f32_e32 v78, v78
	v_pk_fma_f32 v[76:77], v[88:89], v[76:77], s[36:37] op_sel_hi:[1,1,0]
	v_exp_f32_e32 v79, v79
	v_pk_fma_f32 v[76:77], v[88:89], v[76:77], s[38:39] op_sel_hi:[1,1,0]
	v_cmp_gt_f32_e32 vcc, 0, v72
	v_pk_mul_f32 v[76:77], v[88:89], v[76:77]
	v_and_b32_e32 v89, 0x7fffffff, v75
	v_and_b32_e32 v88, 0x7fffffff, v74
	v_pk_fma_f32 v[88:89], v[88:89], s[26:27], 1.0 op_sel_hi:[1,0,0]
	v_pk_mul_f32 v[76:77], v[78:79], v[76:77]
	v_rcp_f32_e32 v88, v88
	v_rcp_f32_e32 v89, v89
	v_pk_mul_f32 v[78:79], v[72:73], v[76:77]
	v_pk_fma_f32 v[76:77], v[72:73], v[76:77], v[72:73] neg_lo:[1,0,0] neg_hi:[1,0,0]
	v_pk_mul_f32 v[84:85], v[74:75], v[74:75]
	v_cndmask_b32_e32 v78, v76, v78, vcc
	v_cmp_gt_f32_e32 vcc, 0, v73
	v_pk_fma_f32 v[72:73], v[88:89], s[28:29], v[86:87] op_sel_hi:[1,0,0]
	s_nop 0
	v_cndmask_b32_e32 v79, v77, v79, vcc
	v_pk_mul_f32 v[76:77], v[84:85], s[40:41] op_sel_hi:[1,0]
	v_pk_fma_f32 v[72:73], v[88:89], v[72:73], s[34:35] op_sel_hi:[1,1,0]
	v_exp_f32_e32 v76, v76
	v_exp_f32_e32 v77, v77
	v_pk_fma_f32 v[72:73], v[88:89], v[72:73], s[36:37] op_sel_hi:[1,1,0]
	v_cmp_gt_f32_e32 vcc, 0, v74
	v_pk_fma_f32 v[72:73], v[88:89], v[72:73], s[38:39] op_sel_hi:[1,1,0]
	s_nop 0
	v_pk_mul_f32 v[72:73], v[88:89], v[72:73]
	s_nop 0
	v_pk_mul_f32 v[72:73], v[76:77], v[72:73]
	s_nop 0
	v_pk_mul_f32 v[76:77], v[74:75], v[72:73]
	v_pk_fma_f32 v[72:73], v[74:75], v[72:73], v[74:75] neg_lo:[1,0,0] neg_hi:[1,0,0]
	s_nop 0
	v_cndmask_b32_e32 v76, v72, v76, vcc
	v_cmp_gt_f32_e32 vcc, 0, v75
	v_cvt_pk_bf16_f32 v72, v83, v90
	s_nop 1
	v_cndmask_b32_e32 v75, v73, v77, vcc
	v_cvt_pk_bf16_f32 v73, v91, v92
	v_cvt_pk_bf16_f32 v74, v78, v79
	v_cvt_pk_bf16_f32 v75, v76, v75
	v_mov_b32_e32 v76, 0
	s_and_b64 vcc, exec, s[8:9]
	v_mov_b32_e32 v77, 0
	global_store_dwordx4 v[80:81], v[72:75], off sc1
	s_cbranch_vccnz .LBB0_243
	v_and_b32_e32 v77, 16, v72
	v_and_b32_e32 v76, 0xffff0000, v72
	v_lshlrev_b32_e32 v85, 16, v73
	v_lshlrev_b32_e32 v84, 16, v74
	v_and_b32_e32 v78, 0xffff0000, v73
	v_mov_b32_e32 v79, v76
	v_pk_mov_b32 v[90:91], v[84:85], v[76:77] op_sel:[1,0]
	v_lshlrev_b32_e32 v72, 16, v72
	v_and_b32_e32 v86, 0xffff0000, v75
	v_mov_b32_e32 v87, v78
	v_and_b32_e32 v74, 0xffff0000, v74
	v_lshlrev_b32_e32 v88, 16, v75
	v_mov_b32_e32 v75, v85
	v_mov_b32_e32 v73, v78
	v_mov_b32_e32 v89, v78
	v_pk_add_f32 v[92:93], v[78:79], v[90:91]
	v_pk_mul_f32 v[78:79], v[78:79], v[90:91]
	v_pk_add_f32 v[76:77], v[72:73], v[76:77] op_sel_hi:[0,1]
	v_mov_b32_e32 v93, v79
	v_pk_add_f32 v[78:79], v[84:85], v[74:75]
	v_pk_mul_f32 v[90:91], v[84:85], v[84:85]
	v_mov_b32_e32 v75, v86
	v_mul_f32_e32 v77, v72, v72
	v_mov_b32_e32 v79, v91
	v_pk_add_f32 v[90:91], v[86:87], v[88:89]
	v_pk_mul_f32 v[72:73], v[86:87], v[72:73]
	v_mov_b32_e32 v85, v88
	v_pk_mul_f32 v[74:75], v[74:75], v[74:75]
	v_mov_b32_e32 v91, v73
	v_pk_fma_f32 v[74:75], v[84:85], v[84:85], v[74:75]
	v_pk_add_f32 v[76:77], v[76:77], v[92:93]
	v_pk_add_f32 v[72:73], v[78:79], v[90:91]
	v_pk_add_f32 v[74:75], v[74:75], v[74:75] op_sel_hi:[0,1]
	v_pk_add_f32 v[72:73], v[76:77], v[72:73]
	v_mov_b32_e32 v137, v75
	v_pk_add_f32 v[76:77], v[72:73], v[136:137]
.LBB0_243:
	v_mov_b32_e32 v83, v82
	v_pk_mul_f32 v[68:69], v[68:69], v[82:83]
	v_mov_b32_e32 v72, v82
	v_and_b32_e32 v75, 0x7fffffff, v69
	v_and_b32_e32 v74, 0x7fffffff, v68
	v_pk_fma_f32 v[74:75], v[74:75], s[26:27], 1.0 op_sel_hi:[1,0,0]
	v_mov_b32_e32 v73, v82
	v_rcp_f32_e32 v74, v74
	v_rcp_f32_e32 v75, v75
	v_pk_mul_f32 v[70:71], v[70:71], v[72:73]
	v_pk_mul_f32 v[66:67], v[66:67], v[72:73]
	v_pk_mul_f32 v[64:65], v[64:65], v[82:83]
	v_mov_b64_e32 v[72:73], s[30:31]
	v_pk_mul_f32 v[82:83], v[68:69], v[68:69]
	v_pk_fma_f32 v[78:79], v[74:75], s[28:29], v[72:73] op_sel_hi:[1,0,0]
	v_pk_mul_f32 v[82:83], v[82:83], s[40:41] op_sel_hi:[1,0]
	v_pk_fma_f32 v[78:79], v[74:75], v[78:79], s[34:35] op_sel_hi:[1,1,0]
	v_exp_f32_e32 v82, v82
	v_exp_f32_e32 v83, v83
	v_pk_fma_f32 v[78:79], v[74:75], v[78:79], s[36:37] op_sel_hi:[1,1,0]
	v_and_b32_e32 v85, 0x7fffffff, v71
	v_and_b32_e32 v84, 0x7fffffff, v70
	v_pk_fma_f32 v[78:79], v[74:75], v[78:79], s[38:39] op_sel_hi:[1,1,0]
	v_pk_fma_f32 v[84:85], v[84:85], s[26:27], 1.0 op_sel_hi:[1,0,0]
	v_pk_mul_f32 v[74:75], v[74:75], v[78:79]
	v_rcp_f32_e32 v84, v84
	v_rcp_f32_e32 v85, v85
	v_pk_mul_f32 v[74:75], v[82:83], v[74:75]
	v_cmp_gt_f32_e32 vcc, 0, v68
	v_pk_mul_f32 v[82:83], v[68:69], v[74:75]
	v_pk_fma_f32 v[74:75], v[68:69], v[74:75], v[68:69] neg_lo:[1,0,0] neg_hi:[1,0,0]
	v_pk_mul_f32 v[78:79], v[70:71], v[70:71]
	v_cndmask_b32_e32 v82, v74, v82, vcc
	v_cmp_gt_f32_e32 vcc, 0, v69
	v_pk_fma_f32 v[68:69], v[84:85], s[28:29], v[72:73] op_sel_hi:[1,0,0]
	s_nop 0
	v_cndmask_b32_e32 v83, v75, v83, vcc
	v_pk_mul_f32 v[74:75], v[78:79], s[40:41] op_sel_hi:[1,0]
	v_pk_fma_f32 v[68:69], v[84:85], v[68:69], s[34:35] op_sel_hi:[1,1,0]
	v_exp_f32_e32 v74, v74
	v_exp_f32_e32 v75, v75
	v_pk_fma_f32 v[68:69], v[84:85], v[68:69], s[36:37] op_sel_hi:[1,1,0]
	v_and_b32_e32 v79, 0x7fffffff, v65
	v_and_b32_e32 v78, 0x7fffffff, v64
	v_pk_fma_f32 v[68:69], v[84:85], v[68:69], s[38:39] op_sel_hi:[1,1,0]
	v_pk_fma_f32 v[78:79], v[78:79], s[26:27], 1.0 op_sel_hi:[1,0,0]
	v_pk_mul_f32 v[68:69], v[84:85], v[68:69]
	v_rcp_f32_e32 v78, v78
	v_rcp_f32_e32 v79, v79
	v_pk_mul_f32 v[68:69], v[74:75], v[68:69]
	v_cmp_gt_f32_e32 vcc, 0, v70
	v_pk_mul_f32 v[74:75], v[70:71], v[68:69]
	v_pk_fma_f32 v[68:69], v[70:71], v[68:69], v[70:71] neg_lo:[1,0,0] neg_hi:[1,0,0]
	s_nop 0
	v_cndmask_b32_e32 v84, v68, v74, vcc
	v_cmp_gt_f32_e32 vcc, 0, v71
	v_pk_mul_f32 v[70:71], v[64:65], v[64:65]
	s_nop 0
	v_cndmask_b32_e32 v85, v69, v75, vcc
	v_pk_fma_f32 v[68:69], v[78:79], s[28:29], v[72:73] op_sel_hi:[1,0,0]
	v_pk_mul_f32 v[70:71], v[70:71], s[40:41] op_sel_hi:[1,0]
	v_pk_fma_f32 v[68:69], v[78:79], v[68:69], s[34:35] op_sel_hi:[1,1,0]
	v_exp_f32_e32 v70, v70
	v_pk_fma_f32 v[68:69], v[78:79], v[68:69], s[36:37] op_sel_hi:[1,1,0]
	v_exp_f32_e32 v71, v71
	v_pk_fma_f32 v[68:69], v[78:79], v[68:69], s[38:39] op_sel_hi:[1,1,0]
	v_cmp_gt_f32_e32 vcc, 0, v64
	v_pk_mul_f32 v[68:69], v[78:79], v[68:69]
	v_and_b32_e32 v79, 0x7fffffff, v67
	v_and_b32_e32 v78, 0x7fffffff, v66
	v_pk_fma_f32 v[78:79], v[78:79], s[26:27], 1.0 op_sel_hi:[1,0,0]
	v_pk_mul_f32 v[68:69], v[70:71], v[68:69]
	v_rcp_f32_e32 v78, v78
	v_rcp_f32_e32 v79, v79
	v_pk_mul_f32 v[70:71], v[64:65], v[68:69]
	v_pk_fma_f32 v[68:69], v[64:65], v[68:69], v[64:65] neg_lo:[1,0,0] neg_hi:[1,0,0]
	v_pk_mul_f32 v[74:75], v[66:67], v[66:67]
	v_cndmask_b32_e32 v70, v68, v70, vcc
	v_cmp_gt_f32_e32 vcc, 0, v65
	v_pk_fma_f32 v[64:65], v[78:79], s[28:29], v[72:73] op_sel_hi:[1,0,0]
	s_nop 0
	v_cndmask_b32_e32 v71, v69, v71, vcc
	v_pk_mul_f32 v[68:69], v[74:75], s[40:41] op_sel_hi:[1,0]
	v_pk_fma_f32 v[64:65], v[78:79], v[64:65], s[34:35] op_sel_hi:[1,1,0]
	v_exp_f32_e32 v68, v68
	v_exp_f32_e32 v69, v69
	v_pk_fma_f32 v[64:65], v[78:79], v[64:65], s[36:37] op_sel_hi:[1,1,0]
	v_cmp_gt_f32_e32 vcc, 0, v66
	v_pk_fma_f32 v[64:65], v[78:79], v[64:65], s[38:39] op_sel_hi:[1,1,0]
	s_nop 0
	v_pk_mul_f32 v[64:65], v[78:79], v[64:65]
	s_nop 0
	v_pk_mul_f32 v[64:65], v[68:69], v[64:65]
	s_nop 0
	v_pk_mul_f32 v[68:69], v[66:67], v[64:65]
	v_pk_fma_f32 v[64:65], v[66:67], v[64:65], v[66:67] neg_lo:[1,0,0] neg_hi:[1,0,0]
	s_nop 0
	v_cndmask_b32_e32 v68, v64, v68, vcc
	v_cmp_gt_f32_e32 vcc, 0, v67
	v_cvt_pk_bf16_f32 v64, v82, v83
	s_nop 1
	v_cndmask_b32_e32 v67, v65, v69, vcc
	s_and_b64 vcc, exec, s[8:9]
	v_cvt_pk_bf16_f32 v65, v84, v85
	v_cvt_pk_bf16_f32 v66, v70, v71
	v_cvt_pk_bf16_f32 v67, v68, v67
	global_store_dwordx4 v[80:81], v[64:67], off offset:256 sc1
	s_cbranch_vccnz .LBB0_247
	v_lshlrev_b32_e32 v68, 16, v64
	v_and_b32_e32 v64, 0xffff0000, v64
	v_lshlrev_b32_e32 v70, 16, v65
	v_and_b32_e32 v72, 0xffff0000, v65
	v_lshlrev_b32_e32 v74, 16, v66
	v_and_b32_e32 v66, 0xffff0000, v66
	v_lshlrev_b32_e32 v78, 16, v67
	v_and_b32_e32 v80, 0xffff0000, v67
	v_mul_f32_e32 v69, v68, v68
	v_mul_f32_e32 v65, v64, v64
	v_mul_f32_e32 v71, v70, v70
	v_mul_f32_e32 v73, v72, v72
	v_mul_f32_e32 v75, v74, v74
	v_mul_f32_e32 v67, v66, v66
	v_mul_f32_e32 v79, v78, v78
	v_mul_f32_e32 v81, v80, v80
	v_pk_add_f32 v[64:65], v[68:69], v[64:65]
	v_pk_add_f32 v[68:69], v[70:71], v[72:73]
	v_pk_add_f32 v[66:67], v[74:75], v[66:67]
	v_pk_add_f32 v[64:65], v[64:65], v[68:69]
	v_pk_add_f32 v[68:69], v[78:79], v[80:81]
	s_nop 0
	v_pk_add_f32 v[66:67], v[66:67], v[68:69]
	s_nop 0
	v_pk_add_f32 v[64:65], v[64:65], v[66:67]
	s_nop 0
	v_pk_add_f32 v[64:65], v[76:77], v[64:65]
	ds_bpermute_b32 v66, v180, v64
	ds_bpermute_b32 v67, v180, v65
	s_waitcnt lgkmcnt(0)
	v_pk_add_f32 v[64:65], v[64:65], v[66:67]
	ds_bpermute_b32 v66, v179, v64
	ds_bpermute_b32 v67, v179, v65
	s_and_saveexec_b64 s[10:11], s[4:5]
	s_cbranch_execz .LBB0_246
	v_lshlrev_b64 v[68:69], 8, v[158:159]
	v_lshl_add_u64 v[68:69], s[16:17], 0, v[68:69]
	v_lshl_add_u64 v[68:69], s[50:51], 2, v[68:69]
	s_waitcnt lgkmcnt(0)
	v_pk_add_f32 v[64:65], v[64:65], v[66:67]
	global_store_dwordx2 v[68:69], v[64:65], off

.LBB0_247:
	s_nop 0
	v_add_f32_e32 v64, v187, v188
	v_fmamk_f32 v64, v64, 0x3a800000, v177
	v_mul_f32_e32 v65, 0x4f800000, v64
	v_cmp_gt_f32_e32 vcc, s65, v64
	v_mov_b64_e32 v[70:71], s[30:31]
	s_nop 0
	v_cndmask_b32_e32 v64, v64, v65, vcc
	v_sqrt_f32_e32 v65, v64
	s_waitcnt lgkmcnt(1)
	v_add_u32_e32 v66, -1, v65
	v_fma_f32 v68, -v66, v65, v64
	s_waitcnt lgkmcnt(0)
	v_add_u32_e32 v67, 1, v65
	v_cmp_ge_f32_e64 s[10:11], 0, v68
	s_nop 1
	v_cndmask_b32_e64 v66, v65, v66, s[10:11]
	v_fma_f32 v65, -v67, v65, v64
	v_cmp_lt_f32_e64 s[10:11], 0, v65
	s_nop 1
	v_cndmask_b32_e64 v65, v66, v67, s[10:11]
	v_mul_f32_e32 v66, 0x37800000, v65
	v_cndmask_b32_e32 v65, v65, v66, vcc
	v_cmp_class_f32_e32 vcc, v64, v178
	s_nop 1
	v_cndmask_b32_e32 v64, v65, v64, vcc
	v_div_scale_f32 v65, s[10:11], v64, v64, 1.0
	v_rcp_f32_e32 v66, v65
	s_nop 0
	v_fma_f32 v67, -v65, v66, 1.0
	v_fmac_f32_e32 v66, v67, v66
	v_div_scale_f32 v67, vcc, 1.0, v64, 1.0
	v_mul_f32_e32 v68, v67, v66
	v_fma_f32 v69, -v65, v68, v67
	v_fmac_f32_e32 v68, v69, v66
	v_fma_f32 v65, -v65, v68, v67
	v_div_fmas_f32 v65, v65, v66, v68
	v_div_fixup_f32 v66, v65, v64, 1.0
	v_pk_mul_f32 v[60:61], v[60:61], v[66:67] op_sel_hi:[1,0]
	v_pk_mul_f32 v[62:63], v[62:63], v[66:67] op_sel_hi:[1,0]
	v_and_b32_e32 v69, 0x7fffffff, v61
	v_and_b32_e32 v68, 0x7fffffff, v60
	v_pk_fma_f32 v[68:69], v[68:69], s[26:27], 1.0 op_sel_hi:[1,0,0]
	v_pk_mul_f32 v[74:75], v[60:61], v[60:61]
	v_rcp_f32_e32 v68, v68
	v_rcp_f32_e32 v69, v69
	v_pk_mul_f32 v[74:75], v[74:75], s[40:41] op_sel_hi:[1,0]
	v_and_b32_e32 v77, 0x7fffffff, v63
	v_exp_f32_e32 v74, v74
	v_pk_fma_f32 v[72:73], v[68:69], s[28:29], v[70:71] op_sel_hi:[1,0,0]
	v_exp_f32_e32 v75, v75
	v_pk_fma_f32 v[72:73], v[68:69], v[72:73], s[34:35] op_sel_hi:[1,1,0]
	v_and_b32_e32 v76, 0x7fffffff, v62
	v_pk_fma_f32 v[72:73], v[68:69], v[72:73], s[36:37] op_sel_hi:[1,1,0]
	v_pk_fma_f32 v[76:77], v[76:77], s[26:27], 1.0 op_sel_hi:[1,0,0]
	v_pk_fma_f32 v[72:73], v[68:69], v[72:73], s[38:39] op_sel_hi:[1,1,0]
	v_rcp_f32_e32 v76, v76
	v_pk_mul_f32 v[68:69], v[68:69], v[72:73]
	v_rcp_f32_e32 v77, v77
	v_pk_mul_f32 v[68:69], v[74:75], v[68:69]
	v_cmp_gt_f32_e32 vcc, 0, v60
	v_pk_mul_f32 v[74:75], v[60:61], v[68:69]
	v_pk_fma_f32 v[68:69], v[60:61], v[68:69], v[60:61] neg_lo:[1,0,0] neg_hi:[1,0,0]
	v_pk_mul_f32 v[58:59], v[58:59], v[66:67] op_sel_hi:[1,0]
	v_pk_mul_f32 v[56:57], v[56:57], v[66:67] op_sel_hi:[1,0]
	v_pk_mul_f32 v[72:73], v[62:63], v[62:63]
	v_cndmask_b32_e32 v67, v68, v74, vcc
	v_cmp_gt_f32_e32 vcc, 0, v61
	v_pk_fma_f32 v[60:61], v[76:77], s[28:29], v[70:71] op_sel_hi:[1,0,0]
	v_lshlrev_b64 v[64:65], 12, v[156:157]
	v_cndmask_b32_e32 v74, v69, v75, vcc
	v_pk_mul_f32 v[68:69], v[72:73], s[40:41] op_sel_hi:[1,0]
	v_pk_fma_f32 v[60:61], v[76:77], v[60:61], s[34:35] op_sel_hi:[1,1,0]
	v_exp_f32_e32 v68, v68
	v_exp_f32_e32 v69, v69
	v_pk_fma_f32 v[60:61], v[76:77], v[60:61], s[36:37] op_sel_hi:[1,1,0]
	v_and_b32_e32 v73, 0x7fffffff, v57
	v_and_b32_e32 v72, 0x7fffffff, v56
	v_pk_fma_f32 v[60:61], v[76:77], v[60:61], s[38:39] op_sel_hi:[1,1,0]
	v_pk_fma_f32 v[72:73], v[72:73], s[26:27], 1.0 op_sel_hi:[1,0,0]
	v_pk_mul_f32 v[60:61], v[76:77], v[60:61]
	v_rcp_f32_e32 v72, v72
	v_rcp_f32_e32 v73, v73
	v_pk_mul_f32 v[60:61], v[68:69], v[60:61]
	v_cmp_gt_f32_e32 vcc, 0, v62
	v_pk_mul_f32 v[68:69], v[62:63], v[60:61]
	v_pk_fma_f32 v[60:61], v[62:63], v[60:61], v[62:63] neg_lo:[1,0,0] neg_hi:[1,0,0]
	v_lshl_add_u64 v[64:65], v[152:153], 0, v[64:65]
	v_cndmask_b32_e32 v75, v60, v68, vcc
	v_cmp_gt_f32_e32 vcc, 0, v63
	v_pk_mul_f32 v[62:63], v[56:57], v[56:57]
	s_nop 0
	v_cndmask_b32_e32 v76, v61, v69, vcc
	v_pk_fma_f32 v[60:61], v[72:73], s[28:29], v[70:71] op_sel_hi:[1,0,0]
	v_pk_mul_f32 v[62:63], v[62:63], s[40:41] op_sel_hi:[1,0]
	v_pk_fma_f32 v[60:61], v[72:73], v[60:61], s[34:35] op_sel_hi:[1,1,0]
	v_exp_f32_e32 v62, v62
	v_pk_fma_f32 v[60:61], v[72:73], v[60:61], s[36:37] op_sel_hi:[1,1,0]
	v_exp_f32_e32 v63, v63
	v_pk_fma_f32 v[60:61], v[72:73], v[60:61], s[38:39] op_sel_hi:[1,1,0]
	v_cmp_gt_f32_e32 vcc, 0, v56
	v_pk_mul_f32 v[60:61], v[72:73], v[60:61]
	v_and_b32_e32 v73, 0x7fffffff, v59
	v_and_b32_e32 v72, 0x7fffffff, v58
	v_pk_fma_f32 v[72:73], v[72:73], s[26:27], 1.0 op_sel_hi:[1,0,0]
	v_pk_mul_f32 v[60:61], v[62:63], v[60:61]
	v_rcp_f32_e32 v72, v72
	v_rcp_f32_e32 v73, v73
	v_pk_mul_f32 v[62:63], v[56:57], v[60:61]
	v_pk_fma_f32 v[60:61], v[56:57], v[60:61], v[56:57] neg_lo:[1,0,0] neg_hi:[1,0,0]
	v_pk_mul_f32 v[68:69], v[58:59], v[58:59]
	v_cndmask_b32_e32 v62, v60, v62, vcc
	v_cmp_gt_f32_e32 vcc, 0, v57
	v_pk_fma_f32 v[56:57], v[72:73], s[28:29], v[70:71] op_sel_hi:[1,0,0]
	s_nop 0
	v_cndmask_b32_e32 v63, v61, v63, vcc
	v_pk_mul_f32 v[60:61], v[68:69], s[40:41] op_sel_hi:[1,0]
	v_pk_fma_f32 v[56:57], v[72:73], v[56:57], s[34:35] op_sel_hi:[1,1,0]
	v_exp_f32_e32 v60, v60
	v_exp_f32_e32 v61, v61
	v_pk_fma_f32 v[56:57], v[72:73], v[56:57], s[36:37] op_sel_hi:[1,1,0]
	v_cmp_gt_f32_e32 vcc, 0, v58
	v_pk_fma_f32 v[56:57], v[72:73], v[56:57], s[38:39] op_sel_hi:[1,1,0]
	s_nop 0
	v_pk_mul_f32 v[56:57], v[72:73], v[56:57]
	s_nop 0
	v_pk_mul_f32 v[56:57], v[60:61], v[56:57]
	s_nop 0
	v_pk_mul_f32 v[60:61], v[58:59], v[56:57]
	v_pk_fma_f32 v[56:57], v[58:59], v[56:57], v[58:59] neg_lo:[1,0,0] neg_hi:[1,0,0]
	s_nop 0
	v_cndmask_b32_e32 v60, v56, v60, vcc
	v_cmp_gt_f32_e32 vcc, 0, v59
	v_cvt_pk_bf16_f32 v56, v67, v74
	s_nop 1
	v_cndmask_b32_e32 v59, v57, v61, vcc
	v_cvt_pk_bf16_f32 v57, v75, v76
	v_cvt_pk_bf16_f32 v58, v62, v63
	v_cvt_pk_bf16_f32 v59, v60, v59
	v_mov_b32_e32 v60, 0
	s_and_b64 vcc, exec, s[8:9]
	v_mov_b32_e32 v61, 0
	global_store_dwordx4 v[64:65], v[56:59], off sc1
	s_cbranch_vccnz .LBB0_249
	v_and_b32_e32 v61, 16, v56
	v_and_b32_e32 v60, 0xffff0000, v56
	v_lshlrev_b32_e32 v69, 16, v57
	v_lshlrev_b32_e32 v68, 16, v58
	v_and_b32_e32 v62, 0xffff0000, v57
	v_mov_b32_e32 v63, v60
	v_pk_mov_b32 v[74:75], v[68:69], v[60:61] op_sel:[1,0]
	v_lshlrev_b32_e32 v56, 16, v56
	v_and_b32_e32 v70, 0xffff0000, v59
	v_mov_b32_e32 v71, v62
	v_and_b32_e32 v58, 0xffff0000, v58
	v_lshlrev_b32_e32 v72, 16, v59
	v_mov_b32_e32 v59, v69
	v_mov_b32_e32 v57, v62
	v_mov_b32_e32 v73, v62
	v_pk_add_f32 v[76:77], v[62:63], v[74:75]
	v_pk_mul_f32 v[62:63], v[62:63], v[74:75]
	v_pk_add_f32 v[60:61], v[56:57], v[60:61] op_sel_hi:[0,1]
	v_mov_b32_e32 v77, v63
	v_pk_add_f32 v[62:63], v[68:69], v[58:59]
	v_pk_mul_f32 v[74:75], v[68:69], v[68:69]
	v_mov_b32_e32 v59, v70
	v_mul_f32_e32 v61, v56, v56
	v_mov_b32_e32 v63, v75
	v_pk_add_f32 v[74:75], v[70:71], v[72:73]
	v_pk_mul_f32 v[56:57], v[70:71], v[56:57]
	v_mov_b32_e32 v69, v72
	v_pk_mul_f32 v[58:59], v[58:59], v[58:59]
	v_mov_b32_e32 v75, v57
	v_pk_fma_f32 v[58:59], v[68:69], v[68:69], v[58:59]
	v_pk_add_f32 v[60:61], v[60:61], v[76:77]
	v_pk_add_f32 v[56:57], v[62:63], v[74:75]
	v_pk_add_f32 v[58:59], v[58:59], v[58:59] op_sel_hi:[0,1]
	v_pk_add_f32 v[56:57], v[60:61], v[56:57]
	v_mov_b32_e32 v137, v59
	v_pk_add_f32 v[60:61], v[56:57], v[136:137]
.LBB0_249:
	v_mov_b32_e32 v67, v66
	v_pk_mul_f32 v[52:53], v[52:53], v[66:67]
	v_mov_b32_e32 v56, v66
	v_and_b32_e32 v59, 0x7fffffff, v53
	v_and_b32_e32 v58, 0x7fffffff, v52
	v_pk_fma_f32 v[58:59], v[58:59], s[26:27], 1.0 op_sel_hi:[1,0,0]
	v_mov_b32_e32 v57, v66
	v_rcp_f32_e32 v58, v58
	v_rcp_f32_e32 v59, v59
	v_pk_mul_f32 v[54:55], v[54:55], v[56:57]
	v_pk_mul_f32 v[50:51], v[50:51], v[56:57]
	v_pk_mul_f32 v[48:49], v[48:49], v[66:67]
	v_mov_b64_e32 v[56:57], s[30:31]
	v_pk_mul_f32 v[66:67], v[52:53], v[52:53]
	v_pk_fma_f32 v[62:63], v[58:59], s[28:29], v[56:57] op_sel_hi:[1,0,0]
	v_pk_mul_f32 v[66:67], v[66:67], s[40:41] op_sel_hi:[1,0]
	v_pk_fma_f32 v[62:63], v[58:59], v[62:63], s[34:35] op_sel_hi:[1,1,0]
	v_exp_f32_e32 v66, v66
	v_exp_f32_e32 v67, v67
	v_pk_fma_f32 v[62:63], v[58:59], v[62:63], s[36:37] op_sel_hi:[1,1,0]
	v_and_b32_e32 v69, 0x7fffffff, v55
	v_and_b32_e32 v68, 0x7fffffff, v54
	v_pk_fma_f32 v[62:63], v[58:59], v[62:63], s[38:39] op_sel_hi:[1,1,0]
	v_pk_fma_f32 v[68:69], v[68:69], s[26:27], 1.0 op_sel_hi:[1,0,0]
	v_pk_mul_f32 v[58:59], v[58:59], v[62:63]
	v_rcp_f32_e32 v68, v68
	v_rcp_f32_e32 v69, v69
	v_pk_mul_f32 v[58:59], v[66:67], v[58:59]
	v_cmp_gt_f32_e32 vcc, 0, v52
	v_pk_mul_f32 v[66:67], v[52:53], v[58:59]
	v_pk_fma_f32 v[58:59], v[52:53], v[58:59], v[52:53] neg_lo:[1,0,0] neg_hi:[1,0,0]
	v_pk_mul_f32 v[62:63], v[54:55], v[54:55]
	v_cndmask_b32_e32 v66, v58, v66, vcc
	v_cmp_gt_f32_e32 vcc, 0, v53
	v_pk_fma_f32 v[52:53], v[68:69], s[28:29], v[56:57] op_sel_hi:[1,0,0]
	s_nop 0
	v_cndmask_b32_e32 v67, v59, v67, vcc
	v_pk_mul_f32 v[58:59], v[62:63], s[40:41] op_sel_hi:[1,0]
	v_pk_fma_f32 v[52:53], v[68:69], v[52:53], s[34:35] op_sel_hi:[1,1,0]
	v_exp_f32_e32 v58, v58
	v_exp_f32_e32 v59, v59
	v_pk_fma_f32 v[52:53], v[68:69], v[52:53], s[36:37] op_sel_hi:[1,1,0]
	v_and_b32_e32 v63, 0x7fffffff, v49
	v_and_b32_e32 v62, 0x7fffffff, v48
	v_pk_fma_f32 v[52:53], v[68:69], v[52:53], s[38:39] op_sel_hi:[1,1,0]
	v_pk_fma_f32 v[62:63], v[62:63], s[26:27], 1.0 op_sel_hi:[1,0,0]
	v_pk_mul_f32 v[52:53], v[68:69], v[52:53]
	v_rcp_f32_e32 v62, v62
	v_rcp_f32_e32 v63, v63
	v_pk_mul_f32 v[52:53], v[58:59], v[52:53]
	v_cmp_gt_f32_e32 vcc, 0, v54
	v_pk_mul_f32 v[58:59], v[54:55], v[52:53]
	v_pk_fma_f32 v[52:53], v[54:55], v[52:53], v[54:55] neg_lo:[1,0,0] neg_hi:[1,0,0]
	s_nop 0
	v_cndmask_b32_e32 v68, v52, v58, vcc
	v_cmp_gt_f32_e32 vcc, 0, v55
	v_pk_mul_f32 v[54:55], v[48:49], v[48:49]
	s_nop 0
	v_cndmask_b32_e32 v69, v53, v59, vcc
	v_pk_fma_f32 v[52:53], v[62:63], s[28:29], v[56:57] op_sel_hi:[1,0,0]
	v_pk_mul_f32 v[54:55], v[54:55], s[40:41] op_sel_hi:[1,0]
	v_pk_fma_f32 v[52:53], v[62:63], v[52:53], s[34:35] op_sel_hi:[1,1,0]
	v_exp_f32_e32 v54, v54
	v_pk_fma_f32 v[52:53], v[62:63], v[52:53], s[36:37] op_sel_hi:[1,1,0]
	v_exp_f32_e32 v55, v55
	v_pk_fma_f32 v[52:53], v[62:63], v[52:53], s[38:39] op_sel_hi:[1,1,0]
	v_cmp_gt_f32_e32 vcc, 0, v48
	v_pk_mul_f32 v[52:53], v[62:63], v[52:53]
	v_and_b32_e32 v63, 0x7fffffff, v51
	v_and_b32_e32 v62, 0x7fffffff, v50
	v_pk_fma_f32 v[62:63], v[62:63], s[26:27], 1.0 op_sel_hi:[1,0,0]
	v_pk_mul_f32 v[52:53], v[54:55], v[52:53]
	v_rcp_f32_e32 v62, v62
	v_rcp_f32_e32 v63, v63
	v_pk_mul_f32 v[54:55], v[48:49], v[52:53]
	v_pk_fma_f32 v[52:53], v[48:49], v[52:53], v[48:49] neg_lo:[1,0,0] neg_hi:[1,0,0]
	v_pk_mul_f32 v[58:59], v[50:51], v[50:51]
	v_cndmask_b32_e32 v54, v52, v54, vcc
	v_cmp_gt_f32_e32 vcc, 0, v49
	v_pk_fma_f32 v[48:49], v[62:63], s[28:29], v[56:57] op_sel_hi:[1,0,0]
	s_nop 0
	v_cndmask_b32_e32 v55, v53, v55, vcc
	v_pk_mul_f32 v[52:53], v[58:59], s[40:41] op_sel_hi:[1,0]
	v_pk_fma_f32 v[48:49], v[62:63], v[48:49], s[34:35] op_sel_hi:[1,1,0]
	v_exp_f32_e32 v52, v52
	v_exp_f32_e32 v53, v53
	v_pk_fma_f32 v[48:49], v[62:63], v[48:49], s[36:37] op_sel_hi:[1,1,0]
	v_cmp_gt_f32_e32 vcc, 0, v50
	v_pk_fma_f32 v[48:49], v[62:63], v[48:49], s[38:39] op_sel_hi:[1,1,0]
	s_nop 0
	v_pk_mul_f32 v[48:49], v[62:63], v[48:49]
	s_nop 0
	v_pk_mul_f32 v[48:49], v[52:53], v[48:49]
	s_nop 0
	v_pk_mul_f32 v[52:53], v[50:51], v[48:49]
	v_pk_fma_f32 v[48:49], v[50:51], v[48:49], v[50:51] neg_lo:[1,0,0] neg_hi:[1,0,0]
	s_nop 0
	v_cndmask_b32_e32 v52, v48, v52, vcc
	v_cmp_gt_f32_e32 vcc, 0, v51
	v_cvt_pk_bf16_f32 v48, v66, v67
	s_nop 1
	v_cndmask_b32_e32 v51, v49, v53, vcc
	s_and_b64 vcc, exec, s[8:9]
	v_cvt_pk_bf16_f32 v49, v68, v69
	v_cvt_pk_bf16_f32 v50, v54, v55
	v_cvt_pk_bf16_f32 v51, v52, v51
	global_store_dwordx4 v[64:65], v[48:51], off offset:256 sc1
	s_cbranch_vccnz .LBB0_253
	v_lshlrev_b32_e32 v52, 16, v48
	v_and_b32_e32 v48, 0xffff0000, v48
	v_lshlrev_b32_e32 v54, 16, v49
	v_and_b32_e32 v56, 0xffff0000, v49
	v_lshlrev_b32_e32 v58, 16, v50
	v_and_b32_e32 v50, 0xffff0000, v50
	v_lshlrev_b32_e32 v62, 16, v51
	v_and_b32_e32 v64, 0xffff0000, v51
	v_mul_f32_e32 v53, v52, v52
	v_mul_f32_e32 v49, v48, v48
	v_mul_f32_e32 v55, v54, v54
	v_mul_f32_e32 v57, v56, v56
	v_mul_f32_e32 v59, v58, v58
	v_mul_f32_e32 v51, v50, v50
	v_mul_f32_e32 v63, v62, v62
	v_mul_f32_e32 v65, v64, v64
	v_pk_add_f32 v[48:49], v[52:53], v[48:49]
	v_pk_add_f32 v[52:53], v[54:55], v[56:57]
	v_pk_add_f32 v[50:51], v[58:59], v[50:51]
	v_pk_add_f32 v[48:49], v[48:49], v[52:53]
	v_pk_add_f32 v[52:53], v[62:63], v[64:65]
	s_nop 0
	v_pk_add_f32 v[50:51], v[50:51], v[52:53]
	s_nop 0
	v_pk_add_f32 v[48:49], v[48:49], v[50:51]
	s_nop 0
	v_pk_add_f32 v[48:49], v[60:61], v[48:49]
	ds_bpermute_b32 v50, v180, v48
	ds_bpermute_b32 v51, v180, v49
	s_waitcnt lgkmcnt(0)
	v_pk_add_f32 v[48:49], v[48:49], v[50:51]
	ds_bpermute_b32 v50, v179, v48
	ds_bpermute_b32 v51, v179, v49
	s_and_saveexec_b64 s[10:11], s[4:5]
	s_cbranch_execz .LBB0_252
	v_lshlrev_b64 v[52:53], 8, v[156:157]
	v_lshl_add_u64 v[52:53], s[16:17], 0, v[52:53]
	v_lshl_add_u64 v[52:53], s[50:51], 2, v[52:53]
	s_waitcnt lgkmcnt(0)
	v_pk_add_f32 v[48:49], v[48:49], v[50:51]
	global_store_dwordx2 v[52:53], v[48:49], off

.LBB0_253:
	s_nop 0
	v_add_f32_e32 v48, v185, v186
	v_fmamk_f32 v48, v48, 0x3a800000, v177
	v_mul_f32_e32 v49, 0x4f800000, v48
	v_cmp_gt_f32_e32 vcc, s65, v48
	v_mov_b64_e32 v[54:55], s[30:31]
	s_nop 0
	v_cndmask_b32_e32 v48, v48, v49, vcc
	v_sqrt_f32_e32 v49, v48
	s_waitcnt lgkmcnt(1)
	v_add_u32_e32 v50, -1, v49
	v_fma_f32 v52, -v50, v49, v48
	s_waitcnt lgkmcnt(0)
	v_add_u32_e32 v51, 1, v49
	v_cmp_ge_f32_e64 s[10:11], 0, v52
	s_nop 1
	v_cndmask_b32_e64 v50, v49, v50, s[10:11]
	v_fma_f32 v49, -v51, v49, v48
	v_cmp_lt_f32_e64 s[10:11], 0, v49
	s_nop 1
	v_cndmask_b32_e64 v49, v50, v51, s[10:11]
	v_mul_f32_e32 v50, 0x37800000, v49
	v_cndmask_b32_e32 v49, v49, v50, vcc
	v_cmp_class_f32_e32 vcc, v48, v178
	s_nop 1
	v_cndmask_b32_e32 v48, v49, v48, vcc
	v_div_scale_f32 v49, s[10:11], v48, v48, 1.0
	v_rcp_f32_e32 v50, v49
	s_nop 0
	v_fma_f32 v51, -v49, v50, 1.0
	v_fmac_f32_e32 v50, v51, v50
	v_div_scale_f32 v51, vcc, 1.0, v48, 1.0
	v_mul_f32_e32 v52, v51, v50
	v_fma_f32 v53, -v49, v52, v51
	v_fmac_f32_e32 v52, v53, v50
	v_fma_f32 v49, -v49, v52, v51
	v_div_fmas_f32 v49, v49, v50, v52
	v_div_fixup_f32 v50, v49, v48, 1.0
	v_pk_mul_f32 v[44:45], v[44:45], v[50:51] op_sel_hi:[1,0]
	v_pk_mul_f32 v[46:47], v[46:47], v[50:51] op_sel_hi:[1,0]
	v_and_b32_e32 v53, 0x7fffffff, v45
	v_and_b32_e32 v52, 0x7fffffff, v44
	v_pk_fma_f32 v[52:53], v[52:53], s[26:27], 1.0 op_sel_hi:[1,0,0]
	v_pk_mul_f32 v[58:59], v[44:45], v[44:45]
	v_rcp_f32_e32 v52, v52
	v_rcp_f32_e32 v53, v53
	v_pk_mul_f32 v[58:59], v[58:59], s[40:41] op_sel_hi:[1,0]
	v_and_b32_e32 v61, 0x7fffffff, v47
	v_exp_f32_e32 v58, v58
	v_pk_fma_f32 v[56:57], v[52:53], s[28:29], v[54:55] op_sel_hi:[1,0,0]
	v_exp_f32_e32 v59, v59
	v_pk_fma_f32 v[56:57], v[52:53], v[56:57], s[34:35] op_sel_hi:[1,1,0]
	v_and_b32_e32 v60, 0x7fffffff, v46
	v_pk_fma_f32 v[56:57], v[52:53], v[56:57], s[36:37] op_sel_hi:[1,1,0]
	v_pk_fma_f32 v[60:61], v[60:61], s[26:27], 1.0 op_sel_hi:[1,0,0]
	v_pk_fma_f32 v[56:57], v[52:53], v[56:57], s[38:39] op_sel_hi:[1,1,0]
	v_rcp_f32_e32 v60, v60
	v_pk_mul_f32 v[52:53], v[52:53], v[56:57]
	v_rcp_f32_e32 v61, v61
	v_pk_mul_f32 v[52:53], v[58:59], v[52:53]
	v_cmp_gt_f32_e32 vcc, 0, v44
	v_pk_mul_f32 v[58:59], v[44:45], v[52:53]
	v_pk_fma_f32 v[52:53], v[44:45], v[52:53], v[44:45] neg_lo:[1,0,0] neg_hi:[1,0,0]
	v_pk_mul_f32 v[42:43], v[42:43], v[50:51] op_sel_hi:[1,0]
	v_pk_mul_f32 v[40:41], v[40:41], v[50:51] op_sel_hi:[1,0]
	v_pk_mul_f32 v[56:57], v[46:47], v[46:47]
	v_cndmask_b32_e32 v51, v52, v58, vcc
	v_cmp_gt_f32_e32 vcc, 0, v45
	v_pk_fma_f32 v[44:45], v[60:61], s[28:29], v[54:55] op_sel_hi:[1,0,0]
	v_lshlrev_b64 v[48:49], 12, v[154:155]
	v_cndmask_b32_e32 v58, v53, v59, vcc
	v_pk_mul_f32 v[52:53], v[56:57], s[40:41] op_sel_hi:[1,0]
	v_pk_fma_f32 v[44:45], v[60:61], v[44:45], s[34:35] op_sel_hi:[1,1,0]
	v_exp_f32_e32 v52, v52
	v_exp_f32_e32 v53, v53
	v_pk_fma_f32 v[44:45], v[60:61], v[44:45], s[36:37] op_sel_hi:[1,1,0]
	v_and_b32_e32 v57, 0x7fffffff, v41
	v_and_b32_e32 v56, 0x7fffffff, v40
	v_pk_fma_f32 v[44:45], v[60:61], v[44:45], s[38:39] op_sel_hi:[1,1,0]
	v_pk_fma_f32 v[56:57], v[56:57], s[26:27], 1.0 op_sel_hi:[1,0,0]
	v_pk_mul_f32 v[44:45], v[60:61], v[44:45]
	v_rcp_f32_e32 v56, v56
	v_rcp_f32_e32 v57, v57
	v_pk_mul_f32 v[44:45], v[52:53], v[44:45]
	v_cmp_gt_f32_e32 vcc, 0, v46
	v_pk_mul_f32 v[52:53], v[46:47], v[44:45]
	v_pk_fma_f32 v[44:45], v[46:47], v[44:45], v[46:47] neg_lo:[1,0,0] neg_hi:[1,0,0]
	v_lshl_add_u64 v[48:49], v[152:153], 0, v[48:49]
	v_cndmask_b32_e32 v59, v44, v52, vcc
	v_cmp_gt_f32_e32 vcc, 0, v47
	v_pk_mul_f32 v[46:47], v[40:41], v[40:41]
	s_nop 0
	v_cndmask_b32_e32 v60, v45, v53, vcc
	v_pk_fma_f32 v[44:45], v[56:57], s[28:29], v[54:55] op_sel_hi:[1,0,0]
	v_pk_mul_f32 v[46:47], v[46:47], s[40:41] op_sel_hi:[1,0]
	v_pk_fma_f32 v[44:45], v[56:57], v[44:45], s[34:35] op_sel_hi:[1,1,0]
	v_exp_f32_e32 v46, v46
	v_pk_fma_f32 v[44:45], v[56:57], v[44:45], s[36:37] op_sel_hi:[1,1,0]
	v_exp_f32_e32 v47, v47
	v_pk_fma_f32 v[44:45], v[56:57], v[44:45], s[38:39] op_sel_hi:[1,1,0]
	v_cmp_gt_f32_e32 vcc, 0, v40
	v_pk_mul_f32 v[44:45], v[56:57], v[44:45]
	v_and_b32_e32 v57, 0x7fffffff, v43
	v_and_b32_e32 v56, 0x7fffffff, v42
	v_pk_fma_f32 v[56:57], v[56:57], s[26:27], 1.0 op_sel_hi:[1,0,0]
	v_pk_mul_f32 v[44:45], v[46:47], v[44:45]
	v_rcp_f32_e32 v56, v56
	v_rcp_f32_e32 v57, v57
	v_pk_mul_f32 v[46:47], v[40:41], v[44:45]
	v_pk_fma_f32 v[44:45], v[40:41], v[44:45], v[40:41] neg_lo:[1,0,0] neg_hi:[1,0,0]
	v_pk_mul_f32 v[52:53], v[42:43], v[42:43]
	v_cndmask_b32_e32 v46, v44, v46, vcc
	v_cmp_gt_f32_e32 vcc, 0, v41
	v_pk_fma_f32 v[40:41], v[56:57], s[28:29], v[54:55] op_sel_hi:[1,0,0]
	s_nop 0
	v_cndmask_b32_e32 v47, v45, v47, vcc
	v_pk_mul_f32 v[44:45], v[52:53], s[40:41] op_sel_hi:[1,0]
	v_pk_fma_f32 v[40:41], v[56:57], v[40:41], s[34:35] op_sel_hi:[1,1,0]
	v_exp_f32_e32 v44, v44
	v_exp_f32_e32 v45, v45
	v_pk_fma_f32 v[40:41], v[56:57], v[40:41], s[36:37] op_sel_hi:[1,1,0]
	v_cmp_gt_f32_e32 vcc, 0, v42
	v_pk_fma_f32 v[40:41], v[56:57], v[40:41], s[38:39] op_sel_hi:[1,1,0]
	s_nop 0
	v_pk_mul_f32 v[40:41], v[56:57], v[40:41]
	s_nop 0
	v_pk_mul_f32 v[40:41], v[44:45], v[40:41]
	s_nop 0
	v_pk_mul_f32 v[44:45], v[42:43], v[40:41]
	v_pk_fma_f32 v[40:41], v[42:43], v[40:41], v[42:43] neg_lo:[1,0,0] neg_hi:[1,0,0]
	s_nop 0
	v_cndmask_b32_e32 v44, v40, v44, vcc
	v_cmp_gt_f32_e32 vcc, 0, v43
	v_cvt_pk_bf16_f32 v40, v51, v58
	s_nop 1
	v_cndmask_b32_e32 v43, v41, v45, vcc
	v_cvt_pk_bf16_f32 v41, v59, v60
	v_cvt_pk_bf16_f32 v42, v46, v47
	v_cvt_pk_bf16_f32 v43, v44, v43
	v_mov_b32_e32 v44, 0
	s_and_b64 vcc, exec, s[8:9]
	v_mov_b32_e32 v45, 0
	global_store_dwordx4 v[48:49], v[40:43], off sc1
	s_cbranch_vccnz .LBB0_255
	v_and_b32_e32 v45, 16, v40
	v_and_b32_e32 v44, 0xffff0000, v40
	v_lshlrev_b32_e32 v53, 16, v41
	v_lshlrev_b32_e32 v52, 16, v42
	v_and_b32_e32 v46, 0xffff0000, v41
	v_mov_b32_e32 v47, v44
	v_pk_mov_b32 v[58:59], v[52:53], v[44:45] op_sel:[1,0]
	v_lshlrev_b32_e32 v40, 16, v40
	v_and_b32_e32 v54, 0xffff0000, v43
	v_mov_b32_e32 v55, v46
	v_and_b32_e32 v42, 0xffff0000, v42
	v_lshlrev_b32_e32 v56, 16, v43
	v_mov_b32_e32 v43, v53
	v_mov_b32_e32 v41, v46
	v_mov_b32_e32 v57, v46
	v_pk_add_f32 v[60:61], v[46:47], v[58:59]
	v_pk_mul_f32 v[46:47], v[46:47], v[58:59]
	v_pk_add_f32 v[44:45], v[40:41], v[44:45] op_sel_hi:[0,1]
	v_mov_b32_e32 v61, v47
	v_pk_add_f32 v[46:47], v[52:53], v[42:43]
	v_pk_mul_f32 v[58:59], v[52:53], v[52:53]
	v_mov_b32_e32 v43, v54
	v_mul_f32_e32 v45, v40, v40
	v_mov_b32_e32 v47, v59
	v_pk_add_f32 v[58:59], v[54:55], v[56:57]
	v_pk_mul_f32 v[40:41], v[54:55], v[40:41]
	v_mov_b32_e32 v53, v56
	v_pk_mul_f32 v[42:43], v[42:43], v[42:43]
	v_mov_b32_e32 v59, v41
	v_pk_fma_f32 v[42:43], v[52:53], v[52:53], v[42:43]
	v_pk_add_f32 v[44:45], v[44:45], v[60:61]
	v_pk_add_f32 v[40:41], v[46:47], v[58:59]
	v_pk_add_f32 v[42:43], v[42:43], v[42:43] op_sel_hi:[0,1]
	v_pk_add_f32 v[40:41], v[44:45], v[40:41]
	v_mov_b32_e32 v137, v43
	v_pk_add_f32 v[44:45], v[40:41], v[136:137]
.LBB0_255:
	v_mov_b32_e32 v51, v50
	v_pk_mul_f32 v[36:37], v[36:37], v[50:51]
	v_mov_b32_e32 v40, v50
	v_and_b32_e32 v43, 0x7fffffff, v37
	v_and_b32_e32 v42, 0x7fffffff, v36
	v_pk_fma_f32 v[42:43], v[42:43], s[26:27], 1.0 op_sel_hi:[1,0,0]
	v_mov_b32_e32 v41, v50
	v_rcp_f32_e32 v42, v42
	v_rcp_f32_e32 v43, v43
	v_pk_mul_f32 v[38:39], v[38:39], v[40:41]
	v_pk_mul_f32 v[34:35], v[34:35], v[40:41]
	v_pk_mul_f32 v[32:33], v[32:33], v[50:51]
	v_mov_b64_e32 v[40:41], s[30:31]
	v_pk_mul_f32 v[50:51], v[36:37], v[36:37]
	v_pk_fma_f32 v[46:47], v[42:43], s[28:29], v[40:41] op_sel_hi:[1,0,0]
	v_pk_mul_f32 v[50:51], v[50:51], s[40:41] op_sel_hi:[1,0]
	v_pk_fma_f32 v[46:47], v[42:43], v[46:47], s[34:35] op_sel_hi:[1,1,0]
	v_exp_f32_e32 v50, v50
	v_exp_f32_e32 v51, v51
	v_pk_fma_f32 v[46:47], v[42:43], v[46:47], s[36:37] op_sel_hi:[1,1,0]
	v_and_b32_e32 v53, 0x7fffffff, v39
	v_and_b32_e32 v52, 0x7fffffff, v38
	v_pk_fma_f32 v[46:47], v[42:43], v[46:47], s[38:39] op_sel_hi:[1,1,0]
	v_pk_fma_f32 v[52:53], v[52:53], s[26:27], 1.0 op_sel_hi:[1,0,0]
	v_pk_mul_f32 v[42:43], v[42:43], v[46:47]
	v_rcp_f32_e32 v52, v52
	v_rcp_f32_e32 v53, v53
	v_pk_mul_f32 v[42:43], v[50:51], v[42:43]
	v_cmp_gt_f32_e32 vcc, 0, v36
	v_pk_mul_f32 v[50:51], v[36:37], v[42:43]
	v_pk_fma_f32 v[42:43], v[36:37], v[42:43], v[36:37] neg_lo:[1,0,0] neg_hi:[1,0,0]
	v_pk_mul_f32 v[46:47], v[38:39], v[38:39]
	v_cndmask_b32_e32 v50, v42, v50, vcc
	v_cmp_gt_f32_e32 vcc, 0, v37
	v_pk_fma_f32 v[36:37], v[52:53], s[28:29], v[40:41] op_sel_hi:[1,0,0]
	s_nop 0
	v_cndmask_b32_e32 v51, v43, v51, vcc
	v_pk_mul_f32 v[42:43], v[46:47], s[40:41] op_sel_hi:[1,0]
	v_pk_fma_f32 v[36:37], v[52:53], v[36:37], s[34:35] op_sel_hi:[1,1,0]
	v_exp_f32_e32 v42, v42
	v_exp_f32_e32 v43, v43
	v_pk_fma_f32 v[36:37], v[52:53], v[36:37], s[36:37] op_sel_hi:[1,1,0]
	v_and_b32_e32 v47, 0x7fffffff, v33
	v_and_b32_e32 v46, 0x7fffffff, v32
	v_pk_fma_f32 v[36:37], v[52:53], v[36:37], s[38:39] op_sel_hi:[1,1,0]
	v_pk_fma_f32 v[46:47], v[46:47], s[26:27], 1.0 op_sel_hi:[1,0,0]
	v_pk_mul_f32 v[36:37], v[52:53], v[36:37]
	v_rcp_f32_e32 v46, v46
	v_rcp_f32_e32 v47, v47
	v_pk_mul_f32 v[36:37], v[42:43], v[36:37]
	v_cmp_gt_f32_e32 vcc, 0, v38
	v_pk_mul_f32 v[42:43], v[38:39], v[36:37]
	v_pk_fma_f32 v[36:37], v[38:39], v[36:37], v[38:39] neg_lo:[1,0,0] neg_hi:[1,0,0]
	s_nop 0
	v_cndmask_b32_e32 v52, v36, v42, vcc
	v_cmp_gt_f32_e32 vcc, 0, v39
	v_pk_mul_f32 v[38:39], v[32:33], v[32:33]
	s_nop 0
	v_cndmask_b32_e32 v53, v37, v43, vcc
	v_pk_fma_f32 v[36:37], v[46:47], s[28:29], v[40:41] op_sel_hi:[1,0,0]
	v_pk_mul_f32 v[38:39], v[38:39], s[40:41] op_sel_hi:[1,0]
	v_pk_fma_f32 v[36:37], v[46:47], v[36:37], s[34:35] op_sel_hi:[1,1,0]
	v_exp_f32_e32 v38, v38
	v_pk_fma_f32 v[36:37], v[46:47], v[36:37], s[36:37] op_sel_hi:[1,1,0]
	v_exp_f32_e32 v39, v39
	v_pk_fma_f32 v[36:37], v[46:47], v[36:37], s[38:39] op_sel_hi:[1,1,0]
	v_cmp_gt_f32_e32 vcc, 0, v32
	v_pk_mul_f32 v[36:37], v[46:47], v[36:37]
	v_and_b32_e32 v47, 0x7fffffff, v35
	v_and_b32_e32 v46, 0x7fffffff, v34
	v_pk_fma_f32 v[46:47], v[46:47], s[26:27], 1.0 op_sel_hi:[1,0,0]
	v_pk_mul_f32 v[36:37], v[38:39], v[36:37]
	v_rcp_f32_e32 v46, v46
	v_rcp_f32_e32 v47, v47
	v_pk_mul_f32 v[38:39], v[32:33], v[36:37]
	v_pk_fma_f32 v[36:37], v[32:33], v[36:37], v[32:33] neg_lo:[1,0,0] neg_hi:[1,0,0]
	v_pk_mul_f32 v[42:43], v[34:35], v[34:35]
	v_cndmask_b32_e32 v38, v36, v38, vcc
	v_cmp_gt_f32_e32 vcc, 0, v33
	v_pk_fma_f32 v[32:33], v[46:47], s[28:29], v[40:41] op_sel_hi:[1,0,0]
	s_nop 0
	v_cndmask_b32_e32 v39, v37, v39, vcc
	v_pk_mul_f32 v[36:37], v[42:43], s[40:41] op_sel_hi:[1,0]
	v_pk_fma_f32 v[32:33], v[46:47], v[32:33], s[34:35] op_sel_hi:[1,1,0]
	v_exp_f32_e32 v36, v36
	v_exp_f32_e32 v37, v37
	v_pk_fma_f32 v[32:33], v[46:47], v[32:33], s[36:37] op_sel_hi:[1,1,0]
	v_cmp_gt_f32_e32 vcc, 0, v34
	v_pk_fma_f32 v[32:33], v[46:47], v[32:33], s[38:39] op_sel_hi:[1,1,0]
	s_nop 0
	v_pk_mul_f32 v[32:33], v[46:47], v[32:33]
	s_nop 0
	v_pk_mul_f32 v[32:33], v[36:37], v[32:33]
	s_nop 0
	v_pk_mul_f32 v[36:37], v[34:35], v[32:33]
	v_pk_fma_f32 v[32:33], v[34:35], v[32:33], v[34:35] neg_lo:[1,0,0] neg_hi:[1,0,0]
	s_nop 0
	v_cndmask_b32_e32 v36, v32, v36, vcc
	v_cmp_gt_f32_e32 vcc, 0, v35
	v_cvt_pk_bf16_f32 v32, v50, v51
	s_nop 1
	v_cndmask_b32_e32 v35, v33, v37, vcc
	s_and_b64 vcc, exec, s[8:9]
	v_cvt_pk_bf16_f32 v33, v52, v53
	v_cvt_pk_bf16_f32 v34, v38, v39
	v_cvt_pk_bf16_f32 v35, v36, v35
	global_store_dwordx4 v[48:49], v[32:35], off offset:256 sc1
	s_cbranch_vccnz .LBB0_259
	v_lshlrev_b32_e32 v36, 16, v32
	v_and_b32_e32 v32, 0xffff0000, v32
	v_lshlrev_b32_e32 v38, 16, v33
	v_and_b32_e32 v40, 0xffff0000, v33
	v_lshlrev_b32_e32 v42, 16, v34
	v_and_b32_e32 v34, 0xffff0000, v34
	v_lshlrev_b32_e32 v46, 16, v35
	v_and_b32_e32 v48, 0xffff0000, v35
	v_mul_f32_e32 v37, v36, v36
	v_mul_f32_e32 v33, v32, v32
	v_mul_f32_e32 v39, v38, v38
	v_mul_f32_e32 v41, v40, v40
	v_mul_f32_e32 v43, v42, v42
	v_mul_f32_e32 v35, v34, v34
	v_mul_f32_e32 v47, v46, v46
	v_mul_f32_e32 v49, v48, v48
	v_pk_add_f32 v[32:33], v[36:37], v[32:33]
	v_pk_add_f32 v[36:37], v[38:39], v[40:41]
	v_pk_add_f32 v[34:35], v[42:43], v[34:35]
	v_pk_add_f32 v[32:33], v[32:33], v[36:37]
	v_pk_add_f32 v[36:37], v[46:47], v[48:49]
	s_nop 0
	v_pk_add_f32 v[34:35], v[34:35], v[36:37]
	s_nop 0
	v_pk_add_f32 v[32:33], v[32:33], v[34:35]
	s_nop 0
	v_pk_add_f32 v[32:33], v[44:45], v[32:33]
	ds_bpermute_b32 v34, v180, v32
	ds_bpermute_b32 v35, v180, v33
	s_waitcnt lgkmcnt(0)
	v_pk_add_f32 v[32:33], v[32:33], v[34:35]
	ds_bpermute_b32 v34, v179, v32
	ds_bpermute_b32 v35, v179, v33
	s_and_saveexec_b64 s[10:11], s[4:5]
	s_cbranch_execz .LBB0_258
	v_lshlrev_b64 v[36:37], 8, v[154:155]
	v_lshl_add_u64 v[36:37], s[16:17], 0, v[36:37]
	v_lshl_add_u64 v[36:37], s[50:51], 2, v[36:37]
	s_waitcnt lgkmcnt(0)
	v_pk_add_f32 v[32:33], v[32:33], v[34:35]
	global_store_dwordx2 v[36:37], v[32:33], off

.LBB0_259:
	s_nop 0
	v_add_f32_e32 v32, v183, v184
	v_fmamk_f32 v32, v32, 0x3a800000, v177
	v_mul_f32_e32 v33, 0x4f800000, v32
	v_cmp_gt_f32_e32 vcc, s65, v32
	v_mov_b64_e32 v[38:39], s[30:31]
	s_nop 0
	v_cndmask_b32_e32 v32, v32, v33, vcc
	v_sqrt_f32_e32 v33, v32
	s_waitcnt lgkmcnt(1)
	v_add_u32_e32 v34, -1, v33
	v_fma_f32 v36, -v34, v33, v32
	s_waitcnt lgkmcnt(0)
	v_add_u32_e32 v35, 1, v33
	v_cmp_ge_f32_e64 s[10:11], 0, v36
	s_nop 1
	v_cndmask_b32_e64 v34, v33, v34, s[10:11]
	v_fma_f32 v33, -v35, v33, v32
	v_cmp_lt_f32_e64 s[10:11], 0, v33
	s_nop 1
	v_cndmask_b32_e64 v33, v34, v35, s[10:11]
	v_mul_f32_e32 v34, 0x37800000, v33
	v_cndmask_b32_e32 v33, v33, v34, vcc
	v_cmp_class_f32_e32 vcc, v32, v178
	s_nop 1
	v_cndmask_b32_e32 v32, v33, v32, vcc
	v_div_scale_f32 v33, s[10:11], v32, v32, 1.0
	v_rcp_f32_e32 v34, v33
	s_nop 0
	v_fma_f32 v35, -v33, v34, 1.0
	v_fmac_f32_e32 v34, v35, v34
	v_div_scale_f32 v35, vcc, 1.0, v32, 1.0
	v_mul_f32_e32 v36, v35, v34
	v_fma_f32 v37, -v33, v36, v35
	v_fmac_f32_e32 v36, v37, v34
	v_fma_f32 v33, -v33, v36, v35
	v_div_fmas_f32 v33, v33, v34, v36
	v_div_fixup_f32 v34, v33, v32, 1.0
	v_pk_mul_f32 v[28:29], v[28:29], v[34:35] op_sel_hi:[1,0]
	v_pk_mul_f32 v[30:31], v[30:31], v[34:35] op_sel_hi:[1,0]
	v_and_b32_e32 v37, 0x7fffffff, v29
	v_and_b32_e32 v36, 0x7fffffff, v28
	v_pk_fma_f32 v[36:37], v[36:37], s[26:27], 1.0 op_sel_hi:[1,0,0]
	v_pk_mul_f32 v[42:43], v[28:29], v[28:29]
	v_rcp_f32_e32 v36, v36
	v_rcp_f32_e32 v37, v37
	v_pk_mul_f32 v[42:43], v[42:43], s[40:41] op_sel_hi:[1,0]
	v_and_b32_e32 v45, 0x7fffffff, v31
	v_exp_f32_e32 v42, v42
	v_pk_fma_f32 v[40:41], v[36:37], s[28:29], v[38:39] op_sel_hi:[1,0,0]
	v_exp_f32_e32 v43, v43
	v_pk_fma_f32 v[40:41], v[36:37], v[40:41], s[34:35] op_sel_hi:[1,1,0]
	v_and_b32_e32 v44, 0x7fffffff, v30
	v_pk_fma_f32 v[40:41], v[36:37], v[40:41], s[36:37] op_sel_hi:[1,1,0]
	v_pk_fma_f32 v[44:45], v[44:45], s[26:27], 1.0 op_sel_hi:[1,0,0]
	v_pk_fma_f32 v[40:41], v[36:37], v[40:41], s[38:39] op_sel_hi:[1,1,0]
	v_rcp_f32_e32 v44, v44
	v_pk_mul_f32 v[36:37], v[36:37], v[40:41]
	v_rcp_f32_e32 v45, v45
	v_pk_mul_f32 v[36:37], v[42:43], v[36:37]
	v_cmp_gt_f32_e32 vcc, 0, v28
	v_pk_mul_f32 v[42:43], v[28:29], v[36:37]
	v_pk_fma_f32 v[36:37], v[28:29], v[36:37], v[28:29] neg_lo:[1,0,0] neg_hi:[1,0,0]
	v_pk_mul_f32 v[26:27], v[26:27], v[34:35] op_sel_hi:[1,0]
	v_pk_mul_f32 v[24:25], v[24:25], v[34:35] op_sel_hi:[1,0]
	v_pk_mul_f32 v[40:41], v[30:31], v[30:31]
	v_cndmask_b32_e32 v35, v36, v42, vcc
	v_cmp_gt_f32_e32 vcc, 0, v29
	v_pk_fma_f32 v[28:29], v[44:45], s[28:29], v[38:39] op_sel_hi:[1,0,0]
	v_lshlrev_b64 v[32:33], 12, v[150:151]
	v_cndmask_b32_e32 v42, v37, v43, vcc
	v_pk_mul_f32 v[36:37], v[40:41], s[40:41] op_sel_hi:[1,0]
	v_pk_fma_f32 v[28:29], v[44:45], v[28:29], s[34:35] op_sel_hi:[1,1,0]
	v_exp_f32_e32 v36, v36
	v_exp_f32_e32 v37, v37
	v_pk_fma_f32 v[28:29], v[44:45], v[28:29], s[36:37] op_sel_hi:[1,1,0]
	v_and_b32_e32 v41, 0x7fffffff, v25
	v_and_b32_e32 v40, 0x7fffffff, v24
	v_pk_fma_f32 v[28:29], v[44:45], v[28:29], s[38:39] op_sel_hi:[1,1,0]
	v_pk_fma_f32 v[40:41], v[40:41], s[26:27], 1.0 op_sel_hi:[1,0,0]
	v_pk_mul_f32 v[28:29], v[44:45], v[28:29]
	v_rcp_f32_e32 v40, v40
	v_rcp_f32_e32 v41, v41
	v_pk_mul_f32 v[28:29], v[36:37], v[28:29]
	v_cmp_gt_f32_e32 vcc, 0, v30
	v_pk_mul_f32 v[36:37], v[30:31], v[28:29]
	v_pk_fma_f32 v[28:29], v[30:31], v[28:29], v[30:31] neg_lo:[1,0,0] neg_hi:[1,0,0]
	v_lshl_add_u64 v[32:33], v[152:153], 0, v[32:33]
	v_cndmask_b32_e32 v43, v28, v36, vcc
	v_cmp_gt_f32_e32 vcc, 0, v31
	v_pk_mul_f32 v[30:31], v[24:25], v[24:25]
	s_nop 0
	v_cndmask_b32_e32 v44, v29, v37, vcc
	v_pk_fma_f32 v[28:29], v[40:41], s[28:29], v[38:39] op_sel_hi:[1,0,0]
	v_pk_mul_f32 v[30:31], v[30:31], s[40:41] op_sel_hi:[1,0]
	v_pk_fma_f32 v[28:29], v[40:41], v[28:29], s[34:35] op_sel_hi:[1,1,0]
	v_exp_f32_e32 v30, v30
	v_pk_fma_f32 v[28:29], v[40:41], v[28:29], s[36:37] op_sel_hi:[1,1,0]
	v_exp_f32_e32 v31, v31
	v_pk_fma_f32 v[28:29], v[40:41], v[28:29], s[38:39] op_sel_hi:[1,1,0]
	v_cmp_gt_f32_e32 vcc, 0, v24
	v_pk_mul_f32 v[28:29], v[40:41], v[28:29]
	v_and_b32_e32 v41, 0x7fffffff, v27
	v_and_b32_e32 v40, 0x7fffffff, v26
	v_pk_fma_f32 v[40:41], v[40:41], s[26:27], 1.0 op_sel_hi:[1,0,0]
	v_pk_mul_f32 v[28:29], v[30:31], v[28:29]
	v_rcp_f32_e32 v40, v40
	v_rcp_f32_e32 v41, v41
	v_pk_mul_f32 v[30:31], v[24:25], v[28:29]
	v_pk_fma_f32 v[28:29], v[24:25], v[28:29], v[24:25] neg_lo:[1,0,0] neg_hi:[1,0,0]
	v_pk_mul_f32 v[36:37], v[26:27], v[26:27]
	v_cndmask_b32_e32 v30, v28, v30, vcc
	v_cmp_gt_f32_e32 vcc, 0, v25
	v_pk_fma_f32 v[24:25], v[40:41], s[28:29], v[38:39] op_sel_hi:[1,0,0]
	s_nop 0
	v_cndmask_b32_e32 v31, v29, v31, vcc
	v_pk_mul_f32 v[28:29], v[36:37], s[40:41] op_sel_hi:[1,0]
	v_pk_fma_f32 v[24:25], v[40:41], v[24:25], s[34:35] op_sel_hi:[1,1,0]
	v_exp_f32_e32 v28, v28
	v_exp_f32_e32 v29, v29
	v_pk_fma_f32 v[24:25], v[40:41], v[24:25], s[36:37] op_sel_hi:[1,1,0]
	v_cmp_gt_f32_e32 vcc, 0, v26
	v_pk_fma_f32 v[24:25], v[40:41], v[24:25], s[38:39] op_sel_hi:[1,1,0]
	s_nop 0
	v_pk_mul_f32 v[24:25], v[40:41], v[24:25]
	s_nop 0
	v_pk_mul_f32 v[24:25], v[28:29], v[24:25]
	s_nop 0
	v_pk_mul_f32 v[28:29], v[26:27], v[24:25]
	v_pk_fma_f32 v[24:25], v[26:27], v[24:25], v[26:27] neg_lo:[1,0,0] neg_hi:[1,0,0]
	s_nop 0
	v_cndmask_b32_e32 v28, v24, v28, vcc
	v_cmp_gt_f32_e32 vcc, 0, v27
	v_cvt_pk_bf16_f32 v24, v35, v42
	s_nop 1
	v_cndmask_b32_e32 v27, v25, v29, vcc
	v_cvt_pk_bf16_f32 v25, v43, v44
	v_cvt_pk_bf16_f32 v26, v30, v31
	v_cvt_pk_bf16_f32 v27, v28, v27
	v_mov_b32_e32 v28, 0
	s_and_b64 vcc, exec, s[8:9]
	v_mov_b32_e32 v29, 0
	global_store_dwordx4 v[32:33], v[24:27], off sc1
	s_cbranch_vccnz .LBB0_261
	v_and_b32_e32 v29, 16, v24
	v_and_b32_e32 v28, 0xffff0000, v24
	v_lshlrev_b32_e32 v37, 16, v25
	v_lshlrev_b32_e32 v36, 16, v26
	v_and_b32_e32 v30, 0xffff0000, v25
	v_mov_b32_e32 v31, v28
	v_pk_mov_b32 v[42:43], v[36:37], v[28:29] op_sel:[1,0]
	v_lshlrev_b32_e32 v24, 16, v24
	v_and_b32_e32 v38, 0xffff0000, v27
	v_mov_b32_e32 v39, v30
	v_and_b32_e32 v26, 0xffff0000, v26
	v_lshlrev_b32_e32 v40, 16, v27
	v_mov_b32_e32 v27, v37
	v_mov_b32_e32 v25, v30
	v_mov_b32_e32 v41, v30
	v_pk_add_f32 v[44:45], v[30:31], v[42:43]
	v_pk_mul_f32 v[30:31], v[30:31], v[42:43]
	v_pk_add_f32 v[28:29], v[24:25], v[28:29] op_sel_hi:[0,1]
	v_mov_b32_e32 v45, v31
	v_pk_add_f32 v[30:31], v[36:37], v[26:27]
	v_pk_mul_f32 v[42:43], v[36:37], v[36:37]
	v_mov_b32_e32 v27, v38
	v_mul_f32_e32 v29, v24, v24
	v_mov_b32_e32 v31, v43
	v_pk_add_f32 v[42:43], v[38:39], v[40:41]
	v_pk_mul_f32 v[24:25], v[38:39], v[24:25]
	v_mov_b32_e32 v37, v40
	v_pk_mul_f32 v[26:27], v[26:27], v[26:27]
	v_mov_b32_e32 v43, v25
	v_pk_fma_f32 v[26:27], v[36:37], v[36:37], v[26:27]
	v_pk_add_f32 v[28:29], v[28:29], v[44:45]
	v_pk_add_f32 v[24:25], v[30:31], v[42:43]
	v_pk_add_f32 v[26:27], v[26:27], v[26:27] op_sel_hi:[0,1]
	v_pk_add_f32 v[24:25], v[28:29], v[24:25]
	v_mov_b32_e32 v137, v27
	v_pk_add_f32 v[28:29], v[24:25], v[136:137]
.LBB0_261:
	v_mov_b32_e32 v35, v34
	v_pk_mul_f32 v[20:21], v[20:21], v[34:35]
	v_mov_b32_e32 v24, v34
	v_and_b32_e32 v27, 0x7fffffff, v21
	v_and_b32_e32 v26, 0x7fffffff, v20
	v_pk_fma_f32 v[26:27], v[26:27], s[26:27], 1.0 op_sel_hi:[1,0,0]
	v_mov_b32_e32 v25, v34
	v_rcp_f32_e32 v26, v26
	v_rcp_f32_e32 v27, v27
	v_pk_mul_f32 v[22:23], v[22:23], v[24:25]
	v_pk_mul_f32 v[18:19], v[18:19], v[24:25]
	v_pk_mul_f32 v[16:17], v[16:17], v[34:35]
	v_mov_b64_e32 v[24:25], s[30:31]
	v_pk_mul_f32 v[34:35], v[20:21], v[20:21]
	v_pk_fma_f32 v[30:31], v[26:27], s[28:29], v[24:25] op_sel_hi:[1,0,0]
	v_pk_mul_f32 v[34:35], v[34:35], s[40:41] op_sel_hi:[1,0]
	v_pk_fma_f32 v[30:31], v[26:27], v[30:31], s[34:35] op_sel_hi:[1,1,0]
	v_exp_f32_e32 v34, v34
	v_exp_f32_e32 v35, v35
	v_pk_fma_f32 v[30:31], v[26:27], v[30:31], s[36:37] op_sel_hi:[1,1,0]
	v_and_b32_e32 v37, 0x7fffffff, v23
	v_and_b32_e32 v36, 0x7fffffff, v22
	v_pk_fma_f32 v[30:31], v[26:27], v[30:31], s[38:39] op_sel_hi:[1,1,0]
	v_pk_fma_f32 v[36:37], v[36:37], s[26:27], 1.0 op_sel_hi:[1,0,0]
	v_pk_mul_f32 v[26:27], v[26:27], v[30:31]
	v_rcp_f32_e32 v36, v36
	v_rcp_f32_e32 v37, v37
	v_pk_mul_f32 v[26:27], v[34:35], v[26:27]
	v_cmp_gt_f32_e32 vcc, 0, v20
	v_pk_mul_f32 v[34:35], v[20:21], v[26:27]
	v_pk_fma_f32 v[26:27], v[20:21], v[26:27], v[20:21] neg_lo:[1,0,0] neg_hi:[1,0,0]
	v_pk_mul_f32 v[30:31], v[22:23], v[22:23]
	v_cndmask_b32_e32 v34, v26, v34, vcc
	v_cmp_gt_f32_e32 vcc, 0, v21
	v_pk_fma_f32 v[20:21], v[36:37], s[28:29], v[24:25] op_sel_hi:[1,0,0]
	s_nop 0
	v_cndmask_b32_e32 v35, v27, v35, vcc
	v_pk_mul_f32 v[26:27], v[30:31], s[40:41] op_sel_hi:[1,0]
	v_pk_fma_f32 v[20:21], v[36:37], v[20:21], s[34:35] op_sel_hi:[1,1,0]
	v_exp_f32_e32 v26, v26
	v_exp_f32_e32 v27, v27
	v_pk_fma_f32 v[20:21], v[36:37], v[20:21], s[36:37] op_sel_hi:[1,1,0]
	v_and_b32_e32 v31, 0x7fffffff, v17
	v_and_b32_e32 v30, 0x7fffffff, v16
	v_pk_fma_f32 v[20:21], v[36:37], v[20:21], s[38:39] op_sel_hi:[1,1,0]
	v_pk_fma_f32 v[30:31], v[30:31], s[26:27], 1.0 op_sel_hi:[1,0,0]
	v_pk_mul_f32 v[20:21], v[36:37], v[20:21]
	v_rcp_f32_e32 v30, v30
	v_rcp_f32_e32 v31, v31
	v_pk_mul_f32 v[20:21], v[26:27], v[20:21]
	v_cmp_gt_f32_e32 vcc, 0, v22
	v_pk_mul_f32 v[26:27], v[22:23], v[20:21]
	v_pk_fma_f32 v[20:21], v[22:23], v[20:21], v[22:23] neg_lo:[1,0,0] neg_hi:[1,0,0]
	s_nop 0
	v_cndmask_b32_e32 v36, v20, v26, vcc
	v_cmp_gt_f32_e32 vcc, 0, v23
	v_pk_mul_f32 v[22:23], v[16:17], v[16:17]
	s_nop 0
	v_cndmask_b32_e32 v37, v21, v27, vcc
	v_pk_fma_f32 v[20:21], v[30:31], s[28:29], v[24:25] op_sel_hi:[1,0,0]
	v_pk_mul_f32 v[22:23], v[22:23], s[40:41] op_sel_hi:[1,0]
	v_pk_fma_f32 v[20:21], v[30:31], v[20:21], s[34:35] op_sel_hi:[1,1,0]
	v_exp_f32_e32 v22, v22
	v_pk_fma_f32 v[20:21], v[30:31], v[20:21], s[36:37] op_sel_hi:[1,1,0]
	v_exp_f32_e32 v23, v23
	v_pk_fma_f32 v[20:21], v[30:31], v[20:21], s[38:39] op_sel_hi:[1,1,0]
	v_cmp_gt_f32_e32 vcc, 0, v16
	v_pk_mul_f32 v[20:21], v[30:31], v[20:21]
	v_and_b32_e32 v31, 0x7fffffff, v19
	v_and_b32_e32 v30, 0x7fffffff, v18
	v_pk_fma_f32 v[30:31], v[30:31], s[26:27], 1.0 op_sel_hi:[1,0,0]
	v_pk_mul_f32 v[20:21], v[22:23], v[20:21]
	v_rcp_f32_e32 v30, v30
	v_rcp_f32_e32 v31, v31
	v_pk_mul_f32 v[22:23], v[16:17], v[20:21]
	v_pk_fma_f32 v[20:21], v[16:17], v[20:21], v[16:17] neg_lo:[1,0,0] neg_hi:[1,0,0]
	v_pk_mul_f32 v[26:27], v[18:19], v[18:19]
	v_cndmask_b32_e32 v22, v20, v22, vcc
	v_cmp_gt_f32_e32 vcc, 0, v17
	v_pk_fma_f32 v[16:17], v[30:31], s[28:29], v[24:25] op_sel_hi:[1,0,0]
	s_nop 0
	v_cndmask_b32_e32 v23, v21, v23, vcc
	v_pk_mul_f32 v[20:21], v[26:27], s[40:41] op_sel_hi:[1,0]
	v_pk_fma_f32 v[16:17], v[30:31], v[16:17], s[34:35] op_sel_hi:[1,1,0]
	v_exp_f32_e32 v20, v20
	v_exp_f32_e32 v21, v21
	v_pk_fma_f32 v[16:17], v[30:31], v[16:17], s[36:37] op_sel_hi:[1,1,0]
	v_cmp_gt_f32_e32 vcc, 0, v18
	v_pk_fma_f32 v[16:17], v[30:31], v[16:17], s[38:39] op_sel_hi:[1,1,0]
	s_nop 0
	v_pk_mul_f32 v[16:17], v[30:31], v[16:17]
	s_nop 0
	v_pk_mul_f32 v[16:17], v[20:21], v[16:17]
	s_nop 0
	v_pk_mul_f32 v[20:21], v[18:19], v[16:17]
	v_pk_fma_f32 v[16:17], v[18:19], v[16:17], v[18:19] neg_lo:[1,0,0] neg_hi:[1,0,0]
	s_nop 0
	v_cndmask_b32_e32 v20, v16, v20, vcc
	v_cmp_gt_f32_e32 vcc, 0, v19
	v_cvt_pk_bf16_f32 v16, v34, v35
	s_nop 1
	v_cndmask_b32_e32 v19, v17, v21, vcc
	s_and_b64 vcc, exec, s[8:9]
	v_cvt_pk_bf16_f32 v17, v36, v37
	v_cvt_pk_bf16_f32 v18, v22, v23
	v_cvt_pk_bf16_f32 v19, v20, v19
	global_store_dwordx4 v[32:33], v[16:19], off offset:256 sc1
	s_cbranch_vccnz .LBB0_265
	v_lshlrev_b32_e32 v20, 16, v16
	v_and_b32_e32 v16, 0xffff0000, v16
	v_lshlrev_b32_e32 v22, 16, v17
	v_and_b32_e32 v24, 0xffff0000, v17
	v_lshlrev_b32_e32 v26, 16, v18
	v_and_b32_e32 v18, 0xffff0000, v18
	v_lshlrev_b32_e32 v30, 16, v19
	v_and_b32_e32 v32, 0xffff0000, v19
	v_mul_f32_e32 v21, v20, v20
	v_mul_f32_e32 v17, v16, v16
	v_mul_f32_e32 v23, v22, v22
	v_mul_f32_e32 v25, v24, v24
	v_mul_f32_e32 v27, v26, v26
	v_mul_f32_e32 v19, v18, v18
	v_mul_f32_e32 v31, v30, v30
	v_mul_f32_e32 v33, v32, v32
	v_pk_add_f32 v[16:17], v[20:21], v[16:17]
	v_pk_add_f32 v[20:21], v[22:23], v[24:25]
	v_pk_add_f32 v[18:19], v[26:27], v[18:19]
	v_pk_add_f32 v[16:17], v[16:17], v[20:21]
	v_pk_add_f32 v[20:21], v[30:31], v[32:33]
	s_nop 0
	v_pk_add_f32 v[18:19], v[18:19], v[20:21]
	s_nop 0
	v_pk_add_f32 v[16:17], v[16:17], v[18:19]
	s_nop 0
	v_pk_add_f32 v[16:17], v[28:29], v[16:17]
	ds_bpermute_b32 v18, v180, v16
	ds_bpermute_b32 v19, v180, v17
	s_waitcnt lgkmcnt(0)
	v_pk_add_f32 v[16:17], v[16:17], v[18:19]
	ds_bpermute_b32 v18, v179, v16
	ds_bpermute_b32 v19, v179, v17
	s_and_saveexec_b64 s[10:11], s[4:5]
	s_cbranch_execz .LBB0_264
	v_lshlrev_b64 v[20:21], 8, v[150:151]
	v_lshl_add_u64 v[20:21], s[16:17], 0, v[20:21]
	v_lshl_add_u64 v[20:21], s[50:51], 2, v[20:21]
	s_waitcnt lgkmcnt(0)
	v_pk_add_f32 v[16:17], v[16:17], v[18:19]
	global_store_dwordx2 v[20:21], v[16:17], off

.LBB0_265:
	s_nop 0
	v_add_f32_e32 v16, v181, v182
	v_fmamk_f32 v16, v16, 0x3a800000, v177
	v_mul_f32_e32 v17, 0x4f800000, v16
	v_cmp_gt_f32_e32 vcc, s65, v16
	v_mov_b64_e32 v[22:23], s[30:31]
	s_nop 0
	v_cndmask_b32_e32 v16, v16, v17, vcc
	v_sqrt_f32_e32 v17, v16
	s_waitcnt lgkmcnt(1)
	v_add_u32_e32 v18, -1, v17
	v_fma_f32 v20, -v18, v17, v16
	s_waitcnt lgkmcnt(0)
	v_add_u32_e32 v19, 1, v17
	v_cmp_ge_f32_e64 s[10:11], 0, v20
	s_nop 1
	v_cndmask_b32_e64 v18, v17, v18, s[10:11]
	v_fma_f32 v17, -v19, v17, v16
	v_cmp_lt_f32_e64 s[10:11], 0, v17
	s_nop 1
	v_cndmask_b32_e64 v17, v18, v19, s[10:11]
	v_mul_f32_e32 v18, 0x37800000, v17
	v_cndmask_b32_e32 v17, v17, v18, vcc
	v_cmp_class_f32_e32 vcc, v16, v178
	s_nop 1
	v_cndmask_b32_e32 v16, v17, v16, vcc
	v_div_scale_f32 v17, s[10:11], v16, v16, 1.0
	v_rcp_f32_e32 v18, v17
	s_nop 0
	v_fma_f32 v19, -v17, v18, 1.0
	v_fmac_f32_e32 v18, v19, v18
	v_div_scale_f32 v19, vcc, 1.0, v16, 1.0
	v_mul_f32_e32 v20, v19, v18
	v_fma_f32 v21, -v17, v20, v19
	v_fmac_f32_e32 v20, v21, v18
	v_fma_f32 v17, -v17, v20, v19
	v_div_fmas_f32 v17, v17, v18, v20
	v_div_fixup_f32 v18, v17, v16, 1.0
	v_pk_mul_f32 v[12:13], v[12:13], v[18:19] op_sel_hi:[1,0]
	v_pk_mul_f32 v[14:15], v[14:15], v[18:19] op_sel_hi:[1,0]
	v_and_b32_e32 v21, 0x7fffffff, v13
	v_and_b32_e32 v20, 0x7fffffff, v12
	v_pk_fma_f32 v[20:21], v[20:21], s[26:27], 1.0 op_sel_hi:[1,0,0]
	v_pk_mul_f32 v[26:27], v[12:13], v[12:13]
	v_rcp_f32_e32 v20, v20
	v_rcp_f32_e32 v21, v21
	v_pk_mul_f32 v[26:27], v[26:27], s[40:41] op_sel_hi:[1,0]
	v_and_b32_e32 v29, 0x7fffffff, v15
	v_exp_f32_e32 v26, v26
	v_pk_fma_f32 v[24:25], v[20:21], s[28:29], v[22:23] op_sel_hi:[1,0,0]
	v_exp_f32_e32 v27, v27
	v_pk_fma_f32 v[24:25], v[20:21], v[24:25], s[34:35] op_sel_hi:[1,1,0]
	v_and_b32_e32 v28, 0x7fffffff, v14
	v_pk_fma_f32 v[24:25], v[20:21], v[24:25], s[36:37] op_sel_hi:[1,1,0]
	v_pk_fma_f32 v[28:29], v[28:29], s[26:27], 1.0 op_sel_hi:[1,0,0]
	v_pk_fma_f32 v[24:25], v[20:21], v[24:25], s[38:39] op_sel_hi:[1,1,0]
	v_rcp_f32_e32 v28, v28
	v_pk_mul_f32 v[20:21], v[20:21], v[24:25]
	v_rcp_f32_e32 v29, v29
	v_pk_mul_f32 v[20:21], v[26:27], v[20:21]
	v_cmp_gt_f32_e32 vcc, 0, v12
	v_pk_mul_f32 v[26:27], v[12:13], v[20:21]
	v_pk_fma_f32 v[20:21], v[12:13], v[20:21], v[12:13] neg_lo:[1,0,0] neg_hi:[1,0,0]
	v_pk_mul_f32 v[10:11], v[10:11], v[18:19] op_sel_hi:[1,0]
	v_pk_mul_f32 v[8:9], v[8:9], v[18:19] op_sel_hi:[1,0]
	v_pk_mul_f32 v[24:25], v[14:15], v[14:15]
	v_cndmask_b32_e32 v19, v20, v26, vcc
	v_cmp_gt_f32_e32 vcc, 0, v13
	v_pk_fma_f32 v[12:13], v[28:29], s[28:29], v[22:23] op_sel_hi:[1,0,0]
	v_lshlrev_b64 v[16:17], 12, v[148:149]
	v_cndmask_b32_e32 v26, v21, v27, vcc
	v_pk_mul_f32 v[20:21], v[24:25], s[40:41] op_sel_hi:[1,0]
	v_pk_fma_f32 v[12:13], v[28:29], v[12:13], s[34:35] op_sel_hi:[1,1,0]
	v_exp_f32_e32 v20, v20
	v_exp_f32_e32 v21, v21
	v_pk_fma_f32 v[12:13], v[28:29], v[12:13], s[36:37] op_sel_hi:[1,1,0]
	v_and_b32_e32 v25, 0x7fffffff, v9
	v_and_b32_e32 v24, 0x7fffffff, v8
	v_pk_fma_f32 v[12:13], v[28:29], v[12:13], s[38:39] op_sel_hi:[1,1,0]
	v_pk_fma_f32 v[24:25], v[24:25], s[26:27], 1.0 op_sel_hi:[1,0,0]
	v_pk_mul_f32 v[12:13], v[28:29], v[12:13]
	v_rcp_f32_e32 v24, v24
	v_rcp_f32_e32 v25, v25
	v_pk_mul_f32 v[12:13], v[20:21], v[12:13]
	v_cmp_gt_f32_e32 vcc, 0, v14
	v_pk_mul_f32 v[20:21], v[14:15], v[12:13]
	v_pk_fma_f32 v[12:13], v[14:15], v[12:13], v[14:15] neg_lo:[1,0,0] neg_hi:[1,0,0]
	v_lshl_add_u64 v[16:17], v[152:153], 0, v[16:17]
	v_cndmask_b32_e32 v27, v12, v20, vcc
	v_cmp_gt_f32_e32 vcc, 0, v15
	v_pk_mul_f32 v[14:15], v[8:9], v[8:9]
	s_nop 0
	v_cndmask_b32_e32 v28, v13, v21, vcc
	v_pk_fma_f32 v[12:13], v[24:25], s[28:29], v[22:23] op_sel_hi:[1,0,0]
	v_pk_mul_f32 v[14:15], v[14:15], s[40:41] op_sel_hi:[1,0]
	v_pk_fma_f32 v[12:13], v[24:25], v[12:13], s[34:35] op_sel_hi:[1,1,0]
	v_exp_f32_e32 v14, v14
	v_pk_fma_f32 v[12:13], v[24:25], v[12:13], s[36:37] op_sel_hi:[1,1,0]
	v_exp_f32_e32 v15, v15
	v_pk_fma_f32 v[12:13], v[24:25], v[12:13], s[38:39] op_sel_hi:[1,1,0]
	v_cmp_gt_f32_e32 vcc, 0, v8
	v_pk_mul_f32 v[12:13], v[24:25], v[12:13]
	v_and_b32_e32 v25, 0x7fffffff, v11
	v_and_b32_e32 v24, 0x7fffffff, v10
	v_pk_fma_f32 v[24:25], v[24:25], s[26:27], 1.0 op_sel_hi:[1,0,0]
	v_pk_mul_f32 v[12:13], v[14:15], v[12:13]
	v_rcp_f32_e32 v24, v24
	v_rcp_f32_e32 v25, v25
	v_pk_mul_f32 v[14:15], v[8:9], v[12:13]
	v_pk_fma_f32 v[12:13], v[8:9], v[12:13], v[8:9] neg_lo:[1,0,0] neg_hi:[1,0,0]
	v_pk_mul_f32 v[20:21], v[10:11], v[10:11]
	v_cndmask_b32_e32 v14, v12, v14, vcc
	v_cmp_gt_f32_e32 vcc, 0, v9
	v_pk_fma_f32 v[8:9], v[24:25], s[28:29], v[22:23] op_sel_hi:[1,0,0]
	s_nop 0
	v_cndmask_b32_e32 v15, v13, v15, vcc
	v_pk_mul_f32 v[12:13], v[20:21], s[40:41] op_sel_hi:[1,0]
	v_pk_fma_f32 v[8:9], v[24:25], v[8:9], s[34:35] op_sel_hi:[1,1,0]
	v_exp_f32_e32 v12, v12
	v_exp_f32_e32 v13, v13
	v_pk_fma_f32 v[8:9], v[24:25], v[8:9], s[36:37] op_sel_hi:[1,1,0]
	v_cmp_gt_f32_e32 vcc, 0, v10
	v_pk_fma_f32 v[8:9], v[24:25], v[8:9], s[38:39] op_sel_hi:[1,1,0]
	s_nop 0
	v_pk_mul_f32 v[8:9], v[24:25], v[8:9]
	s_nop 0
	v_pk_mul_f32 v[8:9], v[12:13], v[8:9]
	s_nop 0
	v_pk_mul_f32 v[12:13], v[10:11], v[8:9]
	v_pk_fma_f32 v[8:9], v[10:11], v[8:9], v[10:11] neg_lo:[1,0,0] neg_hi:[1,0,0]
	s_nop 0
	v_cndmask_b32_e32 v12, v8, v12, vcc
	v_cmp_gt_f32_e32 vcc, 0, v11
	v_cvt_pk_bf16_f32 v8, v19, v26
	s_nop 1
	v_cndmask_b32_e32 v11, v9, v13, vcc
	v_cvt_pk_bf16_f32 v9, v27, v28
	v_cvt_pk_bf16_f32 v10, v14, v15
	v_cvt_pk_bf16_f32 v11, v12, v11
	v_mov_b32_e32 v12, 0
	s_and_b64 vcc, exec, s[8:9]
	v_mov_b32_e32 v13, 0
	global_store_dwordx4 v[16:17], v[8:11], off sc1
	s_cbranch_vccnz .LBB0_267
	v_and_b32_e32 v13, 16, v8
	v_and_b32_e32 v12, 0xffff0000, v8
	v_lshlrev_b32_e32 v21, 16, v9
	v_lshlrev_b32_e32 v20, 16, v10
	v_and_b32_e32 v14, 0xffff0000, v9
	v_mov_b32_e32 v15, v12
	v_pk_mov_b32 v[26:27], v[20:21], v[12:13] op_sel:[1,0]
	v_lshlrev_b32_e32 v8, 16, v8
	v_and_b32_e32 v22, 0xffff0000, v11
	v_mov_b32_e32 v23, v14
	v_and_b32_e32 v10, 0xffff0000, v10
	v_lshlrev_b32_e32 v24, 16, v11
	v_mov_b32_e32 v11, v21
	v_mov_b32_e32 v9, v14
	v_mov_b32_e32 v25, v14
	v_pk_add_f32 v[28:29], v[14:15], v[26:27]
	v_pk_mul_f32 v[14:15], v[14:15], v[26:27]
	v_pk_add_f32 v[12:13], v[8:9], v[12:13] op_sel_hi:[0,1]
	v_mov_b32_e32 v29, v15
	v_pk_add_f32 v[14:15], v[20:21], v[10:11]
	v_pk_mul_f32 v[26:27], v[20:21], v[20:21]
	v_mov_b32_e32 v11, v22
	v_mul_f32_e32 v13, v8, v8
	v_mov_b32_e32 v15, v27
	v_pk_add_f32 v[26:27], v[22:23], v[24:25]
	v_pk_mul_f32 v[8:9], v[22:23], v[8:9]
	v_mov_b32_e32 v21, v24
	v_pk_mul_f32 v[10:11], v[10:11], v[10:11]
	v_mov_b32_e32 v27, v9
	v_pk_fma_f32 v[10:11], v[20:21], v[20:21], v[10:11]
	v_pk_add_f32 v[12:13], v[12:13], v[28:29]
	v_pk_add_f32 v[8:9], v[14:15], v[26:27]
	v_pk_add_f32 v[10:11], v[10:11], v[10:11] op_sel_hi:[0,1]
	v_pk_add_f32 v[8:9], v[12:13], v[8:9]
	v_mov_b32_e32 v137, v11
	v_pk_add_f32 v[12:13], v[8:9], v[136:137]
.LBB0_267:
	v_mov_b32_e32 v19, v18
	v_pk_mul_f32 v[4:5], v[4:5], v[18:19]
	v_mov_b32_e32 v8, v18
	v_and_b32_e32 v11, 0x7fffffff, v5
	v_and_b32_e32 v10, 0x7fffffff, v4
	v_pk_fma_f32 v[10:11], v[10:11], s[26:27], 1.0 op_sel_hi:[1,0,0]
	v_mov_b32_e32 v9, v18
	v_rcp_f32_e32 v10, v10
	v_rcp_f32_e32 v11, v11
	v_pk_mul_f32 v[6:7], v[6:7], v[8:9]
	v_pk_mul_f32 v[2:3], v[2:3], v[8:9]
	v_pk_mul_f32 v[0:1], v[0:1], v[18:19]
	v_mov_b64_e32 v[8:9], s[30:31]
	v_pk_mul_f32 v[18:19], v[4:5], v[4:5]
	v_pk_fma_f32 v[14:15], v[10:11], s[28:29], v[8:9] op_sel_hi:[1,0,0]
	v_pk_mul_f32 v[18:19], v[18:19], s[40:41] op_sel_hi:[1,0]
	v_pk_fma_f32 v[14:15], v[10:11], v[14:15], s[34:35] op_sel_hi:[1,1,0]
	v_exp_f32_e32 v18, v18
	v_exp_f32_e32 v19, v19
	v_pk_fma_f32 v[14:15], v[10:11], v[14:15], s[36:37] op_sel_hi:[1,1,0]
	v_and_b32_e32 v21, 0x7fffffff, v7
	v_and_b32_e32 v20, 0x7fffffff, v6
	v_pk_fma_f32 v[14:15], v[10:11], v[14:15], s[38:39] op_sel_hi:[1,1,0]
	v_pk_fma_f32 v[20:21], v[20:21], s[26:27], 1.0 op_sel_hi:[1,0,0]
	v_pk_mul_f32 v[10:11], v[10:11], v[14:15]
	v_rcp_f32_e32 v20, v20
	v_rcp_f32_e32 v21, v21
	v_pk_mul_f32 v[10:11], v[18:19], v[10:11]
	v_cmp_gt_f32_e32 vcc, 0, v4
	v_pk_mul_f32 v[18:19], v[4:5], v[10:11]
	v_pk_fma_f32 v[10:11], v[4:5], v[10:11], v[4:5] neg_lo:[1,0,0] neg_hi:[1,0,0]
	v_pk_mul_f32 v[14:15], v[6:7], v[6:7]
	v_cndmask_b32_e32 v18, v10, v18, vcc
	v_cmp_gt_f32_e32 vcc, 0, v5
	v_pk_fma_f32 v[4:5], v[20:21], s[28:29], v[8:9] op_sel_hi:[1,0,0]
	s_nop 0
	v_cndmask_b32_e32 v19, v11, v19, vcc
	v_pk_mul_f32 v[10:11], v[14:15], s[40:41] op_sel_hi:[1,0]
	v_pk_fma_f32 v[4:5], v[20:21], v[4:5], s[34:35] op_sel_hi:[1,1,0]
	v_exp_f32_e32 v10, v10
	v_exp_f32_e32 v11, v11
	v_pk_fma_f32 v[4:5], v[20:21], v[4:5], s[36:37] op_sel_hi:[1,1,0]
	v_and_b32_e32 v15, 0x7fffffff, v1
	v_and_b32_e32 v14, 0x7fffffff, v0
	v_pk_fma_f32 v[4:5], v[20:21], v[4:5], s[38:39] op_sel_hi:[1,1,0]
	v_pk_fma_f32 v[14:15], v[14:15], s[26:27], 1.0 op_sel_hi:[1,0,0]
	v_pk_mul_f32 v[4:5], v[20:21], v[4:5]
	v_rcp_f32_e32 v14, v14
	v_rcp_f32_e32 v15, v15
	v_pk_mul_f32 v[4:5], v[10:11], v[4:5]
	v_cmp_gt_f32_e32 vcc, 0, v6
	v_pk_mul_f32 v[10:11], v[6:7], v[4:5]
	v_pk_fma_f32 v[4:5], v[6:7], v[4:5], v[6:7] neg_lo:[1,0,0] neg_hi:[1,0,0]
	s_nop 0
	v_cndmask_b32_e32 v20, v4, v10, vcc
	v_cmp_gt_f32_e32 vcc, 0, v7
	v_pk_mul_f32 v[6:7], v[0:1], v[0:1]
	s_nop 0
	v_cndmask_b32_e32 v21, v5, v11, vcc
	v_pk_fma_f32 v[4:5], v[14:15], s[28:29], v[8:9] op_sel_hi:[1,0,0]
	v_pk_mul_f32 v[6:7], v[6:7], s[40:41] op_sel_hi:[1,0]
	v_pk_fma_f32 v[4:5], v[14:15], v[4:5], s[34:35] op_sel_hi:[1,1,0]
	v_exp_f32_e32 v6, v6
	v_pk_fma_f32 v[4:5], v[14:15], v[4:5], s[36:37] op_sel_hi:[1,1,0]
	v_exp_f32_e32 v7, v7
	v_pk_fma_f32 v[4:5], v[14:15], v[4:5], s[38:39] op_sel_hi:[1,1,0]
	v_cmp_gt_f32_e32 vcc, 0, v0
	v_pk_mul_f32 v[4:5], v[14:15], v[4:5]
	v_and_b32_e32 v15, 0x7fffffff, v3
	v_and_b32_e32 v14, 0x7fffffff, v2
	v_pk_fma_f32 v[14:15], v[14:15], s[26:27], 1.0 op_sel_hi:[1,0,0]
	v_pk_mul_f32 v[4:5], v[6:7], v[4:5]
	v_rcp_f32_e32 v14, v14
	v_rcp_f32_e32 v15, v15
	v_pk_mul_f32 v[6:7], v[0:1], v[4:5]
	v_pk_fma_f32 v[4:5], v[0:1], v[4:5], v[0:1] neg_lo:[1,0,0] neg_hi:[1,0,0]
	v_pk_mul_f32 v[10:11], v[2:3], v[2:3]
	v_cndmask_b32_e32 v6, v4, v6, vcc
	v_cmp_gt_f32_e32 vcc, 0, v1
	v_pk_fma_f32 v[0:1], v[14:15], s[28:29], v[8:9] op_sel_hi:[1,0,0]
	s_nop 0
	v_cndmask_b32_e32 v7, v5, v7, vcc
	v_pk_mul_f32 v[4:5], v[10:11], s[40:41] op_sel_hi:[1,0]
	v_pk_fma_f32 v[0:1], v[14:15], v[0:1], s[34:35] op_sel_hi:[1,1,0]
	v_exp_f32_e32 v4, v4
	v_exp_f32_e32 v5, v5
	v_pk_fma_f32 v[0:1], v[14:15], v[0:1], s[36:37] op_sel_hi:[1,1,0]
	v_cmp_gt_f32_e32 vcc, 0, v2
	v_pk_fma_f32 v[0:1], v[14:15], v[0:1], s[38:39] op_sel_hi:[1,1,0]
	s_nop 0
	v_pk_mul_f32 v[0:1], v[14:15], v[0:1]
	s_nop 0
	v_pk_mul_f32 v[0:1], v[4:5], v[0:1]
	s_nop 0
	v_pk_mul_f32 v[4:5], v[2:3], v[0:1]
	v_pk_fma_f32 v[0:1], v[2:3], v[0:1], v[2:3] neg_lo:[1,0,0] neg_hi:[1,0,0]
	s_nop 0
	v_cndmask_b32_e32 v4, v0, v4, vcc
	v_cmp_gt_f32_e32 vcc, 0, v3
	v_cvt_pk_bf16_f32 v0, v18, v19
	s_nop 1
	v_cndmask_b32_e32 v3, v1, v5, vcc
	s_and_b64 vcc, exec, s[8:9]
	v_cvt_pk_bf16_f32 v1, v20, v21
	v_cvt_pk_bf16_f32 v2, v6, v7
	v_cvt_pk_bf16_f32 v3, v4, v3
	global_store_dwordx4 v[16:17], v[0:3], off offset:256 sc1
	s_cbranch_vccnz .LBB0_271
	v_lshlrev_b32_e32 v4, 16, v0
	v_and_b32_e32 v0, 0xffff0000, v0
	v_lshlrev_b32_e32 v6, 16, v1
	v_and_b32_e32 v8, 0xffff0000, v1
	v_lshlrev_b32_e32 v10, 16, v2
	v_and_b32_e32 v2, 0xffff0000, v2
	v_lshlrev_b32_e32 v14, 16, v3
	v_and_b32_e32 v16, 0xffff0000, v3
	v_mul_f32_e32 v5, v4, v4
	v_mul_f32_e32 v1, v0, v0
	v_mul_f32_e32 v7, v6, v6
	v_mul_f32_e32 v9, v8, v8
	v_mul_f32_e32 v11, v10, v10
	v_mul_f32_e32 v3, v2, v2
	v_mul_f32_e32 v15, v14, v14
	v_mul_f32_e32 v17, v16, v16
	v_pk_add_f32 v[0:1], v[4:5], v[0:1]
	v_pk_add_f32 v[4:5], v[6:7], v[8:9]
	v_pk_add_f32 v[2:3], v[10:11], v[2:3]
	v_pk_add_f32 v[0:1], v[0:1], v[4:5]
	v_pk_add_f32 v[4:5], v[14:15], v[16:17]
	s_nop 0
	v_pk_add_f32 v[2:3], v[2:3], v[4:5]
	s_nop 0
	v_pk_add_f32 v[0:1], v[0:1], v[2:3]
	s_nop 0
	v_pk_add_f32 v[0:1], v[12:13], v[0:1]
	ds_bpermute_b32 v2, v180, v0
	ds_bpermute_b32 v3, v180, v1
	s_waitcnt lgkmcnt(0)
	v_pk_add_f32 v[0:1], v[0:1], v[2:3]
	ds_bpermute_b32 v2, v179, v0
	ds_bpermute_b32 v3, v179, v1
	s_and_saveexec_b64 s[8:9], s[4:5]
	s_cbranch_execz .LBB0_270
	v_lshlrev_b64 v[4:5], 8, v[148:149]
	v_lshl_add_u64 v[4:5], s[16:17], 0, v[4:5]
	v_lshl_add_u64 v[4:5], s[50:51], 2, v[4:5]
	s_waitcnt lgkmcnt(0)
	v_pk_add_f32 v[0:1], v[0:1], v[2:3]
	global_store_dwordx2 v[4:5], v[0:1], off

.LBB0_327:
	ds_read_u16 v0, v220 offset:1056
	ds_read_u16 v1, v220 offset:1584
	ds_read_u16 v2, v220 offset:2112
	ds_read_u16 v3, v220 offset:3168
	ds_read_u16 v4, v220 offset:3696
	ds_read_u16 v5, v220 offset:2640
	ds_read_u16 v6, v220
	ds_read_u16 v7, v220 offset:528
	v_add_u32_e32 v12, v208, v209
	s_waitcnt lgkmcnt(3)
	v_perm_b32 v3, v4, v3, s28
	s_waitcnt lgkmcnt(2)
	v_perm_b32 v2, v5, v2, s28
	v_perm_b32 v1, v1, v0, s28
	s_waitcnt lgkmcnt(0)
	v_perm_b32 v0, v7, v6, s28
	ds_read_b128 v[4:7], v12
	ds_read_b128 v[8:11], v12 offset:8704
	s_ashr_i32 s10, s35, 3
	s_ashr_i32 s11, s10, 31
	s_lshl_b64 s[10:11], s[10:11], 7
	s_waitcnt lgkmcnt(1)
	v_mfma_f32_32x32x16_bf16 v[48:63], v[0:3], v[4:7], 0
	v_lshl_add_u64 v[4:5], s[10:11], 0, v[160:161]
	s_lshl_b32 s16, s36, 9
	v_lshl_add_u64 v[198:199], v[174:175], 0, s[16:17]
	v_lshlrev_b64 v[4:5], 12, v[4:5]
	v_lshl_add_u64 v[200:201], v[198:199], 0, v[4:5]
	ds_read_b128 v[4:7], v12 offset:17408
	s_waitcnt lgkmcnt(1)
	v_mfma_f32_32x32x16_bf16 v[32:47], v[0:3], v[8:11], 0
	v_add_co_u32_e32 v8, vcc, s14, v200
	s_nop 1
	v_addc_co_u32_e32 v9, vcc, 0, v201, vcc
	global_load_dwordx4 v[156:159], v[200:201], off
	global_load_dwordx4 v[152:155], v[8:9], off
	ds_read_b128 v[8:11], v12 offset:26112
	ds_read_u16 v128, v220 offset:8448
	ds_read_u16 v129, v220 offset:8976
	ds_read_u16 v130, v220 offset:9504
	ds_read_u16 v131, v220 offset:10032
	ds_read_u16 v134, v220 offset:10560
	ds_read_u16 v135, v220 offset:11088
	ds_read_u16 v136, v220 offset:11616
	ds_read_u16 v137, v220 offset:12144
	s_waitcnt lgkmcnt(4)
	v_perm_b32 v239, v131, v130, s28
	v_perm_b32 v238, v129, v128, s28
	s_waitcnt lgkmcnt(2)
	v_perm_b32 v240, v135, v134, s28
	ds_read_b128 v[128:131], v221
	s_waitcnt lgkmcnt(1)
	v_perm_b32 v241, v137, v136, s28
	v_add_co_u32_e32 v132, vcc, s15, v200
	s_waitcnt lgkmcnt(0)
	v_mfma_f32_32x32x16_bf16 v[48:63], v[238:241], v[128:131], v[48:63]
	v_addc_co_u32_e32 v133, vcc, 0, v201, vcc
	v_add_co_u32_e32 v134, vcc, s20, v200
	s_nop 1
	v_addc_co_u32_e32 v135, vcc, 0, v201, vcc
	v_add_co_u32_e32 v128, vcc, s25, v200
	v_mfma_f32_32x32x16_bf16 v[16:31], v[0:3], v[4:7], 0
	global_load_dwordx4 v[148:151], v[132:133], off
	global_load_dwordx4 v[144:147], v[134:135], off
	ds_read_b128 v[132:135], v221 offset:8704
	v_addc_co_u32_e32 v129, vcc, 0, v201, vcc
	v_add_co_u32_e32 v130, vcc, s30, v200
	s_nop 1
	v_addc_co_u32_e32 v131, vcc, 0, v201, vcc
	global_load_dwordx4 v[140:143], v[128:129], off
	global_load_dwordx4 v[136:139], v[130:131], off
	ds_read_b128 v[128:131], v221 offset:17408
	ds_read_b128 v[242:245], v221 offset:26112
	s_waitcnt lgkmcnt(2)
	v_mfma_f32_32x32x16_bf16 v[32:47], v[238:241], v[132:135], v[32:47]
	v_add_co_u32_e32 v132, vcc, s31, v200
	s_nop 1
	v_addc_co_u32_e32 v133, vcc, 0, v201, vcc
	v_add_co_u32_e32 v246, vcc, s33, v200
	s_waitcnt lgkmcnt(1)
	v_mfma_f32_32x32x16_bf16 v[16:31], v[238:241], v[128:131], v[16:31]
	v_addc_co_u32_e32 v247, vcc, 0, v201, vcc
	global_load_dwordx4 v[132:135], v[132:133], off
	s_nop 0
	global_load_dwordx4 v[128:131], v[246:247], off
	v_mfma_f32_32x32x16_bf16 v[0:15], v[0:3], v[8:11], 0
	s_waitcnt lgkmcnt(0)
	v_mfma_f32_32x32x16_bf16 v[0:15], v[238:241], v[242:245], v[0:15]
	ds_read_u16 v238, v220 offset:16896
	ds_read_u16 v242, v220 offset:17424
	ds_read_u16 v239, v220 offset:17952
	ds_read_u16 v243, v220 offset:18480
	ds_read_u16 v240, v220 offset:19008
	ds_read_u16 v244, v220 offset:19536
	ds_read_u16 v241, v220 offset:20064
	ds_read_u16 v245, v220 offset:20592
	s_waitcnt lgkmcnt(4)
	v_perm_b32 v239, v243, v239, s28
	v_perm_b32 v238, v242, v238, s28
	s_waitcnt lgkmcnt(2)
	v_perm_b32 v240, v244, v240, s28
	s_waitcnt lgkmcnt(0)
	v_perm_b32 v241, v245, v241, s28
	ds_read_b128 v[242:245], v222 offset:8704
	s_waitcnt lgkmcnt(0)
	v_mfma_f32_32x32x16_bf16 v[32:47], v[238:241], v[242:245], v[32:47]
	ds_read_b128 v[242:245], v222 offset:17408
	s_waitcnt lgkmcnt(0)
	v_mfma_f32_32x32x16_bf16 v[16:31], v[238:241], v[242:245], v[16:31]
	ds_read_b128 v[242:245], v222 offset:26112
	s_waitcnt lgkmcnt(0)
	v_mfma_f32_32x32x16_bf16 v[0:15], v[238:241], v[242:245], v[0:15]
	ds_read_u16 v238, v220 offset:25344
	ds_read_u16 v242, v220 offset:25872
	ds_read_u16 v239, v220 offset:26400
	ds_read_u16 v243, v220 offset:26928
	ds_read_u16 v240, v220 offset:27456
	ds_read_u16 v244, v220 offset:27984
	ds_read_u16 v241, v220 offset:28512
	ds_read_u16 v245, v220 offset:29040
	s_waitcnt lgkmcnt(4)
	v_perm_b32 v239, v243, v239, s28
	v_perm_b32 v238, v242, v238, s28
	s_waitcnt lgkmcnt(2)
	v_perm_b32 v240, v244, v240, s28
	s_waitcnt lgkmcnt(0)
	v_perm_b32 v241, v245, v241, s28
	ds_read_b128 v[242:245], v223 offset:8704
	s_waitcnt lgkmcnt(0)
	v_mfma_f32_32x32x16_bf16 v[32:47], v[238:241], v[242:245], v[32:47]
	ds_read_b128 v[242:245], v223 offset:17408
	s_waitcnt lgkmcnt(0)
	v_mfma_f32_32x32x16_bf16 v[16:31], v[238:241], v[242:245], v[16:31]
	ds_read_b128 v[242:245], v223 offset:26112
	s_waitcnt lgkmcnt(0)
	v_mfma_f32_32x32x16_bf16 v[0:15], v[238:241], v[242:245], v[0:15]
	ds_read_u16 v238, v220 offset:34848
	ds_read_u16 v239, v220 offset:35376
	ds_read_u16 v240, v220 offset:35904
	ds_read_u16 v241, v220 offset:36960
	ds_read_u16 v242, v220 offset:37488
	ds_read_u16 v243, v220 offset:36432
	ds_read_u16 v244, v220 offset:33792
	ds_read_u16 v245, v220 offset:34320
	s_waitcnt lgkmcnt(6)
	v_perm_b32 v239, v239, v238, s28
	s_waitcnt lgkmcnt(3)
	v_perm_b32 v241, v242, v241, s28
	s_waitcnt lgkmcnt(2)
	v_perm_b32 v240, v243, v240, s28
	s_waitcnt lgkmcnt(0)
	v_perm_b32 v238, v245, v244, s28
	ds_read_b128 v[242:245], v224 offset:17408
	ds_read_b128 v[246:249], v224 offset:26112
	s_waitcnt lgkmcnt(1)
	v_mfma_f32_32x32x16_bf16 v[16:31], v[238:241], v[242:245], v[16:31]
	ds_read_u16 v242, v220 offset:43296
	ds_read_u16 v243, v220 offset:43824
	ds_read_u16 v244, v220 offset:44352
	ds_read_u16 v245, v220 offset:45408
	ds_read_u16 v250, v220 offset:45936
	ds_read_u16 v251, v220 offset:44880
	ds_read_u16 v252, v220 offset:42240
	ds_read_u16 v253, v220 offset:42768
	s_waitcnt lgkmcnt(8)
	v_mfma_f32_32x32x16_bf16 v[0:15], v[238:241], v[246:249], v[0:15]
	s_waitcnt lgkmcnt(3)
	v_perm_b32 v241, v250, v245, s28
	s_waitcnt lgkmcnt(2)
	v_perm_b32 v240, v251, v244, s28
	v_perm_b32 v239, v243, v242, s28
	s_waitcnt lgkmcnt(0)
	v_perm_b32 v238, v253, v252, s28
	ds_read_b128 v[242:245], v225 offset:17408
	ds_read_b128 v[246:249], v225 offset:26112
	s_waitcnt lgkmcnt(1)
	v_mfma_f32_32x32x16_bf16 v[16:31], v[238:241], v[242:245], v[16:31]
	s_waitcnt lgkmcnt(0)
	v_mfma_f32_32x32x16_bf16 v[0:15], v[238:241], v[246:249], v[0:15]
	ds_read_u16 v238, v220 offset:50688
	ds_read_u16 v242, v220 offset:51216
	ds_read_u16 v239, v220 offset:51744
	ds_read_u16 v243, v220 offset:52272
	ds_read_u16 v240, v220 offset:52800
	ds_read_u16 v244, v220 offset:53328
	ds_read_u16 v241, v220 offset:53856
	ds_read_u16 v245, v220 offset:54384
	s_waitcnt lgkmcnt(4)
	v_perm_b32 v239, v243, v239, s28
	v_perm_b32 v238, v242, v238, s28
	s_waitcnt lgkmcnt(2)
	v_perm_b32 v240, v244, v240, s28
	s_waitcnt lgkmcnt(0)
	v_perm_b32 v241, v245, v241, s28
	ds_read_b128 v[242:245], v226 offset:26112
	s_waitcnt lgkmcnt(0)
	v_mfma_f32_32x32x16_bf16 v[0:15], v[238:241], v[242:245], v[0:15]
	ds_read_u16 v238, v220 offset:59136
	ds_read_u16 v242, v220 offset:59664
	ds_read_u16 v239, v220 offset:60192
	ds_read_u16 v243, v220 offset:60720
	ds_read_u16 v240, v220 offset:61248
	ds_read_u16 v244, v220 offset:61776
	ds_read_u16 v241, v220 offset:62304
	ds_read_u16 v245, v220 offset:62832
	s_waitcnt lgkmcnt(4)
	v_perm_b32 v239, v243, v239, s28
	v_perm_b32 v238, v242, v238, s28
	s_waitcnt lgkmcnt(2)
	v_perm_b32 v240, v244, v240, s28
	s_waitcnt lgkmcnt(0)
	v_perm_b32 v241, v245, v241, s28
	ds_read_b128 v[242:245], v227 offset:26112
	s_waitcnt lgkmcnt(0)
	v_mfma_f32_32x32x16_bf16 v[0:15], v[238:241], v[242:245], v[0:15]
	s_waitcnt lgkmcnt(0)
	s_barrier
	ds_read_b32 v238, v210
	s_add_i32 s22, s22, s23
	s_and_b64 vcc, exec, s[8:9]
	s_mov_b32 s35, s29
	s_waitcnt lgkmcnt(0)
	v_add_f32_e32 v48, v238, v48
	v_add_f32_e32 v49, v238, v49
	v_add_f32_e32 v50, v238, v50
	v_add_f32_e32 v51, v238, v51
	v_cvt_pk_bf16_f32 v48, v48, v49
	v_cvt_pk_bf16_f32 v49, v50, v51
	ds_write_b64 v228, v[48:49]
	v_add_f32_e32 v48, v238, v52
	v_add_f32_e32 v49, v238, v53
	v_cvt_pk_bf16_f32 v48, v48, v49
	v_add_f32_e32 v49, v238, v54
	v_add_f32_e32 v50, v238, v55
	v_cvt_pk_bf16_f32 v49, v49, v50
	ds_write_b64 v228, v[48:49] offset:16
	v_add_f32_e32 v48, v238, v56
	v_add_f32_e32 v49, v238, v57
	v_cvt_pk_bf16_f32 v48, v48, v49
	v_add_f32_e32 v49, v238, v58
	v_add_f32_e32 v50, v238, v59
	v_cvt_pk_bf16_f32 v49, v49, v50
	ds_write_b64 v228, v[48:49] offset:32
	v_add_f32_e32 v48, v238, v60
	v_add_f32_e32 v49, v238, v61
	v_cvt_pk_bf16_f32 v48, v48, v49
	v_add_f32_e32 v49, v238, v62
	v_add_f32_e32 v50, v238, v63
	v_cvt_pk_bf16_f32 v49, v49, v50
	ds_write_b64 v228, v[48:49] offset:48
	ds_read_b32 v48, v211
	s_waitcnt lgkmcnt(0)
	v_add_f32_e32 v32, v48, v32
	v_add_f32_e32 v33, v48, v33
	v_cvt_pk_bf16_f32 v32, v32, v33
	v_add_f32_e32 v33, v48, v34
	v_add_f32_e32 v34, v48, v35
	v_cvt_pk_bf16_f32 v33, v33, v34
	ds_write_b64 v228, v[32:33] offset:16896
	v_add_f32_e32 v32, v48, v36
	v_add_f32_e32 v33, v48, v37
	v_cvt_pk_bf16_f32 v32, v32, v33
	v_add_f32_e32 v33, v48, v38
	v_add_f32_e32 v34, v48, v39
	v_cvt_pk_bf16_f32 v33, v33, v34
	ds_write_b64 v228, v[32:33] offset:16912
	v_add_f32_e32 v32, v48, v40
	v_add_f32_e32 v33, v48, v41
	v_cvt_pk_bf16_f32 v32, v32, v33
	v_add_f32_e32 v33, v48, v42
	v_add_f32_e32 v34, v48, v43
	v_cvt_pk_bf16_f32 v33, v33, v34
	ds_write_b64 v228, v[32:33] offset:16928
	v_add_f32_e32 v32, v48, v44
	v_add_f32_e32 v33, v48, v45
	v_cvt_pk_bf16_f32 v32, v32, v33
	v_add_f32_e32 v33, v48, v46
	v_add_f32_e32 v34, v48, v47
	v_cvt_pk_bf16_f32 v33, v33, v34
	ds_write_b64 v228, v[32:33] offset:16944
	ds_read_b32 v32, v212
	s_waitcnt lgkmcnt(0)
	v_add_f32_e32 v16, v32, v16
	v_add_f32_e32 v17, v32, v17
	v_cvt_pk_bf16_f32 v16, v16, v17
	v_add_f32_e32 v17, v32, v18
	v_add_f32_e32 v18, v32, v19
	v_cvt_pk_bf16_f32 v17, v17, v18
	ds_write_b64 v228, v[16:17] offset:33792
	v_add_f32_e32 v16, v32, v20
	v_add_f32_e32 v17, v32, v21
	v_cvt_pk_bf16_f32 v16, v16, v17
	v_add_f32_e32 v17, v32, v22
	v_add_f32_e32 v18, v32, v23
	v_cvt_pk_bf16_f32 v17, v17, v18
	ds_write_b64 v228, v[16:17] offset:33808
	v_add_f32_e32 v16, v32, v24
	v_add_f32_e32 v17, v32, v25
	v_cvt_pk_bf16_f32 v16, v16, v17
	v_add_f32_e32 v17, v32, v26
	v_add_f32_e32 v18, v32, v27
	v_cvt_pk_bf16_f32 v17, v17, v18
	ds_write_b64 v228, v[16:17] offset:33824
	v_add_f32_e32 v16, v32, v28
	v_add_f32_e32 v17, v32, v29
	v_cvt_pk_bf16_f32 v16, v16, v17
	v_add_f32_e32 v17, v32, v30
	v_add_f32_e32 v18, v32, v31
	v_cvt_pk_bf16_f32 v17, v17, v18
	ds_write_b64 v228, v[16:17] offset:33840
	ds_read_b32 v16, v213
	s_waitcnt lgkmcnt(0)
	v_add_f32_e32 v0, v16, v0
	v_add_f32_e32 v1, v16, v1
	v_cvt_pk_bf16_f32 v0, v0, v1
	v_add_f32_e32 v1, v16, v2
	v_add_f32_e32 v2, v16, v3
	v_cvt_pk_bf16_f32 v1, v1, v2
	ds_write_b64 v228, v[0:1] offset:50688
	v_add_f32_e32 v0, v16, v4
	v_add_f32_e32 v1, v16, v5
	v_cvt_pk_bf16_f32 v0, v0, v1
	v_add_f32_e32 v1, v16, v6
	v_add_f32_e32 v2, v16, v7
	v_cvt_pk_bf16_f32 v1, v1, v2
	ds_write_b64 v228, v[0:1] offset:50704
	v_add_f32_e32 v0, v16, v8
	v_add_f32_e32 v1, v16, v9
	v_cvt_pk_bf16_f32 v0, v0, v1
	v_add_f32_e32 v1, v16, v10
	v_add_f32_e32 v2, v16, v11
	v_cvt_pk_bf16_f32 v1, v1, v2
	ds_write_b64 v228, v[0:1] offset:50720
	v_add_f32_e32 v0, v16, v12
	v_add_f32_e32 v1, v16, v13
	v_cvt_pk_bf16_f32 v0, v0, v1
	v_add_f32_e32 v1, v16, v14
	v_add_f32_e32 v2, v16, v15
	v_cvt_pk_bf16_f32 v1, v1, v2
	ds_write_b64 v228, v[0:1] offset:50736
	s_waitcnt lgkmcnt(0)
	s_barrier
	ds_read_b128 v[0:3], v230
	s_waitcnt vmcnt(7)
	v_lshlrev_b32_e32 v4, 16, v156
	s_waitcnt vmcnt(6)
	v_lshlrev_b32_e32 v6, 16, v152
	s_waitcnt lgkmcnt(0)
	v_lshlrev_b32_e32 v5, 16, v0
	v_mul_f32_e32 v4, v5, v4
	v_and_b32_e32 v0, 0xffff0000, v0
	v_and_b32_e32 v5, 0xffff0000, v156
	v_mul_f32_e32 v0, v0, v5
	v_cvt_pk_bf16_f32 v0, v4, v0
	v_lshlrev_b32_e32 v4, 16, v157
	v_lshlrev_b32_e32 v5, 16, v1
	v_mul_f32_e32 v4, v5, v4
	v_and_b32_e32 v1, 0xffff0000, v1
	v_and_b32_e32 v5, 0xffff0000, v157
	v_mul_f32_e32 v1, v1, v5
	v_cvt_pk_bf16_f32 v1, v4, v1
	v_lshlrev_b32_e32 v4, 16, v158
	v_lshlrev_b32_e32 v5, 16, v2
	v_mul_f32_e32 v4, v5, v4
	v_and_b32_e32 v2, 0xffff0000, v2
	v_and_b32_e32 v5, 0xffff0000, v158
	v_mul_f32_e32 v2, v2, v5
	v_cvt_pk_bf16_f32 v2, v4, v2
	v_lshlrev_b32_e32 v4, 16, v159
	v_lshlrev_b32_e32 v5, 16, v3
	v_mul_f32_e32 v4, v5, v4
	v_and_b32_e32 v3, 0xffff0000, v3
	v_and_b32_e32 v5, 0xffff0000, v159
	v_mul_f32_e32 v3, v3, v5
	v_cvt_pk_bf16_f32 v3, v4, v3
	global_store_dwordx4 v[200:201], v[0:3], off sc1
	ds_read_b128 v[0:3], v230 offset:8448
	v_lshl_add_u64 v[4:5], s[10:11], 0, v[184:185]
	v_lshlrev_b64 v[4:5], 12, v[4:5]
	v_lshl_add_u64 v[4:5], v[198:199], 0, v[4:5]
	s_waitcnt lgkmcnt(0)
	v_lshlrev_b32_e32 v7, 16, v0
	v_mul_f32_e32 v6, v7, v6
	v_and_b32_e32 v0, 0xffff0000, v0
	v_and_b32_e32 v7, 0xffff0000, v152
	v_mul_f32_e32 v0, v0, v7
	v_cvt_pk_bf16_f32 v0, v6, v0
	v_lshlrev_b32_e32 v6, 16, v153
	v_lshlrev_b32_e32 v7, 16, v1
	v_mul_f32_e32 v6, v7, v6
	v_and_b32_e32 v1, 0xffff0000, v1
	v_and_b32_e32 v7, 0xffff0000, v153
	v_mul_f32_e32 v1, v1, v7
	v_cvt_pk_bf16_f32 v1, v6, v1
	v_lshlrev_b32_e32 v6, 16, v154
	v_lshlrev_b32_e32 v7, 16, v2
	v_mul_f32_e32 v6, v7, v6
	v_and_b32_e32 v2, 0xffff0000, v2
	v_and_b32_e32 v7, 0xffff0000, v154
	v_mul_f32_e32 v2, v2, v7
	v_cvt_pk_bf16_f32 v2, v6, v2
	v_lshlrev_b32_e32 v6, 16, v155
	v_lshlrev_b32_e32 v7, 16, v3
	v_mul_f32_e32 v6, v7, v6
	v_and_b32_e32 v3, 0xffff0000, v3
	v_and_b32_e32 v7, 0xffff0000, v155
	v_mul_f32_e32 v3, v3, v7
	v_cvt_pk_bf16_f32 v3, v6, v3
	global_store_dwordx4 v[4:5], v[0:3], off sc1
	ds_read_b128 v[0:3], v230 offset:16896
	s_waitcnt vmcnt(7)
	v_lshlrev_b32_e32 v6, 16, v148
	v_lshl_add_u64 v[4:5], s[10:11], 0, v[186:187]
	v_lshlrev_b64 v[4:5], 12, v[4:5]
	v_lshl_add_u64 v[4:5], v[198:199], 0, v[4:5]
	s_waitcnt lgkmcnt(0)
	v_lshlrev_b32_e32 v7, 16, v0
	v_mul_f32_e32 v6, v7, v6
	v_and_b32_e32 v0, 0xffff0000, v0
	v_and_b32_e32 v7, 0xffff0000, v148
	v_mul_f32_e32 v0, v0, v7
	v_cvt_pk_bf16_f32 v0, v6, v0
	v_lshlrev_b32_e32 v6, 16, v149
	v_lshlrev_b32_e32 v7, 16, v1
	v_mul_f32_e32 v6, v7, v6
	v_and_b32_e32 v1, 0xffff0000, v1
	v_and_b32_e32 v7, 0xffff0000, v149
	v_mul_f32_e32 v1, v1, v7
	v_cvt_pk_bf16_f32 v1, v6, v1
	v_lshlrev_b32_e32 v6, 16, v150
	v_lshlrev_b32_e32 v7, 16, v2
	v_mul_f32_e32 v6, v7, v6
	v_and_b32_e32 v2, 0xffff0000, v2
	v_and_b32_e32 v7, 0xffff0000, v150
	v_mul_f32_e32 v2, v2, v7
	v_cvt_pk_bf16_f32 v2, v6, v2
	v_lshlrev_b32_e32 v6, 16, v151
	v_lshlrev_b32_e32 v7, 16, v3
	v_mul_f32_e32 v6, v7, v6
	v_and_b32_e32 v3, 0xffff0000, v3
	v_and_b32_e32 v7, 0xffff0000, v151
	v_mul_f32_e32 v3, v3, v7
	v_cvt_pk_bf16_f32 v3, v6, v3
	global_store_dwordx4 v[4:5], v[0:3], off sc1
	ds_read_b128 v[0:3], v230 offset:25344
	s_waitcnt vmcnt(7)
	v_lshlrev_b32_e32 v6, 16, v144
	v_lshl_add_u64 v[4:5], s[10:11], 0, v[188:189]
	v_lshlrev_b64 v[4:5], 12, v[4:5]
	v_lshl_add_u64 v[4:5], v[198:199], 0, v[4:5]
	s_waitcnt lgkmcnt(0)
	v_lshlrev_b32_e32 v7, 16, v0
	v_mul_f32_e32 v6, v7, v6
	v_and_b32_e32 v0, 0xffff0000, v0
	v_and_b32_e32 v7, 0xffff0000, v144
	v_mul_f32_e32 v0, v0, v7
	v_cvt_pk_bf16_f32 v0, v6, v0
	v_lshlrev_b32_e32 v6, 16, v145
	v_lshlrev_b32_e32 v7, 16, v1
	v_mul_f32_e32 v6, v7, v6
	v_and_b32_e32 v1, 0xffff0000, v1
	v_and_b32_e32 v7, 0xffff0000, v145
	v_mul_f32_e32 v1, v1, v7
	v_cvt_pk_bf16_f32 v1, v6, v1
	v_lshlrev_b32_e32 v6, 16, v146
	v_lshlrev_b32_e32 v7, 16, v2
	v_mul_f32_e32 v6, v7, v6
	v_and_b32_e32 v2, 0xffff0000, v2
	v_and_b32_e32 v7, 0xffff0000, v146
	v_mul_f32_e32 v2, v2, v7
	v_cvt_pk_bf16_f32 v2, v6, v2
	v_lshlrev_b32_e32 v6, 16, v147
	v_lshlrev_b32_e32 v7, 16, v3
	v_mul_f32_e32 v6, v7, v6
	v_and_b32_e32 v3, 0xffff0000, v3
	v_and_b32_e32 v7, 0xffff0000, v147
	v_mul_f32_e32 v3, v3, v7
	v_cvt_pk_bf16_f32 v3, v6, v3
	global_store_dwordx4 v[4:5], v[0:3], off sc1
	ds_read_b128 v[0:3], v230 offset:33792
	s_waitcnt vmcnt(7)
	v_lshlrev_b32_e32 v6, 16, v140
	v_lshl_add_u64 v[4:5], s[10:11], 0, v[190:191]
	v_lshlrev_b64 v[4:5], 12, v[4:5]
	v_lshl_add_u64 v[4:5], v[198:199], 0, v[4:5]
	s_waitcnt lgkmcnt(0)
	v_lshlrev_b32_e32 v7, 16, v0
	v_mul_f32_e32 v6, v7, v6
	v_and_b32_e32 v0, 0xffff0000, v0
	v_and_b32_e32 v7, 0xffff0000, v140
	v_mul_f32_e32 v0, v0, v7
	v_cvt_pk_bf16_f32 v0, v6, v0
	v_lshlrev_b32_e32 v6, 16, v141
	v_lshlrev_b32_e32 v7, 16, v1
	v_mul_f32_e32 v6, v7, v6
	v_and_b32_e32 v1, 0xffff0000, v1
	v_and_b32_e32 v7, 0xffff0000, v141
	v_mul_f32_e32 v1, v1, v7
	v_cvt_pk_bf16_f32 v1, v6, v1
	v_lshlrev_b32_e32 v6, 16, v142
	v_lshlrev_b32_e32 v7, 16, v2
	v_mul_f32_e32 v6, v7, v6
	v_and_b32_e32 v2, 0xffff0000, v2
	v_and_b32_e32 v7, 0xffff0000, v142
	v_mul_f32_e32 v2, v2, v7
	v_cvt_pk_bf16_f32 v2, v6, v2
	v_lshlrev_b32_e32 v6, 16, v143
	v_lshlrev_b32_e32 v7, 16, v3
	v_mul_f32_e32 v6, v7, v6
	v_and_b32_e32 v3, 0xffff0000, v3
	v_and_b32_e32 v7, 0xffff0000, v143
	v_mul_f32_e32 v3, v3, v7
	v_cvt_pk_bf16_f32 v3, v6, v3
	global_store_dwordx4 v[4:5], v[0:3], off sc1
	ds_read_b128 v[0:3], v230 offset:42240
	s_waitcnt vmcnt(7)
	v_lshlrev_b32_e32 v6, 16, v136
	v_lshl_add_u64 v[4:5], s[10:11], 0, v[192:193]
	v_lshlrev_b64 v[4:5], 12, v[4:5]
	v_lshl_add_u64 v[4:5], v[198:199], 0, v[4:5]
	s_waitcnt lgkmcnt(0)
	v_lshlrev_b32_e32 v7, 16, v0
	v_mul_f32_e32 v6, v7, v6
	v_and_b32_e32 v0, 0xffff0000, v0
	v_and_b32_e32 v7, 0xffff0000, v136
	v_mul_f32_e32 v0, v0, v7
	v_cvt_pk_bf16_f32 v0, v6, v0
	v_lshlrev_b32_e32 v6, 16, v137
	v_lshlrev_b32_e32 v7, 16, v1
	v_mul_f32_e32 v6, v7, v6
	v_and_b32_e32 v1, 0xffff0000, v1
	v_and_b32_e32 v7, 0xffff0000, v137
	v_mul_f32_e32 v1, v1, v7
	v_cvt_pk_bf16_f32 v1, v6, v1
	v_lshlrev_b32_e32 v6, 16, v138
	v_lshlrev_b32_e32 v7, 16, v2
	v_mul_f32_e32 v6, v7, v6
	v_and_b32_e32 v2, 0xffff0000, v2
	v_and_b32_e32 v7, 0xffff0000, v138
	v_mul_f32_e32 v2, v2, v7
	v_cvt_pk_bf16_f32 v2, v6, v2
	v_lshlrev_b32_e32 v6, 16, v139
	v_lshlrev_b32_e32 v7, 16, v3
	v_mul_f32_e32 v6, v7, v6
	v_and_b32_e32 v3, 0xffff0000, v3
	v_and_b32_e32 v7, 0xffff0000, v139
	v_mul_f32_e32 v3, v3, v7
	v_cvt_pk_bf16_f32 v3, v6, v3
	global_store_dwordx4 v[4:5], v[0:3], off sc1
	ds_read_b128 v[0:3], v230 offset:50688
	s_waitcnt vmcnt(7)
	v_lshlrev_b32_e32 v6, 16, v132
	v_lshl_add_u64 v[4:5], s[10:11], 0, v[194:195]
	v_lshlrev_b64 v[4:5], 12, v[4:5]
	v_lshl_add_u64 v[4:5], v[198:199], 0, v[4:5]
	s_waitcnt lgkmcnt(0)
	v_lshlrev_b32_e32 v7, 16, v0
	v_mul_f32_e32 v6, v7, v6
	v_and_b32_e32 v0, 0xffff0000, v0
	v_and_b32_e32 v7, 0xffff0000, v132
	v_mul_f32_e32 v0, v0, v7
	v_cvt_pk_bf16_f32 v0, v6, v0
	v_lshlrev_b32_e32 v6, 16, v133
	v_lshlrev_b32_e32 v7, 16, v1
	v_mul_f32_e32 v6, v7, v6
	v_and_b32_e32 v1, 0xffff0000, v1
	v_and_b32_e32 v7, 0xffff0000, v133
	v_mul_f32_e32 v1, v1, v7
	v_cvt_pk_bf16_f32 v1, v6, v1
	v_lshlrev_b32_e32 v6, 16, v134
	v_lshlrev_b32_e32 v7, 16, v2
	v_mul_f32_e32 v6, v7, v6
	v_and_b32_e32 v2, 0xffff0000, v2
	v_and_b32_e32 v7, 0xffff0000, v134
	v_mul_f32_e32 v2, v2, v7
	v_cvt_pk_bf16_f32 v2, v6, v2
	v_lshlrev_b32_e32 v6, 16, v135
	v_lshlrev_b32_e32 v7, 16, v3
	v_mul_f32_e32 v6, v7, v6
	v_and_b32_e32 v3, 0xffff0000, v3
	v_and_b32_e32 v7, 0xffff0000, v135
	v_mul_f32_e32 v3, v3, v7
	v_cvt_pk_bf16_f32 v3, v6, v3
	global_store_dwordx4 v[4:5], v[0:3], off sc1
	ds_read_b128 v[0:3], v230 offset:59136
	s_waitcnt vmcnt(7)
	v_lshlrev_b32_e32 v6, 16, v128
	v_lshl_add_u64 v[4:5], s[10:11], 0, v[196:197]
	v_lshlrev_b64 v[4:5], 12, v[4:5]
	v_lshl_add_u64 v[4:5], v[198:199], 0, v[4:5]
	s_waitcnt lgkmcnt(0)
	v_lshlrev_b32_e32 v7, 16, v0
	v_mul_f32_e32 v6, v7, v6
	v_and_b32_e32 v0, 0xffff0000, v0
	v_and_b32_e32 v7, 0xffff0000, v128
	v_mul_f32_e32 v0, v0, v7
	v_cvt_pk_bf16_f32 v0, v6, v0
	v_lshlrev_b32_e32 v6, 16, v129
	v_lshlrev_b32_e32 v7, 16, v1
	v_mul_f32_e32 v6, v7, v6
	v_and_b32_e32 v1, 0xffff0000, v1
	v_and_b32_e32 v7, 0xffff0000, v129
	v_mul_f32_e32 v1, v1, v7
	v_cvt_pk_bf16_f32 v1, v6, v1
	v_lshlrev_b32_e32 v6, 16, v130
	v_lshlrev_b32_e32 v7, 16, v2
	v_mul_f32_e32 v6, v7, v6
	v_and_b32_e32 v2, 0xffff0000, v2
	v_and_b32_e32 v7, 0xffff0000, v130
	v_mul_f32_e32 v2, v2, v7
	v_cvt_pk_bf16_f32 v2, v6, v2
	v_lshlrev_b32_e32 v6, 16, v131
	v_lshlrev_b32_e32 v7, 16, v3
	v_mul_f32_e32 v6, v7, v6
	v_and_b32_e32 v3, 0xffff0000, v3
	v_and_b32_e32 v7, 0xffff0000, v131
	v_mul_f32_e32 v3, v3, v7
	v_cvt_pk_bf16_f32 v3, v6, v3
	global_store_dwordx4 v[4:5], v[0:3], off sc1
	s_waitcnt lgkmcnt(0)
	s_barrier
	s_cbranch_vccnz .LBB0_336

.LBB0_404:
	v_lshl_or_b32 v168, s10, 8, v188
	v_lshl_add_u32 v172, s40, 8, v186
	v_ashrrev_i32_e32 v169, 31, v168
	v_lshlrev_b64 v[204:205], 1, v[168:169]
	v_ashrrev_i32_e32 v173, 31, v172
	v_lshl_add_u64 v[170:171], s[16:17], 0, v[204:205]
	v_lshlrev_b64 v[206:207], 11, v[172:173]
	v_lshl_add_u64 v[128:129], v[170:171], 0, v[206:207]
	global_load_dwordx4 v[194:197], v[128:129], off
	global_load_dwordx4 v[198:201], v[128:129], off offset:256
	v_or_b32_e32 v182, 16, v172
	v_or_b32_e32 v178, 32, v172
	v_or_b32_e32 v174, 48, v172
	v_ashrrev_i32_e32 v183, 31, v182
	v_ashrrev_i32_e32 v179, 31, v178
	v_ashrrev_i32_e32 v175, 31, v174
	v_lshlrev_b64 v[184:185], 11, v[182:183]
	v_lshlrev_b64 v[180:181], 11, v[178:179]
	v_lshlrev_b64 v[176:177], 11, v[174:175]
	v_lshl_add_u64 v[128:129], v[170:171], 0, v[184:185]
	v_lshl_add_u64 v[130:131], v[170:171], 0, v[180:181]
	v_lshl_add_u64 v[208:209], v[170:171], 0, v[176:177]
	global_load_dwordx4 v[148:151], v[128:129], off
	global_load_dwordx4 v[144:147], v[128:129], off offset:256
	global_load_dwordx4 v[140:143], v[130:131], off
	global_load_dwordx4 v[136:139], v[130:131], off offset:256
	global_load_dwordx4 v[132:135], v[208:209], off
	s_nop 0
	global_load_dwordx4 v[128:131], v[208:209], off offset:256
	v_and_b32_e32 v208, 64, v192
	v_xor_b32_e32 v193, 16, v192
	v_add_u32_e32 v208, 64, v208
	v_xor_b32_e32 v209, 32, v192
	v_cmp_lt_i32_e32 vcc, v193, v208
	v_lshl_add_u64 v[206:207], s[16:17], 0, v[206:207]
	v_lshl_add_u64 v[204:205], v[206:207], 0, v[204:205]
	v_cndmask_b32_e32 v193, v192, v193, vcc
	v_cmp_lt_i32_e32 vcc, v209, v208
	v_lshlrev_b32_e32 v193, 2, v193
	s_lshl_b32 s40, s10, 2
	v_cndmask_b32_e32 v214, v192, v209, vcc
	s_ashr_i32 s41, s40, 31
	s_waitcnt vmcnt(0)
	v_lshlrev_b32_e32 v206, 16, v194
	v_and_b32_e32 v207, 0xffff0000, v194
	v_lshlrev_b32_e32 v194, 16, v195
	v_and_b32_e32 v195, 0xffff0000, v195
	v_lshlrev_b32_e32 v208, 16, v196
	v_and_b32_e32 v209, 0xffff0000, v196
	v_lshlrev_b32_e32 v196, 16, v197
	v_and_b32_e32 v197, 0xffff0000, v197
	v_lshlrev_b32_e32 v210, 16, v198
	v_and_b32_e32 v211, 0xffff0000, v198
	v_lshlrev_b32_e32 v198, 16, v199
	v_and_b32_e32 v199, 0xffff0000, v199
	v_lshlrev_b32_e32 v212, 16, v200
	v_and_b32_e32 v213, 0xffff0000, v200
	v_lshlrev_b32_e32 v200, 16, v201
	v_and_b32_e32 v201, 0xffff0000, v201
	v_pk_add_f32 v[126:127], v[126:127], v[194:195]
	v_pk_add_f32 v[124:125], v[124:125], v[206:207]
	v_pk_add_f32 v[122:123], v[122:123], v[196:197]
	v_pk_add_f32 v[120:121], v[120:121], v[208:209]
	v_pk_add_f32 v[118:119], v[118:119], v[198:199]
	v_pk_add_f32 v[116:117], v[116:117], v[210:211]
	v_pk_add_f32 v[194:195], v[114:115], v[200:201]
	v_pk_add_f32 v[196:197], v[112:113], v[212:213]
	v_mul_f32_e32 v114, v125, v125
	v_mul_f32_e32 v115, v127, v127
	v_mul_f32_e32 v198, v121, v121
	v_mul_f32_e32 v199, v123, v123
	v_cvt_pk_bf16_f32 v112, v124, v125
	v_cvt_pk_bf16_f32 v113, v126, v127
	v_mul_f32_e32 v125, v117, v117
	v_mul_f32_e32 v127, v119, v119
	v_mul_f32_e32 v200, v197, v197
	v_mul_f32_e32 v201, v195, v195
	v_fmac_f32_e32 v114, v124, v124
	v_fmac_f32_e32 v115, v126, v126
	v_fmac_f32_e32 v198, v120, v120
	v_fmac_f32_e32 v199, v122, v122
	v_fmac_f32_e32 v125, v116, v116
	v_fmac_f32_e32 v127, v118, v118
	v_fmac_f32_e32 v200, v196, v196
	v_fmac_f32_e32 v201, v194, v194
	v_add_f32_e32 v114, v114, v115
	v_add_f32_e32 v115, v198, v199
	v_add_f32_e32 v124, v125, v127
	v_add_f32_e32 v125, v200, v201
	v_add_f32_e32 v114, v114, v115
	v_add_f32_e32 v115, v124, v125
	v_add_f32_e32 v124, v114, v115
	ds_bpermute_b32 v125, v193, v124
	v_cvt_pk_bf16_f32 v114, v120, v121
	v_cvt_pk_bf16_f32 v115, v122, v123
	global_store_dwordx4 v[204:205], v[112:115], off sc1
	v_cvt_pk_bf16_f32 v116, v116, v117
	v_cvt_pk_bf16_f32 v117, v118, v119
	v_cvt_pk_bf16_f32 v118, v196, v197
	v_cvt_pk_bf16_f32 v119, v194, v195
	global_store_dwordx4 v[204:205], v[116:119], off offset:256 sc1
	s_waitcnt lgkmcnt(0)
	v_add_f32_e32 v113, v124, v125
	v_lshlrev_b32_e32 v112, 2, v214
	ds_bpermute_b32 v114, v112, v113
	s_and_saveexec_b64 s[4:5], s[6:7]
	s_cbranch_execz .LBB0_406
	v_lshlrev_b64 v[116:117], 6, v[172:173]
	v_lshl_add_u64 v[116:117], s[22:23], 0, v[116:117]
	v_lshl_add_u64 v[116:117], s[40:41], 2, v[116:117]
	s_lshl_b32 s10, s51, 2
	v_lshl_add_u64 v[116:117], v[116:117], 0, s[10:11]
	s_waitcnt lgkmcnt(0)
	v_add_f32_e32 v113, v113, v114
	global_store_dword v[116:117], v113, off
.LBB0_406:
	s_or_b64 exec, exec, s[4:5]
	s_waitcnt lgkmcnt(0)
	v_lshlrev_b32_e32 v114, 16, v148
	v_and_b32_e32 v115, 0xffff0000, v148
	v_lshlrev_b32_e32 v116, 16, v149
	v_and_b32_e32 v117, 0xffff0000, v149
	v_lshlrev_b32_e32 v118, 16, v150
	v_and_b32_e32 v119, 0xffff0000, v150
	v_lshlrev_b32_e32 v120, 16, v151
	v_and_b32_e32 v121, 0xffff0000, v151
	v_pk_add_f32 v[110:111], v[110:111], v[116:117]
	v_pk_add_f32 v[108:109], v[108:109], v[114:115]
	v_pk_add_f32 v[114:115], v[106:107], v[120:121]
	v_pk_add_f32 v[106:107], v[104:105], v[118:119]
	v_mul_f32_e32 v104, v109, v109
	v_mul_f32_e32 v105, v111, v111
	v_fmac_f32_e32 v104, v108, v108
	v_fmac_f32_e32 v105, v110, v110
	v_add_f32_e32 v104, v104, v105
	v_mul_f32_e32 v105, v107, v107
	v_mul_f32_e32 v113, v115, v115
	v_fmac_f32_e32 v105, v106, v106
	v_fmac_f32_e32 v113, v114, v114
	v_add_f32_e32 v105, v105, v113
	v_add_f32_e32 v113, v104, v105
	v_cvt_pk_bf16_f32 v104, v108, v109
	v_cvt_pk_bf16_f32 v105, v110, v111
	v_lshlrev_b32_e32 v108, 16, v144
	v_and_b32_e32 v109, 0xffff0000, v144
	v_lshlrev_b32_e32 v110, 16, v145
	v_and_b32_e32 v111, 0xffff0000, v145
	v_cvt_pk_bf16_f32 v106, v106, v107
	v_cvt_pk_bf16_f32 v107, v114, v115
	v_lshlrev_b32_e32 v114, 16, v146
	v_and_b32_e32 v115, 0xffff0000, v146
	v_pk_add_f32 v[102:103], v[102:103], v[110:111]
	v_pk_add_f32 v[100:101], v[100:101], v[108:109]
	v_lshlrev_b32_e32 v116, 16, v147
	v_and_b32_e32 v117, 0xffff0000, v147
	v_pk_add_f32 v[110:111], v[96:97], v[114:115]
	v_mul_f32_e32 v96, v101, v101
	v_mul_f32_e32 v97, v103, v103
	v_pk_add_f32 v[108:109], v[98:99], v[116:117]
	v_fmac_f32_e32 v96, v100, v100
	v_fmac_f32_e32 v97, v102, v102
	v_add_f32_e32 v96, v96, v97
	v_mul_f32_e32 v97, v111, v111
	v_mul_f32_e32 v98, v109, v109
	v_fmac_f32_e32 v97, v110, v110
	v_fmac_f32_e32 v98, v108, v108
	v_add_f32_e32 v97, v97, v98
	v_add_f32_e32 v96, v96, v97
	v_add_f32_e32 v99, v113, v96
	ds_bpermute_b32 v113, v193, v99
	v_lshl_add_u64 v[96:97], s[16:17], 0, v[184:185]
	v_lshl_add_u64 v[114:115], v[168:169], 1, v[96:97]
	global_store_dwordx4 v[114:115], v[104:107], off sc1
	v_cvt_pk_bf16_f32 v98, v100, v101
	s_waitcnt lgkmcnt(0)
	v_add_f32_e32 v96, v99, v113
	ds_bpermute_b32 v97, v112, v96
	v_cvt_pk_bf16_f32 v99, v102, v103
	v_cvt_pk_bf16_f32 v100, v110, v111
	v_cvt_pk_bf16_f32 v101, v108, v109
	global_store_dwordx4 v[114:115], v[98:101], off offset:256 sc1
	s_and_saveexec_b64 s[4:5], s[6:7]
	s_cbranch_execz .LBB0_408
	v_lshlrev_b64 v[98:99], 6, v[182:183]
	v_lshl_add_u64 v[98:99], s[22:23], 0, v[98:99]
	v_lshl_add_u64 v[98:99], s[40:41], 2, v[98:99]
	s_lshl_b32 s10, s51, 2
	v_lshl_add_u64 v[98:99], v[98:99], 0, s[10:11]
	s_waitcnt lgkmcnt(0)
	v_add_f32_e32 v96, v96, v97
	global_store_dword v[98:99], v96, off
.LBB0_408:
	s_or_b64 exec, exec, s[4:5]
	v_lshlrev_b32_e32 v96, 16, v140
	s_waitcnt lgkmcnt(0)
	v_and_b32_e32 v97, 0xffff0000, v140
	v_lshlrev_b32_e32 v98, 16, v141
	v_and_b32_e32 v99, 0xffff0000, v141
	v_lshlrev_b32_e32 v100, 16, v142
	v_and_b32_e32 v101, 0xffff0000, v142
	v_lshlrev_b32_e32 v102, 16, v143
	v_and_b32_e32 v103, 0xffff0000, v143
	v_pk_add_f32 v[94:95], v[94:95], v[98:99]
	v_pk_add_f32 v[92:93], v[92:93], v[96:97]
	v_pk_add_f32 v[96:97], v[90:91], v[102:103]
	v_pk_add_f32 v[90:91], v[88:89], v[100:101]
	v_mul_f32_e32 v88, v93, v93
	v_mul_f32_e32 v89, v95, v95
	v_fmac_f32_e32 v88, v92, v92
	v_fmac_f32_e32 v89, v94, v94
	v_add_f32_e32 v88, v88, v89
	v_mul_f32_e32 v89, v91, v91
	v_mul_f32_e32 v98, v97, v97
	v_fmac_f32_e32 v89, v90, v90
	v_fmac_f32_e32 v98, v96, v96
	v_add_f32_e32 v89, v89, v98
	v_add_f32_e32 v100, v88, v89
	v_cvt_pk_bf16_f32 v88, v92, v93
	v_cvt_pk_bf16_f32 v89, v94, v95
	v_lshlrev_b32_e32 v92, 16, v136
	v_and_b32_e32 v93, 0xffff0000, v136
	v_lshlrev_b32_e32 v94, 16, v137
	v_and_b32_e32 v95, 0xffff0000, v137
	v_cvt_pk_bf16_f32 v90, v90, v91
	v_cvt_pk_bf16_f32 v91, v96, v97
	v_lshlrev_b32_e32 v96, 16, v138
	v_and_b32_e32 v97, 0xffff0000, v138
	v_pk_add_f32 v[86:87], v[86:87], v[94:95]
	v_pk_add_f32 v[84:85], v[84:85], v[92:93]
	v_lshlrev_b32_e32 v98, 16, v139
	v_and_b32_e32 v99, 0xffff0000, v139
	v_pk_add_f32 v[94:95], v[80:81], v[96:97]
	v_mul_f32_e32 v80, v85, v85
	v_mul_f32_e32 v81, v87, v87
	v_pk_add_f32 v[92:93], v[82:83], v[98:99]
	v_fmac_f32_e32 v80, v84, v84
	v_fmac_f32_e32 v81, v86, v86
	v_add_f32_e32 v80, v80, v81
	v_mul_f32_e32 v81, v95, v95
	v_mul_f32_e32 v82, v93, v93
	v_fmac_f32_e32 v81, v94, v94
	v_fmac_f32_e32 v82, v92, v92
	v_add_f32_e32 v81, v81, v82
	v_add_f32_e32 v80, v80, v81
	v_add_f32_e32 v83, v100, v80
	ds_bpermute_b32 v98, v193, v83
	v_lshl_add_u64 v[80:81], s[16:17], 0, v[180:181]
	v_lshl_add_u64 v[96:97], v[168:169], 1, v[80:81]
	global_store_dwordx4 v[96:97], v[88:91], off sc1
	v_cvt_pk_bf16_f32 v82, v84, v85
	s_waitcnt lgkmcnt(0)
	v_add_f32_e32 v80, v83, v98
	ds_bpermute_b32 v81, v112, v80
	v_cvt_pk_bf16_f32 v83, v86, v87
	v_cvt_pk_bf16_f32 v84, v94, v95
	v_cvt_pk_bf16_f32 v85, v92, v93
	global_store_dwordx4 v[96:97], v[82:85], off offset:256 sc1
	s_and_saveexec_b64 s[4:5], s[6:7]
	s_cbranch_execz .LBB0_410
	v_lshlrev_b64 v[82:83], 6, v[178:179]
	v_lshl_add_u64 v[82:83], s[22:23], 0, v[82:83]
	v_lshl_add_u64 v[82:83], s[40:41], 2, v[82:83]
	s_lshl_b32 s10, s51, 2
	v_lshl_add_u64 v[82:83], v[82:83], 0, s[10:11]
	s_waitcnt lgkmcnt(0)
	v_add_f32_e32 v80, v80, v81
	global_store_dword v[82:83], v80, off
.LBB0_410:
	s_or_b64 exec, exec, s[4:5]
	v_lshlrev_b32_e32 v80, 16, v132
	s_waitcnt lgkmcnt(0)
	v_and_b32_e32 v81, 0xffff0000, v132
	v_lshlrev_b32_e32 v82, 16, v133
	v_and_b32_e32 v83, 0xffff0000, v133
	v_lshlrev_b32_e32 v84, 16, v134
	v_and_b32_e32 v85, 0xffff0000, v134
	v_lshlrev_b32_e32 v86, 16, v135
	v_and_b32_e32 v87, 0xffff0000, v135
	v_pk_add_f32 v[78:79], v[78:79], v[82:83]
	v_pk_add_f32 v[76:77], v[76:77], v[80:81]
	v_pk_add_f32 v[80:81], v[74:75], v[86:87]
	v_pk_add_f32 v[74:75], v[72:73], v[84:85]
	v_mul_f32_e32 v72, v77, v77
	v_mul_f32_e32 v73, v79, v79
	v_fmac_f32_e32 v72, v76, v76
	v_fmac_f32_e32 v73, v78, v78
	v_add_f32_e32 v72, v72, v73
	v_mul_f32_e32 v73, v75, v75
	v_mul_f32_e32 v82, v81, v81
	v_fmac_f32_e32 v73, v74, v74
	v_fmac_f32_e32 v82, v80, v80
	v_add_f32_e32 v73, v73, v82
	v_add_f32_e32 v84, v72, v73
	v_cvt_pk_bf16_f32 v72, v76, v77
	v_cvt_pk_bf16_f32 v73, v78, v79
	v_lshlrev_b32_e32 v76, 16, v128
	v_and_b32_e32 v77, 0xffff0000, v128
	v_lshlrev_b32_e32 v78, 16, v129
	v_and_b32_e32 v79, 0xffff0000, v129
	v_cvt_pk_bf16_f32 v74, v74, v75
	v_cvt_pk_bf16_f32 v75, v80, v81
	v_lshlrev_b32_e32 v80, 16, v130
	v_and_b32_e32 v81, 0xffff0000, v130
	v_pk_add_f32 v[70:71], v[70:71], v[78:79]
	v_pk_add_f32 v[68:69], v[68:69], v[76:77]
	v_lshlrev_b32_e32 v82, 16, v131
	v_and_b32_e32 v83, 0xffff0000, v131
	v_pk_add_f32 v[78:79], v[64:65], v[80:81]
	v_mul_f32_e32 v64, v69, v69
	v_mul_f32_e32 v65, v71, v71
	v_pk_add_f32 v[76:77], v[66:67], v[82:83]
	v_fmac_f32_e32 v64, v68, v68
	v_fmac_f32_e32 v65, v70, v70
	v_add_f32_e32 v64, v64, v65
	v_mul_f32_e32 v65, v79, v79
	v_mul_f32_e32 v66, v77, v77
	v_fmac_f32_e32 v65, v78, v78
	v_fmac_f32_e32 v66, v76, v76
	v_add_f32_e32 v65, v65, v66
	v_add_f32_e32 v64, v64, v65
	v_add_f32_e32 v67, v84, v64
	ds_bpermute_b32 v82, v193, v67
	v_lshl_add_u64 v[64:65], s[16:17], 0, v[176:177]
	v_lshl_add_u64 v[80:81], v[168:169], 1, v[64:65]
	global_store_dwordx4 v[80:81], v[72:75], off sc1
	v_cvt_pk_bf16_f32 v66, v68, v69
	s_waitcnt lgkmcnt(0)
	v_add_f32_e32 v64, v67, v82
	ds_bpermute_b32 v65, v112, v64
	v_cvt_pk_bf16_f32 v67, v70, v71
	v_cvt_pk_bf16_f32 v68, v78, v79
	v_cvt_pk_bf16_f32 v69, v76, v77
	global_store_dwordx4 v[80:81], v[66:69], off offset:256 sc1
	s_and_saveexec_b64 s[4:5], s[6:7]
	s_cbranch_execz .LBB0_412
	v_lshlrev_b64 v[66:67], 6, v[174:175]
	v_lshl_add_u64 v[66:67], s[22:23], 0, v[66:67]
	v_lshl_add_u64 v[66:67], s[40:41], 2, v[66:67]
	s_lshl_b32 s10, s51, 2
	v_lshl_add_u64 v[66:67], v[66:67], 0, s[10:11]
	s_waitcnt lgkmcnt(0)
	v_add_f32_e32 v64, v64, v65
	global_store_dword v[66:67], v64, off
.LBB0_412:
	s_or_b64 exec, exec, s[4:5]
	v_add_u32_e32 v100, 0x80, v172
	v_ashrrev_i32_e32 v101, 31, v100
	v_lshlrev_b64 v[110:111], 11, v[100:101]
	s_waitcnt lgkmcnt(0)
	v_lshl_add_u64 v[64:65], v[170:171], 0, v[110:111]
	global_load_dwordx4 v[102:105], v[64:65], off
	global_load_dwordx4 v[106:109], v[64:65], off offset:256
	v_add_u32_e32 v96, 0x90, v172
	v_add_u32_e32 v92, 0xa0, v172
	v_add_u32_e32 v88, 0xb0, v172
	v_ashrrev_i32_e32 v97, 31, v96
	v_ashrrev_i32_e32 v93, 31, v92
	v_ashrrev_i32_e32 v89, 31, v88
	v_lshlrev_b64 v[98:99], 11, v[96:97]
	v_lshlrev_b64 v[94:95], 11, v[92:93]
	v_lshlrev_b64 v[90:91], 11, v[88:89]
	v_lshl_add_u64 v[64:65], v[170:171], 0, v[98:99]
	v_lshl_add_u64 v[66:67], v[170:171], 0, v[94:95]
	v_lshl_add_u64 v[114:115], v[170:171], 0, v[90:91]
	global_load_dwordx4 v[84:87], v[64:65], off
	global_load_dwordx4 v[80:83], v[64:65], off offset:256
	global_load_dwordx4 v[76:79], v[66:67], off
	global_load_dwordx4 v[72:75], v[66:67], off offset:256
	global_load_dwordx4 v[68:71], v[114:115], off
	s_nop 0
	global_load_dwordx4 v[64:67], v[114:115], off offset:256
	s_waitcnt vmcnt(7)
	v_lshlrev_b32_e32 v114, 16, v102
	v_and_b32_e32 v115, 0xffff0000, v102
	v_lshlrev_b32_e32 v102, 16, v103
	v_and_b32_e32 v103, 0xffff0000, v103
	v_lshlrev_b32_e32 v116, 16, v104
	v_and_b32_e32 v117, 0xffff0000, v104
	v_lshlrev_b32_e32 v104, 16, v105
	v_and_b32_e32 v105, 0xffff0000, v105
	s_waitcnt vmcnt(6)
	v_lshlrev_b32_e32 v118, 16, v106
	v_and_b32_e32 v119, 0xffff0000, v106
	v_lshlrev_b32_e32 v106, 16, v107
	v_and_b32_e32 v107, 0xffff0000, v107
	v_lshlrev_b32_e32 v120, 16, v108
	v_and_b32_e32 v121, 0xffff0000, v108
	v_lshlrev_b32_e32 v108, 16, v109
	v_and_b32_e32 v109, 0xffff0000, v109
	v_pk_add_f32 v[62:63], v[62:63], v[102:103]
	v_pk_add_f32 v[60:61], v[60:61], v[114:115]
	v_pk_add_f32 v[58:59], v[58:59], v[104:105]
	v_pk_add_f32 v[56:57], v[56:57], v[116:117]
	v_pk_add_f32 v[54:55], v[54:55], v[106:107]
	v_pk_add_f32 v[52:53], v[52:53], v[118:119]
	v_pk_add_f32 v[102:103], v[50:51], v[108:109]
	v_pk_add_f32 v[104:105], v[48:49], v[120:121]
	v_mul_f32_e32 v106, v61, v61
	v_mul_f32_e32 v107, v63, v63
	v_mul_f32_e32 v108, v57, v57
	v_mul_f32_e32 v109, v59, v59
	v_cvt_pk_bf16_f32 v48, v60, v61
	v_cvt_pk_bf16_f32 v49, v62, v63
	v_cvt_pk_bf16_f32 v50, v56, v57
	v_cvt_pk_bf16_f32 v51, v58, v59
	v_mul_f32_e32 v57, v53, v53
	v_mul_f32_e32 v59, v55, v55
	v_mul_f32_e32 v61, v105, v105
	v_mul_f32_e32 v63, v103, v103
	v_fmac_f32_e32 v106, v60, v60
	v_fmac_f32_e32 v107, v62, v62
	v_fmac_f32_e32 v108, v56, v56
	v_fmac_f32_e32 v109, v58, v58
	v_fmac_f32_e32 v57, v52, v52
	v_fmac_f32_e32 v59, v54, v54
	v_fmac_f32_e32 v61, v104, v104
	v_fmac_f32_e32 v63, v102, v102
	v_add_f32_e32 v56, v106, v107
	v_add_f32_e32 v58, v108, v109
	v_add_f32_e32 v57, v57, v59
	v_add_f32_e32 v59, v61, v63
	v_add_f32_e32 v56, v56, v58
	v_add_f32_e32 v57, v57, v59
	v_add_f32_e32 v58, v56, v57
	ds_bpermute_b32 v59, v193, v58
	v_lshl_add_u64 v[56:57], s[16:17], 0, v[110:111]
	v_lshl_add_u64 v[56:57], v[168:169], 1, v[56:57]
	global_store_dwordx4 v[56:57], v[48:51], off sc1
	s_waitcnt lgkmcnt(0)
	s_nop 0
	v_add_f32_e32 v48, v58, v59
	ds_bpermute_b32 v49, v112, v48
	v_cvt_pk_bf16_f32 v50, v52, v53
	v_cvt_pk_bf16_f32 v51, v54, v55
	v_cvt_pk_bf16_f32 v52, v104, v105
	v_cvt_pk_bf16_f32 v53, v102, v103
	global_store_dwordx4 v[56:57], v[50:53], off offset:256 sc1
	s_and_saveexec_b64 s[4:5], s[6:7]
	s_cbranch_execz .LBB0_414
	v_lshlrev_b64 v[50:51], 6, v[100:101]
	v_lshl_add_u64 v[50:51], s[22:23], 0, v[50:51]
	v_lshl_add_u64 v[50:51], s[40:41], 2, v[50:51]
	s_lshl_b32 s10, s51, 2
	v_lshl_add_u64 v[50:51], v[50:51], 0, s[10:11]
	s_waitcnt lgkmcnt(0)
	v_add_f32_e32 v48, v48, v49
	global_store_dword v[50:51], v48, off
.LBB0_414:
	s_or_b64 exec, exec, s[4:5]
	s_waitcnt vmcnt(7)
	v_lshlrev_b32_e32 v48, 16, v84
	s_waitcnt lgkmcnt(0)
	v_and_b32_e32 v49, 0xffff0000, v84
	v_lshlrev_b32_e32 v50, 16, v85
	v_and_b32_e32 v51, 0xffff0000, v85
	v_lshlrev_b32_e32 v52, 16, v86
	v_and_b32_e32 v53, 0xffff0000, v86
	v_lshlrev_b32_e32 v54, 16, v87
	v_and_b32_e32 v55, 0xffff0000, v87
	v_pk_add_f32 v[46:47], v[46:47], v[50:51]
	v_pk_add_f32 v[44:45], v[44:45], v[48:49]
	v_pk_add_f32 v[48:49], v[42:43], v[54:55]
	v_pk_add_f32 v[42:43], v[40:41], v[52:53]
	v_mul_f32_e32 v40, v45, v45
	v_mul_f32_e32 v41, v47, v47
	v_fmac_f32_e32 v40, v44, v44
	v_fmac_f32_e32 v41, v46, v46
	v_add_f32_e32 v40, v40, v41
	v_mul_f32_e32 v41, v43, v43
	v_mul_f32_e32 v50, v49, v49
	v_fmac_f32_e32 v41, v42, v42
	v_fmac_f32_e32 v50, v48, v48
	v_add_f32_e32 v41, v41, v50
	v_add_f32_e32 v52, v40, v41
	v_cvt_pk_bf16_f32 v40, v44, v45
	v_cvt_pk_bf16_f32 v41, v46, v47
	s_waitcnt vmcnt(6)
	v_lshlrev_b32_e32 v44, 16, v80
	v_and_b32_e32 v45, 0xffff0000, v80
	v_lshlrev_b32_e32 v46, 16, v81
	v_and_b32_e32 v47, 0xffff0000, v81
	v_cvt_pk_bf16_f32 v42, v42, v43
	v_cvt_pk_bf16_f32 v43, v48, v49
	v_lshlrev_b32_e32 v48, 16, v82
	v_and_b32_e32 v49, 0xffff0000, v82
	v_pk_add_f32 v[38:39], v[38:39], v[46:47]
	v_pk_add_f32 v[36:37], v[36:37], v[44:45]
	v_lshlrev_b32_e32 v50, 16, v83
	v_and_b32_e32 v51, 0xffff0000, v83
	v_pk_add_f32 v[46:47], v[32:33], v[48:49]
	v_mul_f32_e32 v32, v37, v37
	v_mul_f32_e32 v33, v39, v39
	v_pk_add_f32 v[44:45], v[34:35], v[50:51]
	v_fmac_f32_e32 v32, v36, v36
	v_fmac_f32_e32 v33, v38, v38
	v_add_f32_e32 v32, v32, v33
	v_mul_f32_e32 v33, v47, v47
	v_mul_f32_e32 v34, v45, v45
	v_fmac_f32_e32 v33, v46, v46
	v_fmac_f32_e32 v34, v44, v44
	v_add_f32_e32 v33, v33, v34
	v_add_f32_e32 v32, v32, v33
	v_add_f32_e32 v35, v52, v32
	ds_bpermute_b32 v50, v193, v35
	v_lshl_add_u64 v[32:33], s[16:17], 0, v[98:99]
	v_lshl_add_u64 v[48:49], v[168:169], 1, v[32:33]
	global_store_dwordx4 v[48:49], v[40:43], off sc1
	v_cvt_pk_bf16_f32 v34, v36, v37
	s_waitcnt lgkmcnt(0)
	v_add_f32_e32 v32, v35, v50
	ds_bpermute_b32 v33, v112, v32
	v_cvt_pk_bf16_f32 v35, v38, v39
	v_cvt_pk_bf16_f32 v36, v46, v47
	v_cvt_pk_bf16_f32 v37, v44, v45
	global_store_dwordx4 v[48:49], v[34:37], off offset:256 sc1
	s_and_saveexec_b64 s[4:5], s[6:7]
	s_cbranch_execz .LBB0_416
	v_lshlrev_b64 v[34:35], 6, v[96:97]
	v_lshl_add_u64 v[34:35], s[22:23], 0, v[34:35]
	v_lshl_add_u64 v[34:35], s[40:41], 2, v[34:35]
	s_lshl_b32 s10, s51, 2
	v_lshl_add_u64 v[34:35], v[34:35], 0, s[10:11]
	s_waitcnt lgkmcnt(0)
	v_add_f32_e32 v32, v32, v33
	global_store_dword v[34:35], v32, off
.LBB0_416:
	s_or_b64 exec, exec, s[4:5]
	s_waitcnt vmcnt(7)
	v_lshlrev_b32_e32 v32, 16, v76
	s_waitcnt lgkmcnt(0)
	v_and_b32_e32 v33, 0xffff0000, v76
	v_lshlrev_b32_e32 v34, 16, v77
	v_and_b32_e32 v35, 0xffff0000, v77
	v_lshlrev_b32_e32 v36, 16, v78
	v_and_b32_e32 v37, 0xffff0000, v78
	v_lshlrev_b32_e32 v38, 16, v79
	v_and_b32_e32 v39, 0xffff0000, v79
	v_pk_add_f32 v[30:31], v[30:31], v[34:35]
	v_pk_add_f32 v[28:29], v[28:29], v[32:33]
	v_pk_add_f32 v[32:33], v[26:27], v[38:39]
	v_pk_add_f32 v[26:27], v[24:25], v[36:37]
	v_mul_f32_e32 v24, v29, v29
	v_mul_f32_e32 v25, v31, v31
	v_fmac_f32_e32 v24, v28, v28
	v_fmac_f32_e32 v25, v30, v30
	v_add_f32_e32 v24, v24, v25
	v_mul_f32_e32 v25, v27, v27
	v_mul_f32_e32 v34, v33, v33
	v_fmac_f32_e32 v25, v26, v26
	v_fmac_f32_e32 v34, v32, v32
	v_add_f32_e32 v25, v25, v34
	v_add_f32_e32 v36, v24, v25
	v_cvt_pk_bf16_f32 v24, v28, v29
	v_cvt_pk_bf16_f32 v25, v30, v31
	s_waitcnt vmcnt(6)
	v_lshlrev_b32_e32 v28, 16, v72
	v_and_b32_e32 v29, 0xffff0000, v72
	v_lshlrev_b32_e32 v30, 16, v73
	v_and_b32_e32 v31, 0xffff0000, v73
	v_cvt_pk_bf16_f32 v26, v26, v27
	v_cvt_pk_bf16_f32 v27, v32, v33
	v_lshlrev_b32_e32 v32, 16, v74
	v_and_b32_e32 v33, 0xffff0000, v74
	v_pk_add_f32 v[22:23], v[22:23], v[30:31]
	v_pk_add_f32 v[20:21], v[20:21], v[28:29]
	v_lshlrev_b32_e32 v34, 16, v75
	v_and_b32_e32 v35, 0xffff0000, v75
	v_pk_add_f32 v[30:31], v[16:17], v[32:33]
	v_mul_f32_e32 v16, v21, v21
	v_mul_f32_e32 v17, v23, v23
	v_pk_add_f32 v[28:29], v[18:19], v[34:35]
	v_fmac_f32_e32 v16, v20, v20
	v_fmac_f32_e32 v17, v22, v22
	v_add_f32_e32 v16, v16, v17
	v_mul_f32_e32 v17, v31, v31
	v_mul_f32_e32 v18, v29, v29
	v_fmac_f32_e32 v17, v30, v30
	v_fmac_f32_e32 v18, v28, v28
	v_add_f32_e32 v17, v17, v18
	v_add_f32_e32 v16, v16, v17
	v_add_f32_e32 v19, v36, v16
	ds_bpermute_b32 v34, v193, v19
	v_lshl_add_u64 v[16:17], s[16:17], 0, v[94:95]
	v_lshl_add_u64 v[32:33], v[168:169], 1, v[16:17]
	global_store_dwordx4 v[32:33], v[24:27], off sc1
	v_cvt_pk_bf16_f32 v18, v20, v21
	s_waitcnt lgkmcnt(0)
	v_add_f32_e32 v16, v19, v34
	ds_bpermute_b32 v17, v112, v16
	v_cvt_pk_bf16_f32 v19, v22, v23
	v_cvt_pk_bf16_f32 v20, v30, v31
	v_cvt_pk_bf16_f32 v21, v28, v29
	global_store_dwordx4 v[32:33], v[18:21], off offset:256 sc1
	s_and_saveexec_b64 s[4:5], s[6:7]
	s_cbranch_execz .LBB0_418
	v_lshlrev_b64 v[18:19], 6, v[92:93]
	v_lshl_add_u64 v[18:19], s[22:23], 0, v[18:19]
	v_lshl_add_u64 v[18:19], s[40:41], 2, v[18:19]
	s_lshl_b32 s10, s51, 2
	v_lshl_add_u64 v[18:19], v[18:19], 0, s[10:11]
	s_waitcnt lgkmcnt(0)
	v_add_f32_e32 v16, v16, v17
	global_store_dword v[18:19], v16, off
.LBB0_418:
	s_or_b64 exec, exec, s[4:5]
	s_waitcnt vmcnt(7)
	v_lshlrev_b32_e32 v16, 16, v68
	s_waitcnt lgkmcnt(0)
	v_and_b32_e32 v17, 0xffff0000, v68
	v_lshlrev_b32_e32 v18, 16, v69
	v_and_b32_e32 v19, 0xffff0000, v69
	v_lshlrev_b32_e32 v20, 16, v70
	v_and_b32_e32 v21, 0xffff0000, v70
	v_lshlrev_b32_e32 v22, 16, v71
	v_and_b32_e32 v23, 0xffff0000, v71
	v_pk_add_f32 v[14:15], v[14:15], v[18:19]
	v_pk_add_f32 v[12:13], v[12:13], v[16:17]
	v_pk_add_f32 v[16:17], v[10:11], v[22:23]
	v_pk_add_f32 v[10:11], v[8:9], v[20:21]
	v_mul_f32_e32 v8, v13, v13
	v_mul_f32_e32 v9, v15, v15
	v_fmac_f32_e32 v8, v12, v12
	v_fmac_f32_e32 v9, v14, v14
	v_add_f32_e32 v8, v8, v9
	v_mul_f32_e32 v9, v11, v11
	v_mul_f32_e32 v18, v17, v17
	v_fmac_f32_e32 v9, v10, v10
	v_fmac_f32_e32 v18, v16, v16
	v_add_f32_e32 v9, v9, v18
	v_add_f32_e32 v20, v8, v9
	v_cvt_pk_bf16_f32 v8, v12, v13
	v_cvt_pk_bf16_f32 v9, v14, v15
	s_waitcnt vmcnt(6)
	v_lshlrev_b32_e32 v12, 16, v64
	v_and_b32_e32 v13, 0xffff0000, v64
	v_lshlrev_b32_e32 v14, 16, v65
	v_and_b32_e32 v15, 0xffff0000, v65
	v_cvt_pk_bf16_f32 v10, v10, v11
	v_cvt_pk_bf16_f32 v11, v16, v17
	v_lshlrev_b32_e32 v16, 16, v66
	v_and_b32_e32 v17, 0xffff0000, v66
	v_pk_add_f32 v[6:7], v[6:7], v[14:15]
	v_pk_add_f32 v[4:5], v[4:5], v[12:13]
	v_lshlrev_b32_e32 v18, 16, v67
	v_and_b32_e32 v19, 0xffff0000, v67
	v_pk_add_f32 v[14:15], v[0:1], v[16:17]
	v_mul_f32_e32 v0, v5, v5
	v_mul_f32_e32 v1, v7, v7
	v_pk_add_f32 v[12:13], v[2:3], v[18:19]
	v_fmac_f32_e32 v0, v4, v4
	v_fmac_f32_e32 v1, v6, v6
	v_add_f32_e32 v0, v0, v1
	v_mul_f32_e32 v1, v15, v15
	v_mul_f32_e32 v2, v13, v13
	v_fmac_f32_e32 v1, v14, v14
	v_fmac_f32_e32 v2, v12, v12
	v_add_f32_e32 v1, v1, v2
	v_add_f32_e32 v0, v0, v1
	v_add_f32_e32 v3, v20, v0
	ds_bpermute_b32 v18, v193, v3
	v_lshl_add_u64 v[0:1], s[16:17], 0, v[90:91]
	v_lshl_add_u64 v[16:17], v[168:169], 1, v[0:1]
	global_store_dwordx4 v[16:17], v[8:11], off sc1
	v_cvt_pk_bf16_f32 v2, v4, v5
	s_waitcnt lgkmcnt(0)
	v_add_f32_e32 v0, v3, v18
	ds_bpermute_b32 v1, v112, v0
	v_cvt_pk_bf16_f32 v3, v6, v7
	v_cvt_pk_bf16_f32 v4, v14, v15
	v_cvt_pk_bf16_f32 v5, v12, v13
	global_store_dwordx4 v[16:17], v[2:5], off offset:256 sc1
	s_and_saveexec_b64 s[4:5], s[6:7]
	s_cbranch_execz .LBB0_420
	v_lshlrev_b64 v[2:3], 6, v[88:89]
	v_lshl_add_u64 v[2:3], s[22:23], 0, v[2:3]
	v_lshl_add_u64 v[2:3], s[40:41], 2, v[2:3]
	s_lshl_b32 s10, s51, 2
	v_lshl_add_u64 v[2:3], v[2:3], 0, s[10:11]
	s_waitcnt lgkmcnt(0)
	v_add_f32_e32 v0, v0, v1
	global_store_dword v[2:3], v0, off

.LBB0_486:
	v_lshl_add_u32 v162, s8, 8, v159
	s_mov_b64 s[60:61], 0x2000
	v_lshlrev_b32_e32 v204, 6, v162
	v_mov_b32_e32 v205, 0
	v_mbcnt_lo_u32_b32 v248, -1, 0
	v_mbcnt_hi_u32_b32 v248, -1, v248
	v_xor_b32_e32 v248, 16, v248
	v_lshl_add_u64 v[204:205], v[136:137], 0, v[204:205]
	v_lshlrev_b32_e32 v248, 2, v248
	v_lshl_add_u64 v[206:207], v[204:205], 0, s[60:61]
	global_load_dwordx4 v[208:211], v[204:205], off
	global_load_dwordx4 v[212:215], v[204:205], off offset:1024
	global_load_dwordx4 v[216:219], v[204:205], off offset:2048
	global_load_dwordx4 v[220:223], v[204:205], off offset:3072
	global_load_dwordx4 v[224:227], v[206:207], off
	global_load_dwordx4 v[228:231], v[206:207], off offset:1024
	global_load_dwordx4 v[232:235], v[206:207], off offset:2048
	global_load_dwordx4 v[236:239], v[206:207], off offset:3072
	s_waitcnt vmcnt(0)
	v_add_f32_e32 v208, v208, v209
	v_add_f32_e32 v210, v210, v211
	v_add_f32_e32 v212, v212, v213
	v_add_f32_e32 v214, v214, v215
	v_add_f32_e32 v216, v216, v217
	v_add_f32_e32 v218, v218, v219
	v_add_f32_e32 v220, v220, v221
	v_add_f32_e32 v222, v222, v223
	v_add_f32_e32 v224, v224, v225
	v_add_f32_e32 v226, v226, v227
	v_add_f32_e32 v228, v228, v229
	v_add_f32_e32 v230, v230, v231
	v_add_f32_e32 v232, v232, v233
	v_add_f32_e32 v234, v234, v235
	v_add_f32_e32 v236, v236, v237
	v_add_f32_e32 v238, v238, v239
	v_add_f32_e32 v208, v208, v210
	v_add_f32_e32 v212, v212, v214
	v_add_f32_e32 v216, v216, v218
	v_add_f32_e32 v220, v220, v222
	v_add_f32_e32 v224, v224, v226
	v_add_f32_e32 v228, v228, v230
	v_add_f32_e32 v232, v232, v234
	v_add_f32_e32 v236, v236, v238
	ds_bpermute_b32 v209, v248, v208
	ds_bpermute_b32 v213, v248, v212
	ds_bpermute_b32 v217, v248, v216
	ds_bpermute_b32 v221, v248, v220
	ds_bpermute_b32 v225, v248, v224
	ds_bpermute_b32 v229, v248, v228
	ds_bpermute_b32 v233, v248, v232
	ds_bpermute_b32 v237, v248, v236
	s_waitcnt lgkmcnt(0)
	v_add_f32_e32 v208, v208, v209
	v_add_f32_e32 v212, v212, v213
	v_add_f32_e32 v216, v216, v217
	v_add_f32_e32 v220, v220, v221
	v_add_f32_e32 v224, v224, v225
	v_add_f32_e32 v228, v228, v229
	v_add_f32_e32 v232, v232, v233
	v_add_f32_e32 v236, v236, v237
	v_mov_b32_e32 v209, v208
	v_mov_b32_e32 v213, v212
	v_mov_b32_e32 v217, v216
	v_mov_b32_e32 v221, v220
	v_mov_b32_e32 v225, v224
	v_mov_b32_e32 v229, v228
	v_mov_b32_e32 v233, v232
	v_mov_b32_e32 v237, v236
	s_nop 1
	v_permlane32_swap_b32_e32 v208, v209
	v_permlane32_swap_b32_e32 v212, v213
	v_permlane32_swap_b32_e32 v216, v217
	v_permlane32_swap_b32_e32 v220, v221
	v_permlane32_swap_b32_e32 v224, v225
	v_permlane32_swap_b32_e32 v228, v229
	v_permlane32_swap_b32_e32 v232, v233
	v_permlane32_swap_b32_e32 v236, v237
	v_add_f32_e32 v208, v208, v209
	v_add_f32_e32 v212, v212, v213
	v_add_f32_e32 v216, v216, v217
	v_add_f32_e32 v220, v220, v221
	v_add_f32_e32 v224, v224, v225
	v_add_f32_e32 v228, v228, v229
	v_add_f32_e32 v232, v232, v233
	v_add_f32_e32 v236, v236, v237
	v_fmamk_f32 v208, v208, 0x3a800000, v177
	v_fmamk_f32 v212, v212, 0x3a800000, v177
	v_fmamk_f32 v216, v216, 0x3a800000, v177
	v_fmamk_f32 v220, v220, 0x3a800000, v177
	v_fmamk_f32 v224, v224, 0x3a800000, v177
	v_fmamk_f32 v228, v228, 0x3a800000, v177
	v_fmamk_f32 v232, v232, 0x3a800000, v177
	v_fmamk_f32 v236, v236, 0x3a800000, v177
	v_rsq_f32_e32 v176, v208
	v_rsq_f32_e32 v174, v212
	v_rsq_f32_e32 v172, v216
	v_rsq_f32_e32 v170, v220
	v_rsq_f32_e32 v168, v224
	v_rsq_f32_e32 v166, v228
	v_rsq_f32_e32 v164, v232
	v_rsq_f32_e32 v158, v236
	s_nop 0
	v_or_b32_e32 v160, 16, v162
	v_or_b32_e32 v156, 32, v162
	v_or_b32_e32 v154, 48, v162
	v_add_u32_e32 v148, 0x80, v162
	s_waitcnt vmcnt(0)
	s_waitcnt lgkmcnt(2)
	s_waitcnt lgkmcnt(2)
	s_waitcnt lgkmcnt(1)
	s_waitcnt lgkmcnt(2)
	s_waitcnt lgkmcnt(1)
	s_waitcnt lgkmcnt(0)
	s_nop 0
	s_nop 0
	v_add_u32_e32 v152, 0x90, v162
	s_waitcnt lgkmcnt(0)
	s_waitcnt lgkmcnt(0)
	s_waitcnt vmcnt(0)
	v_add_u32_e32 v150, 0xa0, v162
	s_waitcnt lgkmcnt(0)
	s_waitcnt lgkmcnt(0)
	s_nop 0
	s_nop 1
	v_add_u32_e32 v146, 0xb0, v162
	s_waitcnt lgkmcnt(0)
	s_waitcnt lgkmcnt(0)
	s_waitcnt vmcnt(1)
	s_waitcnt lgkmcnt(0)
	s_waitcnt lgkmcnt(0)
	s_waitcnt vmcnt(0)
	v_mov_b32_e32 v180, v120
	s_waitcnt lgkmcnt(0)
	s_waitcnt lgkmcnt(0)
	v_mov_b32_e32 v181, v124
	v_pk_mul_f32 v[180:181], v[180:181], v[176:177] op_sel_hi:[1,0]
	v_mov_b32_e32 v124, v121
	v_mul_f32_e32 v120, 0xbfb8aa3b, v181
	v_exp_f32_e32 v147, v120
	v_pk_mul_f32 v[120:121], v[124:125], v[176:177] op_sel_hi:[1,0]
	s_andn2_b64 vcc, exec, s[6:7]
	v_mul_f32_e32 v124, 0xbfb8aa3b, v121
	v_exp_f32_e32 v125, v124
	v_add_f32_e32 v147, 1.0, v147
	v_rcp_f32_e32 v147, v147
	v_lshl_or_b32 v124, s33, 7, v167
	v_add_f32_e32 v125, 1.0, v125
	v_rcp_f32_e32 v149, v125
	v_mul_f32_e32 v147, v181, v147
	v_mul_f32_e32 v147, v180, v147
	v_mov_b32_e32 v180, v122
	v_mov_b32_e32 v181, v126
	v_pk_mul_f32 v[180:181], v[180:181], v[176:177] op_sel_hi:[1,0]
	v_mov_b32_e32 v126, v123
	v_mul_f32_e32 v122, 0xbfb8aa3b, v181
	v_mul_f32_e32 v121, v121, v149
	v_exp_f32_e32 v149, v122
	v_pk_mul_f32 v[122:123], v[126:127], v[176:177] op_sel_hi:[1,0]
	v_mul_f32_e32 v127, v120, v121
	v_mul_f32_e32 v126, 0xbfb8aa3b, v123
	v_exp_f32_e32 v126, v126
	v_add_f32_e32 v120, 1.0, v149
	v_rcp_f32_e32 v149, v120
	v_mov_b32_e32 v121, v116
	v_add_f32_e32 v120, 1.0, v126
	v_rcp_f32_e32 v126, v120
	v_mov_b32_e32 v120, v112
	v_pk_mul_f32 v[120:121], v[120:121], v[176:177] op_sel_hi:[1,0]
	v_mul_f32_e32 v116, v181, v149
	v_mul_f32_e32 v112, 0xbfb8aa3b, v121
	v_exp_f32_e32 v112, v112
	v_mul_f32_e32 v149, v180, v116
	v_mov_b32_e32 v116, v113
	v_mul_f32_e32 v123, v123, v126
	v_add_f32_e32 v112, 1.0, v112
	v_rcp_f32_e32 v126, v112
	v_pk_mul_f32 v[112:113], v[116:117], v[176:177] op_sel_hi:[1,0]
	v_mul_f32_e32 v122, v122, v123
	v_mul_f32_e32 v116, 0xbfb8aa3b, v113
	v_exp_f32_e32 v116, v116
	v_mul_f32_e32 v117, v121, v126
	v_mul_f32_e32 v120, v120, v117
	v_mov_b32_e32 v117, v118
	v_add_f32_e32 v116, 1.0, v116
	v_rcp_f32_e32 v121, v116
	v_mov_b32_e32 v116, v114
	v_pk_mul_f32 v[116:117], v[116:117], v[176:177] op_sel_hi:[1,0]
	v_mov_b32_e32 v118, v115
	v_mul_f32_e32 v114, 0xbfb8aa3b, v117
	v_exp_f32_e32 v123, v114
	v_pk_mul_f32 v[114:115], v[118:119], v[176:177] op_sel_hi:[1,0]
	v_mul_f32_e32 v113, v113, v121
	v_mul_f32_e32 v118, 0xbfb8aa3b, v115
	v_exp_f32_e32 v118, v118
	v_add_f32_e32 v119, 1.0, v123
	v_rcp_f32_e32 v119, v119
	v_mul_f32_e32 v112, v112, v113
	v_add_f32_e32 v118, 1.0, v118
	v_rcp_f32_e32 v118, v118
	v_mul_f32_e32 v113, v117, v119
	v_mul_f32_e32 v113, v116, v113
	v_cvt_pk_bf16_f32 v116, v147, v127
	v_cvt_pk_bf16_f32 v117, v149, v122
	v_mov_b32_e32 v122, v104
	v_mov_b32_e32 v123, v108
	v_mul_f32_e32 v115, v115, v118
	v_pk_mul_f32 v[122:123], v[122:123], v[174:175] op_sel_hi:[1,0]
	v_ashrrev_i32_e32 v125, 31, v124
	v_mul_f32_e32 v114, v114, v115
	v_mul_f32_e32 v104, 0xbfb8aa3b, v123
	v_cvt_pk_bf16_f32 v118, v120, v112
	v_cvt_pk_bf16_f32 v119, v113, v114
	v_lshlrev_b64 v[114:115], 1, v[124:125]
	v_exp_f32_e32 v124, v104
	v_mov_b32_e32 v108, v105
	v_mov_b64_e32 v[112:113], s[26:27]
	v_pk_mul_f32 v[104:105], v[108:109], v[174:175] op_sel_hi:[1,0]
	v_mad_i64_i32 v[120:121], s[4:5], v162, s52, v[112:113]
	v_mul_f32_e32 v108, 0xbfb8aa3b, v105
	v_exp_f32_e32 v125, v108
	v_lshl_add_u64 v[108:109], v[120:121], 0, v[114:115]
	v_add_f32_e32 v120, 1.0, v124
	v_rcp_f32_e32 v120, v120
	global_store_dwordx4 v[108:109], v[116:119], off sc1
	v_mov_b32_e32 v109, v110
	v_add_f32_e32 v121, 1.0, v125
	v_mul_f32_e32 v108, v123, v120
	v_mul_f32_e32 v116, v122, v108
	v_mov_b32_e32 v108, v106
	v_pk_mul_f32 v[108:109], v[108:109], v[174:175] op_sel_hi:[1,0]
	v_mov_b32_e32 v110, v107
	v_mul_f32_e32 v106, 0xbfb8aa3b, v109
	v_rcp_f32_e32 v121, v121
	v_exp_f32_e32 v117, v106
	v_pk_mul_f32 v[106:107], v[110:111], v[174:175] op_sel_hi:[1,0]
	v_mul_f32_e32 v105, v105, v121
	v_mul_f32_e32 v110, 0xbfb8aa3b, v107
	v_exp_f32_e32 v110, v110
	v_mul_f32_e32 v111, v104, v105
	v_add_f32_e32 v104, 1.0, v117
	v_rcp_f32_e32 v117, v104
	v_add_f32_e32 v104, 1.0, v110
	v_rcp_f32_e32 v110, v104
	v_mov_b32_e32 v104, v96
	v_mov_b32_e32 v105, v100
	v_pk_mul_f32 v[104:105], v[104:105], v[174:175] op_sel_hi:[1,0]
	v_mul_f32_e32 v100, v109, v117
	v_mul_f32_e32 v96, 0xbfb8aa3b, v105
	v_exp_f32_e32 v96, v96
	v_mul_f32_e32 v108, v108, v100
	v_mov_b32_e32 v100, v97
	v_mul_f32_e32 v107, v107, v110
	v_add_f32_e32 v96, 1.0, v96
	v_rcp_f32_e32 v109, v96
	v_pk_mul_f32 v[96:97], v[100:101], v[174:175] op_sel_hi:[1,0]
	v_mul_f32_e32 v106, v106, v107
	v_mul_f32_e32 v100, 0xbfb8aa3b, v97
	v_exp_f32_e32 v100, v100
	v_mul_f32_e32 v101, v105, v109
	v_mul_f32_e32 v104, v104, v101
	v_mov_b32_e32 v101, v102
	v_add_f32_e32 v100, 1.0, v100
	v_rcp_f32_e32 v105, v100
	v_mov_b32_e32 v100, v98
	v_pk_mul_f32 v[100:101], v[100:101], v[174:175] op_sel_hi:[1,0]
	v_mov_b32_e32 v102, v99
	v_mul_f32_e32 v98, 0xbfb8aa3b, v101
	v_exp_f32_e32 v107, v98
	v_pk_mul_f32 v[98:99], v[102:103], v[174:175] op_sel_hi:[1,0]
	v_mul_f32_e32 v97, v97, v105
	v_mul_f32_e32 v102, 0xbfb8aa3b, v99
	v_exp_f32_e32 v102, v102
	v_add_f32_e32 v103, 1.0, v107
	v_rcp_f32_e32 v103, v103
	v_mul_f32_e32 v105, v96, v97
	v_add_f32_e32 v102, 1.0, v102
	v_rcp_f32_e32 v102, v102
	v_mul_f32_e32 v96, v101, v103
	v_mul_f32_e32 v100, v100, v96
	v_mov_b32_e32 v103, v92
	v_mul_f32_e32 v96, v99, v102
	v_mov_b32_e32 v102, v88
	v_pk_mul_f32 v[102:103], v[102:103], v[172:173] op_sel_hi:[1,0]
	v_mul_f32_e32 v99, v98, v96
	v_mul_f32_e32 v88, 0xbfb8aa3b, v103
	v_cvt_pk_bf16_f32 v96, v116, v111
	v_cvt_pk_bf16_f32 v97, v108, v106
	v_cvt_pk_bf16_f32 v98, v104, v105
	v_exp_f32_e32 v104, v88
	v_mov_b32_e32 v92, v89
	v_pk_mul_f32 v[88:89], v[92:93], v[172:173] op_sel_hi:[1,0]
	v_cvt_pk_bf16_f32 v99, v100, v99
	v_mad_i64_i32 v[100:101], s[4:5], v160, s52, v[112:113]
	v_mul_f32_e32 v92, 0xbfb8aa3b, v89
	v_exp_f32_e32 v105, v92
	v_lshl_add_u64 v[92:93], v[100:101], 0, v[114:115]
	v_add_f32_e32 v100, 1.0, v104
	v_rcp_f32_e32 v100, v100
	global_store_dwordx4 v[92:93], v[96:99], off sc1
	v_mov_b32_e32 v93, v94
	v_add_f32_e32 v101, 1.0, v105
	v_mul_f32_e32 v92, v103, v100
	v_mul_f32_e32 v96, v102, v92
	v_mov_b32_e32 v92, v90
	v_pk_mul_f32 v[92:93], v[92:93], v[172:173] op_sel_hi:[1,0]
	v_mov_b32_e32 v94, v91
	v_mul_f32_e32 v90, 0xbfb8aa3b, v93
	v_rcp_f32_e32 v101, v101
	v_exp_f32_e32 v97, v90
	v_pk_mul_f32 v[90:91], v[94:95], v[172:173] op_sel_hi:[1,0]
	v_mul_f32_e32 v89, v89, v101
	v_mul_f32_e32 v94, 0xbfb8aa3b, v91
	v_exp_f32_e32 v94, v94
	v_mul_f32_e32 v95, v88, v89
	v_add_f32_e32 v88, 1.0, v97
	v_rcp_f32_e32 v97, v88
	v_add_f32_e32 v88, 1.0, v94
	v_rcp_f32_e32 v94, v88
	v_mov_b32_e32 v88, v80
	v_mov_b32_e32 v89, v84
	v_pk_mul_f32 v[88:89], v[88:89], v[172:173] op_sel_hi:[1,0]
	v_mul_f32_e32 v84, v93, v97
	v_mul_f32_e32 v80, 0xbfb8aa3b, v89
	v_exp_f32_e32 v80, v80
	v_mul_f32_e32 v92, v92, v84
	v_mov_b32_e32 v84, v81
	v_mul_f32_e32 v91, v91, v94
	v_add_f32_e32 v80, 1.0, v80
	v_rcp_f32_e32 v93, v80
	v_pk_mul_f32 v[80:81], v[84:85], v[172:173] op_sel_hi:[1,0]
	v_mul_f32_e32 v90, v90, v91
	v_mul_f32_e32 v84, 0xbfb8aa3b, v81
	v_exp_f32_e32 v84, v84
	v_mul_f32_e32 v85, v89, v93
	v_mul_f32_e32 v88, v88, v85
	v_mov_b32_e32 v85, v86
	v_add_f32_e32 v84, 1.0, v84
	v_rcp_f32_e32 v89, v84
	v_mov_b32_e32 v84, v82
	v_pk_mul_f32 v[84:85], v[84:85], v[172:173] op_sel_hi:[1,0]
	v_mov_b32_e32 v86, v83
	v_mul_f32_e32 v82, 0xbfb8aa3b, v85
	v_exp_f32_e32 v91, v82
	v_pk_mul_f32 v[82:83], v[86:87], v[172:173] op_sel_hi:[1,0]
	v_mul_f32_e32 v81, v81, v89
	v_mul_f32_e32 v86, 0xbfb8aa3b, v83
	v_exp_f32_e32 v86, v86
	v_add_f32_e32 v87, 1.0, v91
	v_rcp_f32_e32 v87, v87
	v_mul_f32_e32 v89, v80, v81
	v_add_f32_e32 v86, 1.0, v86
	v_rcp_f32_e32 v86, v86
	v_mul_f32_e32 v80, v85, v87
	v_mul_f32_e32 v84, v84, v80
	v_mov_b32_e32 v87, v76
	v_mul_f32_e32 v80, v83, v86
	v_mov_b32_e32 v86, v72
	v_pk_mul_f32 v[86:87], v[86:87], v[170:171] op_sel_hi:[1,0]
	v_mul_f32_e32 v83, v82, v80
	v_mul_f32_e32 v72, 0xbfb8aa3b, v87
	v_cvt_pk_bf16_f32 v80, v96, v95
	v_cvt_pk_bf16_f32 v81, v92, v90
	v_cvt_pk_bf16_f32 v82, v88, v89
	v_exp_f32_e32 v88, v72
	v_mov_b32_e32 v76, v73
	v_pk_mul_f32 v[72:73], v[76:77], v[170:171] op_sel_hi:[1,0]
	v_cvt_pk_bf16_f32 v83, v84, v83
	v_mad_i64_i32 v[84:85], s[4:5], v156, s52, v[112:113]
	v_mul_f32_e32 v76, 0xbfb8aa3b, v73
	v_exp_f32_e32 v89, v76
	v_lshl_add_u64 v[76:77], v[84:85], 0, v[114:115]
	v_add_f32_e32 v84, 1.0, v88
	v_rcp_f32_e32 v84, v84
	global_store_dwordx4 v[76:77], v[80:83], off sc1
	v_mov_b32_e32 v77, v78
	v_add_f32_e32 v85, 1.0, v89
	v_mul_f32_e32 v76, v87, v84
	v_mul_f32_e32 v80, v86, v76
	v_mov_b32_e32 v76, v74
	v_pk_mul_f32 v[76:77], v[76:77], v[170:171] op_sel_hi:[1,0]
	v_mov_b32_e32 v78, v75
	v_mul_f32_e32 v74, 0xbfb8aa3b, v77
	v_rcp_f32_e32 v85, v85
	v_exp_f32_e32 v81, v74
	v_pk_mul_f32 v[74:75], v[78:79], v[170:171] op_sel_hi:[1,0]
	v_mul_f32_e32 v73, v73, v85
	v_mul_f32_e32 v78, 0xbfb8aa3b, v75
	v_exp_f32_e32 v78, v78
	v_mul_f32_e32 v79, v72, v73
	v_add_f32_e32 v72, 1.0, v81
	v_rcp_f32_e32 v81, v72
	v_add_f32_e32 v72, 1.0, v78
	v_rcp_f32_e32 v78, v72
	v_mov_b32_e32 v72, v64
	v_mov_b32_e32 v73, v68
	v_pk_mul_f32 v[72:73], v[72:73], v[170:171] op_sel_hi:[1,0]
	v_mul_f32_e32 v68, v77, v81
	v_mul_f32_e32 v64, 0xbfb8aa3b, v73
	v_exp_f32_e32 v64, v64
	v_mul_f32_e32 v76, v76, v68
	v_mov_b32_e32 v68, v65
	v_mul_f32_e32 v75, v75, v78
	v_add_f32_e32 v64, 1.0, v64
	v_rcp_f32_e32 v77, v64
	v_pk_mul_f32 v[64:65], v[68:69], v[170:171] op_sel_hi:[1,0]
	v_mul_f32_e32 v74, v74, v75
	v_mul_f32_e32 v68, 0xbfb8aa3b, v65
	v_exp_f32_e32 v68, v68
	v_mul_f32_e32 v69, v73, v77
	v_mul_f32_e32 v72, v72, v69
	v_mov_b32_e32 v69, v70
	v_add_f32_e32 v68, 1.0, v68
	v_rcp_f32_e32 v73, v68
	v_mov_b32_e32 v68, v66
	v_pk_mul_f32 v[68:69], v[68:69], v[170:171] op_sel_hi:[1,0]
	v_mov_b32_e32 v70, v67
	v_mul_f32_e32 v66, 0xbfb8aa3b, v69
	v_exp_f32_e32 v75, v66
	v_pk_mul_f32 v[66:67], v[70:71], v[170:171] op_sel_hi:[1,0]
	v_mul_f32_e32 v65, v65, v73
	v_mul_f32_e32 v70, 0xbfb8aa3b, v67
	v_exp_f32_e32 v70, v70
	v_add_f32_e32 v71, 1.0, v75
	v_rcp_f32_e32 v71, v71
	v_mul_f32_e32 v73, v64, v65
	v_add_f32_e32 v70, 1.0, v70
	v_rcp_f32_e32 v70, v70
	v_mul_f32_e32 v64, v69, v71
	v_mul_f32_e32 v68, v68, v64
	v_mov_b32_e32 v71, v60
	v_mul_f32_e32 v64, v67, v70
	v_mov_b32_e32 v70, v56
	v_pk_mul_f32 v[70:71], v[70:71], v[168:169] op_sel_hi:[1,0]
	v_mul_f32_e32 v67, v66, v64
	v_mul_f32_e32 v56, 0xbfb8aa3b, v71
	v_cvt_pk_bf16_f32 v64, v80, v79
	v_cvt_pk_bf16_f32 v65, v76, v74
	v_cvt_pk_bf16_f32 v66, v72, v73
	v_exp_f32_e32 v72, v56
	v_mov_b32_e32 v60, v57
	v_pk_mul_f32 v[56:57], v[60:61], v[168:169] op_sel_hi:[1,0]
	v_cvt_pk_bf16_f32 v67, v68, v67
	v_mad_i64_i32 v[68:69], s[4:5], v154, s52, v[112:113]
	v_mul_f32_e32 v60, 0xbfb8aa3b, v57
	v_exp_f32_e32 v73, v60
	v_lshl_add_u64 v[60:61], v[68:69], 0, v[114:115]
	v_add_f32_e32 v68, 1.0, v72
	v_rcp_f32_e32 v68, v68
	global_store_dwordx4 v[60:61], v[64:67], off sc1
	v_mov_b32_e32 v61, v62
	v_add_f32_e32 v69, 1.0, v73
	v_mul_f32_e32 v60, v71, v68
	v_mul_f32_e32 v64, v70, v60
	v_mov_b32_e32 v60, v58
	v_pk_mul_f32 v[60:61], v[60:61], v[168:169] op_sel_hi:[1,0]
	v_mov_b32_e32 v62, v59
	v_mul_f32_e32 v58, 0xbfb8aa3b, v61
	v_rcp_f32_e32 v69, v69
	v_exp_f32_e32 v65, v58
	v_pk_mul_f32 v[58:59], v[62:63], v[168:169] op_sel_hi:[1,0]
	v_mul_f32_e32 v57, v57, v69
	v_mul_f32_e32 v62, 0xbfb8aa3b, v59
	v_exp_f32_e32 v62, v62
	v_mul_f32_e32 v63, v56, v57
	v_add_f32_e32 v56, 1.0, v65
	v_rcp_f32_e32 v65, v56
	v_add_f32_e32 v56, 1.0, v62
	v_rcp_f32_e32 v62, v56
	v_mov_b32_e32 v56, v48
	v_mov_b32_e32 v57, v52
	v_pk_mul_f32 v[56:57], v[56:57], v[168:169] op_sel_hi:[1,0]
	v_mul_f32_e32 v52, v61, v65
	v_mul_f32_e32 v48, 0xbfb8aa3b, v57
	v_exp_f32_e32 v48, v48
	v_mul_f32_e32 v60, v60, v52
	v_mov_b32_e32 v52, v49
	v_mul_f32_e32 v59, v59, v62
	v_add_f32_e32 v48, 1.0, v48
	v_rcp_f32_e32 v61, v48
	v_pk_mul_f32 v[48:49], v[52:53], v[168:169] op_sel_hi:[1,0]
	v_mul_f32_e32 v58, v58, v59
	v_mul_f32_e32 v52, 0xbfb8aa3b, v49
	v_exp_f32_e32 v52, v52
	v_mul_f32_e32 v53, v57, v61
	v_mul_f32_e32 v56, v56, v53
	v_mov_b32_e32 v53, v54
	v_add_f32_e32 v52, 1.0, v52
	v_rcp_f32_e32 v57, v52
	v_mov_b32_e32 v52, v50
	v_pk_mul_f32 v[52:53], v[52:53], v[168:169] op_sel_hi:[1,0]
	v_mov_b32_e32 v54, v51
	v_mul_f32_e32 v50, 0xbfb8aa3b, v53
	v_exp_f32_e32 v59, v50
	v_pk_mul_f32 v[50:51], v[54:55], v[168:169] op_sel_hi:[1,0]
	v_mul_f32_e32 v49, v49, v57
	v_mul_f32_e32 v54, 0xbfb8aa3b, v51
	v_exp_f32_e32 v54, v54
	v_add_f32_e32 v55, 1.0, v59
	v_rcp_f32_e32 v55, v55
	v_mul_f32_e32 v57, v48, v49
	v_add_f32_e32 v54, 1.0, v54
	v_rcp_f32_e32 v54, v54
	v_mul_f32_e32 v48, v53, v55
	v_mul_f32_e32 v52, v52, v48
	v_mov_b32_e32 v55, v44
	v_mul_f32_e32 v48, v51, v54
	v_mov_b32_e32 v54, v40
	v_pk_mul_f32 v[54:55], v[54:55], v[166:167] op_sel_hi:[1,0]
	v_mul_f32_e32 v51, v50, v48
	v_mul_f32_e32 v40, 0xbfb8aa3b, v55
	v_cvt_pk_bf16_f32 v48, v64, v63
	v_cvt_pk_bf16_f32 v49, v60, v58
	v_cvt_pk_bf16_f32 v50, v56, v57
	v_exp_f32_e32 v56, v40
	v_mov_b32_e32 v44, v41
	v_pk_mul_f32 v[40:41], v[44:45], v[166:167] op_sel_hi:[1,0]
	v_cvt_pk_bf16_f32 v51, v52, v51
	v_mad_i64_i32 v[52:53], s[4:5], v148, s52, v[112:113]
	v_mul_f32_e32 v44, 0xbfb8aa3b, v41
	v_exp_f32_e32 v57, v44
	v_lshl_add_u64 v[44:45], v[52:53], 0, v[114:115]
	v_add_f32_e32 v52, 1.0, v56
	v_rcp_f32_e32 v52, v52
	global_store_dwordx4 v[44:45], v[48:51], off sc1
	v_mov_b32_e32 v45, v46
	v_add_f32_e32 v53, 1.0, v57
	v_mul_f32_e32 v44, v55, v52
	v_mul_f32_e32 v48, v54, v44
	v_mov_b32_e32 v44, v42
	v_pk_mul_f32 v[44:45], v[44:45], v[166:167] op_sel_hi:[1,0]
	v_mov_b32_e32 v46, v43
	v_mul_f32_e32 v42, 0xbfb8aa3b, v45
	v_rcp_f32_e32 v53, v53
	v_exp_f32_e32 v49, v42
	v_pk_mul_f32 v[42:43], v[46:47], v[166:167] op_sel_hi:[1,0]
	v_mul_f32_e32 v41, v41, v53
	v_mul_f32_e32 v46, 0xbfb8aa3b, v43
	v_exp_f32_e32 v46, v46
	v_mul_f32_e32 v47, v40, v41
	v_add_f32_e32 v40, 1.0, v49
	v_rcp_f32_e32 v49, v40
	v_add_f32_e32 v40, 1.0, v46
	v_rcp_f32_e32 v46, v40
	v_mov_b32_e32 v40, v32
	v_mov_b32_e32 v41, v36
	v_pk_mul_f32 v[40:41], v[40:41], v[166:167] op_sel_hi:[1,0]
	v_mul_f32_e32 v36, v45, v49
	v_mul_f32_e32 v32, 0xbfb8aa3b, v41
	v_exp_f32_e32 v32, v32
	v_mul_f32_e32 v44, v44, v36
	v_mov_b32_e32 v36, v33
	v_mul_f32_e32 v43, v43, v46
	v_add_f32_e32 v32, 1.0, v32
	v_rcp_f32_e32 v45, v32
	v_pk_mul_f32 v[32:33], v[36:37], v[166:167] op_sel_hi:[1,0]
	v_mul_f32_e32 v42, v42, v43
	v_mul_f32_e32 v36, 0xbfb8aa3b, v33
	v_exp_f32_e32 v36, v36
	v_mul_f32_e32 v37, v41, v45
	v_mul_f32_e32 v40, v40, v37
	v_mov_b32_e32 v37, v38
	v_add_f32_e32 v36, 1.0, v36
	v_rcp_f32_e32 v41, v36
	v_mov_b32_e32 v36, v34
	v_pk_mul_f32 v[36:37], v[36:37], v[166:167] op_sel_hi:[1,0]
	v_mov_b32_e32 v38, v35
	v_mul_f32_e32 v34, 0xbfb8aa3b, v37
	v_exp_f32_e32 v43, v34
	v_pk_mul_f32 v[34:35], v[38:39], v[166:167] op_sel_hi:[1,0]
	v_mul_f32_e32 v33, v33, v41
	v_mul_f32_e32 v38, 0xbfb8aa3b, v35
	v_exp_f32_e32 v38, v38
	v_add_f32_e32 v39, 1.0, v43
	v_rcp_f32_e32 v39, v39
	v_mul_f32_e32 v41, v32, v33
	v_add_f32_e32 v38, 1.0, v38
	v_rcp_f32_e32 v38, v38
	v_mul_f32_e32 v32, v37, v39
	v_mul_f32_e32 v36, v36, v32
	v_mov_b32_e32 v39, v28
	v_mul_f32_e32 v32, v35, v38
	v_mov_b32_e32 v38, v24
	v_pk_mul_f32 v[38:39], v[38:39], v[164:165] op_sel_hi:[1,0]
	v_mul_f32_e32 v35, v34, v32
	v_mul_f32_e32 v24, 0xbfb8aa3b, v39
	v_cvt_pk_bf16_f32 v32, v48, v47
	v_cvt_pk_bf16_f32 v33, v44, v42
	v_cvt_pk_bf16_f32 v34, v40, v41
	v_exp_f32_e32 v40, v24
	v_mov_b32_e32 v28, v25
	v_pk_mul_f32 v[24:25], v[28:29], v[164:165] op_sel_hi:[1,0]
	v_cvt_pk_bf16_f32 v35, v36, v35
	v_mad_i64_i32 v[36:37], s[4:5], v152, s52, v[112:113]
	v_mul_f32_e32 v28, 0xbfb8aa3b, v25
	v_exp_f32_e32 v41, v28
	v_lshl_add_u64 v[28:29], v[36:37], 0, v[114:115]
	v_add_f32_e32 v36, 1.0, v40
	v_rcp_f32_e32 v36, v36
	global_store_dwordx4 v[28:29], v[32:35], off sc1
	v_mov_b32_e32 v29, v30
	v_add_f32_e32 v37, 1.0, v41
	v_mul_f32_e32 v28, v39, v36
	v_mul_f32_e32 v32, v38, v28
	v_mov_b32_e32 v28, v26
	v_pk_mul_f32 v[28:29], v[28:29], v[164:165] op_sel_hi:[1,0]
	v_mov_b32_e32 v30, v27
	v_mul_f32_e32 v26, 0xbfb8aa3b, v29
	v_rcp_f32_e32 v37, v37
	v_exp_f32_e32 v33, v26
	v_pk_mul_f32 v[26:27], v[30:31], v[164:165] op_sel_hi:[1,0]
	v_mul_f32_e32 v25, v25, v37
	v_mul_f32_e32 v30, 0xbfb8aa3b, v27
	v_exp_f32_e32 v30, v30
	v_mul_f32_e32 v31, v24, v25
	v_add_f32_e32 v24, 1.0, v33
	v_rcp_f32_e32 v33, v24
	v_add_f32_e32 v24, 1.0, v30
	v_rcp_f32_e32 v30, v24
	v_mov_b32_e32 v24, v16
	v_mov_b32_e32 v25, v20
	v_pk_mul_f32 v[24:25], v[24:25], v[164:165] op_sel_hi:[1,0]
	v_mul_f32_e32 v20, v29, v33
	v_mul_f32_e32 v16, 0xbfb8aa3b, v25
	v_exp_f32_e32 v16, v16
	v_mul_f32_e32 v28, v28, v20
	v_mov_b32_e32 v20, v17
	v_mul_f32_e32 v27, v27, v30
	v_add_f32_e32 v16, 1.0, v16
	v_rcp_f32_e32 v29, v16
	v_pk_mul_f32 v[16:17], v[20:21], v[164:165] op_sel_hi:[1,0]
	v_mul_f32_e32 v26, v26, v27
	v_mul_f32_e32 v20, 0xbfb8aa3b, v17
	v_exp_f32_e32 v20, v20
	v_mul_f32_e32 v21, v25, v29
	v_mul_f32_e32 v24, v24, v21
	v_mov_b32_e32 v21, v22
	v_add_f32_e32 v20, 1.0, v20
	v_rcp_f32_e32 v25, v20
	v_mov_b32_e32 v20, v18
	v_pk_mul_f32 v[20:21], v[20:21], v[164:165] op_sel_hi:[1,0]
	v_mov_b32_e32 v22, v19
	v_mul_f32_e32 v18, 0xbfb8aa3b, v21
	v_exp_f32_e32 v27, v18
	v_pk_mul_f32 v[18:19], v[22:23], v[164:165] op_sel_hi:[1,0]
	v_mul_f32_e32 v17, v17, v25
	v_mul_f32_e32 v22, 0xbfb8aa3b, v19
	v_exp_f32_e32 v22, v22
	v_add_f32_e32 v23, 1.0, v27
	v_rcp_f32_e32 v23, v23
	v_mul_f32_e32 v25, v16, v17
	v_add_f32_e32 v22, 1.0, v22
	v_rcp_f32_e32 v22, v22
	v_mul_f32_e32 v16, v21, v23
	v_mul_f32_e32 v20, v20, v16
	v_mov_b32_e32 v23, v12
	v_mul_f32_e32 v16, v19, v22
	v_mov_b32_e32 v22, v8
	v_pk_mul_f32 v[22:23], v[22:23], v[158:159] op_sel_hi:[1,0]
	v_mul_f32_e32 v19, v18, v16
	v_mul_f32_e32 v8, 0xbfb8aa3b, v23
	v_cvt_pk_bf16_f32 v16, v32, v31
	v_cvt_pk_bf16_f32 v17, v28, v26
	v_cvt_pk_bf16_f32 v18, v24, v25
	v_exp_f32_e32 v24, v8
	v_mov_b32_e32 v12, v9
	v_pk_mul_f32 v[8:9], v[12:13], v[158:159] op_sel_hi:[1,0]
	v_cvt_pk_bf16_f32 v19, v20, v19
	v_mad_i64_i32 v[20:21], s[4:5], v150, s52, v[112:113]
	v_mul_f32_e32 v12, 0xbfb8aa3b, v9
	v_exp_f32_e32 v25, v12
	v_lshl_add_u64 v[12:13], v[20:21], 0, v[114:115]
	v_add_f32_e32 v20, 1.0, v24
	v_rcp_f32_e32 v20, v20
	global_store_dwordx4 v[12:13], v[16:19], off sc1
	v_mov_b32_e32 v13, v14
	v_add_f32_e32 v21, 1.0, v25
	v_mul_f32_e32 v12, v23, v20
	v_mul_f32_e32 v16, v22, v12
	v_mov_b32_e32 v12, v10
	v_pk_mul_f32 v[12:13], v[12:13], v[158:159] op_sel_hi:[1,0]
	v_mov_b32_e32 v14, v11
	v_mul_f32_e32 v10, 0xbfb8aa3b, v13
	v_rcp_f32_e32 v21, v21
	v_exp_f32_e32 v17, v10
	v_pk_mul_f32 v[10:11], v[14:15], v[158:159] op_sel_hi:[1,0]
	v_mul_f32_e32 v9, v9, v21
	v_mul_f32_e32 v14, 0xbfb8aa3b, v11
	v_exp_f32_e32 v14, v14
	v_mul_f32_e32 v15, v8, v9
	v_add_f32_e32 v8, 1.0, v17
	v_rcp_f32_e32 v17, v8
	v_add_f32_e32 v8, 1.0, v14
	v_rcp_f32_e32 v14, v8
	v_mov_b32_e32 v8, v0
	v_mov_b32_e32 v9, v4
	v_pk_mul_f32 v[8:9], v[8:9], v[158:159] op_sel_hi:[1,0]
	v_mul_f32_e32 v4, v13, v17
	v_mul_f32_e32 v0, 0xbfb8aa3b, v9
	v_exp_f32_e32 v0, v0
	v_mul_f32_e32 v12, v12, v4
	v_mov_b32_e32 v4, v1
	v_mul_f32_e32 v11, v11, v14
	v_add_f32_e32 v0, 1.0, v0
	v_rcp_f32_e32 v13, v0
	v_pk_mul_f32 v[0:1], v[4:5], v[158:159] op_sel_hi:[1,0]
	v_mul_f32_e32 v10, v10, v11
	v_mul_f32_e32 v4, 0xbfb8aa3b, v1
	v_exp_f32_e32 v4, v4
	v_mul_f32_e32 v5, v9, v13
	v_mul_f32_e32 v8, v8, v5
	v_mov_b32_e32 v5, v6
	v_add_f32_e32 v4, 1.0, v4
	v_rcp_f32_e32 v9, v4
	v_mov_b32_e32 v4, v2
	v_pk_mul_f32 v[4:5], v[4:5], v[158:159] op_sel_hi:[1,0]
	v_mov_b32_e32 v6, v3
	v_mul_f32_e32 v2, 0xbfb8aa3b, v5
	v_exp_f32_e32 v11, v2
	v_pk_mul_f32 v[2:3], v[6:7], v[158:159] op_sel_hi:[1,0]
	v_mul_f32_e32 v1, v1, v9
	v_mul_f32_e32 v6, 0xbfb8aa3b, v3
	v_exp_f32_e32 v6, v6
	v_add_f32_e32 v7, 1.0, v11
	v_rcp_f32_e32 v7, v7
	v_mul_f32_e32 v9, v0, v1
	v_add_f32_e32 v6, 1.0, v6
	v_rcp_f32_e32 v6, v6
	v_mul_f32_e32 v0, v5, v7
	v_mul_f32_e32 v4, v4, v0
	v_mul_f32_e32 v0, v3, v6
	v_mul_f32_e32 v3, v2, v0
	v_cvt_pk_bf16_f32 v0, v16, v15
	v_cvt_pk_bf16_f32 v1, v12, v10
	v_cvt_pk_bf16_f32 v2, v8, v9
	v_cvt_pk_bf16_f32 v3, v4, v3
	v_mad_i64_i32 v[4:5], s[4:5], v146, s52, v[112:113]
	v_lshl_add_u64 v[4:5], v[4:5], 0, v[114:115]
	s_mov_b64 s[4:5], -1
	global_store_dwordx4 v[4:5], v[0:3], off sc1
	s_cbranch_vccnz .LBB0_479
	s_andn2_b64 vcc, exec, s[16:17]
	s_cbranch_vccnz .LBB0_478
	s_barrier
	s_branch .LBB0_478

.LBB0_562:
	v_lshl_or_b32 v168, s12, 8, v188
	v_lshl_add_u32 v172, s54, 8, v186
	v_ashrrev_i32_e32 v169, 31, v168
	v_lshlrev_b64 v[204:205], 1, v[168:169]
	v_ashrrev_i32_e32 v173, 31, v172
	v_lshl_add_u64 v[170:171], s[26:27], 0, v[204:205]
	v_lshlrev_b64 v[206:207], 11, v[172:173]
	v_lshl_add_u64 v[128:129], v[170:171], 0, v[206:207]
	global_load_dwordx4 v[194:197], v[128:129], off
	global_load_dwordx4 v[198:201], v[128:129], off offset:256
	v_or_b32_e32 v182, 16, v172
	v_or_b32_e32 v178, 32, v172
	v_or_b32_e32 v174, 48, v172
	v_ashrrev_i32_e32 v183, 31, v182
	v_ashrrev_i32_e32 v179, 31, v178
	v_ashrrev_i32_e32 v175, 31, v174
	v_lshlrev_b64 v[184:185], 11, v[182:183]
	v_lshlrev_b64 v[180:181], 11, v[178:179]
	v_lshlrev_b64 v[176:177], 11, v[174:175]
	v_lshl_add_u64 v[128:129], v[170:171], 0, v[184:185]
	v_lshl_add_u64 v[130:131], v[170:171], 0, v[180:181]
	v_lshl_add_u64 v[208:209], v[170:171], 0, v[176:177]
	global_load_dwordx4 v[148:151], v[128:129], off
	global_load_dwordx4 v[144:147], v[128:129], off offset:256
	global_load_dwordx4 v[140:143], v[130:131], off
	global_load_dwordx4 v[136:139], v[130:131], off offset:256
	global_load_dwordx4 v[132:135], v[208:209], off
	s_nop 0
	global_load_dwordx4 v[128:131], v[208:209], off offset:256
	v_and_b32_e32 v208, 64, v192
	v_xor_b32_e32 v193, 16, v192
	v_add_u32_e32 v208, 64, v208
	v_xor_b32_e32 v209, 32, v192
	v_cmp_lt_i32_e32 vcc, v193, v208
	v_lshl_add_u64 v[206:207], s[26:27], 0, v[206:207]
	v_lshl_add_u64 v[204:205], v[206:207], 0, v[204:205]
	v_cndmask_b32_e32 v193, v192, v193, vcc
	v_cmp_lt_i32_e32 vcc, v209, v208
	v_lshlrev_b32_e32 v193, 2, v193
	s_lshl_b32 s38, s12, 2
	v_cndmask_b32_e32 v214, v192, v209, vcc
	s_ashr_i32 s39, s38, 31
	s_waitcnt vmcnt(0)
	v_lshlrev_b32_e32 v206, 16, v194
	v_and_b32_e32 v207, 0xffff0000, v194
	v_lshlrev_b32_e32 v194, 16, v195
	v_and_b32_e32 v195, 0xffff0000, v195
	v_lshlrev_b32_e32 v208, 16, v196
	v_and_b32_e32 v209, 0xffff0000, v196
	v_lshlrev_b32_e32 v196, 16, v197
	v_and_b32_e32 v197, 0xffff0000, v197
	v_lshlrev_b32_e32 v210, 16, v198
	v_and_b32_e32 v211, 0xffff0000, v198
	v_lshlrev_b32_e32 v198, 16, v199
	v_and_b32_e32 v199, 0xffff0000, v199
	v_lshlrev_b32_e32 v212, 16, v200
	v_and_b32_e32 v213, 0xffff0000, v200
	v_lshlrev_b32_e32 v200, 16, v201
	v_and_b32_e32 v201, 0xffff0000, v201
	v_pk_add_f32 v[126:127], v[126:127], v[194:195]
	v_pk_add_f32 v[124:125], v[124:125], v[206:207]
	v_pk_add_f32 v[122:123], v[122:123], v[196:197]
	v_pk_add_f32 v[120:121], v[120:121], v[208:209]
	v_pk_add_f32 v[118:119], v[118:119], v[198:199]
	v_pk_add_f32 v[116:117], v[116:117], v[210:211]
	v_pk_add_f32 v[194:195], v[114:115], v[200:201]
	v_pk_add_f32 v[196:197], v[112:113], v[212:213]
	v_mul_f32_e32 v114, v125, v125
	v_mul_f32_e32 v115, v127, v127
	v_mul_f32_e32 v198, v121, v121
	v_mul_f32_e32 v199, v123, v123
	v_cvt_pk_bf16_f32 v112, v124, v125
	v_cvt_pk_bf16_f32 v113, v126, v127
	v_mul_f32_e32 v125, v117, v117
	v_mul_f32_e32 v127, v119, v119
	v_mul_f32_e32 v200, v197, v197
	v_mul_f32_e32 v201, v195, v195
	v_fmac_f32_e32 v114, v124, v124
	v_fmac_f32_e32 v115, v126, v126
	v_fmac_f32_e32 v198, v120, v120
	v_fmac_f32_e32 v199, v122, v122
	v_fmac_f32_e32 v125, v116, v116
	v_fmac_f32_e32 v127, v118, v118
	v_fmac_f32_e32 v200, v196, v196
	v_fmac_f32_e32 v201, v194, v194
	v_add_f32_e32 v114, v114, v115
	v_add_f32_e32 v115, v198, v199
	v_add_f32_e32 v124, v125, v127
	v_add_f32_e32 v125, v200, v201
	v_add_f32_e32 v114, v114, v115
	v_add_f32_e32 v115, v124, v125
	v_add_f32_e32 v124, v114, v115
	ds_bpermute_b32 v125, v193, v124
	v_cvt_pk_bf16_f32 v114, v120, v121
	v_cvt_pk_bf16_f32 v115, v122, v123
	global_store_dwordx4 v[204:205], v[112:115], off sc1
	v_cvt_pk_bf16_f32 v116, v116, v117
	v_cvt_pk_bf16_f32 v117, v118, v119
	v_cvt_pk_bf16_f32 v118, v196, v197
	v_cvt_pk_bf16_f32 v119, v194, v195
	global_store_dwordx4 v[204:205], v[116:119], off offset:256 sc1
	s_waitcnt lgkmcnt(0)
	v_add_f32_e32 v113, v124, v125
	v_lshlrev_b32_e32 v112, 2, v214
	ds_bpermute_b32 v114, v112, v113
	s_and_saveexec_b64 s[4:5], s[6:7]
	s_cbranch_execz .LBB0_564
	v_lshlrev_b64 v[116:117], 6, v[172:173]
	v_lshl_add_u64 v[116:117], s[28:29], 0, v[116:117]
	v_lshl_add_u64 v[116:117], s[38:39], 2, v[116:117]
	s_lshl_b32 s12, s47, 2
	v_lshl_add_u64 v[116:117], v[116:117], 0, s[12:13]
	s_waitcnt lgkmcnt(0)
	v_add_f32_e32 v113, v113, v114
	global_store_dword v[116:117], v113, off
.LBB0_564:
	s_or_b64 exec, exec, s[4:5]
	s_waitcnt lgkmcnt(0)
	v_lshlrev_b32_e32 v114, 16, v148
	v_and_b32_e32 v115, 0xffff0000, v148
	v_lshlrev_b32_e32 v116, 16, v149
	v_and_b32_e32 v117, 0xffff0000, v149
	v_lshlrev_b32_e32 v118, 16, v150
	v_and_b32_e32 v119, 0xffff0000, v150
	v_lshlrev_b32_e32 v120, 16, v151
	v_and_b32_e32 v121, 0xffff0000, v151
	v_pk_add_f32 v[110:111], v[110:111], v[116:117]
	v_pk_add_f32 v[108:109], v[108:109], v[114:115]
	v_pk_add_f32 v[114:115], v[106:107], v[120:121]
	v_pk_add_f32 v[106:107], v[104:105], v[118:119]
	v_mul_f32_e32 v104, v109, v109
	v_mul_f32_e32 v105, v111, v111
	v_fmac_f32_e32 v104, v108, v108
	v_fmac_f32_e32 v105, v110, v110
	v_add_f32_e32 v104, v104, v105
	v_mul_f32_e32 v105, v107, v107
	v_mul_f32_e32 v113, v115, v115
	v_fmac_f32_e32 v105, v106, v106
	v_fmac_f32_e32 v113, v114, v114
	v_add_f32_e32 v105, v105, v113
	v_add_f32_e32 v113, v104, v105
	v_cvt_pk_bf16_f32 v104, v108, v109
	v_cvt_pk_bf16_f32 v105, v110, v111
	v_lshlrev_b32_e32 v108, 16, v144
	v_and_b32_e32 v109, 0xffff0000, v144
	v_lshlrev_b32_e32 v110, 16, v145
	v_and_b32_e32 v111, 0xffff0000, v145
	v_cvt_pk_bf16_f32 v106, v106, v107
	v_cvt_pk_bf16_f32 v107, v114, v115
	v_lshlrev_b32_e32 v114, 16, v146
	v_and_b32_e32 v115, 0xffff0000, v146
	v_pk_add_f32 v[102:103], v[102:103], v[110:111]
	v_pk_add_f32 v[100:101], v[100:101], v[108:109]
	v_lshlrev_b32_e32 v116, 16, v147
	v_and_b32_e32 v117, 0xffff0000, v147
	v_pk_add_f32 v[110:111], v[96:97], v[114:115]
	v_mul_f32_e32 v96, v101, v101
	v_mul_f32_e32 v97, v103, v103
	v_pk_add_f32 v[108:109], v[98:99], v[116:117]
	v_fmac_f32_e32 v96, v100, v100
	v_fmac_f32_e32 v97, v102, v102
	v_add_f32_e32 v96, v96, v97
	v_mul_f32_e32 v97, v111, v111
	v_mul_f32_e32 v98, v109, v109
	v_fmac_f32_e32 v97, v110, v110
	v_fmac_f32_e32 v98, v108, v108
	v_add_f32_e32 v97, v97, v98
	v_add_f32_e32 v96, v96, v97
	v_add_f32_e32 v99, v113, v96
	ds_bpermute_b32 v113, v193, v99
	v_lshl_add_u64 v[96:97], s[26:27], 0, v[184:185]
	v_lshl_add_u64 v[114:115], v[168:169], 1, v[96:97]
	global_store_dwordx4 v[114:115], v[104:107], off sc1
	v_cvt_pk_bf16_f32 v98, v100, v101
	s_waitcnt lgkmcnt(0)
	v_add_f32_e32 v96, v99, v113
	ds_bpermute_b32 v97, v112, v96
	v_cvt_pk_bf16_f32 v99, v102, v103
	v_cvt_pk_bf16_f32 v100, v110, v111
	v_cvt_pk_bf16_f32 v101, v108, v109
	global_store_dwordx4 v[114:115], v[98:101], off offset:256 sc1
	s_and_saveexec_b64 s[4:5], s[6:7]
	s_cbranch_execz .LBB0_566
	v_lshlrev_b64 v[98:99], 6, v[182:183]
	v_lshl_add_u64 v[98:99], s[28:29], 0, v[98:99]
	v_lshl_add_u64 v[98:99], s[38:39], 2, v[98:99]
	s_lshl_b32 s12, s47, 2
	v_lshl_add_u64 v[98:99], v[98:99], 0, s[12:13]
	s_waitcnt lgkmcnt(0)
	v_add_f32_e32 v96, v96, v97
	global_store_dword v[98:99], v96, off
.LBB0_566:
	s_or_b64 exec, exec, s[4:5]
	v_lshlrev_b32_e32 v96, 16, v140
	s_waitcnt lgkmcnt(0)
	v_and_b32_e32 v97, 0xffff0000, v140
	v_lshlrev_b32_e32 v98, 16, v141
	v_and_b32_e32 v99, 0xffff0000, v141
	v_lshlrev_b32_e32 v100, 16, v142
	v_and_b32_e32 v101, 0xffff0000, v142
	v_lshlrev_b32_e32 v102, 16, v143
	v_and_b32_e32 v103, 0xffff0000, v143
	v_pk_add_f32 v[94:95], v[94:95], v[98:99]
	v_pk_add_f32 v[92:93], v[92:93], v[96:97]
	v_pk_add_f32 v[96:97], v[90:91], v[102:103]
	v_pk_add_f32 v[90:91], v[88:89], v[100:101]
	v_mul_f32_e32 v88, v93, v93
	v_mul_f32_e32 v89, v95, v95
	v_fmac_f32_e32 v88, v92, v92
	v_fmac_f32_e32 v89, v94, v94
	v_add_f32_e32 v88, v88, v89
	v_mul_f32_e32 v89, v91, v91
	v_mul_f32_e32 v98, v97, v97
	v_fmac_f32_e32 v89, v90, v90
	v_fmac_f32_e32 v98, v96, v96
	v_add_f32_e32 v89, v89, v98
	v_add_f32_e32 v100, v88, v89
	v_cvt_pk_bf16_f32 v88, v92, v93
	v_cvt_pk_bf16_f32 v89, v94, v95
	v_lshlrev_b32_e32 v92, 16, v136
	v_and_b32_e32 v93, 0xffff0000, v136
	v_lshlrev_b32_e32 v94, 16, v137
	v_and_b32_e32 v95, 0xffff0000, v137
	v_cvt_pk_bf16_f32 v90, v90, v91
	v_cvt_pk_bf16_f32 v91, v96, v97
	v_lshlrev_b32_e32 v96, 16, v138
	v_and_b32_e32 v97, 0xffff0000, v138
	v_pk_add_f32 v[86:87], v[86:87], v[94:95]
	v_pk_add_f32 v[84:85], v[84:85], v[92:93]
	v_lshlrev_b32_e32 v98, 16, v139
	v_and_b32_e32 v99, 0xffff0000, v139
	v_pk_add_f32 v[94:95], v[80:81], v[96:97]
	v_mul_f32_e32 v80, v85, v85
	v_mul_f32_e32 v81, v87, v87
	v_pk_add_f32 v[92:93], v[82:83], v[98:99]
	v_fmac_f32_e32 v80, v84, v84
	v_fmac_f32_e32 v81, v86, v86
	v_add_f32_e32 v80, v80, v81
	v_mul_f32_e32 v81, v95, v95
	v_mul_f32_e32 v82, v93, v93
	v_fmac_f32_e32 v81, v94, v94
	v_fmac_f32_e32 v82, v92, v92
	v_add_f32_e32 v81, v81, v82
	v_add_f32_e32 v80, v80, v81
	v_add_f32_e32 v83, v100, v80
	ds_bpermute_b32 v98, v193, v83
	v_lshl_add_u64 v[80:81], s[26:27], 0, v[180:181]
	v_lshl_add_u64 v[96:97], v[168:169], 1, v[80:81]
	global_store_dwordx4 v[96:97], v[88:91], off sc1
	v_cvt_pk_bf16_f32 v82, v84, v85
	s_waitcnt lgkmcnt(0)
	v_add_f32_e32 v80, v83, v98
	ds_bpermute_b32 v81, v112, v80
	v_cvt_pk_bf16_f32 v83, v86, v87
	v_cvt_pk_bf16_f32 v84, v94, v95
	v_cvt_pk_bf16_f32 v85, v92, v93
	global_store_dwordx4 v[96:97], v[82:85], off offset:256 sc1
	s_and_saveexec_b64 s[4:5], s[6:7]
	s_cbranch_execz .LBB0_568
	v_lshlrev_b64 v[82:83], 6, v[178:179]
	v_lshl_add_u64 v[82:83], s[28:29], 0, v[82:83]
	v_lshl_add_u64 v[82:83], s[38:39], 2, v[82:83]
	s_lshl_b32 s12, s47, 2
	v_lshl_add_u64 v[82:83], v[82:83], 0, s[12:13]
	s_waitcnt lgkmcnt(0)
	v_add_f32_e32 v80, v80, v81
	global_store_dword v[82:83], v80, off
.LBB0_568:
	s_or_b64 exec, exec, s[4:5]
	v_lshlrev_b32_e32 v80, 16, v132
	s_waitcnt lgkmcnt(0)
	v_and_b32_e32 v81, 0xffff0000, v132
	v_lshlrev_b32_e32 v82, 16, v133
	v_and_b32_e32 v83, 0xffff0000, v133
	v_lshlrev_b32_e32 v84, 16, v134
	v_and_b32_e32 v85, 0xffff0000, v134
	v_lshlrev_b32_e32 v86, 16, v135
	v_and_b32_e32 v87, 0xffff0000, v135
	v_pk_add_f32 v[78:79], v[78:79], v[82:83]
	v_pk_add_f32 v[76:77], v[76:77], v[80:81]
	v_pk_add_f32 v[80:81], v[74:75], v[86:87]
	v_pk_add_f32 v[74:75], v[72:73], v[84:85]
	v_mul_f32_e32 v72, v77, v77
	v_mul_f32_e32 v73, v79, v79
	v_fmac_f32_e32 v72, v76, v76
	v_fmac_f32_e32 v73, v78, v78
	v_add_f32_e32 v72, v72, v73
	v_mul_f32_e32 v73, v75, v75
	v_mul_f32_e32 v82, v81, v81
	v_fmac_f32_e32 v73, v74, v74
	v_fmac_f32_e32 v82, v80, v80
	v_add_f32_e32 v73, v73, v82
	v_add_f32_e32 v84, v72, v73
	v_cvt_pk_bf16_f32 v72, v76, v77
	v_cvt_pk_bf16_f32 v73, v78, v79
	v_lshlrev_b32_e32 v76, 16, v128
	v_and_b32_e32 v77, 0xffff0000, v128
	v_lshlrev_b32_e32 v78, 16, v129
	v_and_b32_e32 v79, 0xffff0000, v129
	v_cvt_pk_bf16_f32 v74, v74, v75
	v_cvt_pk_bf16_f32 v75, v80, v81
	v_lshlrev_b32_e32 v80, 16, v130
	v_and_b32_e32 v81, 0xffff0000, v130
	v_pk_add_f32 v[70:71], v[70:71], v[78:79]
	v_pk_add_f32 v[68:69], v[68:69], v[76:77]
	v_lshlrev_b32_e32 v82, 16, v131
	v_and_b32_e32 v83, 0xffff0000, v131
	v_pk_add_f32 v[78:79], v[64:65], v[80:81]
	v_mul_f32_e32 v64, v69, v69
	v_mul_f32_e32 v65, v71, v71
	v_pk_add_f32 v[76:77], v[66:67], v[82:83]
	v_fmac_f32_e32 v64, v68, v68
	v_fmac_f32_e32 v65, v70, v70
	v_add_f32_e32 v64, v64, v65
	v_mul_f32_e32 v65, v79, v79
	v_mul_f32_e32 v66, v77, v77
	v_fmac_f32_e32 v65, v78, v78
	v_fmac_f32_e32 v66, v76, v76
	v_add_f32_e32 v65, v65, v66
	v_add_f32_e32 v64, v64, v65
	v_add_f32_e32 v67, v84, v64
	ds_bpermute_b32 v82, v193, v67
	v_lshl_add_u64 v[64:65], s[26:27], 0, v[176:177]
	v_lshl_add_u64 v[80:81], v[168:169], 1, v[64:65]
	global_store_dwordx4 v[80:81], v[72:75], off sc1
	v_cvt_pk_bf16_f32 v66, v68, v69
	s_waitcnt lgkmcnt(0)
	v_add_f32_e32 v64, v67, v82
	ds_bpermute_b32 v65, v112, v64
	v_cvt_pk_bf16_f32 v67, v70, v71
	v_cvt_pk_bf16_f32 v68, v78, v79
	v_cvt_pk_bf16_f32 v69, v76, v77
	global_store_dwordx4 v[80:81], v[66:69], off offset:256 sc1
	s_and_saveexec_b64 s[4:5], s[6:7]
	s_cbranch_execz .LBB0_570
	v_lshlrev_b64 v[66:67], 6, v[174:175]
	v_lshl_add_u64 v[66:67], s[28:29], 0, v[66:67]
	v_lshl_add_u64 v[66:67], s[38:39], 2, v[66:67]
	s_lshl_b32 s12, s47, 2
	v_lshl_add_u64 v[66:67], v[66:67], 0, s[12:13]
	s_waitcnt lgkmcnt(0)
	v_add_f32_e32 v64, v64, v65
	global_store_dword v[66:67], v64, off
.LBB0_570:
	s_or_b64 exec, exec, s[4:5]
	v_add_u32_e32 v100, 0x80, v172
	v_ashrrev_i32_e32 v101, 31, v100
	v_lshlrev_b64 v[110:111], 11, v[100:101]
	s_waitcnt lgkmcnt(0)
	v_lshl_add_u64 v[64:65], v[170:171], 0, v[110:111]
	global_load_dwordx4 v[102:105], v[64:65], off
	global_load_dwordx4 v[106:109], v[64:65], off offset:256
	v_add_u32_e32 v96, 0x90, v172
	v_add_u32_e32 v92, 0xa0, v172
	v_add_u32_e32 v88, 0xb0, v172
	v_ashrrev_i32_e32 v97, 31, v96
	v_ashrrev_i32_e32 v93, 31, v92
	v_ashrrev_i32_e32 v89, 31, v88
	v_lshlrev_b64 v[98:99], 11, v[96:97]
	v_lshlrev_b64 v[94:95], 11, v[92:93]
	v_lshlrev_b64 v[90:91], 11, v[88:89]
	v_lshl_add_u64 v[64:65], v[170:171], 0, v[98:99]
	v_lshl_add_u64 v[66:67], v[170:171], 0, v[94:95]
	v_lshl_add_u64 v[114:115], v[170:171], 0, v[90:91]
	global_load_dwordx4 v[84:87], v[64:65], off
	global_load_dwordx4 v[80:83], v[64:65], off offset:256
	global_load_dwordx4 v[76:79], v[66:67], off
	global_load_dwordx4 v[72:75], v[66:67], off offset:256
	global_load_dwordx4 v[68:71], v[114:115], off
	s_nop 0
	global_load_dwordx4 v[64:67], v[114:115], off offset:256
	s_waitcnt vmcnt(7)
	v_lshlrev_b32_e32 v114, 16, v102
	v_and_b32_e32 v115, 0xffff0000, v102
	v_lshlrev_b32_e32 v102, 16, v103
	v_and_b32_e32 v103, 0xffff0000, v103
	v_lshlrev_b32_e32 v116, 16, v104
	v_and_b32_e32 v117, 0xffff0000, v104
	v_lshlrev_b32_e32 v104, 16, v105
	v_and_b32_e32 v105, 0xffff0000, v105
	s_waitcnt vmcnt(6)
	v_lshlrev_b32_e32 v118, 16, v106
	v_and_b32_e32 v119, 0xffff0000, v106
	v_lshlrev_b32_e32 v106, 16, v107
	v_and_b32_e32 v107, 0xffff0000, v107
	v_lshlrev_b32_e32 v120, 16, v108
	v_and_b32_e32 v121, 0xffff0000, v108
	v_lshlrev_b32_e32 v108, 16, v109
	v_and_b32_e32 v109, 0xffff0000, v109
	v_pk_add_f32 v[62:63], v[62:63], v[102:103]
	v_pk_add_f32 v[60:61], v[60:61], v[114:115]
	v_pk_add_f32 v[58:59], v[58:59], v[104:105]
	v_pk_add_f32 v[56:57], v[56:57], v[116:117]
	v_pk_add_f32 v[54:55], v[54:55], v[106:107]
	v_pk_add_f32 v[52:53], v[52:53], v[118:119]
	v_pk_add_f32 v[102:103], v[50:51], v[108:109]
	v_pk_add_f32 v[104:105], v[48:49], v[120:121]
	v_mul_f32_e32 v106, v61, v61
	v_mul_f32_e32 v107, v63, v63
	v_mul_f32_e32 v108, v57, v57
	v_mul_f32_e32 v109, v59, v59
	v_cvt_pk_bf16_f32 v48, v60, v61
	v_cvt_pk_bf16_f32 v49, v62, v63
	v_cvt_pk_bf16_f32 v50, v56, v57
	v_cvt_pk_bf16_f32 v51, v58, v59
	v_mul_f32_e32 v57, v53, v53
	v_mul_f32_e32 v59, v55, v55
	v_mul_f32_e32 v61, v105, v105
	v_mul_f32_e32 v63, v103, v103
	v_fmac_f32_e32 v106, v60, v60
	v_fmac_f32_e32 v107, v62, v62
	v_fmac_f32_e32 v108, v56, v56
	v_fmac_f32_e32 v109, v58, v58
	v_fmac_f32_e32 v57, v52, v52
	v_fmac_f32_e32 v59, v54, v54
	v_fmac_f32_e32 v61, v104, v104
	v_fmac_f32_e32 v63, v102, v102
	v_add_f32_e32 v56, v106, v107
	v_add_f32_e32 v58, v108, v109
	v_add_f32_e32 v57, v57, v59
	v_add_f32_e32 v59, v61, v63
	v_add_f32_e32 v56, v56, v58
	v_add_f32_e32 v57, v57, v59
	v_add_f32_e32 v58, v56, v57
	ds_bpermute_b32 v59, v193, v58
	v_lshl_add_u64 v[56:57], s[26:27], 0, v[110:111]
	v_lshl_add_u64 v[56:57], v[168:169], 1, v[56:57]
	global_store_dwordx4 v[56:57], v[48:51], off sc1
	s_waitcnt lgkmcnt(0)
	s_nop 0
	v_add_f32_e32 v48, v58, v59
	ds_bpermute_b32 v49, v112, v48
	v_cvt_pk_bf16_f32 v50, v52, v53
	v_cvt_pk_bf16_f32 v51, v54, v55
	v_cvt_pk_bf16_f32 v52, v104, v105
	v_cvt_pk_bf16_f32 v53, v102, v103
	global_store_dwordx4 v[56:57], v[50:53], off offset:256 sc1
	s_and_saveexec_b64 s[4:5], s[6:7]
	s_cbranch_execz .LBB0_572
	v_lshlrev_b64 v[50:51], 6, v[100:101]
	v_lshl_add_u64 v[50:51], s[28:29], 0, v[50:51]
	v_lshl_add_u64 v[50:51], s[38:39], 2, v[50:51]
	s_lshl_b32 s12, s47, 2
	v_lshl_add_u64 v[50:51], v[50:51], 0, s[12:13]
	s_waitcnt lgkmcnt(0)
	v_add_f32_e32 v48, v48, v49
	global_store_dword v[50:51], v48, off
.LBB0_572:
	s_or_b64 exec, exec, s[4:5]
	s_waitcnt vmcnt(7)
	v_lshlrev_b32_e32 v48, 16, v84
	s_waitcnt lgkmcnt(0)
	v_and_b32_e32 v49, 0xffff0000, v84
	v_lshlrev_b32_e32 v50, 16, v85
	v_and_b32_e32 v51, 0xffff0000, v85
	v_lshlrev_b32_e32 v52, 16, v86
	v_and_b32_e32 v53, 0xffff0000, v86
	v_lshlrev_b32_e32 v54, 16, v87
	v_and_b32_e32 v55, 0xffff0000, v87
	v_pk_add_f32 v[46:47], v[46:47], v[50:51]
	v_pk_add_f32 v[44:45], v[44:45], v[48:49]
	v_pk_add_f32 v[48:49], v[42:43], v[54:55]
	v_pk_add_f32 v[42:43], v[40:41], v[52:53]
	v_mul_f32_e32 v40, v45, v45
	v_mul_f32_e32 v41, v47, v47
	v_fmac_f32_e32 v40, v44, v44
	v_fmac_f32_e32 v41, v46, v46
	v_add_f32_e32 v40, v40, v41
	v_mul_f32_e32 v41, v43, v43
	v_mul_f32_e32 v50, v49, v49
	v_fmac_f32_e32 v41, v42, v42
	v_fmac_f32_e32 v50, v48, v48
	v_add_f32_e32 v41, v41, v50
	v_add_f32_e32 v52, v40, v41
	v_cvt_pk_bf16_f32 v40, v44, v45
	v_cvt_pk_bf16_f32 v41, v46, v47
	s_waitcnt vmcnt(6)
	v_lshlrev_b32_e32 v44, 16, v80
	v_and_b32_e32 v45, 0xffff0000, v80
	v_lshlrev_b32_e32 v46, 16, v81
	v_and_b32_e32 v47, 0xffff0000, v81
	v_cvt_pk_bf16_f32 v42, v42, v43
	v_cvt_pk_bf16_f32 v43, v48, v49
	v_lshlrev_b32_e32 v48, 16, v82
	v_and_b32_e32 v49, 0xffff0000, v82
	v_pk_add_f32 v[38:39], v[38:39], v[46:47]
	v_pk_add_f32 v[36:37], v[36:37], v[44:45]
	v_lshlrev_b32_e32 v50, 16, v83
	v_and_b32_e32 v51, 0xffff0000, v83
	v_pk_add_f32 v[46:47], v[32:33], v[48:49]
	v_mul_f32_e32 v32, v37, v37
	v_mul_f32_e32 v33, v39, v39
	v_pk_add_f32 v[44:45], v[34:35], v[50:51]
	v_fmac_f32_e32 v32, v36, v36
	v_fmac_f32_e32 v33, v38, v38
	v_add_f32_e32 v32, v32, v33
	v_mul_f32_e32 v33, v47, v47
	v_mul_f32_e32 v34, v45, v45
	v_fmac_f32_e32 v33, v46, v46
	v_fmac_f32_e32 v34, v44, v44
	v_add_f32_e32 v33, v33, v34
	v_add_f32_e32 v32, v32, v33
	v_add_f32_e32 v35, v52, v32
	ds_bpermute_b32 v50, v193, v35
	v_lshl_add_u64 v[32:33], s[26:27], 0, v[98:99]
	v_lshl_add_u64 v[48:49], v[168:169], 1, v[32:33]
	global_store_dwordx4 v[48:49], v[40:43], off sc1
	v_cvt_pk_bf16_f32 v34, v36, v37
	s_waitcnt lgkmcnt(0)
	v_add_f32_e32 v32, v35, v50
	ds_bpermute_b32 v33, v112, v32
	v_cvt_pk_bf16_f32 v35, v38, v39
	v_cvt_pk_bf16_f32 v36, v46, v47
	v_cvt_pk_bf16_f32 v37, v44, v45
	global_store_dwordx4 v[48:49], v[34:37], off offset:256 sc1
	s_and_saveexec_b64 s[4:5], s[6:7]
	s_cbranch_execz .LBB0_574
	v_lshlrev_b64 v[34:35], 6, v[96:97]
	v_lshl_add_u64 v[34:35], s[28:29], 0, v[34:35]
	v_lshl_add_u64 v[34:35], s[38:39], 2, v[34:35]
	s_lshl_b32 s12, s47, 2
	v_lshl_add_u64 v[34:35], v[34:35], 0, s[12:13]
	s_waitcnt lgkmcnt(0)
	v_add_f32_e32 v32, v32, v33
	global_store_dword v[34:35], v32, off
.LBB0_574:
	s_or_b64 exec, exec, s[4:5]
	s_waitcnt vmcnt(7)
	v_lshlrev_b32_e32 v32, 16, v76
	s_waitcnt lgkmcnt(0)
	v_and_b32_e32 v33, 0xffff0000, v76
	v_lshlrev_b32_e32 v34, 16, v77
	v_and_b32_e32 v35, 0xffff0000, v77
	v_lshlrev_b32_e32 v36, 16, v78
	v_and_b32_e32 v37, 0xffff0000, v78
	v_lshlrev_b32_e32 v38, 16, v79
	v_and_b32_e32 v39, 0xffff0000, v79
	v_pk_add_f32 v[30:31], v[30:31], v[34:35]
	v_pk_add_f32 v[28:29], v[28:29], v[32:33]
	v_pk_add_f32 v[32:33], v[26:27], v[38:39]
	v_pk_add_f32 v[26:27], v[24:25], v[36:37]
	v_mul_f32_e32 v24, v29, v29
	v_mul_f32_e32 v25, v31, v31
	v_fmac_f32_e32 v24, v28, v28
	v_fmac_f32_e32 v25, v30, v30
	v_add_f32_e32 v24, v24, v25
	v_mul_f32_e32 v25, v27, v27
	v_mul_f32_e32 v34, v33, v33
	v_fmac_f32_e32 v25, v26, v26
	v_fmac_f32_e32 v34, v32, v32
	v_add_f32_e32 v25, v25, v34
	v_add_f32_e32 v36, v24, v25
	v_cvt_pk_bf16_f32 v24, v28, v29
	v_cvt_pk_bf16_f32 v25, v30, v31
	s_waitcnt vmcnt(6)
	v_lshlrev_b32_e32 v28, 16, v72
	v_and_b32_e32 v29, 0xffff0000, v72
	v_lshlrev_b32_e32 v30, 16, v73
	v_and_b32_e32 v31, 0xffff0000, v73
	v_cvt_pk_bf16_f32 v26, v26, v27
	v_cvt_pk_bf16_f32 v27, v32, v33
	v_lshlrev_b32_e32 v32, 16, v74
	v_and_b32_e32 v33, 0xffff0000, v74
	v_pk_add_f32 v[22:23], v[22:23], v[30:31]
	v_pk_add_f32 v[20:21], v[20:21], v[28:29]
	v_lshlrev_b32_e32 v34, 16, v75
	v_and_b32_e32 v35, 0xffff0000, v75
	v_pk_add_f32 v[30:31], v[16:17], v[32:33]
	v_mul_f32_e32 v16, v21, v21
	v_mul_f32_e32 v17, v23, v23
	v_pk_add_f32 v[28:29], v[18:19], v[34:35]
	v_fmac_f32_e32 v16, v20, v20
	v_fmac_f32_e32 v17, v22, v22
	v_add_f32_e32 v16, v16, v17
	v_mul_f32_e32 v17, v31, v31
	v_mul_f32_e32 v18, v29, v29
	v_fmac_f32_e32 v17, v30, v30
	v_fmac_f32_e32 v18, v28, v28
	v_add_f32_e32 v17, v17, v18
	v_add_f32_e32 v16, v16, v17
	v_add_f32_e32 v19, v36, v16
	ds_bpermute_b32 v34, v193, v19
	v_lshl_add_u64 v[16:17], s[26:27], 0, v[94:95]
	v_lshl_add_u64 v[32:33], v[168:169], 1, v[16:17]
	global_store_dwordx4 v[32:33], v[24:27], off sc1
	v_cvt_pk_bf16_f32 v18, v20, v21
	s_waitcnt lgkmcnt(0)
	v_add_f32_e32 v16, v19, v34
	ds_bpermute_b32 v17, v112, v16
	v_cvt_pk_bf16_f32 v19, v22, v23
	v_cvt_pk_bf16_f32 v20, v30, v31
	v_cvt_pk_bf16_f32 v21, v28, v29
	global_store_dwordx4 v[32:33], v[18:21], off offset:256 sc1
	s_and_saveexec_b64 s[4:5], s[6:7]
	s_cbranch_execz .LBB0_576
	v_lshlrev_b64 v[18:19], 6, v[92:93]
	v_lshl_add_u64 v[18:19], s[28:29], 0, v[18:19]
	v_lshl_add_u64 v[18:19], s[38:39], 2, v[18:19]
	s_lshl_b32 s12, s47, 2
	v_lshl_add_u64 v[18:19], v[18:19], 0, s[12:13]
	s_waitcnt lgkmcnt(0)
	v_add_f32_e32 v16, v16, v17
	global_store_dword v[18:19], v16, off
.LBB0_576:
	s_or_b64 exec, exec, s[4:5]
	s_waitcnt vmcnt(7)
	v_lshlrev_b32_e32 v16, 16, v68
	s_waitcnt lgkmcnt(0)
	v_and_b32_e32 v17, 0xffff0000, v68
	v_lshlrev_b32_e32 v18, 16, v69
	v_and_b32_e32 v19, 0xffff0000, v69
	v_lshlrev_b32_e32 v20, 16, v70
	v_and_b32_e32 v21, 0xffff0000, v70
	v_lshlrev_b32_e32 v22, 16, v71
	v_and_b32_e32 v23, 0xffff0000, v71
	v_pk_add_f32 v[14:15], v[14:15], v[18:19]
	v_pk_add_f32 v[12:13], v[12:13], v[16:17]
	v_pk_add_f32 v[16:17], v[10:11], v[22:23]
	v_pk_add_f32 v[10:11], v[8:9], v[20:21]
	v_mul_f32_e32 v8, v13, v13
	v_mul_f32_e32 v9, v15, v15
	v_fmac_f32_e32 v8, v12, v12
	v_fmac_f32_e32 v9, v14, v14
	v_add_f32_e32 v8, v8, v9
	v_mul_f32_e32 v9, v11, v11
	v_mul_f32_e32 v18, v17, v17
	v_fmac_f32_e32 v9, v10, v10
	v_fmac_f32_e32 v18, v16, v16
	v_add_f32_e32 v9, v9, v18
	v_add_f32_e32 v20, v8, v9
	v_cvt_pk_bf16_f32 v8, v12, v13
	v_cvt_pk_bf16_f32 v9, v14, v15
	s_waitcnt vmcnt(6)
	v_lshlrev_b32_e32 v12, 16, v64
	v_and_b32_e32 v13, 0xffff0000, v64
	v_lshlrev_b32_e32 v14, 16, v65
	v_and_b32_e32 v15, 0xffff0000, v65
	v_cvt_pk_bf16_f32 v10, v10, v11
	v_cvt_pk_bf16_f32 v11, v16, v17
	v_lshlrev_b32_e32 v16, 16, v66
	v_and_b32_e32 v17, 0xffff0000, v66
	v_pk_add_f32 v[6:7], v[6:7], v[14:15]
	v_pk_add_f32 v[4:5], v[4:5], v[12:13]
	v_lshlrev_b32_e32 v18, 16, v67
	v_and_b32_e32 v19, 0xffff0000, v67
	v_pk_add_f32 v[14:15], v[0:1], v[16:17]
	v_mul_f32_e32 v0, v5, v5
	v_mul_f32_e32 v1, v7, v7
	v_pk_add_f32 v[12:13], v[2:3], v[18:19]
	v_fmac_f32_e32 v0, v4, v4
	v_fmac_f32_e32 v1, v6, v6
	v_add_f32_e32 v0, v0, v1
	v_mul_f32_e32 v1, v15, v15
	v_mul_f32_e32 v2, v13, v13
	v_fmac_f32_e32 v1, v14, v14
	v_fmac_f32_e32 v2, v12, v12
	v_add_f32_e32 v1, v1, v2
	v_add_f32_e32 v0, v0, v1
	v_add_f32_e32 v3, v20, v0
	ds_bpermute_b32 v18, v193, v3
	v_lshl_add_u64 v[0:1], s[26:27], 0, v[90:91]
	v_lshl_add_u64 v[16:17], v[168:169], 1, v[0:1]
	global_store_dwordx4 v[16:17], v[8:11], off sc1
	v_cvt_pk_bf16_f32 v2, v4, v5
	s_waitcnt lgkmcnt(0)
	v_add_f32_e32 v0, v3, v18
	ds_bpermute_b32 v1, v112, v0
	v_cvt_pk_bf16_f32 v3, v6, v7
	v_cvt_pk_bf16_f32 v4, v14, v15
	v_cvt_pk_bf16_f32 v5, v12, v13
	global_store_dwordx4 v[16:17], v[2:5], off offset:256 sc1
	s_and_saveexec_b64 s[4:5], s[6:7]
	s_cbranch_execz .LBB0_578
	v_lshlrev_b64 v[2:3], 6, v[88:89]
	v_lshl_add_u64 v[2:3], s[28:29], 0, v[2:3]
	v_lshl_add_u64 v[2:3], s[38:39], 2, v[2:3]
	s_lshl_b32 s12, s47, 2
	v_lshl_add_u64 v[2:3], v[2:3], 0, s[12:13]
	s_waitcnt lgkmcnt(0)
	v_add_f32_e32 v0, v0, v1
	global_store_dword v[2:3], v0, off

.LBB0_650:
	s_lshl_b32 s22, s16, 8
	s_ashr_i32 s5, s4, 31
	s_lshl_b64 s[16:17], s[4:5], 26
	s_and_b32 s5, s22, 0x300
	s_add_u32 s16, s54, s16
	v_or_b32_e32 v120, s5, v190
	s_addc_u32 s17, s55, s17
	v_lshlrev_b32_e32 v144, 1, v120
	s_cmp_eq_u32 s4, 2
	v_lshl_add_u64 v[122:123], s[16:17], 0, v[144:145]
	v_lshlrev_b64 v[120:121], 11, v[170:171]
	s_cselect_b64 vcc, -1, 0
	v_lshl_add_u64 v[124:125], v[122:123], 0, v[120:121]
	v_cndmask_b32_e32 v120, 1.0, v197, vcc
	v_pk_mul_f32 v[126:127], v[120:121], v[126:127] op_sel_hi:[0,1]
	v_mov_b32_e32 v181, v180
	v_pk_mul_f32 v[170:171], v[120:121], v[182:183] op_sel_hi:[0,1]
	v_cvt_pk_bf16_f32 v182, v170, v171
	v_cvt_pk_bf16_f32 v183, v126, v127
	v_mov_b32_e32 v126, v180
	v_mov_b32_e32 v127, v180
	v_pk_mul_f32 v[216:217], v[120:121], v[184:185] op_sel_hi:[0,1]
	v_pk_mul_f32 v[184:185], v[120:121], v[186:187] op_sel_hi:[0,1]
	v_pk_mul_f32 v[118:119], v[118:119], v[126:127]
	v_pk_mul_f32 v[116:117], v[116:117], v[180:181]
	v_pk_mul_f32 v[114:115], v[114:115], v[126:127]
	s_and_b64 vcc, exec, s[12:13]
	v_pk_mul_f32 v[112:113], v[112:113], v[180:181]
	v_cvt_pk_bf16_f32 v184, v184, v185
	v_cvt_pk_bf16_f32 v185, v216, v217
	global_store_dwordx4 v[124:125], v[182:185], off sc1
	s_cbranch_vccnz .LBB0_652
	ds_bpermute_b32 v126, v198, v116
	ds_bpermute_b32 v127, v198, v117
	ds_bpermute_b32 v170, v198, v112
	ds_bpermute_b32 v180, v198, v118
	ds_bpermute_b32 v181, v198, v119
	ds_bpermute_b32 v171, v198, v113
	ds_bpermute_b32 v182, v198, v114
	ds_bpermute_b32 v183, v198, v115
	s_waitcnt lgkmcnt(6)
	v_pk_mul_f32 v[126:127], v[176:177], v[126:127]
	s_waitcnt lgkmcnt(3)
	v_pk_mul_f32 v[176:177], v[178:179], v[180:181]
	s_waitcnt vmcnt(2)
	v_pk_fma_f32 v[116:117], v[116:117], v[132:133], v[126:127]
	s_waitcnt lgkmcnt(2)
	v_pk_mul_f32 v[126:127], v[174:175], v[170:171]
	s_waitcnt lgkmcnt(0)
	v_pk_mul_f32 v[132:133], v[172:173], v[182:183]
	v_pk_fma_f32 v[118:119], v[118:119], v[134:135], v[176:177]
	s_waitcnt vmcnt(1)
	v_pk_fma_f32 v[114:115], v[114:115], v[130:131], v[132:133]
	v_pk_fma_f32 v[112:113], v[112:113], v[128:129], v[126:127]
.LBB0_652:
	v_mov_b32_e32 v121, v120
	v_mov_b32_e32 v126, v120
	v_mov_b32_e32 v127, v120
	v_pk_mul_f32 v[118:119], v[126:127], v[118:119]
	v_pk_mul_f32 v[126:127], v[126:127], v[114:115]
	v_pk_mul_f32 v[114:115], v[120:121], v[112:113]
	v_pk_mul_f32 v[116:117], v[120:121], v[116:117]
	s_waitcnt vmcnt(1)
	v_mov_b32_e32 v128, 0
	v_cvt_pk_bf16_f32 v112, v116, v117
	v_cvt_pk_bf16_f32 v113, v118, v119
	v_cvt_pk_bf16_f32 v114, v114, v115
	v_cvt_pk_bf16_f32 v115, v126, v127
	global_store_dwordx4 v[124:125], v[112:115], off offset:256 sc1
	v_mov_b32_e32 v116, 1.0
	v_mov_b32_e32 v117, 1.0
	v_mov_b32_e32 v118, 1.0
	v_mov_b32_e32 v119, 1.0
	v_mov_b32_e32 v112, 1.0
	v_mov_b32_e32 v113, 1.0
	v_mov_b32_e32 v114, 1.0
	v_mov_b32_e32 v115, 1.0
	v_mov_b32_e32 v129, 0
	v_mov_b32_e32 v130, 0
	v_mov_b32_e32 v131, 0
	v_mov_b32_e32 v126, 0
	v_mov_b32_e32 v127, 0
	v_mov_b32_e32 v124, 0
	v_mov_b32_e32 v125, 0
	s_and_saveexec_b64 s[4:5], s[46:47]
	s_cbranch_execz .LBB0_654
	v_lshlrev_b32_e32 v112, 6, v168
	v_and_b32_e32 v112, 0x7f7c0, v112
	global_load_dwordx4 v[124:127], v112, s[28:29] offset:32
	global_load_dwordx4 v[132:135], v112, s[28:29] offset:48
	global_load_dwordx4 v[116:119], v112, s[28:29]
	s_nop 0
	global_load_dwordx4 v[112:115], v112, s[28:29] offset:16
	s_waitcnt vmcnt(3)
	v_xor_b32_e32 v131, 0x80000000, v127
	v_xor_b32_e32 v130, 0x80000000, v126
	v_xor_b32_e32 v129, 0x80000000, v125
	v_xor_b32_e32 v128, 0x80000000, v124
	s_waitcnt vmcnt(2)
	v_xor_b32_e32 v144, 0x80000000, v135
	v_xor_b32_e32 v170, 0x80000000, v134
	v_xor_b32_e32 v171, 0x80000000, v133
	v_xor_b32_e32 v172, 0x80000000, v132
	v_cndmask_b32_e64 v128, v124, v128, s[8:9]
	v_cndmask_b32_e64 v129, v125, v129, s[8:9]
	v_cndmask_b32_e64 v130, v126, v130, s[8:9]
	v_cndmask_b32_e64 v131, v127, v131, s[8:9]
	v_cndmask_b32_e64 v126, v132, v172, s[8:9]
	v_cndmask_b32_e64 v127, v133, v171, s[8:9]
	v_cndmask_b32_e64 v124, v134, v170, s[8:9]
	v_cndmask_b32_e64 v125, v135, v144, s[8:9]

.LBB0_656:
	v_lshlrev_b64 v[104:105], 11, v[168:169]
	v_mov_b32_e32 v106, v120
	v_mov_b32_e32 v107, v120
	v_pk_mul_f32 v[108:109], v[120:121], v[108:109]
	v_lshl_add_u64 v[104:105], v[122:123], 0, v[104:105]
	v_pk_mul_f32 v[110:111], v[106:107], v[110:111]
	v_cvt_pk_bf16_f32 v108, v108, v109
	v_mov_b32_e32 v133, v132
	v_cvt_pk_bf16_f32 v109, v110, v111
	v_pk_mul_f32 v[134:135], v[106:107], v[134:135]
	v_pk_mul_f32 v[168:169], v[120:121], v[170:171]
	v_pk_mul_f32 v[100:101], v[100:101], v[132:133]
	v_cvt_pk_bf16_f32 v110, v168, v169
	v_cvt_pk_bf16_f32 v111, v134, v135
	global_store_dwordx4 v[104:105], v[108:111], off sc1
	s_and_b64 vcc, exec, s[12:13]
	v_pk_mul_f32 v[96:97], v[96:97], v[132:133]
	v_mov_b32_e32 v108, v132
	v_mov_b32_e32 v109, v132
	v_pk_mul_f32 v[102:103], v[102:103], v[108:109]
	v_pk_mul_f32 v[98:99], v[98:99], v[108:109]
	s_cbranch_vccnz .LBB0_658
	ds_bpermute_b32 v108, v198, v100
	ds_bpermute_b32 v109, v198, v101
	ds_bpermute_b32 v110, v198, v96
	ds_bpermute_b32 v132, v198, v102
	ds_bpermute_b32 v133, v198, v103
	ds_bpermute_b32 v111, v198, v97
	ds_bpermute_b32 v134, v198, v98
	ds_bpermute_b32 v135, v198, v99
	s_waitcnt lgkmcnt(6)
	v_pk_mul_f32 v[108:109], v[128:129], v[108:109]
	s_waitcnt lgkmcnt(3)
	v_pk_mul_f32 v[128:129], v[130:131], v[132:133]
	s_waitcnt vmcnt(2)
	v_pk_fma_f32 v[100:101], v[100:101], v[116:117], v[108:109]
	s_waitcnt lgkmcnt(2)
	v_pk_mul_f32 v[108:109], v[126:127], v[110:111]
	s_waitcnt lgkmcnt(0)
	v_pk_mul_f32 v[110:111], v[124:125], v[134:135]
	v_pk_fma_f32 v[102:103], v[102:103], v[118:119], v[128:129]
	s_waitcnt vmcnt(1)
	v_pk_fma_f32 v[98:99], v[98:99], v[114:115], v[110:111]
	v_pk_fma_f32 v[96:97], v[96:97], v[112:113], v[108:109]
.LBB0_658:
	v_pk_mul_f32 v[102:103], v[106:107], v[102:103]
	v_pk_mul_f32 v[106:107], v[106:107], v[98:99]
	v_pk_mul_f32 v[98:99], v[120:121], v[96:97]
	v_pk_mul_f32 v[100:101], v[120:121], v[100:101]
	v_mov_b32_e32 v108, 0
	v_cvt_pk_bf16_f32 v96, v100, v101
	v_cvt_pk_bf16_f32 v97, v102, v103
	v_cvt_pk_bf16_f32 v98, v98, v99
	v_cvt_pk_bf16_f32 v99, v106, v107
	global_store_dwordx4 v[104:105], v[96:99], off offset:256 sc1
	v_mov_b32_e32 v100, 1.0
	v_mov_b32_e32 v101, 1.0
	v_mov_b32_e32 v102, 1.0
	v_mov_b32_e32 v103, 1.0
	v_mov_b32_e32 v96, 1.0
	v_mov_b32_e32 v97, 1.0
	v_mov_b32_e32 v98, 1.0
	v_mov_b32_e32 v99, 1.0
	v_mov_b32_e32 v109, 0
	v_mov_b32_e32 v110, 0
	v_mov_b32_e32 v111, 0
	v_mov_b32_e32 v106, 0
	v_mov_b32_e32 v107, 0
	v_mov_b32_e32 v104, 0
	v_mov_b32_e32 v105, 0
	s_and_saveexec_b64 s[4:5], s[46:47]
	s_cbranch_execz .LBB0_660
	v_lshlrev_b32_e32 v96, 6, v166
	v_and_b32_e32 v96, 0x7fbc0, v96
	global_load_dwordx4 v[104:107], v96, s[28:29] offset:32
	global_load_dwordx4 v[112:115], v96, s[28:29] offset:48
	global_load_dwordx4 v[100:103], v96, s[28:29]
	s_nop 0
	global_load_dwordx4 v[96:99], v96, s[28:29] offset:16
	s_waitcnt vmcnt(3)
	v_xor_b32_e32 v111, 0x80000000, v107
	v_xor_b32_e32 v110, 0x80000000, v106
	v_xor_b32_e32 v109, 0x80000000, v105
	v_xor_b32_e32 v108, 0x80000000, v104
	s_waitcnt vmcnt(2)
	v_xor_b32_e32 v116, 0x80000000, v115
	v_xor_b32_e32 v117, 0x80000000, v114
	v_xor_b32_e32 v118, 0x80000000, v113
	v_xor_b32_e32 v119, 0x80000000, v112
	v_cndmask_b32_e64 v108, v104, v108, s[8:9]
	v_cndmask_b32_e64 v109, v105, v109, s[8:9]
	v_cndmask_b32_e64 v110, v106, v110, s[8:9]
	v_cndmask_b32_e64 v111, v107, v111, s[8:9]
	v_cndmask_b32_e64 v106, v112, v119, s[8:9]
	v_cndmask_b32_e64 v107, v113, v118, s[8:9]
	v_cndmask_b32_e64 v104, v114, v117, s[8:9]
	v_cndmask_b32_e64 v105, v115, v116, s[8:9]

.LBB0_662:
	v_lshlrev_b64 v[88:89], 11, v[166:167]
	v_mov_b32_e32 v90, v120
	v_mov_b32_e32 v91, v120
	v_pk_mul_f32 v[92:93], v[120:121], v[92:93]
	v_lshl_add_u64 v[88:89], v[122:123], 0, v[88:89]
	v_pk_mul_f32 v[94:95], v[90:91], v[94:95]
	v_cvt_pk_bf16_f32 v92, v92, v93
	v_mov_b32_e32 v113, v112
	v_cvt_pk_bf16_f32 v93, v94, v95
	v_pk_mul_f32 v[114:115], v[90:91], v[114:115]
	v_pk_mul_f32 v[116:117], v[120:121], v[116:117]
	v_pk_mul_f32 v[84:85], v[84:85], v[112:113]
	v_cvt_pk_bf16_f32 v94, v116, v117
	v_cvt_pk_bf16_f32 v95, v114, v115
	global_store_dwordx4 v[88:89], v[92:95], off sc1
	s_and_b64 vcc, exec, s[12:13]
	v_pk_mul_f32 v[80:81], v[80:81], v[112:113]
	v_mov_b32_e32 v92, v112
	v_mov_b32_e32 v93, v112
	v_pk_mul_f32 v[86:87], v[86:87], v[92:93]
	v_pk_mul_f32 v[82:83], v[82:83], v[92:93]
	s_cbranch_vccnz .LBB0_664
	ds_bpermute_b32 v92, v198, v84
	ds_bpermute_b32 v93, v198, v85
	ds_bpermute_b32 v94, v198, v80
	ds_bpermute_b32 v112, v198, v86
	ds_bpermute_b32 v113, v198, v87
	ds_bpermute_b32 v95, v198, v81
	ds_bpermute_b32 v114, v198, v82
	ds_bpermute_b32 v115, v198, v83
	s_waitcnt lgkmcnt(6)
	v_pk_mul_f32 v[92:93], v[108:109], v[92:93]
	s_waitcnt lgkmcnt(3)
	v_pk_mul_f32 v[108:109], v[110:111], v[112:113]
	s_waitcnt vmcnt(2)
	v_pk_fma_f32 v[84:85], v[84:85], v[100:101], v[92:93]
	s_waitcnt lgkmcnt(2)
	v_pk_mul_f32 v[92:93], v[106:107], v[94:95]
	s_waitcnt lgkmcnt(0)
	v_pk_mul_f32 v[94:95], v[104:105], v[114:115]
	v_pk_fma_f32 v[86:87], v[86:87], v[102:103], v[108:109]
	s_waitcnt vmcnt(1)
	v_pk_fma_f32 v[82:83], v[82:83], v[98:99], v[94:95]
	v_pk_fma_f32 v[80:81], v[80:81], v[96:97], v[92:93]
.LBB0_664:
	v_pk_mul_f32 v[86:87], v[90:91], v[86:87]
	v_pk_mul_f32 v[90:91], v[90:91], v[82:83]
	v_pk_mul_f32 v[82:83], v[120:121], v[80:81]
	v_pk_mul_f32 v[84:85], v[120:121], v[84:85]
	v_mov_b32_e32 v92, 0
	v_cvt_pk_bf16_f32 v80, v84, v85
	v_cvt_pk_bf16_f32 v81, v86, v87
	v_cvt_pk_bf16_f32 v82, v82, v83
	v_cvt_pk_bf16_f32 v83, v90, v91
	global_store_dwordx4 v[88:89], v[80:83], off offset:256 sc1
	v_mov_b32_e32 v84, 1.0
	v_mov_b32_e32 v85, 1.0
	v_mov_b32_e32 v86, 1.0
	v_mov_b32_e32 v87, 1.0
	v_mov_b32_e32 v80, 1.0
	v_mov_b32_e32 v81, 1.0
	v_mov_b32_e32 v82, 1.0
	v_mov_b32_e32 v83, 1.0
	v_mov_b32_e32 v93, 0
	v_mov_b32_e32 v94, 0
	v_mov_b32_e32 v95, 0
	v_mov_b32_e32 v90, 0
	v_mov_b32_e32 v91, 0
	v_mov_b32_e32 v88, 0
	v_mov_b32_e32 v89, 0
	s_and_saveexec_b64 s[4:5], s[46:47]
	s_cbranch_execz .LBB0_666
	v_lshlrev_b32_e32 v80, 6, v164
	v_and_b32_e32 v80, 0x7ffc0, v80
	global_load_dwordx4 v[88:91], v80, s[28:29] offset:32
	global_load_dwordx4 v[96:99], v80, s[28:29] offset:48
	global_load_dwordx4 v[84:87], v80, s[28:29]
	s_nop 0
	global_load_dwordx4 v[80:83], v80, s[28:29] offset:16
	s_waitcnt vmcnt(3)
	v_xor_b32_e32 v95, 0x80000000, v91
	v_xor_b32_e32 v94, 0x80000000, v90
	v_xor_b32_e32 v93, 0x80000000, v89
	v_xor_b32_e32 v92, 0x80000000, v88
	s_waitcnt vmcnt(2)
	v_xor_b32_e32 v100, 0x80000000, v99
	v_xor_b32_e32 v101, 0x80000000, v98
	v_xor_b32_e32 v102, 0x80000000, v97
	v_xor_b32_e32 v103, 0x80000000, v96
	v_cndmask_b32_e64 v92, v88, v92, s[8:9]
	v_cndmask_b32_e64 v93, v89, v93, s[8:9]
	v_cndmask_b32_e64 v94, v90, v94, s[8:9]
	v_cndmask_b32_e64 v95, v91, v95, s[8:9]
	v_cndmask_b32_e64 v90, v96, v103, s[8:9]
	v_cndmask_b32_e64 v91, v97, v102, s[8:9]
	v_cndmask_b32_e64 v88, v98, v101, s[8:9]
	v_cndmask_b32_e64 v89, v99, v100, s[8:9]

.LBB0_668:
	v_lshlrev_b64 v[72:73], 11, v[164:165]
	v_mov_b32_e32 v74, v120
	v_mov_b32_e32 v75, v120
	v_pk_mul_f32 v[76:77], v[120:121], v[76:77]
	v_lshl_add_u64 v[72:73], v[122:123], 0, v[72:73]
	v_pk_mul_f32 v[78:79], v[74:75], v[78:79]
	v_cvt_pk_bf16_f32 v76, v76, v77
	v_mov_b32_e32 v97, v96
	v_cvt_pk_bf16_f32 v77, v78, v79
	v_pk_mul_f32 v[98:99], v[74:75], v[98:99]
	v_pk_mul_f32 v[100:101], v[120:121], v[100:101]
	v_pk_mul_f32 v[68:69], v[68:69], v[96:97]
	v_cvt_pk_bf16_f32 v78, v100, v101
	v_cvt_pk_bf16_f32 v79, v98, v99
	global_store_dwordx4 v[72:73], v[76:79], off sc1
	s_and_b64 vcc, exec, s[12:13]
	v_pk_mul_f32 v[64:65], v[64:65], v[96:97]
	v_mov_b32_e32 v76, v96
	v_mov_b32_e32 v77, v96
	v_pk_mul_f32 v[70:71], v[70:71], v[76:77]
	v_pk_mul_f32 v[66:67], v[66:67], v[76:77]
	s_cbranch_vccnz .LBB0_670
	ds_bpermute_b32 v76, v198, v68
	ds_bpermute_b32 v77, v198, v69
	ds_bpermute_b32 v78, v198, v64
	ds_bpermute_b32 v96, v198, v70
	ds_bpermute_b32 v97, v198, v71
	ds_bpermute_b32 v79, v198, v65
	ds_bpermute_b32 v98, v198, v66
	ds_bpermute_b32 v99, v198, v67
	s_waitcnt lgkmcnt(6)
	v_pk_mul_f32 v[76:77], v[92:93], v[76:77]
	s_waitcnt lgkmcnt(3)
	v_pk_mul_f32 v[92:93], v[94:95], v[96:97]
	s_waitcnt vmcnt(2)
	v_pk_fma_f32 v[68:69], v[68:69], v[84:85], v[76:77]
	s_waitcnt lgkmcnt(2)
	v_pk_mul_f32 v[76:77], v[90:91], v[78:79]
	s_waitcnt lgkmcnt(0)
	v_pk_mul_f32 v[78:79], v[88:89], v[98:99]
	v_pk_fma_f32 v[70:71], v[70:71], v[86:87], v[92:93]
	s_waitcnt vmcnt(1)
	v_pk_fma_f32 v[66:67], v[66:67], v[82:83], v[78:79]
	v_pk_fma_f32 v[64:65], v[64:65], v[80:81], v[76:77]
.LBB0_670:
	v_pk_mul_f32 v[70:71], v[74:75], v[70:71]
	v_pk_mul_f32 v[74:75], v[74:75], v[66:67]
	v_pk_mul_f32 v[66:67], v[120:121], v[64:65]
	v_pk_mul_f32 v[68:69], v[120:121], v[68:69]
	v_mov_b32_e32 v76, 0
	v_cvt_pk_bf16_f32 v64, v68, v69
	v_cvt_pk_bf16_f32 v65, v70, v71
	v_cvt_pk_bf16_f32 v66, v66, v67
	v_cvt_pk_bf16_f32 v67, v74, v75
	global_store_dwordx4 v[72:73], v[64:67], off offset:256 sc1
	v_mov_b32_e32 v68, 1.0
	v_mov_b32_e32 v69, 1.0
	v_mov_b32_e32 v70, 1.0
	v_mov_b32_e32 v71, 1.0
	v_mov_b32_e32 v64, 1.0
	v_mov_b32_e32 v65, 1.0
	v_mov_b32_e32 v66, 1.0
	v_mov_b32_e32 v67, 1.0
	v_mov_b32_e32 v77, 0
	v_mov_b32_e32 v78, 0
	v_mov_b32_e32 v79, 0
	v_mov_b32_e32 v74, 0
	v_mov_b32_e32 v75, 0
	v_mov_b32_e32 v72, 0
	v_mov_b32_e32 v73, 0
	s_and_saveexec_b64 s[4:5], s[46:47]
	s_cbranch_execz .LBB0_672
	v_lshlrev_b32_e32 v64, 6, v162
	v_and_b32_e32 v64, 0x7f3c0, v64
	global_load_dwordx4 v[72:75], v64, s[28:29] offset:32
	global_load_dwordx4 v[80:83], v64, s[28:29] offset:48
	global_load_dwordx4 v[68:71], v64, s[28:29]
	s_nop 0
	global_load_dwordx4 v[64:67], v64, s[28:29] offset:16
	s_waitcnt vmcnt(3)
	v_xor_b32_e32 v79, 0x80000000, v75
	v_xor_b32_e32 v78, 0x80000000, v74
	v_xor_b32_e32 v77, 0x80000000, v73
	v_xor_b32_e32 v76, 0x80000000, v72
	s_waitcnt vmcnt(2)
	v_xor_b32_e32 v84, 0x80000000, v83
	v_xor_b32_e32 v85, 0x80000000, v82
	v_xor_b32_e32 v86, 0x80000000, v81
	v_xor_b32_e32 v87, 0x80000000, v80
	v_cndmask_b32_e64 v76, v72, v76, s[8:9]
	v_cndmask_b32_e64 v77, v73, v77, s[8:9]
	v_cndmask_b32_e64 v78, v74, v78, s[8:9]
	v_cndmask_b32_e64 v79, v75, v79, s[8:9]
	v_cndmask_b32_e64 v74, v80, v87, s[8:9]
	v_cndmask_b32_e64 v75, v81, v86, s[8:9]
	v_cndmask_b32_e64 v72, v82, v85, s[8:9]
	v_cndmask_b32_e64 v73, v83, v84, s[8:9]

.LBB0_674:
	v_lshlrev_b64 v[56:57], 11, v[162:163]
	v_mov_b32_e32 v58, v120
	v_mov_b32_e32 v59, v120
	v_pk_mul_f32 v[60:61], v[120:121], v[60:61]
	v_lshl_add_u64 v[56:57], v[122:123], 0, v[56:57]
	v_pk_mul_f32 v[62:63], v[58:59], v[62:63]
	v_cvt_pk_bf16_f32 v60, v60, v61
	v_mov_b32_e32 v81, v80
	v_cvt_pk_bf16_f32 v61, v62, v63
	v_pk_mul_f32 v[82:83], v[58:59], v[82:83]
	v_pk_mul_f32 v[84:85], v[120:121], v[84:85]
	v_pk_mul_f32 v[52:53], v[52:53], v[80:81]
	v_cvt_pk_bf16_f32 v62, v84, v85
	v_cvt_pk_bf16_f32 v63, v82, v83
	global_store_dwordx4 v[56:57], v[60:63], off sc1
	s_and_b64 vcc, exec, s[12:13]
	v_pk_mul_f32 v[48:49], v[48:49], v[80:81]
	v_mov_b32_e32 v60, v80
	v_mov_b32_e32 v61, v80
	v_pk_mul_f32 v[54:55], v[54:55], v[60:61]
	v_pk_mul_f32 v[50:51], v[50:51], v[60:61]
	s_cbranch_vccnz .LBB0_676
	ds_bpermute_b32 v60, v198, v52
	ds_bpermute_b32 v61, v198, v53
	ds_bpermute_b32 v62, v198, v48
	ds_bpermute_b32 v80, v198, v54
	ds_bpermute_b32 v81, v198, v55
	ds_bpermute_b32 v63, v198, v49
	ds_bpermute_b32 v82, v198, v50
	ds_bpermute_b32 v83, v198, v51
	s_waitcnt lgkmcnt(6)
	v_pk_mul_f32 v[60:61], v[76:77], v[60:61]
	s_waitcnt lgkmcnt(3)
	v_pk_mul_f32 v[76:77], v[78:79], v[80:81]
	s_waitcnt vmcnt(2)
	v_pk_fma_f32 v[52:53], v[52:53], v[68:69], v[60:61]
	s_waitcnt lgkmcnt(2)
	v_pk_mul_f32 v[60:61], v[74:75], v[62:63]
	s_waitcnt lgkmcnt(0)
	v_pk_mul_f32 v[62:63], v[72:73], v[82:83]
	v_pk_fma_f32 v[54:55], v[54:55], v[70:71], v[76:77]
	s_waitcnt vmcnt(1)
	v_pk_fma_f32 v[50:51], v[50:51], v[66:67], v[62:63]
	v_pk_fma_f32 v[48:49], v[48:49], v[64:65], v[60:61]
.LBB0_676:
	v_pk_mul_f32 v[54:55], v[58:59], v[54:55]
	v_pk_mul_f32 v[58:59], v[58:59], v[50:51]
	v_pk_mul_f32 v[50:51], v[120:121], v[48:49]
	v_pk_mul_f32 v[52:53], v[120:121], v[52:53]
	v_mov_b32_e32 v60, 0
	v_cvt_pk_bf16_f32 v48, v52, v53
	v_cvt_pk_bf16_f32 v49, v54, v55
	v_cvt_pk_bf16_f32 v50, v50, v51
	v_cvt_pk_bf16_f32 v51, v58, v59
	global_store_dwordx4 v[56:57], v[48:51], off offset:256 sc1
	v_mov_b32_e32 v52, 1.0
	v_mov_b32_e32 v53, 1.0
	v_mov_b32_e32 v54, 1.0
	v_mov_b32_e32 v55, 1.0
	v_mov_b32_e32 v48, 1.0
	v_mov_b32_e32 v49, 1.0
	v_mov_b32_e32 v50, 1.0
	v_mov_b32_e32 v51, 1.0
	v_mov_b32_e32 v61, 0
	v_mov_b32_e32 v62, 0
	v_mov_b32_e32 v63, 0
	v_mov_b32_e32 v58, 0
	v_mov_b32_e32 v59, 0
	v_mov_b32_e32 v56, 0
	v_mov_b32_e32 v57, 0
	s_and_saveexec_b64 s[4:5], s[46:47]
	s_cbranch_execz .LBB0_678
	v_lshlrev_b32_e32 v48, 6, v160
	v_and_b32_e32 v48, 0x7f7c0, v48
	global_load_dwordx4 v[56:59], v48, s[28:29] offset:32
	global_load_dwordx4 v[64:67], v48, s[28:29] offset:48
	global_load_dwordx4 v[52:55], v48, s[28:29]
	s_nop 0
	global_load_dwordx4 v[48:51], v48, s[28:29] offset:16
	s_waitcnt vmcnt(3)
	v_xor_b32_e32 v63, 0x80000000, v59
	v_xor_b32_e32 v62, 0x80000000, v58
	v_xor_b32_e32 v61, 0x80000000, v57
	v_xor_b32_e32 v60, 0x80000000, v56
	s_waitcnt vmcnt(2)
	v_xor_b32_e32 v68, 0x80000000, v67
	v_xor_b32_e32 v69, 0x80000000, v66
	v_xor_b32_e32 v70, 0x80000000, v65
	v_xor_b32_e32 v71, 0x80000000, v64
	v_cndmask_b32_e64 v60, v56, v60, s[8:9]
	v_cndmask_b32_e64 v61, v57, v61, s[8:9]
	v_cndmask_b32_e64 v62, v58, v62, s[8:9]
	v_cndmask_b32_e64 v63, v59, v63, s[8:9]
	v_cndmask_b32_e64 v58, v64, v71, s[8:9]
	v_cndmask_b32_e64 v59, v65, v70, s[8:9]
	v_cndmask_b32_e64 v56, v66, v69, s[8:9]
	v_cndmask_b32_e64 v57, v67, v68, s[8:9]

.LBB0_680:
	v_lshlrev_b64 v[40:41], 11, v[160:161]
	v_mov_b32_e32 v42, v120
	v_mov_b32_e32 v43, v120
	v_pk_mul_f32 v[44:45], v[120:121], v[44:45]
	v_lshl_add_u64 v[40:41], v[122:123], 0, v[40:41]
	v_pk_mul_f32 v[46:47], v[42:43], v[46:47]
	v_cvt_pk_bf16_f32 v44, v44, v45
	v_mov_b32_e32 v65, v64
	v_cvt_pk_bf16_f32 v45, v46, v47
	v_pk_mul_f32 v[66:67], v[42:43], v[66:67]
	v_pk_mul_f32 v[68:69], v[120:121], v[68:69]
	v_pk_mul_f32 v[36:37], v[36:37], v[64:65]
	v_cvt_pk_bf16_f32 v46, v68, v69
	v_cvt_pk_bf16_f32 v47, v66, v67
	global_store_dwordx4 v[40:41], v[44:47], off sc1
	s_and_b64 vcc, exec, s[12:13]
	v_pk_mul_f32 v[32:33], v[32:33], v[64:65]
	v_mov_b32_e32 v44, v64
	v_mov_b32_e32 v45, v64
	v_pk_mul_f32 v[38:39], v[38:39], v[44:45]
	v_pk_mul_f32 v[34:35], v[34:35], v[44:45]
	s_cbranch_vccnz .LBB0_682
	ds_bpermute_b32 v44, v198, v36
	ds_bpermute_b32 v45, v198, v37
	ds_bpermute_b32 v46, v198, v32
	ds_bpermute_b32 v64, v198, v38
	ds_bpermute_b32 v65, v198, v39
	ds_bpermute_b32 v47, v198, v33
	ds_bpermute_b32 v66, v198, v34
	ds_bpermute_b32 v67, v198, v35
	s_waitcnt lgkmcnt(6)
	v_pk_mul_f32 v[44:45], v[60:61], v[44:45]
	s_waitcnt lgkmcnt(3)
	v_pk_mul_f32 v[60:61], v[62:63], v[64:65]
	s_waitcnt vmcnt(2)
	v_pk_fma_f32 v[36:37], v[36:37], v[52:53], v[44:45]
	s_waitcnt lgkmcnt(2)
	v_pk_mul_f32 v[44:45], v[58:59], v[46:47]
	s_waitcnt lgkmcnt(0)
	v_pk_mul_f32 v[46:47], v[56:57], v[66:67]
	v_pk_fma_f32 v[38:39], v[38:39], v[54:55], v[60:61]
	s_waitcnt vmcnt(1)
	v_pk_fma_f32 v[34:35], v[34:35], v[50:51], v[46:47]
	v_pk_fma_f32 v[32:33], v[32:33], v[48:49], v[44:45]
.LBB0_682:
	v_pk_mul_f32 v[38:39], v[42:43], v[38:39]
	v_pk_mul_f32 v[42:43], v[42:43], v[34:35]
	v_pk_mul_f32 v[34:35], v[120:121], v[32:33]
	v_pk_mul_f32 v[36:37], v[120:121], v[36:37]
	v_mov_b32_e32 v44, 0
	v_cvt_pk_bf16_f32 v32, v36, v37
	v_cvt_pk_bf16_f32 v33, v38, v39
	v_cvt_pk_bf16_f32 v34, v34, v35
	v_cvt_pk_bf16_f32 v35, v42, v43
	global_store_dwordx4 v[40:41], v[32:35], off offset:256 sc1
	v_mov_b32_e32 v36, 1.0
	v_mov_b32_e32 v37, 1.0
	v_mov_b32_e32 v38, 1.0
	v_mov_b32_e32 v39, 1.0
	v_mov_b32_e32 v32, 1.0
	v_mov_b32_e32 v33, 1.0
	v_mov_b32_e32 v34, 1.0
	v_mov_b32_e32 v35, 1.0
	v_mov_b32_e32 v45, 0
	v_mov_b32_e32 v46, 0
	v_mov_b32_e32 v47, 0
	v_mov_b32_e32 v42, 0
	v_mov_b32_e32 v43, 0
	v_mov_b32_e32 v40, 0
	v_mov_b32_e32 v41, 0
	s_and_saveexec_b64 s[4:5], s[46:47]
	s_cbranch_execz .LBB0_684
	v_lshlrev_b32_e32 v32, 6, v158
	v_and_b32_e32 v32, 0x7fbc0, v32
	global_load_dwordx4 v[40:43], v32, s[28:29] offset:32
	global_load_dwordx4 v[48:51], v32, s[28:29] offset:48
	global_load_dwordx4 v[36:39], v32, s[28:29]
	s_nop 0
	global_load_dwordx4 v[32:35], v32, s[28:29] offset:16
	s_waitcnt vmcnt(3)
	v_xor_b32_e32 v47, 0x80000000, v43
	v_xor_b32_e32 v46, 0x80000000, v42
	v_xor_b32_e32 v45, 0x80000000, v41
	v_xor_b32_e32 v44, 0x80000000, v40
	s_waitcnt vmcnt(2)
	v_xor_b32_e32 v52, 0x80000000, v51
	v_xor_b32_e32 v53, 0x80000000, v50
	v_xor_b32_e32 v54, 0x80000000, v49
	v_xor_b32_e32 v55, 0x80000000, v48
	v_cndmask_b32_e64 v44, v40, v44, s[8:9]
	v_cndmask_b32_e64 v45, v41, v45, s[8:9]
	v_cndmask_b32_e64 v46, v42, v46, s[8:9]
	v_cndmask_b32_e64 v47, v43, v47, s[8:9]
	v_cndmask_b32_e64 v42, v48, v55, s[8:9]
	v_cndmask_b32_e64 v43, v49, v54, s[8:9]
	v_cndmask_b32_e64 v40, v50, v53, s[8:9]
	v_cndmask_b32_e64 v41, v51, v52, s[8:9]

.LBB0_686:
	v_lshlrev_b64 v[24:25], 11, v[158:159]
	v_mov_b32_e32 v26, v120
	v_mov_b32_e32 v27, v120
	v_pk_mul_f32 v[28:29], v[120:121], v[28:29]
	v_lshl_add_u64 v[24:25], v[122:123], 0, v[24:25]
	v_pk_mul_f32 v[30:31], v[26:27], v[30:31]
	v_cvt_pk_bf16_f32 v28, v28, v29
	v_mov_b32_e32 v49, v48
	v_cvt_pk_bf16_f32 v29, v30, v31
	v_pk_mul_f32 v[50:51], v[26:27], v[50:51]
	v_pk_mul_f32 v[52:53], v[120:121], v[52:53]
	v_pk_mul_f32 v[20:21], v[20:21], v[48:49]
	v_cvt_pk_bf16_f32 v30, v52, v53
	v_cvt_pk_bf16_f32 v31, v50, v51
	global_store_dwordx4 v[24:25], v[28:31], off sc1
	s_and_b64 vcc, exec, s[12:13]
	v_pk_mul_f32 v[16:17], v[16:17], v[48:49]
	v_mov_b32_e32 v28, v48
	v_mov_b32_e32 v29, v48
	v_pk_mul_f32 v[22:23], v[22:23], v[28:29]
	v_pk_mul_f32 v[18:19], v[18:19], v[28:29]
	s_cbranch_vccnz .LBB0_688
	ds_bpermute_b32 v28, v198, v20
	ds_bpermute_b32 v29, v198, v21
	ds_bpermute_b32 v30, v198, v16
	ds_bpermute_b32 v48, v198, v22
	ds_bpermute_b32 v49, v198, v23
	ds_bpermute_b32 v31, v198, v17
	ds_bpermute_b32 v50, v198, v18
	ds_bpermute_b32 v51, v198, v19
	s_waitcnt lgkmcnt(6)
	v_pk_mul_f32 v[28:29], v[44:45], v[28:29]
	s_waitcnt lgkmcnt(3)
	v_pk_mul_f32 v[44:45], v[46:47], v[48:49]
	s_waitcnt vmcnt(2)
	v_pk_fma_f32 v[20:21], v[20:21], v[36:37], v[28:29]
	s_waitcnt lgkmcnt(2)
	v_pk_mul_f32 v[28:29], v[42:43], v[30:31]
	s_waitcnt lgkmcnt(0)
	v_pk_mul_f32 v[30:31], v[40:41], v[50:51]
	v_pk_fma_f32 v[22:23], v[22:23], v[38:39], v[44:45]
	s_waitcnt vmcnt(1)
	v_pk_fma_f32 v[18:19], v[18:19], v[34:35], v[30:31]
	v_pk_fma_f32 v[16:17], v[16:17], v[32:33], v[28:29]
.LBB0_688:
	v_pk_mul_f32 v[22:23], v[26:27], v[22:23]
	v_pk_mul_f32 v[26:27], v[26:27], v[18:19]
	v_pk_mul_f32 v[18:19], v[120:121], v[16:17]
	v_pk_mul_f32 v[20:21], v[120:121], v[20:21]
	v_mov_b32_e32 v28, 0
	v_cvt_pk_bf16_f32 v16, v20, v21
	v_cvt_pk_bf16_f32 v17, v22, v23
	v_cvt_pk_bf16_f32 v18, v18, v19
	v_cvt_pk_bf16_f32 v19, v26, v27
	global_store_dwordx4 v[24:25], v[16:19], off offset:256 sc1
	v_mov_b32_e32 v20, 1.0
	v_mov_b32_e32 v21, 1.0
	v_mov_b32_e32 v22, 1.0
	v_mov_b32_e32 v23, 1.0
	v_mov_b32_e32 v16, 1.0
	v_mov_b32_e32 v17, 1.0
	v_mov_b32_e32 v18, 1.0
	v_mov_b32_e32 v19, 1.0
	v_mov_b32_e32 v29, 0
	v_mov_b32_e32 v30, 0
	v_mov_b32_e32 v31, 0
	v_mov_b32_e32 v26, 0
	v_mov_b32_e32 v27, 0
	v_mov_b32_e32 v24, 0
	v_mov_b32_e32 v25, 0
	s_and_saveexec_b64 s[4:5], s[46:47]
	s_cbranch_execz .LBB0_690
	v_lshlrev_b32_e32 v16, 6, v156
	v_and_b32_e32 v16, 0x7ffc0, v16
	global_load_dwordx4 v[24:27], v16, s[28:29] offset:32
	global_load_dwordx4 v[32:35], v16, s[28:29] offset:48
	global_load_dwordx4 v[20:23], v16, s[28:29]
	s_nop 0
	global_load_dwordx4 v[16:19], v16, s[28:29] offset:16
	s_waitcnt vmcnt(3)
	v_xor_b32_e32 v31, 0x80000000, v27
	v_xor_b32_e32 v30, 0x80000000, v26
	v_xor_b32_e32 v29, 0x80000000, v25
	v_xor_b32_e32 v28, 0x80000000, v24
	s_waitcnt vmcnt(2)
	v_xor_b32_e32 v36, 0x80000000, v35
	v_xor_b32_e32 v37, 0x80000000, v34
	v_xor_b32_e32 v38, 0x80000000, v33
	v_xor_b32_e32 v39, 0x80000000, v32
	v_cndmask_b32_e64 v28, v24, v28, s[8:9]
	v_cndmask_b32_e64 v29, v25, v29, s[8:9]
	v_cndmask_b32_e64 v30, v26, v30, s[8:9]
	v_cndmask_b32_e64 v31, v27, v31, s[8:9]
	v_cndmask_b32_e64 v26, v32, v39, s[8:9]
	v_cndmask_b32_e64 v27, v33, v38, s[8:9]
	v_cndmask_b32_e64 v24, v34, v37, s[8:9]
	v_cndmask_b32_e64 v25, v35, v36, s[8:9]

.LBB0_692:
	v_lshlrev_b64 v[8:9], 11, v[156:157]
	v_mov_b32_e32 v10, v120
	v_mov_b32_e32 v11, v120
	v_pk_mul_f32 v[12:13], v[120:121], v[12:13]
	v_lshl_add_u64 v[8:9], v[122:123], 0, v[8:9]
	v_pk_mul_f32 v[14:15], v[10:11], v[14:15]
	v_cvt_pk_bf16_f32 v12, v12, v13
	v_mov_b32_e32 v33, v32
	v_cvt_pk_bf16_f32 v13, v14, v15
	v_pk_mul_f32 v[34:35], v[10:11], v[34:35]
	v_pk_mul_f32 v[36:37], v[120:121], v[36:37]
	v_pk_mul_f32 v[4:5], v[4:5], v[32:33]
	v_cvt_pk_bf16_f32 v14, v36, v37
	v_cvt_pk_bf16_f32 v15, v34, v35
	global_store_dwordx4 v[8:9], v[12:15], off sc1
	s_and_b64 vcc, exec, s[12:13]
	v_pk_mul_f32 v[0:1], v[0:1], v[32:33]
	v_mov_b32_e32 v12, v32
	v_mov_b32_e32 v13, v32
	v_pk_mul_f32 v[6:7], v[6:7], v[12:13]
	v_pk_mul_f32 v[2:3], v[2:3], v[12:13]
	s_cbranch_vccnz .LBB0_694
	ds_bpermute_b32 v12, v198, v4
	ds_bpermute_b32 v13, v198, v5
	ds_bpermute_b32 v14, v198, v0
	ds_bpermute_b32 v32, v198, v6
	ds_bpermute_b32 v33, v198, v7
	ds_bpermute_b32 v15, v198, v1
	ds_bpermute_b32 v34, v198, v2
	ds_bpermute_b32 v35, v198, v3
	s_waitcnt lgkmcnt(6)
	v_pk_mul_f32 v[12:13], v[28:29], v[12:13]
	s_waitcnt lgkmcnt(3)
	v_pk_mul_f32 v[28:29], v[30:31], v[32:33]
	s_waitcnt vmcnt(2)
	v_pk_fma_f32 v[4:5], v[4:5], v[20:21], v[12:13]
	s_waitcnt lgkmcnt(2)
	v_pk_mul_f32 v[12:13], v[26:27], v[14:15]
	s_waitcnt lgkmcnt(0)
	v_pk_mul_f32 v[14:15], v[24:25], v[34:35]
	v_pk_fma_f32 v[6:7], v[6:7], v[22:23], v[28:29]
	s_waitcnt vmcnt(1)
	v_pk_fma_f32 v[2:3], v[2:3], v[18:19], v[14:15]
	v_pk_fma_f32 v[0:1], v[0:1], v[16:17], v[12:13]
.LBB0_694:
	v_pk_mul_f32 v[6:7], v[10:11], v[6:7]
	v_pk_mul_f32 v[10:11], v[10:11], v[2:3]
	v_pk_mul_f32 v[2:3], v[120:121], v[0:1]
	s_andn2_b64 vcc, exec, s[10:11]
	s_mov_b64 s[4:5], -1
	v_pk_mul_f32 v[4:5], v[120:121], v[4:5]
	s_nop 0
	v_cvt_pk_bf16_f32 v0, v4, v5
	v_cvt_pk_bf16_f32 v1, v6, v7
	v_cvt_pk_bf16_f32 v2, v2, v3
	v_cvt_pk_bf16_f32 v3, v10, v11
	global_store_dwordx4 v[8:9], v[0:3], off offset:256 sc1
	s_cbranch_vccnz .LBB0_639
	s_andn2_b64 vcc, exec, s[26:27]
	s_cbranch_vccnz .LBB0_638
	s_barrier
	s_branch .LBB0_638

.LBB0_749:
	s_or_b64 exec, exec, s[4:5]
	s_waitcnt lgkmcnt(0)
	ds_read_b128 v[68:71], v66 offset:128
	ds_read_b128 v[72:75], v66 offset:160
	s_mov_b64 s[6:7], s[0:1]
	s_add_u32 s4, s10, s13
	s_addc_u32 s5, s37, s14
	s_waitcnt lgkmcnt(1)
	v_rcp_f32_e32 v67, v68
	v_rcp_f32_e32 v76, v69
	v_rcp_f32_e32 v77, v70
	v_rcp_f32_e32 v78, v71
	s_waitcnt lgkmcnt(0)
	v_rcp_f32_e32 v79, v72
	ds_read_b128 v[68:71], v66 offset:192
	v_rcp_f32_e32 v80, v73
	v_rcp_f32_e32 v81, v74
	v_rcp_f32_e32 v82, v75
	ds_read_b128 v[72:75], v66 offset:224
	s_load_dwordx2 s[6:7], s[6:7], 0xa0
	s_lshl_b64 s[4:5], s[4:5], 11
	s_waitcnt lgkmcnt(0)
	v_rcp_f32_e32 v66, v68
	v_rcp_f32_e32 v68, v69
	v_rcp_f32_e32 v69, v70
	s_add_u32 s8, s6, s4
	v_rcp_f32_e32 v70, v71
	v_rcp_f32_e32 v71, v72
	v_rcp_f32_e32 v72, v73
	v_rcp_f32_e32 v73, v74
	v_rcp_f32_e32 v74, v75
	s_addc_u32 s9, s7, s5
	s_lshl_b32 s4, s12, 12
	s_add_i32 s10, s4, 0
	v_mul_f32_e32 v18, v18, v67
	v_mul_f32_e32 v50, v50, v67
	v_mul_f32_e32 v34, v34, v67
	v_mul_f32_e32 v67, v2, v67
	s_add_i32 s10, s10, 0x16800
	v_lshlrev_b32_e32 v2, 4, v1
	v_mul_f32_e32 v75, v3, v76
	s_mov_b64 s[4:5], s[0:1]
	v_and_b32_e32 v3, 0x380, v2
	v_add_u32_e32 v2, s10, v188
	v_mul_f32_e32 v89, v48, v73
	v_mul_f32_e32 v48, v65, v74
	v_add_u32_e32 v65, v2, v3
	v_mul_f32_e32 v19, v19, v76
	v_mul_f32_e32 v51, v51, v76
	v_mul_f32_e32 v35, v35, v76
	v_mul_f32_e32 v76, v4, v77
	s_load_dwordx2 s[4:5], s[4:5], 0x70
	v_lshlrev_b32_e32 v3, 1, v207
	v_lshlrev_b32_e32 v4, 9, v208
	s_waitcnt vmcnt(5)
	ds_write_b128 v65, v[138:141]
	ds_write_b128 v65, v[130:133] offset:1024
	ds_write_b128 v65, v[134:137] offset:2048
	s_waitcnt vmcnt(3)
	ds_write_b128 v65, v[142:145] offset:3072
	v_mul_f32_e32 v85, v10, v66
	v_mul_f32_e32 v10, v27, v68
	v_mul_f32_e32 v27, v59, v68
	v_mul_f32_e32 v59, v60, v69
	v_mul_f32_e32 v60, v12, v69
	v_mul_f32_e32 v12, v29, v70
	v_mul_f32_e32 v29, v61, v70
	v_mul_f32_e32 v30, v30, v71
	v_mul_f32_e32 v61, v62, v71
	v_mul_f32_e32 v86, v46, v71
	v_mul_f32_e32 v87, v14, v71
	v_add3_u32 v71, s10, v3, v4
	s_waitcnt lgkmcnt(0)
	v_mul_f32_e32 v20, v20, v77
	v_mul_f32_e32 v52, v52, v77
	v_mul_f32_e32 v36, v36, v77
	v_mul_f32_e32 v21, v21, v78
	v_mul_f32_e32 v53, v53, v78
	v_mul_f32_e32 v77, v37, v78
	v_mul_f32_e32 v78, v5, v78
	v_mul_f32_e32 v5, v22, v79
	v_mul_f32_e32 v22, v54, v79
	v_mul_f32_e32 v38, v38, v79
	v_mul_f32_e32 v79, v6, v79
	v_mul_f32_e32 v6, v23, v80
	v_mul_f32_e32 v23, v55, v80
	v_mul_f32_e32 v83, v39, v80
	v_mul_f32_e32 v80, v7, v80
	v_mul_f32_e32 v7, v24, v81
	v_mul_f32_e32 v24, v56, v81
	v_mul_f32_e32 v84, v40, v81
	v_mul_f32_e32 v81, v8, v81
	v_mul_f32_e32 v8, v25, v82
	v_mul_f32_e32 v25, v57, v82
	v_mul_f32_e32 v41, v41, v82
	v_mul_f32_e32 v57, v9, v82
	v_mul_f32_e32 v9, v26, v66
	v_mul_f32_e32 v26, v58, v66
	v_mul_f32_e32 v82, v42, v66
	v_mul_f32_e32 v28, v28, v69
	v_mul_f32_e32 v44, v44, v69
	v_mul_f32_e32 v66, v31, v72
	v_mul_f32_e32 v69, v32, v73
	v_mul_f32_e32 v90, v16, v73
	v_mul_f32_e32 v16, v33, v74
	ds_read_u16 v14, v71
	ds_read_u16 v31, v71 offset:64
	ds_read_u16 v32, v71 offset:128
	ds_read_u16 v33, v71 offset:192
	ds_read_u16 v37, v71 offset:256
	ds_read_u16 v39, v71 offset:320
	ds_read_u16 v40, v71 offset:384
	ds_read_u16 v42, v71 offset:448
	s_waitcnt lgkmcnt(0)
	v_lshlrev_b32_e32 v14, 16, v14
	v_fma_f32 v92, -v203, v18, v14
	v_lshlrev_b32_e32 v14, 16, v31
	v_fma_f32 v93, -v203, v50, v14
	v_lshlrev_b32_e32 v14, 16, v32
	v_fma_f32 v94, -v203, v19, v14
	v_lshlrev_b32_e32 v14, 16, v33
	v_fma_f32 v51, -v203, v51, v14
	v_lshlrev_b32_e32 v14, 16, v37
	v_fma_f32 v37, -v203, v20, v14
	v_lshlrev_b32_e32 v14, 16, v39
	v_fma_f32 v32, -v203, v52, v14
	v_lshlrev_b32_e32 v14, 16, v40
	v_fma_f32 v46, -v203, v21, v14
	v_lshlrev_b32_e32 v14, 16, v42
	v_fma_f32 v40, -v203, v53, v14
	ds_read_u16 v14, v71 offset:1024
	ds_read_u16 v18, v71 offset:1088
	ds_read_u16 v19, v71 offset:1152
	ds_read_u16 v20, v71 offset:1216
	ds_read_u16 v21, v71 offset:1280
	ds_read_u16 v31, v71 offset:1344
	ds_read_u16 v33, v71 offset:1408
	ds_read_u16 v39, v71 offset:1472
	s_waitcnt lgkmcnt(7)
	v_lshlrev_b32_e32 v14, 16, v14
	v_fma_f32 v55, -v203, v5, v14
	s_waitcnt lgkmcnt(6)
	v_lshlrev_b32_e32 v5, 16, v18
	v_mul_f32_e32 v91, v49, v74
	v_fma_f32 v49, -v203, v22, v5
	s_waitcnt lgkmcnt(5)
	v_lshlrev_b32_e32 v5, 16, v19
	v_mul_f32_e32 v43, v43, v68
	v_mul_f32_e32 v11, v11, v68
	v_mul_f32_e32 v68, v63, v72
	v_fma_f32 v63, -v203, v6, v5
	s_waitcnt lgkmcnt(4)
	v_lshlrev_b32_e32 v5, 16, v20
	v_fma_f32 v58, -v203, v23, v5
	s_waitcnt lgkmcnt(3)
	v_lshlrev_b32_e32 v5, 16, v21
	v_mul_f32_e32 v45, v45, v70
	v_mul_f32_e32 v13, v13, v70
	v_mul_f32_e32 v70, v64, v73
	v_fma_f32 v64, -v203, v7, v5
	s_waitcnt lgkmcnt(2)
	v_lshlrev_b32_e32 v5, 16, v31
	v_fma_f32 v62, -v203, v24, v5
	s_waitcnt lgkmcnt(1)
	v_lshlrev_b32_e32 v5, 16, v33
	v_fma_f32 v56, -v203, v8, v5
	s_waitcnt lgkmcnt(0)
	v_lshlrev_b32_e32 v5, 16, v39
	v_fma_f32 v54, -v203, v25, v5
	ds_read_u16 v5, v71 offset:2048
	ds_read_u16 v6, v71 offset:2112
	ds_read_u16 v7, v71 offset:2176
	ds_read_u16 v8, v71 offset:2240
	ds_read_u16 v14, v71 offset:2304
	ds_read_u16 v18, v71 offset:2368
	ds_read_u16 v19, v71 offset:2432
	ds_read_u16 v20, v71 offset:2496
	s_waitcnt lgkmcnt(7)
	v_lshlrev_b32_e32 v5, 16, v5
	v_fma_f32 v50, -v203, v9, v5
	s_waitcnt lgkmcnt(6)
	v_lshlrev_b32_e32 v5, 16, v6
	v_mul_f32_e32 v88, v47, v72
	v_fma_f32 v47, -v203, v26, v5
	s_waitcnt lgkmcnt(5)
	v_lshlrev_b32_e32 v5, 16, v7
	v_fma_f32 v42, -v203, v10, v5
	s_waitcnt lgkmcnt(4)
	v_lshlrev_b32_e32 v5, 16, v8
	v_fma_f32 v39, -v203, v27, v5
	s_waitcnt lgkmcnt(3)
	v_lshlrev_b32_e32 v5, 16, v14
	v_fma_f32 v33, -v203, v28, v5
	s_waitcnt lgkmcnt(2)
	v_lshlrev_b32_e32 v5, 16, v18
	v_fma_f32 v31, -v203, v59, v5
	s_waitcnt lgkmcnt(1)
	v_lshlrev_b32_e32 v5, 16, v19
	v_fma_f32 v23, -v203, v12, v5
	s_waitcnt lgkmcnt(0)
	v_lshlrev_b32_e32 v5, 16, v20
	v_fma_f32 v21, -v203, v29, v5
	ds_read_u16 v5, v71 offset:3072
	ds_read_u16 v6, v71 offset:3136
	ds_read_u16 v7, v71 offset:3200
	ds_read_u16 v8, v71 offset:3264
	ds_read_u16 v18, v71 offset:3328
	ds_read_u16 v19, v71 offset:3392
	ds_read_u16 v20, v71 offset:3456
	ds_read_u16 v22, v71 offset:3520
	s_waitcnt lgkmcnt(7)
	v_lshlrev_b32_e32 v5, 16, v5
	v_fma_f32 v14, -v203, v30, v5
	s_waitcnt lgkmcnt(6)
	v_lshlrev_b32_e32 v5, 16, v6
	v_fma_f32 v12, -v203, v61, v5
	s_waitcnt lgkmcnt(5)
	v_lshlrev_b32_e32 v5, 16, v7
	v_fma_f32 v9, -v203, v66, v5
	s_waitcnt lgkmcnt(4)
	v_lshlrev_b32_e32 v5, 16, v8
	v_fma_f32 v10, -v203, v68, v5
	s_waitcnt lgkmcnt(3)
	v_lshlrev_b32_e32 v5, 16, v18
	v_fma_f32 v8, -v203, v69, v5
	s_waitcnt lgkmcnt(2)
	v_lshlrev_b32_e32 v5, 16, v19
	s_waitcnt lgkmcnt(0)
	ds_write_b128 v65, v[114:117]
	s_waitcnt vmcnt(2)
	ds_write_b128 v65, v[118:121] offset:1024
	s_waitcnt vmcnt(1)
	ds_write_b128 v65, v[122:125] offset:2048
	s_waitcnt vmcnt(0)
	ds_write_b128 v65, v[126:129] offset:3072
	v_fma_f32 v7, -v203, v70, v5
	s_waitcnt lgkmcnt(5)
	v_lshlrev_b32_e32 v5, 16, v20
	s_waitcnt lgkmcnt(0)
	v_fma_f32 v5, -v203, v16, v5
	s_waitcnt lgkmcnt(4)
	v_lshlrev_b32_e32 v6, 16, v22
	ds_read_u16 v16, v71
	ds_read_u16 v18, v71 offset:64
	ds_read_u16 v19, v71 offset:128
	ds_read_u16 v20, v71 offset:192
	ds_read_u16 v22, v71 offset:256
	ds_read_u16 v24, v71 offset:320
	ds_read_u16 v25, v71 offset:384
	ds_read_u16 v26, v71 offset:448
	s_waitcnt lgkmcnt(7)
	v_lshlrev_b32_e32 v16, 16, v16
	v_fma_f32 v29, -v203, v34, v16
	s_waitcnt lgkmcnt(6)
	v_lshlrev_b32_e32 v16, 16, v18
	v_fma_f32 v52, -v203, v67, v16
	s_waitcnt lgkmcnt(5)
	v_lshlrev_b32_e32 v16, 16, v19
	v_fma_f32 v59, -v203, v35, v16
	s_waitcnt lgkmcnt(4)
	v_lshlrev_b32_e32 v16, 16, v20
	v_fma_f32 v6, -v203, v48, v6
	v_fma_f32 v67, -v203, v75, v16
	ds_read_u16 v16, v71 offset:1024
	ds_read_u16 v18, v71 offset:1088
	ds_read_u16 v19, v71 offset:1152
	ds_read_u16 v20, v71 offset:1216
	ds_read_u16 v27, v71 offset:1280
	ds_read_u16 v28, v71 offset:1344
	ds_read_u16 v30, v71 offset:1408
	ds_read_u16 v34, v71 offset:1472
	ds_read_u16 v35, v71 offset:2048
	ds_read_u16 v48, v71 offset:2112
	ds_read_u16 v53, v71 offset:2176
	ds_read_u16 v75, v71 offset:2240
	ds_read_u16 v95, v71 offset:2304
	ds_read_u16 v96, v71 offset:2368
	ds_read_u16 v97, v71 offset:2432
	ds_read_u16 v98, v71 offset:2496
	ds_read_u16 v99, v71 offset:3072
	ds_read_u16 v100, v71 offset:3136
	ds_read_u16 v101, v71 offset:3200
	ds_read_u16 v102, v71 offset:3264
	ds_read_u16 v103, v71 offset:3328
	ds_read_u16 v104, v71 offset:3392
	ds_read_u16 v105, v71 offset:3456
	ds_read_u16 v106, v71 offset:3520
	s_waitcnt lgkmcnt(14)
	v_lshlrev_b32_e32 v22, 16, v22
	v_fma_f32 v109, -v203, v36, v22
	v_lshlrev_b32_e32 v22, 16, v24
	v_lshlrev_b32_e32 v16, 16, v16
	v_fma_f32 v76, -v203, v76, v22
	v_lshlrev_b32_e32 v22, 16, v25
	v_fma_f32 v110, -v203, v38, v16
	v_lshlrev_b32_e32 v16, 16, v18
	s_waitcnt lgkmcnt(0)
	v_lshlrev_b32_e32 v61, 2, v207
	v_fma_f32 v77, -v203, v77, v22
	v_lshlrev_b32_e32 v22, 16, v26
	v_fma_f32 v66, -v203, v79, v16
	v_lshlrev_b32_e32 v16, 16, v19
	global_load_dword v107, v61, s[4:5]
	global_load_dword v108, v61, s[4:5] offset:128
	v_fma_f32 v78, -v203, v78, v22
	v_fma_f32 v71, -v203, v83, v16
	v_lshlrev_b32_e32 v16, 16, v20
	global_load_dword v20, v61, s[4:5] offset:256
	global_load_dword v22, v61, s[4:5] offset:384
	v_fma_f32 v70, -v203, v80, v16
	v_lshlrev_b32_e32 v16, 16, v27
	v_mul_f32_e32 v17, v17, v74
	v_fma_f32 v74, -v203, v84, v16
	v_lshlrev_b32_e32 v16, 16, v28
	v_fma_f32 v73, -v203, v81, v16
	v_lshlrev_b32_e32 v16, 16, v30
	v_mul_f32_e32 v15, v15, v72
	v_fma_f32 v72, -v203, v41, v16
	v_lshlrev_b32_e32 v16, 16, v34
	v_fma_f32 v69, -v203, v57, v16
	v_lshlrev_b32_e32 v16, 16, v35
	v_fma_f32 v68, -v203, v82, v16
	v_lshlrev_b32_e32 v16, 16, v48
	v_fma_f32 v65, -v203, v85, v16
	s_waitcnt lgkmcnt(13)
	v_lshlrev_b32_e32 v16, 16, v53
	v_fma_f32 v61, -v203, v43, v16
	s_waitcnt lgkmcnt(12)
	v_lshlrev_b32_e32 v16, 16, v75
	v_fma_f32 v57, -v203, v11, v16
	v_mul_f32_e32 v16, v93, v93
	v_mul_f32_e32 v18, v52, v52
	v_fmac_f32_e32 v16, v92, v92
	v_fmac_f32_e32 v18, v29, v29
	v_add_f32_e32 v16, v16, v18
	ds_bpermute_b32 v18, v198, v16
	s_waitcnt lgkmcnt(12)
	v_lshlrev_b32_e32 v11, 16, v95
	v_fma_f32 v53, -v203, v44, v11
	s_waitcnt lgkmcnt(11)
	v_lshlrev_b32_e32 v11, 16, v96
	v_fma_f32 v48, -v203, v60, v11
	s_waitcnt lgkmcnt(0)
	v_add_f32_e32 v16, v16, v18
	ds_bpermute_b32 v18, v199, v16
	v_lshlrev_b32_e32 v11, 16, v97
	v_fma_f32 v45, -v203, v45, v11
	v_lshlrev_b32_e32 v11, 16, v98
	v_fma_f32 v41, -v203, v13, v11
	s_waitcnt lgkmcnt(0)
	v_add_f32_e32 v13, v16, v18
	ds_bpermute_b32 v16, v200, v13
	v_lshlrev_b32_e32 v11, 16, v99
	v_fma_f32 v38, -v203, v86, v11
	v_lshlrev_b32_e32 v11, 16, v100
	v_fma_f32 v34, -v203, v87, v11
	s_waitcnt lgkmcnt(0)
	v_add_f32_e32 v13, v13, v16
	ds_bpermute_b32 v18, v201, v13
	v_lshlrev_b32_e32 v11, 16, v101
	v_fma_f32 v30, -v203, v88, v11
	v_lshlrev_b32_e32 v11, 16, v102
	v_fma_f32 v24, -v203, v15, v11
	s_waitcnt lgkmcnt(0)
	v_add_f32_e32 v15, v13, v18
	ds_bpermute_b32 v18, v196, v15
	v_lshlrev_b32_e32 v11, 16, v103
	v_fma_f32 v16, -v203, v89, v11
	v_lshlrev_b32_e32 v11, 16, v104
	v_fma_f32 v19, -v203, v90, v11
	s_waitcnt lgkmcnt(0)
	v_add_f32_e32 v15, v15, v18
	v_fmamk_f32 v15, v15, 0x3c000000, v204
	v_mul_f32_e32 v18, 0x4f800000, v15
	v_cmp_gt_f32_e32 vcc, s34, v15
	v_lshlrev_b32_e32 v11, 16, v105
	v_fma_f32 v13, -v203, v91, v11
	v_cndmask_b32_e32 v25, v15, v18, vcc
	v_sqrt_f32_e32 v26, v25
	v_lshlrev_b32_e32 v11, 16, v106
	v_fma_f32 v15, -v203, v17, v11
	v_lshrrev_b32_e32 v1, 3, v1
	v_add_u32_e32 v11, -1, v26
	v_fma_f32 v27, -v11, v26, v25
	v_cmp_ge_f32_e64 s[6:7], 0, v27
	v_add_u32_e32 v27, 1, v26
	v_mov_b32_e32 v189, v146
	v_cndmask_b32_e64 v11, v26, v11, s[6:7]
	v_fma_f32 v26, -v27, v26, v25
	v_cmp_lt_f32_e64 s[6:7], 0, v26
	s_waitcnt vmcnt(3)
	v_mul_f32_e32 v18, 0x3f24fd5c, v107
	v_cndmask_b32_e64 v11, v11, v27, s[6:7]
	v_mul_f32_e32 v26, 0x37800000, v11
	v_cndmask_b32_e32 v11, v11, v26, vcc
	v_mul_f32_e32 v26, v51, v51
	v_mul_f32_e32 v27, v67, v67
	v_fmac_f32_e32 v26, v94, v94
	v_fmac_f32_e32 v27, v59, v59
	v_add_f32_e32 v26, v26, v27
	ds_bpermute_b32 v27, v198, v26
	v_cmp_class_f32_e32 vcc, v25, v205
	s_waitcnt vmcnt(2)
	v_mul_f32_e32 v17, 0x3f24fd5c, v108
	s_waitcnt lgkmcnt(0)
	v_add_f32_e32 v27, v26, v27
	v_cndmask_b32_e32 v11, v11, v25, vcc
	v_div_scale_f32 v28, s[4:5], v11, v11, 1.0
	v_rcp_f32_e32 v35, v28
	ds_bpermute_b32 v36, v199, v27
	s_waitcnt vmcnt(1)
	v_mul_f32_e32 v26, 0x3f24fd5c, v20
	s_waitcnt vmcnt(0)
	v_mul_f32_e32 v25, 0x3f24fd5c, v22
	v_fma_f32 v20, -v28, v35, 1.0
	v_fmac_f32_e32 v35, v20, v35
	s_waitcnt lgkmcnt(0)
	v_add_f32_e32 v20, v27, v36
	ds_bpermute_b32 v22, v200, v20
	v_div_scale_f32 v27, vcc, 1.0, v11, 1.0
	v_mul_f32_e32 v36, v27, v35
	v_fma_f32 v43, -v28, v36, v27
	s_waitcnt lgkmcnt(0)
	v_add_f32_e32 v20, v20, v22
	ds_bpermute_b32 v22, v201, v20
	v_fmac_f32_e32 v36, v43, v35
	v_fma_f32 v27, -v28, v36, v27
	v_div_fmas_f32 v27, v27, v35, v36
	v_div_fixup_f32 v35, v27, v11, 1.0
	s_waitcnt lgkmcnt(0)
	v_add_f32_e32 v20, v20, v22
	ds_bpermute_b32 v22, v196, v20
	v_mul_f32_e32 v11, v18, v35
	v_mul_f32_e32 v27, v92, v11
	v_mul_f32_e32 v11, v17, v35
	v_mul_f32_e32 v28, v93, v11
	s_waitcnt lgkmcnt(0)
	v_add_f32_e32 v20, v20, v22
	v_fmamk_f32 v20, v20, 0x3c000000, v204
	v_mul_f32_e32 v22, 0x4f800000, v20
	v_cmp_gt_f32_e32 vcc, s34, v20
	v_mul_f32_e32 v11, v26, v35
	v_mul_f32_e32 v11, v29, v11
	v_cndmask_b32_e32 v20, v20, v22, vcc
	v_sqrt_f32_e32 v22, v20
	s_nop 0
	v_add_u32_e32 v29, -1, v22
	v_fma_f32 v36, -v29, v22, v20
	v_cmp_ge_f32_e64 s[6:7], 0, v36
	v_add_u32_e32 v36, 1, v22
	s_nop 0
	v_cndmask_b32_e64 v29, v22, v29, s[6:7]
	v_fma_f32 v22, -v36, v22, v20
	v_cmp_lt_f32_e64 s[6:7], 0, v22
	s_nop 1
	v_cndmask_b32_e64 v22, v29, v36, s[6:7]
	v_mul_f32_e32 v29, 0x37800000, v22
	v_cndmask_b32_e32 v22, v22, v29, vcc
	v_mul_f32_e32 v29, v32, v32
	v_mul_f32_e32 v36, v76, v76
	v_fmac_f32_e32 v29, v37, v37
	v_fmac_f32_e32 v36, v109, v109
	v_add_f32_e32 v29, v29, v36
	ds_bpermute_b32 v36, v198, v29
	v_cmp_class_f32_e32 vcc, v20, v205
	s_waitcnt lgkmcnt(0)
	v_add_f32_e32 v29, v29, v36
	v_cndmask_b32_e32 v22, v22, v20, vcc
	v_div_scale_f32 v43, s[4:5], v22, v22, 1.0
	ds_bpermute_b32 v36, v199, v29
	v_rcp_f32_e32 v44, v43
	v_mul_f32_e32 v20, v25, v35
	v_mul_f32_e32 v20, v52, v20
	v_fma_f32 v35, -v43, v44, 1.0
	s_waitcnt lgkmcnt(0)
	v_add_f32_e32 v29, v29, v36
	v_fmac_f32_e32 v44, v35, v44
	ds_bpermute_b32 v35, v200, v29
	v_div_scale_f32 v36, vcc, 1.0, v22, 1.0
	v_mul_f32_e32 v52, v36, v44
	v_fma_f32 v60, -v43, v52, v36
	s_waitcnt lgkmcnt(0)
	v_add_f32_e32 v29, v29, v35
	ds_bpermute_b32 v35, v201, v29
	v_fmac_f32_e32 v52, v60, v44
	v_fma_f32 v36, -v43, v52, v36
	v_div_fmas_f32 v36, v36, v44, v52
	v_div_fixup_f32 v44, v36, v22, 1.0
	s_waitcnt lgkmcnt(0)
	v_add_f32_e32 v29, v29, v35
	ds_bpermute_b32 v43, v196, v29
	v_mul_f32_e32 v22, v18, v44
	v_mul_f32_e32 v35, v94, v22
	v_mul_f32_e32 v22, v17, v44
	s_waitcnt lgkmcnt(0)
	v_add_f32_e32 v29, v29, v43
	v_fmamk_f32 v29, v29, 0x3c000000, v204
	v_mul_f32_e32 v36, 0x4f800000, v29
	v_cmp_gt_f32_e32 vcc, s34, v29
	s_nop 1
	v_cndmask_b32_e32 v29, v29, v36, vcc
	v_sqrt_f32_e32 v43, v29
	v_mul_f32_e32 v36, v51, v22
	v_mul_f32_e32 v22, v26, v44
	v_mul_f32_e32 v22, v59, v22
	v_add_u32_e32 v51, -1, v43
	v_fma_f32 v52, -v51, v43, v29
	v_cmp_ge_f32_e64 s[6:7], 0, v52
	v_add_u32_e32 v52, 1, v43
	s_nop 0
	v_cndmask_b32_e64 v51, v43, v51, s[6:7]
	v_fma_f32 v43, -v52, v43, v29
	v_cmp_lt_f32_e64 s[6:7], 0, v43
	s_nop 1
	v_cndmask_b32_e64 v43, v51, v52, s[6:7]
	v_mul_f32_e32 v51, 0x37800000, v43
	v_cndmask_b32_e32 v43, v43, v51, vcc
	v_mul_f32_e32 v51, v40, v40
	v_mul_f32_e32 v52, v78, v78
	v_fmac_f32_e32 v51, v46, v46
	v_fmac_f32_e32 v52, v77, v77
	v_add_f32_e32 v51, v51, v52
	ds_bpermute_b32 v52, v198, v51
	v_cmp_class_f32_e32 vcc, v29, v205
	s_waitcnt lgkmcnt(0)
	v_add_f32_e32 v51, v51, v52
	v_cndmask_b32_e32 v43, v43, v29, vcc
	v_div_scale_f32 v59, s[4:5], v43, v43, 1.0
	v_rcp_f32_e32 v60, v59
	ds_bpermute_b32 v52, v199, v51
	v_mul_f32_e32 v29, v25, v44
	v_mul_f32_e32 v29, v67, v29
	v_fma_f32 v44, -v59, v60, 1.0
	v_fmac_f32_e32 v60, v44, v60
	s_waitcnt lgkmcnt(0)
	v_add_f32_e32 v44, v51, v52
	ds_bpermute_b32 v51, v200, v44
	v_div_scale_f32 v52, vcc, 1.0, v43, 1.0
	v_mul_f32_e32 v67, v52, v60
	v_fma_f32 v75, -v59, v67, v52
	s_waitcnt lgkmcnt(0)
	v_add_f32_e32 v44, v44, v51
	ds_bpermute_b32 v51, v201, v44
	v_fmac_f32_e32 v67, v75, v60
	v_fma_f32 v52, -v59, v67, v52
	v_div_fmas_f32 v52, v52, v60, v67
	v_div_fixup_f32 v52, v52, v43, 1.0
	s_waitcnt lgkmcnt(0)
	v_add_f32_e32 v44, v44, v51
	ds_bpermute_b32 v51, v196, v44
	v_mul_f32_e32 v43, v18, v52
	v_mul_f32_e32 v43, v37, v43
	v_mul_f32_e32 v37, v17, v52
	s_waitcnt lgkmcnt(0)
	v_add_f32_e32 v44, v44, v51
	v_fmamk_f32 v44, v44, 0x3c000000, v204
	v_mul_f32_e32 v51, 0x4f800000, v44
	v_cmp_gt_f32_e32 vcc, s34, v44
	s_nop 1
	v_cndmask_b32_e32 v51, v44, v51, vcc
	v_sqrt_f32_e32 v59, v51
	v_mul_f32_e32 v44, v32, v37
	v_mul_f32_e32 v32, v26, v52
	v_mul_f32_e32 v32, v109, v32
	v_add_u32_e32 v37, -1, v59
	v_fma_f32 v60, -v37, v59, v51
	v_cmp_ge_f32_e64 s[6:7], 0, v60
	v_add_u32_e32 v60, 1, v59
	s_nop 0
	v_cndmask_b32_e64 v37, v59, v37, s[6:7]
	v_fma_f32 v59, -v60, v59, v51
	v_cmp_lt_f32_e64 s[6:7], 0, v59
	s_nop 1
	v_cndmask_b32_e64 v37, v37, v60, s[6:7]
	v_mul_f32_e32 v59, 0x37800000, v37
	v_cndmask_b32_e32 v37, v37, v59, vcc
	v_mul_f32_e32 v59, v49, v49
	v_mul_f32_e32 v60, v66, v66
	v_fmac_f32_e32 v59, v55, v55
	v_fmac_f32_e32 v60, v110, v110
	v_add_f32_e32 v59, v59, v60
	ds_bpermute_b32 v60, v198, v59
	v_cmp_class_f32_e32 vcc, v51, v205
	s_waitcnt lgkmcnt(0)
	v_add_f32_e32 v59, v59, v60
	v_cndmask_b32_e32 v51, v37, v51, vcc
	v_div_scale_f32 v67, s[4:5], v51, v51, 1.0
	v_rcp_f32_e32 v75, v67
	ds_bpermute_b32 v60, v199, v59
	v_mul_f32_e32 v37, v25, v52
	v_mul_f32_e32 v37, v76, v37
	v_fma_f32 v52, -v67, v75, 1.0
	v_fmac_f32_e32 v75, v52, v75
	s_waitcnt lgkmcnt(0)
	v_add_f32_e32 v52, v59, v60
	ds_bpermute_b32 v59, v200, v52
	v_div_scale_f32 v60, vcc, 1.0, v51, 1.0
	v_mul_f32_e32 v76, v60, v75
	v_fma_f32 v79, -v67, v76, v60
	s_waitcnt lgkmcnt(0)
	v_add_f32_e32 v52, v52, v59
	ds_bpermute_b32 v59, v201, v52
	v_fmac_f32_e32 v76, v79, v75
	v_fma_f32 v60, -v67, v76, v60
	v_div_fmas_f32 v60, v60, v75, v76
	v_div_fixup_f32 v60, v60, v51, 1.0
	s_waitcnt lgkmcnt(0)
	v_add_f32_e32 v52, v52, v59
	ds_bpermute_b32 v59, v196, v52
	v_mul_f32_e32 v51, v18, v60
	v_mul_f32_e32 v51, v46, v51
	v_mul_f32_e32 v46, v17, v60
	s_waitcnt lgkmcnt(0)
	v_add_f32_e32 v52, v52, v59
	v_fmamk_f32 v52, v52, 0x3c000000, v204
	v_mul_f32_e32 v59, 0x4f800000, v52
	v_cmp_gt_f32_e32 vcc, s34, v52
	s_nop 1
	v_cndmask_b32_e32 v59, v52, v59, vcc
	v_sqrt_f32_e32 v67, v59
	v_mul_f32_e32 v52, v40, v46
	v_mul_f32_e32 v40, v26, v60
	v_mul_f32_e32 v40, v77, v40
	v_add_u32_e32 v46, -1, v67
	v_fma_f32 v75, -v46, v67, v59
	v_cmp_ge_f32_e64 s[6:7], 0, v75
	v_add_u32_e32 v75, 1, v67
	s_nop 0
	v_cndmask_b32_e64 v46, v67, v46, s[6:7]
	v_fma_f32 v67, -v75, v67, v59
	v_cmp_lt_f32_e64 s[6:7], 0, v67
	s_nop 1
	v_cndmask_b32_e64 v46, v46, v75, s[6:7]
	v_mul_f32_e32 v67, 0x37800000, v46
	v_cndmask_b32_e32 v46, v46, v67, vcc
	v_mul_f32_e32 v67, v58, v58
	v_mul_f32_e32 v75, v70, v70
	v_fmac_f32_e32 v67, v63, v63
	v_fmac_f32_e32 v75, v71, v71
	v_add_f32_e32 v67, v67, v75
	ds_bpermute_b32 v75, v198, v67
	v_cmp_class_f32_e32 vcc, v59, v205
	s_waitcnt lgkmcnt(0)
	v_add_f32_e32 v67, v67, v75
	v_cndmask_b32_e32 v59, v46, v59, vcc
	v_div_scale_f32 v76, s[4:5], v59, v59, 1.0
	v_rcp_f32_e32 v77, v76
	ds_bpermute_b32 v75, v199, v67
	v_mul_f32_e32 v46, v25, v60
	v_mul_f32_e32 v46, v78, v46
	v_fma_f32 v60, -v76, v77, 1.0
	v_fmac_f32_e32 v77, v60, v77
	s_waitcnt lgkmcnt(0)
	v_add_f32_e32 v60, v67, v75
	ds_bpermute_b32 v67, v200, v60
	v_div_scale_f32 v75, vcc, 1.0, v59, 1.0
	v_mul_f32_e32 v78, v75, v77
	v_fma_f32 v79, -v76, v78, v75
	s_waitcnt lgkmcnt(0)
	v_add_f32_e32 v60, v60, v67
	ds_bpermute_b32 v67, v201, v60
	v_fmac_f32_e32 v78, v79, v77
	v_fma_f32 v75, -v76, v78, v75
	v_div_fmas_f32 v75, v75, v77, v78
	v_div_fixup_f32 v75, v75, v59, 1.0
	s_waitcnt lgkmcnt(0)
	v_add_f32_e32 v60, v60, v67
	ds_bpermute_b32 v67, v196, v60
	v_mul_f32_e32 v59, v18, v75
	v_mul_f32_e32 v59, v55, v59
	v_mul_f32_e32 v55, v17, v75
	s_waitcnt lgkmcnt(0)
	v_add_f32_e32 v60, v60, v67
	v_fmamk_f32 v60, v60, 0x3c000000, v204
	v_mul_f32_e32 v67, 0x4f800000, v60
	v_cmp_gt_f32_e32 vcc, s34, v60
	s_nop 1
	v_cndmask_b32_e32 v67, v60, v67, vcc
	v_sqrt_f32_e32 v76, v67
	v_mul_f32_e32 v60, v49, v55
	v_mul_f32_e32 v49, v26, v75
	v_mul_f32_e32 v49, v110, v49
	v_add_u32_e32 v55, -1, v76
	v_fma_f32 v77, -v55, v76, v67
	v_cmp_ge_f32_e64 s[6:7], 0, v77
	v_add_u32_e32 v77, 1, v76
	s_nop 0
	v_cndmask_b32_e64 v55, v76, v55, s[6:7]
	v_fma_f32 v76, -v77, v76, v67
	v_cmp_lt_f32_e64 s[6:7], 0, v76
	s_nop 1
	v_cndmask_b32_e64 v55, v55, v77, s[6:7]
	v_mul_f32_e32 v76, 0x37800000, v55
	v_cndmask_b32_e32 v55, v55, v76, vcc
	v_mul_f32_e32 v76, v62, v62
	v_mul_f32_e32 v77, v73, v73
	v_fmac_f32_e32 v76, v64, v64
	v_fmac_f32_e32 v77, v74, v74
	v_add_f32_e32 v76, v76, v77
	ds_bpermute_b32 v77, v198, v76
	v_cmp_class_f32_e32 vcc, v67, v205
	s_waitcnt lgkmcnt(0)
	v_add_f32_e32 v76, v76, v77
	v_cndmask_b32_e32 v67, v55, v67, vcc
	v_div_scale_f32 v78, s[4:5], v67, v67, 1.0
	v_rcp_f32_e32 v79, v78
	ds_bpermute_b32 v77, v199, v76
	v_mul_f32_e32 v55, v25, v75
	v_mul_f32_e32 v55, v66, v55
	v_fma_f32 v66, -v78, v79, 1.0
	v_fmac_f32_e32 v79, v66, v79
	s_waitcnt lgkmcnt(0)
	v_add_f32_e32 v66, v76, v77
	ds_bpermute_b32 v75, v200, v66
	v_div_scale_f32 v76, vcc, 1.0, v67, 1.0
	v_mul_f32_e32 v77, v76, v79
	v_fma_f32 v80, -v78, v77, v76
	s_waitcnt lgkmcnt(0)
	v_add_f32_e32 v66, v66, v75
	ds_bpermute_b32 v75, v201, v66
	v_fmac_f32_e32 v77, v80, v79
	v_fma_f32 v76, -v78, v77, v76
	v_div_fmas_f32 v76, v76, v79, v77
	v_div_fixup_f32 v76, v76, v67, 1.0
	s_waitcnt lgkmcnt(0)
	v_add_f32_e32 v75, v66, v75
	ds_bpermute_b32 v77, v196, v75
	v_mul_f32_e32 v66, v18, v76
	v_mul_f32_e32 v66, v63, v66
	v_mul_f32_e32 v63, v17, v76
	s_waitcnt lgkmcnt(0)
	v_add_f32_e32 v67, v75, v77
	v_fmamk_f32 v67, v67, 0x3c000000, v204
	v_mul_f32_e32 v75, 0x4f800000, v67
	v_cmp_gt_f32_e32 vcc, s34, v67
	s_nop 1
	v_cndmask_b32_e32 v75, v67, v75, vcc
	v_sqrt_f32_e32 v77, v75
	v_mul_f32_e32 v67, v58, v63
	v_mul_f32_e32 v58, v26, v76
	v_mul_f32_e32 v58, v71, v58
	v_add_u32_e32 v63, -1, v77
	v_fma_f32 v71, -v63, v77, v75
	v_cmp_ge_f32_e64 s[6:7], 0, v71
	v_add_u32_e32 v71, 1, v77
	s_nop 0
	v_cndmask_b32_e64 v63, v77, v63, s[6:7]
	v_fma_f32 v77, -v71, v77, v75
	v_cmp_lt_f32_e64 s[6:7], 0, v77
	v_mul_f32_e32 v77, v69, v69
	v_fmac_f32_e32 v77, v72, v72
	v_cndmask_b32_e64 v63, v63, v71, s[6:7]
	v_mul_f32_e32 v71, 0x37800000, v63
	v_cndmask_b32_e32 v63, v63, v71, vcc
	v_mul_f32_e32 v71, v54, v54
	v_fmac_f32_e32 v71, v56, v56
	v_add_f32_e32 v71, v71, v77
	ds_bpermute_b32 v77, v198, v71
	v_cmp_class_f32_e32 vcc, v75, v205
	s_waitcnt lgkmcnt(0)
	v_add_f32_e32 v71, v71, v77
	v_cndmask_b32_e32 v75, v63, v75, vcc
	v_div_scale_f32 v78, s[4:5], v75, v75, 1.0
	v_rcp_f32_e32 v79, v78
	ds_bpermute_b32 v77, v199, v71
	v_mul_f32_e32 v63, v25, v76
	v_mul_f32_e32 v63, v70, v63
	v_fma_f32 v70, -v78, v79, 1.0
	v_fmac_f32_e32 v79, v70, v79
	s_waitcnt lgkmcnt(0)
	v_add_f32_e32 v70, v71, v77
	ds_bpermute_b32 v71, v200, v70
	v_div_scale_f32 v76, vcc, 1.0, v75, 1.0
	v_mul_f32_e32 v77, v76, v79
	v_fma_f32 v80, -v78, v77, v76
	s_waitcnt lgkmcnt(0)
	v_add_f32_e32 v70, v70, v71
	ds_bpermute_b32 v71, v201, v70
	v_fmac_f32_e32 v77, v80, v79
	v_fma_f32 v76, -v78, v77, v76
	v_div_fmas_f32 v76, v76, v79, v77
	v_div_fixup_f32 v75, v76, v75, 1.0
	s_waitcnt lgkmcnt(0)
	v_add_f32_e32 v71, v70, v71
	ds_bpermute_b32 v77, v196, v71
	v_mul_f32_e32 v70, v18, v75
	v_mul_f32_e32 v70, v64, v70
	v_mul_f32_e32 v64, v17, v75
	s_waitcnt lgkmcnt(0)
	v_add_f32_e32 v71, v71, v77
	v_fmamk_f32 v71, v71, 0x3c000000, v204
	v_mul_f32_e32 v76, 0x4f800000, v71
	v_cmp_gt_f32_e32 vcc, s34, v71
	s_nop 1
	v_cndmask_b32_e32 v76, v71, v76, vcc
	v_sqrt_f32_e32 v77, v76
	v_mul_f32_e32 v71, v62, v64
	v_mul_f32_e32 v62, v26, v75
	v_mul_f32_e32 v62, v74, v62
	v_add_u32_e32 v64, -1, v77
	v_fma_f32 v74, -v64, v77, v76
	v_cmp_ge_f32_e64 s[6:7], 0, v74
	v_add_u32_e32 v74, 1, v77
	s_nop 0
	v_cndmask_b32_e64 v64, v77, v64, s[6:7]
	v_fma_f32 v77, -v74, v77, v76
	v_cmp_lt_f32_e64 s[6:7], 0, v77
	v_mul_f32_e32 v77, v65, v65
	v_fmac_f32_e32 v77, v68, v68
	v_cndmask_b32_e64 v64, v64, v74, s[6:7]
	v_mul_f32_e32 v74, 0x37800000, v64
	v_cndmask_b32_e32 v64, v64, v74, vcc
	v_mul_f32_e32 v74, v47, v47
	v_fmac_f32_e32 v74, v50, v50
	v_add_f32_e32 v74, v74, v77
	ds_bpermute_b32 v77, v198, v74
	v_cmp_class_f32_e32 vcc, v76, v205
	s_waitcnt lgkmcnt(0)
	v_add_f32_e32 v74, v74, v77
	v_cndmask_b32_e32 v76, v64, v76, vcc
	v_div_scale_f32 v78, s[4:5], v76, v76, 1.0
	v_rcp_f32_e32 v79, v78
	ds_bpermute_b32 v77, v199, v74
	v_mul_f32_e32 v64, v25, v75
	v_mul_f32_e32 v64, v73, v64
	v_fma_f32 v73, -v78, v79, 1.0
	v_fmac_f32_e32 v79, v73, v79
	s_waitcnt lgkmcnt(0)
	v_add_f32_e32 v73, v74, v77
	ds_bpermute_b32 v74, v200, v73
	v_div_scale_f32 v75, vcc, 1.0, v76, 1.0
	v_mul_f32_e32 v77, v75, v79
	v_fma_f32 v80, -v78, v77, v75
	s_waitcnt lgkmcnt(0)
	v_add_f32_e32 v73, v73, v74
	ds_bpermute_b32 v74, v201, v73
	v_fmac_f32_e32 v77, v80, v79
	v_fma_f32 v75, -v78, v77, v75
	v_div_fmas_f32 v75, v75, v79, v77
	v_div_fixup_f32 v75, v75, v76, 1.0
	s_waitcnt lgkmcnt(0)
	v_add_f32_e32 v74, v73, v74
	ds_bpermute_b32 v77, v196, v74
	v_mul_f32_e32 v73, v18, v75
	v_mul_f32_e32 v73, v56, v73
	v_mul_f32_e32 v56, v17, v75
	s_waitcnt lgkmcnt(0)
	v_add_f32_e32 v74, v74, v77
	v_fmamk_f32 v74, v74, 0x3c000000, v204
	v_mul_f32_e32 v76, 0x4f800000, v74
	v_cmp_gt_f32_e32 vcc, s34, v74
	s_nop 1
	v_cndmask_b32_e32 v76, v74, v76, vcc
	v_sqrt_f32_e32 v77, v76
	v_mul_f32_e32 v74, v54, v56
	v_mul_f32_e32 v54, v26, v75
	v_mul_f32_e32 v54, v72, v54
	v_add_u32_e32 v56, -1, v77
	v_fma_f32 v72, -v56, v77, v76
	v_cmp_ge_f32_e64 s[6:7], 0, v72
	v_add_u32_e32 v72, 1, v77
	s_nop 0
	v_cndmask_b32_e64 v56, v77, v56, s[6:7]
	v_fma_f32 v77, -v72, v77, v76
	v_cmp_lt_f32_e64 s[6:7], 0, v77
	v_mul_f32_e32 v77, v57, v57
	v_fmac_f32_e32 v77, v61, v61
	v_cndmask_b32_e64 v56, v56, v72, s[6:7]
	v_mul_f32_e32 v72, 0x37800000, v56
	v_cndmask_b32_e32 v56, v56, v72, vcc
	v_mul_f32_e32 v72, v39, v39
	v_fmac_f32_e32 v72, v42, v42
	v_add_f32_e32 v72, v72, v77
	ds_bpermute_b32 v77, v198, v72
	v_cmp_class_f32_e32 vcc, v76, v205
	s_waitcnt lgkmcnt(0)
	v_add_f32_e32 v72, v72, v77
	v_cndmask_b32_e32 v76, v56, v76, vcc
	v_div_scale_f32 v78, s[4:5], v76, v76, 1.0
	v_rcp_f32_e32 v79, v78
	ds_bpermute_b32 v77, v199, v72
	v_mul_f32_e32 v56, v25, v75
	v_mul_f32_e32 v56, v69, v56
	v_fma_f32 v69, -v78, v79, 1.0
	v_fmac_f32_e32 v79, v69, v79
	s_waitcnt lgkmcnt(0)
	v_add_f32_e32 v69, v72, v77
	ds_bpermute_b32 v72, v200, v69
	v_div_scale_f32 v75, vcc, 1.0, v76, 1.0
	v_mul_f32_e32 v77, v75, v79
	v_fma_f32 v80, -v78, v77, v75
	s_waitcnt lgkmcnt(0)
	v_add_f32_e32 v69, v69, v72
	ds_bpermute_b32 v72, v201, v69
	v_fmac_f32_e32 v77, v80, v79
	v_fma_f32 v75, -v78, v77, v75
	v_div_fmas_f32 v75, v75, v79, v77
	v_div_fixup_f32 v75, v75, v76, 1.0
	s_waitcnt lgkmcnt(0)
	v_add_f32_e32 v72, v69, v72
	ds_bpermute_b32 v77, v196, v72
	v_mul_f32_e32 v69, v18, v75
	v_mul_f32_e32 v69, v50, v69
	v_mul_f32_e32 v50, v17, v75
	s_waitcnt lgkmcnt(0)
	v_add_f32_e32 v72, v72, v77
	v_fmamk_f32 v72, v72, 0x3c000000, v204
	v_mul_f32_e32 v76, 0x4f800000, v72
	v_cmp_gt_f32_e32 vcc, s34, v72
	s_nop 1
	v_cndmask_b32_e32 v76, v72, v76, vcc
	v_sqrt_f32_e32 v77, v76
	v_mul_f32_e32 v72, v47, v50
	v_mul_f32_e32 v47, v26, v75
	v_mul_f32_e32 v47, v68, v47
	v_add_u32_e32 v50, -1, v77
	v_fma_f32 v68, -v50, v77, v76
	v_cmp_ge_f32_e64 s[6:7], 0, v68
	v_add_u32_e32 v68, 1, v77
	s_nop 0
	v_cndmask_b32_e64 v50, v77, v50, s[6:7]
	v_fma_f32 v77, -v68, v77, v76
	v_cmp_lt_f32_e64 s[6:7], 0, v77
	v_mul_f32_e32 v77, v48, v48
	v_fmac_f32_e32 v77, v53, v53
	v_cndmask_b32_e64 v50, v50, v68, s[6:7]
	v_mul_f32_e32 v68, 0x37800000, v50
	v_cndmask_b32_e32 v50, v50, v68, vcc
	v_mul_f32_e32 v68, v31, v31
	v_fmac_f32_e32 v68, v33, v33
	v_add_f32_e32 v68, v68, v77
	ds_bpermute_b32 v77, v198, v68
	v_cmp_class_f32_e32 vcc, v76, v205
	s_waitcnt lgkmcnt(0)
	v_add_f32_e32 v68, v68, v77
	v_cndmask_b32_e32 v76, v50, v76, vcc
	v_div_scale_f32 v78, s[4:5], v76, v76, 1.0
	v_rcp_f32_e32 v79, v78
	ds_bpermute_b32 v77, v199, v68
	v_mul_f32_e32 v50, v25, v75
	v_mul_f32_e32 v50, v65, v50
	v_fma_f32 v65, -v78, v79, 1.0
	v_fmac_f32_e32 v79, v65, v79
	s_waitcnt lgkmcnt(0)
	v_add_f32_e32 v65, v68, v77
	ds_bpermute_b32 v68, v200, v65
	v_div_scale_f32 v75, vcc, 1.0, v76, 1.0
	v_mul_f32_e32 v77, v75, v79
	v_fma_f32 v80, -v78, v77, v75
	s_waitcnt lgkmcnt(0)
	v_add_f32_e32 v65, v65, v68
	ds_bpermute_b32 v68, v201, v65
	v_fmac_f32_e32 v77, v80, v79
	v_fma_f32 v75, -v78, v77, v75
	v_div_fmas_f32 v75, v75, v79, v77
	v_div_fixup_f32 v75, v75, v76, 1.0
	s_waitcnt lgkmcnt(0)
	v_add_f32_e32 v65, v65, v68
	ds_bpermute_b32 v68, v196, v65
	v_mul_f32_e32 v76, v18, v75
	v_mul_f32_e32 v76, v42, v76
	v_mul_f32_e32 v42, v17, v75
	v_mul_f32_e32 v77, v39, v42
	s_waitcnt lgkmcnt(0)
	v_add_f32_e32 v65, v65, v68
	v_fmamk_f32 v65, v65, 0x3c000000, v204
	v_mul_f32_e32 v68, 0x4f800000, v65
	v_cmp_gt_f32_e32 vcc, s34, v65
	v_mul_f32_e32 v39, v26, v75
	v_mul_f32_e32 v39, v61, v39
	v_cndmask_b32_e32 v65, v65, v68, vcc
	v_sqrt_f32_e32 v68, v65
	s_nop 0
	v_add_u32_e32 v42, -1, v68
	v_fma_f32 v61, -v42, v68, v65
	v_cmp_ge_f32_e64 s[6:7], 0, v61
	v_add_u32_e32 v61, 1, v68
	s_nop 0
	v_cndmask_b32_e64 v42, v68, v42, s[6:7]
	v_fma_f32 v68, -v61, v68, v65
	v_cmp_lt_f32_e64 s[6:7], 0, v68
	v_mul_f32_e32 v68, v41, v41
	v_fmac_f32_e32 v68, v45, v45
	v_cndmask_b32_e64 v42, v42, v61, s[6:7]
	v_mul_f32_e32 v61, 0x37800000, v42
	v_cndmask_b32_e32 v42, v42, v61, vcc
	v_mul_f32_e32 v61, v21, v21
	v_fmac_f32_e32 v61, v23, v23
	v_add_f32_e32 v61, v61, v68
	ds_bpermute_b32 v68, v198, v61
	v_cmp_class_f32_e32 vcc, v65, v205
	s_waitcnt lgkmcnt(0)
	v_add_f32_e32 v61, v61, v68
	v_cndmask_b32_e32 v65, v42, v65, vcc
	v_div_scale_f32 v78, s[4:5], v65, v65, 1.0
	v_rcp_f32_e32 v79, v78
	ds_bpermute_b32 v68, v199, v61
	v_mul_f32_e32 v42, v25, v75
	v_mul_f32_e32 v42, v57, v42
	v_fma_f32 v57, -v78, v79, 1.0
	v_fmac_f32_e32 v79, v57, v79
	s_waitcnt lgkmcnt(0)
	v_add_f32_e32 v57, v61, v68
	ds_bpermute_b32 v61, v200, v57
	v_div_scale_f32 v68, vcc, 1.0, v65, 1.0
	v_mul_f32_e32 v75, v68, v79
	v_fma_f32 v80, -v78, v75, v68
	s_waitcnt lgkmcnt(0)
	v_add_f32_e32 v57, v57, v61
	ds_bpermute_b32 v61, v201, v57
	v_fmac_f32_e32 v75, v80, v79
	v_fma_f32 v68, -v78, v75, v68
	v_div_fmas_f32 v68, v68, v79, v75
	v_div_fixup_f32 v65, v68, v65, 1.0
	s_waitcnt lgkmcnt(0)
	v_add_f32_e32 v57, v57, v61
	ds_bpermute_b32 v61, v196, v57
	v_mul_f32_e32 v68, v18, v65
	v_mul_f32_e32 v33, v33, v68
	v_mul_f32_e32 v68, v17, v65
	v_mul_f32_e32 v31, v31, v68
	s_waitcnt lgkmcnt(0)
	v_add_f32_e32 v57, v57, v61
	v_fmamk_f32 v57, v57, 0x3c000000, v204
	v_mul_f32_e32 v61, 0x4f800000, v57
	v_cmp_gt_f32_e32 vcc, s34, v57
	v_mul_f32_e32 v68, v26, v65
	v_mul_f32_e32 v53, v53, v68
	v_cndmask_b32_e32 v57, v57, v61, vcc
	v_sqrt_f32_e32 v61, v57
	v_mul_f32_e32 v65, v25, v65
	v_mul_f32_e32 v48, v48, v65
	v_add_u32_e32 v68, -1, v61
	v_fma_f32 v75, -v68, v61, v57
	v_cmp_ge_f32_e64 s[6:7], 0, v75
	v_add_u32_e32 v75, 1, v61
	s_nop 0
	v_cndmask_b32_e64 v68, v61, v68, s[6:7]
	v_fma_f32 v61, -v75, v61, v57
	v_cmp_lt_f32_e64 s[6:7], 0, v61
	s_nop 1
	v_cndmask_b32_e64 v61, v68, v75, s[6:7]
	v_mul_f32_e32 v68, 0x37800000, v61
	v_cndmask_b32_e32 v61, v61, v68, vcc
	v_mul_f32_e32 v68, v12, v12
	v_mul_f32_e32 v75, v34, v34
	v_fmac_f32_e32 v68, v14, v14
	v_fmac_f32_e32 v75, v38, v38
	v_add_f32_e32 v68, v68, v75
	ds_bpermute_b32 v75, v198, v68
	v_cmp_class_f32_e32 vcc, v57, v205
	s_waitcnt lgkmcnt(0)
	v_add_f32_e32 v68, v68, v75
	v_cndmask_b32_e32 v57, v61, v57, vcc
	v_div_scale_f32 v61, s[4:5], v57, v57, 1.0
	v_rcp_f32_e32 v78, v61
	ds_bpermute_b32 v75, v199, v68
	v_fma_f32 v65, -v61, v78, 1.0
	v_fmac_f32_e32 v78, v65, v78
	s_waitcnt lgkmcnt(0)
	v_add_f32_e32 v65, v68, v75
	ds_bpermute_b32 v68, v200, v65
	v_div_scale_f32 v75, vcc, 1.0, v57, 1.0
	v_mul_f32_e32 v79, v75, v78
	v_fma_f32 v80, -v61, v79, v75
	s_waitcnt lgkmcnt(0)
	v_add_f32_e32 v65, v65, v68
	ds_bpermute_b32 v68, v201, v65
	v_fmac_f32_e32 v79, v80, v78
	v_fma_f32 v61, -v61, v79, v75
	v_div_fmas_f32 v61, v61, v78, v79
	v_div_fixup_f32 v57, v61, v57, 1.0
	s_waitcnt lgkmcnt(0)
	v_add_f32_e32 v65, v65, v68
	ds_bpermute_b32 v68, v196, v65
	v_mul_f32_e32 v61, v18, v57
	v_mul_f32_e32 v23, v23, v61
	v_mul_f32_e32 v61, v17, v57
	v_mul_f32_e32 v21, v21, v61
	s_waitcnt lgkmcnt(0)
	v_add_f32_e32 v65, v65, v68
	v_fmamk_f32 v65, v65, 0x3c000000, v204
	v_mul_f32_e32 v68, 0x4f800000, v65
	v_cmp_gt_f32_e32 vcc, s34, v65
	v_mul_f32_e32 v61, v26, v57
	v_mul_f32_e32 v45, v45, v61
	v_cndmask_b32_e32 v65, v65, v68, vcc
	v_sqrt_f32_e32 v68, v65
	v_mul_f32_e32 v57, v25, v57
	v_mul_f32_e32 v41, v41, v57
	v_add_u32_e32 v61, -1, v68
	v_fma_f32 v75, -v61, v68, v65
	v_cmp_ge_f32_e64 s[6:7], 0, v75
	v_add_u32_e32 v75, 1, v68
	s_nop 0
	v_cndmask_b32_e64 v61, v68, v61, s[6:7]
	v_fma_f32 v68, -v75, v68, v65
	v_cmp_lt_f32_e64 s[6:7], 0, v68
	s_nop 1
	v_cndmask_b32_e64 v61, v61, v75, s[6:7]
	v_mul_f32_e32 v68, 0x37800000, v61
	v_cndmask_b32_e32 v61, v61, v68, vcc
	v_mul_f32_e32 v68, v10, v10
	v_mul_f32_e32 v75, v24, v24
	v_fmac_f32_e32 v68, v9, v9
	v_fmac_f32_e32 v75, v30, v30
	v_add_f32_e32 v68, v68, v75
	ds_bpermute_b32 v75, v198, v68
	v_cmp_class_f32_e32 vcc, v65, v205
	s_waitcnt lgkmcnt(0)
	v_add_f32_e32 v68, v68, v75
	v_cndmask_b32_e32 v61, v61, v65, vcc
	v_div_scale_f32 v65, s[4:5], v61, v61, 1.0
	v_rcp_f32_e32 v78, v65
	ds_bpermute_b32 v75, v199, v68
	v_fma_f32 v57, -v65, v78, 1.0
	v_fmac_f32_e32 v78, v57, v78
	s_waitcnt lgkmcnt(0)
	v_add_f32_e32 v57, v68, v75
	ds_bpermute_b32 v68, v200, v57
	v_div_scale_f32 v75, vcc, 1.0, v61, 1.0
	v_mul_f32_e32 v79, v75, v78
	v_fma_f32 v80, -v65, v79, v75
	s_waitcnt lgkmcnt(0)
	v_add_f32_e32 v57, v57, v68
	ds_bpermute_b32 v68, v201, v57
	v_fmac_f32_e32 v79, v80, v78
	v_fma_f32 v65, -v65, v79, v75
	v_div_fmas_f32 v65, v65, v78, v79
	v_div_fixup_f32 v61, v65, v61, 1.0
	s_waitcnt lgkmcnt(0)
	v_add_f32_e32 v57, v57, v68
	ds_bpermute_b32 v68, v196, v57
	v_mul_f32_e32 v65, v18, v61
	v_mul_f32_e32 v14, v14, v65
	v_mul_f32_e32 v65, v17, v61
	v_mul_f32_e32 v12, v12, v65
	s_waitcnt lgkmcnt(0)
	v_add_f32_e32 v57, v57, v68
	v_fmamk_f32 v57, v57, 0x3c000000, v204
	v_mul_f32_e32 v68, 0x4f800000, v57
	v_cmp_gt_f32_e32 vcc, s34, v57
	v_mul_f32_e32 v65, v26, v61
	v_mul_f32_e32 v38, v38, v65
	v_cndmask_b32_e32 v57, v57, v68, vcc
	v_sqrt_f32_e32 v68, v57
	v_mul_f32_e32 v61, v25, v61
	v_mul_f32_e32 v34, v34, v61
	v_add_u32_e32 v65, -1, v68
	v_fma_f32 v75, -v65, v68, v57
	v_cmp_ge_f32_e64 s[6:7], 0, v75
	v_add_u32_e32 v75, 1, v68
	s_nop 0
	v_cndmask_b32_e64 v65, v68, v65, s[6:7]
	v_fma_f32 v68, -v75, v68, v57
	v_cmp_lt_f32_e64 s[6:7], 0, v68
	s_nop 1
	v_cndmask_b32_e64 v65, v65, v75, s[6:7]
	v_mul_f32_e32 v68, 0x37800000, v65
	v_cndmask_b32_e32 v65, v65, v68, vcc
	v_mul_f32_e32 v68, v7, v7
	v_mul_f32_e32 v75, v19, v19
	v_fmac_f32_e32 v68, v8, v8
	v_fmac_f32_e32 v75, v16, v16
	v_add_f32_e32 v68, v68, v75
	ds_bpermute_b32 v75, v198, v68
	v_cmp_class_f32_e32 vcc, v57, v205
	s_waitcnt lgkmcnt(0)
	v_add_f32_e32 v68, v68, v75
	v_cndmask_b32_e32 v57, v65, v57, vcc
	v_div_scale_f32 v65, s[4:5], v57, v57, 1.0
	v_rcp_f32_e32 v78, v65
	ds_bpermute_b32 v75, v199, v68
	v_fma_f32 v61, -v65, v78, 1.0
	v_fmac_f32_e32 v78, v61, v78
	s_waitcnt lgkmcnt(0)
	v_add_f32_e32 v61, v68, v75
	ds_bpermute_b32 v68, v200, v61
	v_div_scale_f32 v75, vcc, 1.0, v57, 1.0
	v_mul_f32_e32 v79, v75, v78
	v_fma_f32 v80, -v65, v79, v75
	s_waitcnt lgkmcnt(0)
	v_add_f32_e32 v61, v61, v68
	ds_bpermute_b32 v68, v201, v61
	v_fmac_f32_e32 v79, v80, v78
	v_fma_f32 v65, -v65, v79, v75
	v_div_fmas_f32 v65, v65, v78, v79
	v_div_fixup_f32 v57, v65, v57, 1.0
	s_waitcnt lgkmcnt(0)
	v_add_f32_e32 v61, v61, v68
	ds_bpermute_b32 v65, v196, v61
	v_mul_f32_e32 v68, v18, v57
	v_mul_f32_e32 v68, v9, v68
	v_mul_f32_e32 v9, v17, v57
	v_mul_f32_e32 v10, v10, v9
	s_waitcnt lgkmcnt(0)
	v_add_f32_e32 v9, v61, v65
	v_fmamk_f32 v9, v9, 0x3c000000, v204
	v_mul_f32_e32 v61, 0x4f800000, v9
	v_cmp_gt_f32_e32 vcc, s34, v9
	v_mul_f32_e32 v65, v26, v57
	v_mul_f32_e32 v65, v30, v65
	v_cndmask_b32_e32 v9, v9, v61, vcc
	v_sqrt_f32_e32 v61, v9
	v_mul_f32_e32 v30, v25, v57
	v_mul_f32_e32 v79, v24, v30
	v_add_u32_e32 v57, -1, v61
	v_fma_f32 v75, -v57, v61, v9
	v_cmp_ge_f32_e64 s[6:7], 0, v75
	v_add_u32_e32 v75, 1, v61
	s_nop 0
	v_cndmask_b32_e64 v57, v61, v57, s[6:7]
	v_fma_f32 v61, -v75, v61, v9
	v_cmp_lt_f32_e64 s[6:7], 0, v61
	v_mul_f32_e32 v61, v6, v6
	v_fmac_f32_e32 v61, v5, v5
	v_cndmask_b32_e64 v57, v57, v75, s[6:7]
	v_mul_f32_e32 v75, v15, v15
	v_fmac_f32_e32 v75, v13, v13
	v_add_f32_e32 v61, v61, v75
	ds_bpermute_b32 v75, v198, v61
	v_mul_f32_e32 v78, 0x37800000, v57
	v_cndmask_b32_e32 v57, v57, v78, vcc
	v_cmp_class_f32_e32 vcc, v9, v205
	s_nop 1
	v_cndmask_b32_e32 v9, v57, v9, vcc
	s_waitcnt lgkmcnt(0)
	v_add_f32_e32 v57, v61, v75
	ds_bpermute_b32 v61, v199, v57
	v_div_scale_f32 v75, s[4:5], v9, v9, 1.0
	v_rcp_f32_e32 v78, v75
	s_waitcnt lgkmcnt(0)
	v_add_f32_e32 v24, v57, v61
	ds_bpermute_b32 v30, v200, v24
	v_fma_f32 v57, -v75, v78, 1.0
	v_fmac_f32_e32 v78, v57, v78
	v_div_scale_f32 v57, vcc, 1.0, v9, 1.0
	s_waitcnt lgkmcnt(0)
	v_add_f32_e32 v24, v24, v30
	ds_bpermute_b32 v30, v201, v24
	v_mul_f32_e32 v61, v57, v78
	v_fma_f32 v80, -v75, v61, v57
	v_fmac_f32_e32 v61, v80, v78
	v_fma_f32 v57, -v75, v61, v57
	s_waitcnt lgkmcnt(0)
	v_add_f32_e32 v24, v24, v30
	ds_bpermute_b32 v30, v196, v24
	v_div_fmas_f32 v57, v57, v78, v61
	v_div_fixup_f32 v9, v57, v9, 1.0
	v_mul_f32_e32 v57, v18, v9
	v_mul_f32_e32 v57, v8, v57
	s_waitcnt lgkmcnt(0)
	v_add_f32_e32 v8, v24, v30
	v_fmamk_f32 v8, v8, 0x3c000000, v204
	v_mul_f32_e32 v24, 0x4f800000, v8
	v_cmp_gt_f32_e32 vcc, s34, v8
	v_add3_u32 v78, s10, v4, v3
	v_cvt_pk_bf16_f32 v3, v27, s0
	v_cndmask_b32_e32 v8, v8, v24, vcc
	ds_write_b16 v78, v3
	v_cvt_pk_bf16_f32 v3, v28, s0
	v_sqrt_f32_e32 v24, v8
	ds_write_b16 v78, v3 offset:64
	v_cvt_pk_bf16_f32 v3, v35, s0
	ds_write_b16 v78, v3 offset:128
	v_cvt_pk_bf16_f32 v3, v36, s0
	ds_write_b16 v78, v3 offset:192
	v_cvt_pk_bf16_f32 v3, v43, s0
	ds_write_b16 v78, v3 offset:256
	v_cvt_pk_bf16_f32 v3, v44, s0
	v_add_u32_e32 v61, -1, v24
	ds_write_b16 v78, v3 offset:320
	v_cvt_pk_bf16_f32 v3, v51, s0
	v_fma_f32 v75, -v61, v24, v8
	ds_write_b16 v78, v3 offset:384
	v_cvt_pk_bf16_f32 v3, v52, s0
	v_cmp_ge_f32_e64 s[6:7], 0, v75
	v_add_u32_e32 v75, 1, v24
	ds_write_b16 v78, v3 offset:448
	v_cvt_pk_bf16_f32 v3, v59, s0
	v_cndmask_b32_e64 v61, v24, v61, s[6:7]
	v_fma_f32 v24, -v75, v24, v8
	ds_write_b16 v78, v3 offset:1024
	v_cvt_pk_bf16_f32 v3, v60, s0
	v_cmp_lt_f32_e64 s[6:7], 0, v24
	ds_write_b16 v78, v3 offset:1088
	v_cvt_pk_bf16_f32 v3, v66, s0
	v_cndmask_b32_e64 v24, v61, v75, s[6:7]
	ds_write_b16 v78, v3 offset:1152
	v_cvt_pk_bf16_f32 v3, v67, s0
	v_mul_f32_e32 v61, 0x37800000, v24
	ds_write_b16 v78, v3 offset:1216
	v_cvt_pk_bf16_f32 v3, v70, s0
	v_cndmask_b32_e32 v24, v24, v61, vcc
	v_cmp_class_f32_e32 vcc, v8, v205
	ds_write_b16 v78, v3 offset:1280
	v_cvt_pk_bf16_f32 v3, v71, s0
	v_cndmask_b32_e32 v8, v24, v8, vcc
	ds_write_b16 v78, v3 offset:1344
	v_cvt_pk_bf16_f32 v3, v73, s0
	v_div_scale_f32 v24, s[4:5], v8, v8, 1.0
	ds_write_b16 v78, v3 offset:1408
	v_cvt_pk_bf16_f32 v3, v74, s0
	v_rcp_f32_e32 v61, v24
	ds_write_b16 v78, v3 offset:1472
	v_cvt_pk_bf16_f32 v3, v69, s0
	ds_write_b16 v78, v3 offset:2048
	v_cvt_pk_bf16_f32 v3, v72, s0
	v_mul_f32_e32 v30, v17, v9
	ds_write_b16 v78, v3 offset:2112
	v_cvt_pk_bf16_f32 v3, v76, s0
	v_mul_f32_e32 v7, v7, v30
	v_mul_f32_e32 v30, v26, v9
	v_mul_f32_e32 v9, v25, v9
	ds_write_b16 v78, v3 offset:2176
	v_cvt_pk_bf16_f32 v3, v77, s0
	v_mul_f32_e32 v75, v19, v9
	v_fma_f32 v9, -v24, v61, 1.0
	ds_write_b16 v78, v3 offset:2240
	v_cvt_pk_bf16_f32 v3, v33, s0
	v_fmac_f32_e32 v61, v9, v61
	v_div_scale_f32 v9, vcc, 1.0, v8, 1.0
	ds_write_b16 v78, v3 offset:2304
	v_cvt_pk_bf16_f32 v3, v31, s0
	v_mul_f32_e32 v19, v9, v61
	ds_write_b16 v78, v3 offset:2368
	v_cvt_pk_bf16_f32 v3, v23, s0
	v_mul_f32_e32 v16, v16, v30
	v_fma_f32 v30, -v24, v19, v9
	ds_write_b16 v78, v3 offset:2432
	v_cvt_pk_bf16_f32 v3, v21, s0
	v_fmac_f32_e32 v19, v30, v61
	ds_write_b16 v78, v3 offset:2496
	v_cvt_pk_bf16_f32 v3, v14, s0
	v_fma_f32 v9, -v24, v19, v9
	ds_write_b16 v78, v3 offset:3072
	v_cvt_pk_bf16_f32 v3, v12, s0
	v_div_fmas_f32 v9, v9, v61, v19
	ds_write_b16 v78, v3 offset:3136
	v_cvt_pk_bf16_f32 v3, v68, s0
	v_div_fixup_f32 v8, v9, v8, 1.0
	ds_write_b16 v78, v3 offset:3200
	v_cvt_pk_bf16_f32 v3, v10, s0
	v_mul_f32_e32 v9, v18, v8
	ds_write_b16 v78, v3 offset:3264
	v_cvt_pk_bf16_f32 v3, v57, s0
	v_mul_f32_e32 v18, v5, v9
	v_mul_f32_e32 v5, v17, v8
	ds_write_b16 v78, v3 offset:3328
	v_cvt_pk_bf16_f32 v3, v7, s0
	v_mul_f32_e32 v6, v6, v5
	ds_write_b16 v78, v3 offset:3392
	v_cvt_pk_bf16_f32 v3, v18, s0
	v_mul_f32_e32 v5, v26, v8
	s_add_u32 s4, s8, s64
	ds_write_b16 v78, v3 offset:3456
	v_cvt_pk_bf16_f32 v3, v6, s0
	v_mul_f32_e32 v17, v13, v5
	v_mul_f32_e32 v5, v25, v8
	s_addc_u32 s5, s9, s65
	ds_write_b16 v78, v3 offset:3520
	v_mul_f32_e32 v61, v15, v5
	v_lshl_add_u64 v[4:5], s[4:5], 0, v[188:189]
	s_mov_b64 s[4:5], 0x18800000
	v_lshl_add_u32 v80, v1, 7, v2
	s_waitcnt lgkmcnt(0)
	v_lshl_add_u64 v[8:9], v[4:5], 0, s[4:5]
	ds_read_b128 v[4:7], v80
	v_or_b32_e32 v3, 8, v1
	v_lshlrev_b32_e32 v12, 11, v1
	v_mov_b32_e32 v13, v146
	v_lshl_add_u32 v10, v3, 7, v2
	v_lshl_add_u64 v[18:19], v[8:9], 0, v[12:13]
	ds_read_b128 v[12:15], v10
	s_waitcnt lgkmcnt(1)
	global_store_dwordx4 v[18:19], v[4:7], off sc1
	s_mov_b64 s[6:7], 0
	s_nop 0
	v_lshlrev_b32_e32 v4, 11, v3
	v_mov_b32_e32 v5, v146
	v_or_b32_e32 v3, 16, v1
	v_lshl_add_u64 v[24:25], v[8:9], 0, v[4:5]
	v_lshl_add_u32 v21, v3, 7, v2
	v_or_b32_e32 v1, 24, v1
	ds_read_b128 v[4:7], v21
	s_waitcnt lgkmcnt(1)
	global_store_dwordx4 v[24:25], v[12:15], off sc1
	v_lshl_add_u32 v23, v1, 7, v2
	v_lshlrev_b32_e32 v2, 11, v1
	v_lshlrev_b32_e32 v12, 11, v3
	v_mov_b32_e32 v13, v146
	v_lshl_add_u64 v[26:27], v[8:9], 0, v[12:13]
	ds_read_b128 v[12:15], v23
	v_mov_b32_e32 v3, v146
	v_lshl_add_u64 v[30:31], v[8:9], 0, v[2:3]
	s_waitcnt lgkmcnt(1)
	global_store_dwordx4 v[26:27], v[4:7], off sc1
	v_cvt_pk_bf16_f32 v1, v11, s0
	s_waitcnt lgkmcnt(0)
	global_store_dwordx4 v[30:31], v[12:15], off sc1
	s_waitcnt lgkmcnt(0)
	ds_write_b16 v78, v1
	v_cvt_pk_bf16_f32 v1, v20, s0
	ds_write_b16 v78, v1 offset:64
	v_cvt_pk_bf16_f32 v1, v22, s0
	ds_write_b16 v78, v1 offset:128
	v_cvt_pk_bf16_f32 v1, v29, s0
	ds_write_b16 v78, v1 offset:192
	v_cvt_pk_bf16_f32 v1, v32, s0
	ds_write_b16 v78, v1 offset:256
	v_cvt_pk_bf16_f32 v1, v37, s0
	ds_write_b16 v78, v1 offset:320
	v_cvt_pk_bf16_f32 v1, v40, s0
	ds_write_b16 v78, v1 offset:384
	v_cvt_pk_bf16_f32 v1, v46, s0
	ds_write_b16 v78, v1 offset:448
	v_cvt_pk_bf16_f32 v1, v49, s0
	ds_write_b16 v78, v1 offset:1024
	v_cvt_pk_bf16_f32 v1, v55, s0
	ds_write_b16 v78, v1 offset:1088
	v_cvt_pk_bf16_f32 v1, v58, s0
	ds_write_b16 v78, v1 offset:1152
	v_cvt_pk_bf16_f32 v1, v63, s0
	ds_write_b16 v78, v1 offset:1216
	v_cvt_pk_bf16_f32 v1, v62, s0
	ds_write_b16 v78, v1 offset:1280
	v_cvt_pk_bf16_f32 v1, v64, s0
	ds_write_b16 v78, v1 offset:1344
	v_cvt_pk_bf16_f32 v1, v54, s0
	ds_write_b16 v78, v1 offset:1408
	v_cvt_pk_bf16_f32 v1, v56, s0
	ds_write_b16 v78, v1 offset:1472
	v_cvt_pk_bf16_f32 v1, v47, s0
	ds_write_b16 v78, v1 offset:2048
	v_cvt_pk_bf16_f32 v1, v50, s0
	ds_write_b16 v78, v1 offset:2112
	v_cvt_pk_bf16_f32 v1, v39, s0
	ds_write_b16 v78, v1 offset:2176
	v_cvt_pk_bf16_f32 v1, v42, s0
	ds_write_b16 v78, v1 offset:2240
	v_cvt_pk_bf16_f32 v1, v53, s0
	ds_write_b16 v78, v1 offset:2304
	v_cvt_pk_bf16_f32 v1, v48, s0
	ds_write_b16 v78, v1 offset:2368
	v_cvt_pk_bf16_f32 v1, v45, s0
	ds_write_b16 v78, v1 offset:2432
	v_cvt_pk_bf16_f32 v1, v41, s0
	ds_write_b16 v78, v1 offset:2496
	v_cvt_pk_bf16_f32 v1, v38, s0
	ds_write_b16 v78, v1 offset:3072
	v_cvt_pk_bf16_f32 v1, v34, s0
	ds_write_b16 v78, v1 offset:3136
	v_cvt_pk_bf16_f32 v1, v65, s0
	ds_write_b16 v78, v1 offset:3200
	v_cvt_pk_bf16_f32 v1, v79, s0
	ds_write_b16 v78, v1 offset:3264
	v_cvt_pk_bf16_f32 v1, v16, s0
	ds_write_b16 v78, v1 offset:3328
	v_cvt_pk_bf16_f32 v1, v75, s0
	ds_write_b16 v78, v1 offset:3392
	v_cvt_pk_bf16_f32 v1, v17, s0
	ds_write_b16 v78, v1 offset:3456
	v_cvt_pk_bf16_f32 v1, v61, s0
	ds_write_b16 v78, v1 offset:3520
	s_waitcnt lgkmcnt(0)
	ds_read_b128 v[2:5], v80
	ds_read_b128 v[6:9], v10
	ds_read_b128 v[10:13], v21
	ds_read_b128 v[14:17], v23
	s_waitcnt lgkmcnt(3)
	global_store_dwordx4 v[18:19], v[2:5], off offset:128 sc1
	s_waitcnt lgkmcnt(2)
	global_store_dwordx4 v[24:25], v[6:9], off offset:128 sc1
	s_waitcnt lgkmcnt(1)
	global_store_dwordx4 v[26:27], v[10:13], off offset:128 sc1
	s_waitcnt lgkmcnt(0)
	global_store_dwordx4 v[30:31], v[14:17], off offset:128 sc1
	s_waitcnt lgkmcnt(0)
	s_waitcnt lgkmcnt(0)
	s_barrier

.LBB0_833:
	ds_read_b64_tr_b16 v[76:77], v147 offset:49152
	ds_read_b64_tr_b16 v[78:79], v147 offset:49664
	v_cvt_pk_bf16_f32 v68, v68, v69
	v_cvt_pk_bf16_f32 v69, v70, v71
	v_cvt_pk_bf16_f32 v70, v72, v73
	v_cvt_pk_bf16_f32 v71, v74, v75
	s_waitcnt lgkmcnt(0)
	v_mfma_f32_32x32x16_bf16 v[18:33], v[164:167], v[76:79], v[18:33]
	ds_read_b64_tr_b16 v[76:77], v147 offset:50176
	ds_read_b64_tr_b16 v[78:79], v147 offset:50688
	v_add_f32_e32 v67, v213, v67
	s_waitcnt lgkmcnt(0)
	v_mfma_f32_32x32x16_bf16 v[18:33], v[168:171], v[76:79], v[18:33]
	ds_read_b64_tr_b16 v[76:77], v147 offset:51200
	ds_read_b64_tr_b16 v[78:79], v147 offset:51712
	ds_read_b64_tr_b16 v[80:81], v147 offset:52224
	ds_read_b64_tr_b16 v[82:83], v147 offset:52736
	ds_read_b64_tr_b16 v[72:73], v147 offset:53248
	ds_read_b64_tr_b16 v[74:75], v147 offset:53760
	s_waitcnt lgkmcnt(0)
	v_mfma_f32_32x32x16_bf16 v[50:65], v[164:167], v[72:75], v[50:65]
	ds_read_b64_tr_b16 v[72:73], v147 offset:54272
	ds_read_b64_tr_b16 v[74:75], v147 offset:54784
	s_waitcnt lgkmcnt(0)
	v_mfma_f32_32x32x16_bf16 v[50:65], v[168:171], v[72:75], v[50:65]
	ds_read_b64_tr_b16 v[72:73], v147 offset:55296
	ds_read_b64_tr_b16 v[74:75], v147 offset:55808
	s_waitcnt lgkmcnt(0)
	v_mfma_f32_32x32x16_bf16 v[50:65], v[172:175], v[72:75], v[50:65]
	ds_read_b64_tr_b16 v[72:73], v147 offset:56320
	ds_read_b64_tr_b16 v[74:75], v147 offset:56832
	v_mfma_f32_32x32x16_bf16 v[18:33], v[172:175], v[76:79], v[18:33]
	v_add_u32_e32 v76, 0xe000, v147
	s_waitcnt lgkmcnt(0)
	v_mfma_f32_32x32x16_bf16 v[50:65], v[68:71], v[72:75], v[50:65]
	ds_read_b64_tr_b16 v[72:73], v76 offset:24576
	ds_read_b64_tr_b16 v[74:75], v76 offset:25088
	s_waitcnt lgkmcnt(0)
	v_mfma_f32_32x32x16_bf16 v[34:49], v[164:167], v[72:75], v[34:49]
	ds_read_b64_tr_b16 v[72:73], v76 offset:25600
	ds_read_b64_tr_b16 v[74:75], v76 offset:26112
	s_waitcnt lgkmcnt(0)
	v_mfma_f32_32x32x16_bf16 v[34:49], v[168:171], v[72:75], v[34:49]
	ds_read_b64_tr_b16 v[72:73], v76 offset:26624
	ds_read_b64_tr_b16 v[74:75], v76 offset:27136
	s_waitcnt lgkmcnt(0)
	v_mfma_f32_32x32x16_bf16 v[34:49], v[172:175], v[72:75], v[34:49]
	ds_read_b64_tr_b16 v[72:73], v76 offset:27648
	ds_read_b64_tr_b16 v[74:75], v76 offset:28160
	s_waitcnt lgkmcnt(0)
	v_mfma_f32_32x32x16_bf16 v[34:49], v[68:71], v[72:75], v[34:49]
	ds_read_b64_tr_b16 v[72:73], v76 offset:28672
	ds_read_b64_tr_b16 v[74:75], v76 offset:29184
	s_waitcnt lgkmcnt(0)
	v_mfma_f32_32x32x16_bf16 v[2:17], v[164:167], v[72:75], v[2:17]
	ds_read_b64_tr_b16 v[72:73], v76 offset:29696
	ds_read_b64_tr_b16 v[74:75], v76 offset:30208
	s_waitcnt lgkmcnt(0)
	v_mfma_f32_32x32x16_bf16 v[2:17], v[168:171], v[72:75], v[2:17]
	ds_read_b64_tr_b16 v[72:73], v76 offset:30720
	ds_read_b64_tr_b16 v[74:75], v76 offset:31232
	s_waitcnt lgkmcnt(0)
	v_mfma_f32_32x32x16_bf16 v[2:17], v[172:175], v[72:75], v[2:17]
	ds_read_b64_tr_b16 v[72:73], v76 offset:31744
	ds_read_b64_tr_b16 v[74:75], v76 offset:32256
	v_mfma_f32_32x32x16_bf16 v[18:33], v[68:71], v[80:83], v[18:33]
	s_waitcnt lgkmcnt(0)
	v_mfma_f32_32x32x16_bf16 v[2:17], v[68:71], v[72:75], v[2:17]
	s_setprio 0
	v_mov_b32_e32 v68, v67
	s_nop 1
	v_permlane32_swap_b32_e32 v67, v68
	v_cmp_gt_u32_e32 vcc, 32, v207
	s_and_saveexec_b64 s[4:5], vcc
	v_add_f32_e32 v67, v67, v68
	ds_write_b32 v1, v67 offset:128
	s_or_b64 exec, exec, s[4:5]
	s_waitcnt lgkmcnt(0)
	ds_read_b128 v[68:71], v66 offset:128
	ds_read_b128 v[72:75], v66 offset:160
	s_mov_b64 s[4:5], s[0:1]
	s_lshl_b32 s12, s12, 12
	s_lshl_b64 s[8:9], s[80:81], 1
	s_waitcnt lgkmcnt(1)
	v_rcp_f32_e32 v1, v68
	v_rcp_f32_e32 v67, v69
	v_rcp_f32_e32 v76, v70
	v_rcp_f32_e32 v77, v71
	s_waitcnt lgkmcnt(0)
	v_rcp_f32_e32 v78, v72
	ds_read_b128 v[68:71], v66 offset:192
	v_rcp_f32_e32 v79, v73
	v_rcp_f32_e32 v80, v74
	v_rcp_f32_e32 v81, v75
	ds_read_b128 v[72:75], v66 offset:224
	s_load_dwordx2 s[4:5], s[4:5], 0xa0
	s_waitcnt lgkmcnt(0)
	v_rcp_f32_e32 v66, v68
	v_rcp_f32_e32 v68, v69
	v_rcp_f32_e32 v69, v70
	v_rcp_f32_e32 v70, v71
	s_add_u32 s4, s4, s8
	s_addc_u32 s5, s5, s9
	s_add_u32 s4, s4, s64
	s_addc_u32 s5, s5, s65
	s_add_i32 s8, s12, 0
	v_mul_f32_e32 v18, v18, v1
	v_mul_f32_e32 v50, v50, v1
	v_mul_f32_e32 v34, v34, v1
	v_mul_f32_e32 v1, v2, v1
	v_mul_f32_e32 v19, v19, v67
	v_mul_f32_e32 v51, v51, v67
	v_mul_f32_e32 v35, v35, v67
	v_mul_f32_e32 v67, v3, v67
	s_add_i32 s8, s8, 0x16800
	v_lshlrev_b32_e32 v2, 9, v209
	v_lshlrev_b32_e32 v3, 1, v208
	v_rcp_f32_e32 v71, v72
	v_rcp_f32_e32 v72, v73
	v_rcp_f32_e32 v73, v74
	v_rcp_f32_e32 v74, v75
	v_mul_f32_e32 v75, v4, v76
	v_mul_f32_e32 v4, v21, v77
	v_mul_f32_e32 v21, v53, v77
	v_mul_f32_e32 v53, v5, v77
	v_mul_f32_e32 v5, v22, v78
	v_mul_f32_e32 v22, v54, v78
	v_mul_f32_e32 v54, v6, v78
	v_mul_f32_e32 v6, v23, v79
	v_mul_f32_e32 v23, v55, v79
	v_mul_f32_e32 v55, v7, v79
	v_mul_f32_e32 v7, v24, v80
	v_mul_f32_e32 v24, v56, v80
	v_mul_f32_e32 v56, v8, v80
	v_mul_f32_e32 v8, v25, v81
	v_mul_f32_e32 v25, v57, v81
	v_mul_f32_e32 v57, v9, v81
	v_mul_f32_e32 v9, v26, v66
	v_mul_f32_e32 v26, v58, v66
	v_mul_f32_e32 v42, v42, v66
	v_mul_f32_e32 v58, v10, v66
	v_mul_f32_e32 v27, v27, v68
	v_mul_f32_e32 v59, v59, v68
	v_mul_f32_e32 v43, v43, v68
	v_mul_f32_e32 v66, v11, v68
	v_add3_u32 v68, s8, v2, v3
	v_lshlrev_b32_e32 v2, 1, v210
	v_and_b32_e32 v2, 0x70, v2
	v_mov_b32_e32 v3, v146
	v_mul_f32_e32 v29, v29, v70
	v_mul_f32_e32 v61, v61, v70
	v_mul_f32_e32 v45, v45, v70
	v_mul_f32_e32 v13, v13, v70
	v_add_u32_e32 v70, s8, v2
	v_lshl_add_u64 v[2:3], s[4:5], 0, v[2:3]
	v_lshl_add_u64 v[10:11], v[2:3], 0, s[86:87]
	v_cvt_pk_bf16_f32 v2, v18, s0
	ds_write_b16 v68, v2
	v_cvt_pk_bf16_f32 v2, v50, s0
	ds_write_b16 v68, v2 offset:64
	v_cvt_pk_bf16_f32 v2, v19, s0
	v_mul_f32_e32 v20, v20, v76
	ds_write_b16 v68, v2 offset:128
	v_cvt_pk_bf16_f32 v2, v51, s0
	v_mul_f32_e32 v52, v52, v76
	ds_write_b16 v68, v2 offset:192
	v_cvt_pk_bf16_f32 v2, v20, s0
	ds_write_b16 v68, v2 offset:256
	v_cvt_pk_bf16_f32 v2, v52, s0
	ds_write_b16 v68, v2 offset:320
	v_cvt_pk_bf16_f32 v2, v4, s0
	ds_write_b16 v68, v2 offset:384
	v_cvt_pk_bf16_f32 v2, v21, s0
	ds_write_b16 v68, v2 offset:448
	v_cvt_pk_bf16_f32 v2, v5, s0
	ds_write_b16 v68, v2 offset:1024
	v_cvt_pk_bf16_f32 v2, v22, s0
	ds_write_b16 v68, v2 offset:1088
	v_cvt_pk_bf16_f32 v2, v6, s0
	ds_write_b16 v68, v2 offset:1152
	v_cvt_pk_bf16_f32 v2, v23, s0
	ds_write_b16 v68, v2 offset:1216
	v_cvt_pk_bf16_f32 v2, v7, s0
	ds_write_b16 v68, v2 offset:1280
	v_cvt_pk_bf16_f32 v2, v24, s0
	ds_write_b16 v68, v2 offset:1344
	v_cvt_pk_bf16_f32 v2, v8, s0
	ds_write_b16 v68, v2 offset:1408
	v_cvt_pk_bf16_f32 v2, v25, s0
	ds_write_b16 v68, v2 offset:1472
	v_cvt_pk_bf16_f32 v2, v9, s0
	ds_write_b16 v68, v2 offset:2048
	v_cvt_pk_bf16_f32 v2, v26, s0
	ds_write_b16 v68, v2 offset:2112
	v_cvt_pk_bf16_f32 v2, v27, s0
	v_mul_f32_e32 v28, v28, v69
	ds_write_b16 v68, v2 offset:2176
	v_cvt_pk_bf16_f32 v2, v59, s0
	v_mul_f32_e32 v60, v60, v69
	ds_write_b16 v68, v2 offset:2240
	v_cvt_pk_bf16_f32 v2, v28, s0
	ds_write_b16 v68, v2 offset:2304
	v_cvt_pk_bf16_f32 v2, v60, s0
	ds_write_b16 v68, v2 offset:2368
	v_cvt_pk_bf16_f32 v2, v29, s0
	v_mul_f32_e32 v30, v30, v71
	ds_write_b16 v68, v2 offset:2432
	v_cvt_pk_bf16_f32 v2, v61, s0
	v_mul_f32_e32 v62, v62, v71
	ds_write_b16 v68, v2 offset:2496
	v_cvt_pk_bf16_f32 v2, v30, s0
	v_mul_f32_e32 v31, v31, v72
	ds_write_b16 v68, v2 offset:3072
	v_cvt_pk_bf16_f32 v2, v62, s0
	v_mul_f32_e32 v63, v63, v72
	ds_write_b16 v68, v2 offset:3136
	v_cvt_pk_bf16_f32 v2, v31, s0
	v_mul_f32_e32 v32, v32, v73
	ds_write_b16 v68, v2 offset:3200
	v_cvt_pk_bf16_f32 v2, v63, s0
	v_mul_f32_e32 v64, v64, v73
	ds_write_b16 v68, v2 offset:3264
	v_cvt_pk_bf16_f32 v2, v32, s0
	v_mul_f32_e32 v33, v33, v74
	ds_write_b16 v68, v2 offset:3328
	v_cvt_pk_bf16_f32 v2, v64, s0
	v_mul_f32_e32 v65, v65, v74
	ds_write_b16 v68, v2 offset:3392
	v_cvt_pk_bf16_f32 v2, v33, s0
	ds_write_b16 v68, v2 offset:3456
	v_cvt_pk_bf16_f32 v2, v65, s0
	v_mul_f32_e32 v44, v44, v69
	v_mul_f32_e32 v12, v12, v69
	v_lshrrev_b32_e32 v69, 3, v207
	ds_write_b16 v68, v2 offset:3520
	v_mul_f32_e32 v46, v46, v71
	v_mul_f32_e32 v14, v14, v71
	v_lshl_add_u32 v71, v69, 7, v70
	s_waitcnt lgkmcnt(0)
	ds_read_b128 v[2:5], v71
	v_or_b32_e32 v20, 8, v69
	v_lshlrev_b32_e32 v6, 11, v69
	v_mov_b32_e32 v7, v146
	v_lshl_add_u32 v26, v20, 7, v70
	v_lshl_add_u64 v[18:19], v[10:11], 0, v[6:7]
	ds_read_b128 v[6:9], v26
	s_waitcnt lgkmcnt(1)
	global_store_dwordx4 v[18:19], v[2:5], off sc1
	v_or_b32_e32 v24, 24, v69
	v_lshl_add_u32 v28, v24, 7, v70
	v_lshlrev_b32_e32 v2, 11, v20
	v_mov_b32_e32 v3, v146
	v_lshl_add_u64 v[20:21], v[10:11], 0, v[2:3]
	s_waitcnt lgkmcnt(0)
	global_store_dwordx4 v[20:21], v[6:9], off sc1
	v_cvt_pk_bf16_f32 v1, v1, s0
	v_mul_f32_e32 v36, v36, v76
	v_or_b32_e32 v6, 16, v69
	v_lshl_add_u32 v27, v6, 7, v70
	ds_read_b128 v[2:5], v27
	v_lshlrev_b32_e32 v6, 11, v6
	v_mov_b32_e32 v7, v146
	v_lshl_add_u64 v[22:23], v[10:11], 0, v[6:7]
	ds_read_b128 v[6:9], v28
	s_waitcnt lgkmcnt(1)
	global_store_dwordx4 v[22:23], v[2:5], off sc1
	v_mul_f32_e32 v37, v37, v77
	v_mul_f32_e32 v38, v38, v78
	v_lshlrev_b32_e32 v2, 11, v24
	v_mov_b32_e32 v3, v146
	v_lshl_add_u64 v[24:25], v[10:11], 0, v[2:3]
	s_waitcnt lgkmcnt(0)
	global_store_dwordx4 v[24:25], v[6:9], off sc1
	s_waitcnt lgkmcnt(0)
	ds_write_b16 v68, v1 offset:64
	v_cvt_pk_bf16_f32 v1, v35, s0
	ds_write_b16 v68, v1 offset:128
	v_cvt_pk_bf16_f32 v1, v67, s0
	ds_write_b16 v68, v1 offset:192
	v_cvt_pk_bf16_f32 v1, v36, s0
	ds_write_b16 v68, v1 offset:256
	v_cvt_pk_bf16_f32 v1, v75, s0
	ds_write_b16 v68, v1 offset:320
	v_cvt_pk_bf16_f32 v1, v37, s0
	ds_write_b16 v68, v1 offset:384
	v_cvt_pk_bf16_f32 v1, v53, s0
	ds_write_b16 v68, v1 offset:448
	v_cvt_pk_bf16_f32 v1, v38, s0
	v_mul_f32_e32 v39, v39, v79
	ds_write_b16 v68, v1 offset:1024
	v_cvt_pk_bf16_f32 v1, v54, s0
	ds_write_b16 v68, v1 offset:1088
	v_cvt_pk_bf16_f32 v1, v39, s0
	v_mul_f32_e32 v40, v40, v80
	ds_write_b16 v68, v1 offset:1152
	v_cvt_pk_bf16_f32 v1, v55, s0
	ds_write_b16 v68, v1 offset:1216
	v_cvt_pk_bf16_f32 v1, v40, s0
	v_mul_f32_e32 v41, v41, v81
	ds_write_b16 v68, v1 offset:1280
	v_cvt_pk_bf16_f32 v1, v56, s0
	ds_write_b16 v68, v1 offset:1344
	v_cvt_pk_bf16_f32 v1, v41, s0
	ds_write_b16 v68, v1 offset:1408
	v_cvt_pk_bf16_f32 v1, v57, s0
	ds_write_b16 v68, v1 offset:1472
	v_cvt_pk_bf16_f32 v1, v42, s0
	ds_write_b16 v68, v1 offset:2048
	v_cvt_pk_bf16_f32 v1, v58, s0
	ds_write_b16 v68, v1 offset:2112
	v_cvt_pk_bf16_f32 v1, v43, s0
	ds_write_b16 v68, v1 offset:2176
	v_cvt_pk_bf16_f32 v1, v66, s0
	ds_write_b16 v68, v1 offset:2240
	v_cvt_pk_bf16_f32 v1, v44, s0
	ds_write_b16 v68, v1 offset:2304
	v_cvt_pk_bf16_f32 v1, v12, s0
	ds_write_b16 v68, v1 offset:2368
	v_cvt_pk_bf16_f32 v1, v45, s0
	ds_write_b16 v68, v1 offset:2432
	v_cvt_pk_bf16_f32 v1, v13, s0
	ds_write_b16 v68, v1 offset:2496
	v_cvt_pk_bf16_f32 v1, v46, s0
	v_mul_f32_e32 v47, v47, v72
	ds_write_b16 v68, v1 offset:3072
	v_cvt_pk_bf16_f32 v1, v14, s0
	v_mul_f32_e32 v15, v15, v72
	ds_write_b16 v68, v1 offset:3136
	v_cvt_pk_bf16_f32 v1, v47, s0
	v_mul_f32_e32 v48, v48, v73
	ds_write_b16 v68, v1 offset:3200
	v_cvt_pk_bf16_f32 v1, v15, s0
	v_mul_f32_e32 v16, v16, v73
	ds_write_b16 v68, v1 offset:3264
	v_cvt_pk_bf16_f32 v1, v48, s0
	v_mul_f32_e32 v49, v49, v74
	ds_write_b16 v68, v1 offset:3328
	v_cvt_pk_bf16_f32 v1, v16, s0
	v_mul_f32_e32 v17, v17, v74
	ds_write_b16 v68, v1 offset:3392
	v_cvt_pk_bf16_f32 v1, v49, s0
	v_cvt_pk_bf16_f32 v2, v34, s0
	ds_write_b16 v68, v1 offset:3456
	v_cvt_pk_bf16_f32 v1, v17, s0
	ds_write_b16 v68, v2
	ds_write_b16 v68, v1 offset:3520
	s_waitcnt lgkmcnt(0)
	ds_read_b128 v[2:5], v71
	ds_read_b128 v[6:9], v26
	ds_read_b128 v[10:13], v27
	ds_read_b128 v[14:17], v28
	s_waitcnt lgkmcnt(3)
	global_store_dwordx4 v[18:19], v[2:5], off offset:128 sc1
	s_waitcnt lgkmcnt(2)
	global_store_dwordx4 v[20:21], v[6:9], off offset:128 sc1
	s_waitcnt lgkmcnt(1)
	global_store_dwordx4 v[22:23], v[10:13], off offset:128 sc1
	s_waitcnt lgkmcnt(0)
	global_store_dwordx4 v[24:25], v[14:17], off offset:128 sc1
	s_waitcnt lgkmcnt(0)
	s_waitcnt vmcnt(0)
	s_mov_b64 s[4:5], s[0:1]
	s_waitcnt lgkmcnt(0)
	s_barrier
	s_load_dwordx2 s[22:23], s[4:5], 0xa0
	v_mov_b32_e32 v34, v202
	v_mov_b32_e32 v2, v0
	v_readfirstlane_b32 s14, v34
	v_mov_b32_e32 v3, v0
	v_mov_b32_e32 v4, v0
	v_mov_b32_e32 v5, v0
	v_mov_b32_e32 v6, v0
	v_mov_b32_e32 v7, v0
	v_mov_b32_e32 v8, v0
	v_mov_b32_e32 v9, v0
	v_mov_b32_e32 v10, v0
	v_mov_b32_e32 v11, v0
	v_mov_b32_e32 v12, v0
	v_mov_b32_e32 v13, v0
	v_mov_b32_e32 v14, v0
	v_mov_b32_e32 v15, v0
	s_ashr_i32 s12, s14, 6
	v_mov_b32_e32 v1, v0
	v_mov_b64_e32 v[16:17], v[14:15]
	v_mov_b64_e32 v[14:15], v[12:13]
	v_mov_b64_e32 v[12:13], v[10:11]
	v_mov_b64_e32 v[10:11], v[8:9]
	v_mov_b64_e32 v[8:9], v[6:7]
	v_mov_b64_e32 v[6:7], v[4:5]
	v_mov_b64_e32 v[4:5], v[2:3]
	v_mov_b64_e32 v[2:3], v[0:1]
	s_cmp_lt_i32 s12, 4
	s_cbranch_scc1 .LBB0_837
	s_setprio 1

.LBB0_969:
	v_lshl_or_b32 v168, s10, 8, v188
	v_lshl_add_u32 v172, s40, 8, v186
	v_ashrrev_i32_e32 v169, 31, v168
	v_lshlrev_b64 v[204:205], 1, v[168:169]
	v_ashrrev_i32_e32 v173, 31, v172
	v_lshl_add_u64 v[170:171], s[16:17], 0, v[204:205]
	v_lshlrev_b64 v[206:207], 11, v[172:173]
	v_lshl_add_u64 v[128:129], v[170:171], 0, v[206:207]
	global_load_dwordx4 v[192:195], v[128:129], off
	global_load_dwordx4 v[198:201], v[128:129], off offset:256
	v_or_b32_e32 v182, 16, v172
	v_or_b32_e32 v178, 32, v172
	v_or_b32_e32 v174, 48, v172
	v_ashrrev_i32_e32 v183, 31, v182
	v_ashrrev_i32_e32 v179, 31, v178
	v_ashrrev_i32_e32 v175, 31, v174
	v_lshlrev_b64 v[184:185], 11, v[182:183]
	v_lshlrev_b64 v[180:181], 11, v[178:179]
	v_lshlrev_b64 v[176:177], 11, v[174:175]
	v_lshl_add_u64 v[128:129], v[170:171], 0, v[184:185]
	v_lshl_add_u64 v[130:131], v[170:171], 0, v[180:181]
	v_lshl_add_u64 v[208:209], v[170:171], 0, v[176:177]
	global_load_dwordx4 v[148:151], v[128:129], off
	global_load_dwordx4 v[144:147], v[128:129], off offset:256
	global_load_dwordx4 v[140:143], v[130:131], off
	global_load_dwordx4 v[136:139], v[130:131], off offset:256
	global_load_dwordx4 v[132:135], v[208:209], off
	s_nop 0
	global_load_dwordx4 v[128:131], v[208:209], off offset:256
	s_lshl_b32 s40, s10, 2
	s_ashr_i32 s41, s40, 31
	s_waitcnt vmcnt(0)
	v_lshlrev_b32_e32 v208, 16, v192
	v_and_b32_e32 v209, 0xffff0000, v192
	v_lshlrev_b32_e32 v192, 16, v193
	v_and_b32_e32 v193, 0xffff0000, v193
	v_lshlrev_b32_e32 v210, 16, v194
	v_and_b32_e32 v211, 0xffff0000, v194
	v_lshlrev_b32_e32 v194, 16, v195
	v_and_b32_e32 v195, 0xffff0000, v195
	v_lshlrev_b32_e32 v212, 16, v198
	v_and_b32_e32 v213, 0xffff0000, v198
	v_lshlrev_b32_e32 v198, 16, v199
	v_and_b32_e32 v199, 0xffff0000, v199
	v_lshlrev_b32_e32 v214, 16, v200
	v_and_b32_e32 v215, 0xffff0000, v200
	v_lshlrev_b32_e32 v200, 16, v201
	v_and_b32_e32 v201, 0xffff0000, v201
	v_pk_add_f32 v[126:127], v[126:127], v[192:193]
	v_pk_add_f32 v[124:125], v[124:125], v[208:209]
	v_pk_add_f32 v[122:123], v[122:123], v[194:195]
	v_pk_add_f32 v[120:121], v[120:121], v[210:211]
	v_pk_add_f32 v[118:119], v[118:119], v[198:199]
	v_pk_add_f32 v[116:117], v[116:117], v[212:213]
	v_pk_add_f32 v[192:193], v[114:115], v[200:201]
	v_pk_add_f32 v[194:195], v[112:113], v[214:215]
	v_mul_f32_e32 v198, v125, v125
	v_mul_f32_e32 v199, v127, v127
	v_mul_f32_e32 v200, v121, v121
	v_mul_f32_e32 v201, v123, v123
	v_cvt_pk_bf16_f32 v112, v124, v125
	v_cvt_pk_bf16_f32 v113, v126, v127
	v_cvt_pk_bf16_f32 v114, v120, v121
	v_cvt_pk_bf16_f32 v115, v122, v123
	v_mul_f32_e32 v121, v117, v117
	v_mul_f32_e32 v123, v119, v119
	v_mul_f32_e32 v125, v195, v195
	v_mul_f32_e32 v127, v193, v193
	v_fmac_f32_e32 v198, v124, v124
	v_fmac_f32_e32 v199, v126, v126
	v_fmac_f32_e32 v200, v120, v120
	v_fmac_f32_e32 v201, v122, v122
	v_fmac_f32_e32 v121, v116, v116
	v_fmac_f32_e32 v123, v118, v118
	v_fmac_f32_e32 v125, v194, v194
	v_fmac_f32_e32 v127, v192, v192
	v_add_f32_e32 v120, v198, v199
	v_add_f32_e32 v122, v200, v201
	v_add_f32_e32 v121, v121, v123
	v_add_f32_e32 v123, v125, v127
	v_add_f32_e32 v120, v120, v122
	v_add_f32_e32 v121, v121, v123
	v_add_f32_e32 v122, v120, v121
	ds_bpermute_b32 v123, v196, v122
	v_lshl_add_u64 v[120:121], s[16:17], 0, v[206:207]
	v_lshl_add_u64 v[120:121], v[120:121], 0, v[204:205]
	global_store_dwordx4 v[120:121], v[112:115], off sc1
	s_waitcnt lgkmcnt(0)
	s_nop 0
	v_add_f32_e32 v112, v122, v123
	ds_bpermute_b32 v113, v197, v112
	v_cvt_pk_bf16_f32 v114, v116, v117
	v_cvt_pk_bf16_f32 v115, v118, v119
	v_cvt_pk_bf16_f32 v116, v194, v195
	v_cvt_pk_bf16_f32 v117, v192, v193
	global_store_dwordx4 v[120:121], v[114:117], off offset:256 sc1
	s_and_saveexec_b64 s[4:5], s[6:7]
	s_cbranch_execz .LBB0_971
	v_lshlrev_b64 v[114:115], 6, v[172:173]
	v_lshl_add_u64 v[114:115], s[24:25], 0, v[114:115]
	v_lshl_add_u64 v[114:115], s[40:41], 2, v[114:115]
	s_lshl_b32 s10, s49, 2
	v_lshl_add_u64 v[114:115], v[114:115], 0, s[10:11]
	s_waitcnt lgkmcnt(0)
	v_add_f32_e32 v112, v112, v113
	global_store_dword v[114:115], v112, off
.LBB0_971:
	s_or_b64 exec, exec, s[4:5]
	v_lshlrev_b32_e32 v112, 16, v148
	s_waitcnt lgkmcnt(0)
	v_and_b32_e32 v113, 0xffff0000, v148
	v_lshlrev_b32_e32 v114, 16, v149
	v_and_b32_e32 v115, 0xffff0000, v149
	v_lshlrev_b32_e32 v116, 16, v150
	v_and_b32_e32 v117, 0xffff0000, v150
	v_lshlrev_b32_e32 v118, 16, v151
	v_and_b32_e32 v119, 0xffff0000, v151
	v_pk_add_f32 v[110:111], v[110:111], v[114:115]
	v_pk_add_f32 v[108:109], v[108:109], v[112:113]
	v_pk_add_f32 v[112:113], v[106:107], v[118:119]
	v_pk_add_f32 v[106:107], v[104:105], v[116:117]
	v_mul_f32_e32 v104, v109, v109
	v_mul_f32_e32 v105, v111, v111
	v_fmac_f32_e32 v104, v108, v108
	v_fmac_f32_e32 v105, v110, v110
	v_add_f32_e32 v104, v104, v105
	v_mul_f32_e32 v105, v107, v107
	v_mul_f32_e32 v114, v113, v113
	v_fmac_f32_e32 v105, v106, v106
	v_fmac_f32_e32 v114, v112, v112
	v_add_f32_e32 v105, v105, v114
	v_add_f32_e32 v116, v104, v105
	v_cvt_pk_bf16_f32 v104, v108, v109
	v_cvt_pk_bf16_f32 v105, v110, v111
	v_lshlrev_b32_e32 v108, 16, v144
	v_and_b32_e32 v109, 0xffff0000, v144
	v_lshlrev_b32_e32 v110, 16, v145
	v_and_b32_e32 v111, 0xffff0000, v145
	v_cvt_pk_bf16_f32 v106, v106, v107
	v_cvt_pk_bf16_f32 v107, v112, v113
	v_lshlrev_b32_e32 v112, 16, v146
	v_and_b32_e32 v113, 0xffff0000, v146
	v_pk_add_f32 v[102:103], v[102:103], v[110:111]
	v_pk_add_f32 v[100:101], v[100:101], v[108:109]
	v_lshlrev_b32_e32 v114, 16, v147
	v_and_b32_e32 v115, 0xffff0000, v147
	v_pk_add_f32 v[110:111], v[96:97], v[112:113]
	v_mul_f32_e32 v96, v101, v101
	v_mul_f32_e32 v97, v103, v103
	v_pk_add_f32 v[108:109], v[98:99], v[114:115]
	v_fmac_f32_e32 v96, v100, v100
	v_fmac_f32_e32 v97, v102, v102
	v_add_f32_e32 v96, v96, v97
	v_mul_f32_e32 v97, v111, v111
	v_mul_f32_e32 v98, v109, v109
	v_fmac_f32_e32 v97, v110, v110
	v_fmac_f32_e32 v98, v108, v108
	v_add_f32_e32 v97, v97, v98
	v_add_f32_e32 v96, v96, v97
	v_add_f32_e32 v99, v116, v96
	ds_bpermute_b32 v114, v196, v99
	v_lshl_add_u64 v[96:97], s[16:17], 0, v[184:185]
	v_lshl_add_u64 v[112:113], v[168:169], 1, v[96:97]
	global_store_dwordx4 v[112:113], v[104:107], off sc1
	v_cvt_pk_bf16_f32 v98, v100, v101
	s_waitcnt lgkmcnt(0)
	v_add_f32_e32 v96, v99, v114
	ds_bpermute_b32 v97, v197, v96
	v_cvt_pk_bf16_f32 v99, v102, v103
	v_cvt_pk_bf16_f32 v100, v110, v111
	v_cvt_pk_bf16_f32 v101, v108, v109
	global_store_dwordx4 v[112:113], v[98:101], off offset:256 sc1
	s_and_saveexec_b64 s[4:5], s[6:7]
	s_cbranch_execz .LBB0_973
	v_lshlrev_b64 v[98:99], 6, v[182:183]
	v_lshl_add_u64 v[98:99], s[24:25], 0, v[98:99]
	v_lshl_add_u64 v[98:99], s[40:41], 2, v[98:99]
	s_lshl_b32 s10, s49, 2
	v_lshl_add_u64 v[98:99], v[98:99], 0, s[10:11]
	s_waitcnt lgkmcnt(0)
	v_add_f32_e32 v96, v96, v97
	global_store_dword v[98:99], v96, off
.LBB0_973:
	s_or_b64 exec, exec, s[4:5]
	v_lshlrev_b32_e32 v96, 16, v140
	s_waitcnt lgkmcnt(0)
	v_and_b32_e32 v97, 0xffff0000, v140
	v_lshlrev_b32_e32 v98, 16, v141
	v_and_b32_e32 v99, 0xffff0000, v141
	v_lshlrev_b32_e32 v100, 16, v142
	v_and_b32_e32 v101, 0xffff0000, v142
	v_lshlrev_b32_e32 v102, 16, v143
	v_and_b32_e32 v103, 0xffff0000, v143
	v_pk_add_f32 v[94:95], v[94:95], v[98:99]
	v_pk_add_f32 v[92:93], v[92:93], v[96:97]
	v_pk_add_f32 v[96:97], v[90:91], v[102:103]
	v_pk_add_f32 v[90:91], v[88:89], v[100:101]
	v_mul_f32_e32 v88, v93, v93
	v_mul_f32_e32 v89, v95, v95
	v_fmac_f32_e32 v88, v92, v92
	v_fmac_f32_e32 v89, v94, v94
	v_add_f32_e32 v88, v88, v89
	v_mul_f32_e32 v89, v91, v91
	v_mul_f32_e32 v98, v97, v97
	v_fmac_f32_e32 v89, v90, v90
	v_fmac_f32_e32 v98, v96, v96
	v_add_f32_e32 v89, v89, v98
	v_add_f32_e32 v100, v88, v89
	v_cvt_pk_bf16_f32 v88, v92, v93
	v_cvt_pk_bf16_f32 v89, v94, v95
	v_lshlrev_b32_e32 v92, 16, v136
	v_and_b32_e32 v93, 0xffff0000, v136
	v_lshlrev_b32_e32 v94, 16, v137
	v_and_b32_e32 v95, 0xffff0000, v137
	v_cvt_pk_bf16_f32 v90, v90, v91
	v_cvt_pk_bf16_f32 v91, v96, v97
	v_lshlrev_b32_e32 v96, 16, v138
	v_and_b32_e32 v97, 0xffff0000, v138
	v_pk_add_f32 v[86:87], v[86:87], v[94:95]
	v_pk_add_f32 v[84:85], v[84:85], v[92:93]
	v_lshlrev_b32_e32 v98, 16, v139
	v_and_b32_e32 v99, 0xffff0000, v139
	v_pk_add_f32 v[94:95], v[80:81], v[96:97]
	v_mul_f32_e32 v80, v85, v85
	v_mul_f32_e32 v81, v87, v87
	v_pk_add_f32 v[92:93], v[82:83], v[98:99]
	v_fmac_f32_e32 v80, v84, v84
	v_fmac_f32_e32 v81, v86, v86
	v_add_f32_e32 v80, v80, v81
	v_mul_f32_e32 v81, v95, v95
	v_mul_f32_e32 v82, v93, v93
	v_fmac_f32_e32 v81, v94, v94
	v_fmac_f32_e32 v82, v92, v92
	v_add_f32_e32 v81, v81, v82
	v_add_f32_e32 v80, v80, v81
	v_add_f32_e32 v83, v100, v80
	ds_bpermute_b32 v98, v196, v83
	v_lshl_add_u64 v[80:81], s[16:17], 0, v[180:181]
	v_lshl_add_u64 v[96:97], v[168:169], 1, v[80:81]
	global_store_dwordx4 v[96:97], v[88:91], off sc1
	v_cvt_pk_bf16_f32 v82, v84, v85
	s_waitcnt lgkmcnt(0)
	v_add_f32_e32 v80, v83, v98
	ds_bpermute_b32 v81, v197, v80
	v_cvt_pk_bf16_f32 v83, v86, v87
	v_cvt_pk_bf16_f32 v84, v94, v95
	v_cvt_pk_bf16_f32 v85, v92, v93
	global_store_dwordx4 v[96:97], v[82:85], off offset:256 sc1
	s_and_saveexec_b64 s[4:5], s[6:7]
	s_cbranch_execz .LBB0_975
	v_lshlrev_b64 v[82:83], 6, v[178:179]
	v_lshl_add_u64 v[82:83], s[24:25], 0, v[82:83]
	v_lshl_add_u64 v[82:83], s[40:41], 2, v[82:83]
	s_lshl_b32 s10, s49, 2
	v_lshl_add_u64 v[82:83], v[82:83], 0, s[10:11]
	s_waitcnt lgkmcnt(0)
	v_add_f32_e32 v80, v80, v81
	global_store_dword v[82:83], v80, off
.LBB0_975:
	s_or_b64 exec, exec, s[4:5]
	v_lshlrev_b32_e32 v80, 16, v132
	s_waitcnt lgkmcnt(0)
	v_and_b32_e32 v81, 0xffff0000, v132
	v_lshlrev_b32_e32 v82, 16, v133
	v_and_b32_e32 v83, 0xffff0000, v133
	v_lshlrev_b32_e32 v84, 16, v134
	v_and_b32_e32 v85, 0xffff0000, v134
	v_lshlrev_b32_e32 v86, 16, v135
	v_and_b32_e32 v87, 0xffff0000, v135
	v_pk_add_f32 v[78:79], v[78:79], v[82:83]
	v_pk_add_f32 v[76:77], v[76:77], v[80:81]
	v_pk_add_f32 v[80:81], v[74:75], v[86:87]
	v_pk_add_f32 v[74:75], v[72:73], v[84:85]
	v_mul_f32_e32 v72, v77, v77
	v_mul_f32_e32 v73, v79, v79
	v_fmac_f32_e32 v72, v76, v76
	v_fmac_f32_e32 v73, v78, v78
	v_add_f32_e32 v72, v72, v73
	v_mul_f32_e32 v73, v75, v75
	v_mul_f32_e32 v82, v81, v81
	v_fmac_f32_e32 v73, v74, v74
	v_fmac_f32_e32 v82, v80, v80
	v_add_f32_e32 v73, v73, v82
	v_add_f32_e32 v84, v72, v73
	v_cvt_pk_bf16_f32 v72, v76, v77
	v_cvt_pk_bf16_f32 v73, v78, v79
	v_lshlrev_b32_e32 v76, 16, v128
	v_and_b32_e32 v77, 0xffff0000, v128
	v_lshlrev_b32_e32 v78, 16, v129
	v_and_b32_e32 v79, 0xffff0000, v129
	v_cvt_pk_bf16_f32 v74, v74, v75
	v_cvt_pk_bf16_f32 v75, v80, v81
	v_lshlrev_b32_e32 v80, 16, v130
	v_and_b32_e32 v81, 0xffff0000, v130
	v_pk_add_f32 v[70:71], v[70:71], v[78:79]
	v_pk_add_f32 v[68:69], v[68:69], v[76:77]
	v_lshlrev_b32_e32 v82, 16, v131
	v_and_b32_e32 v83, 0xffff0000, v131
	v_pk_add_f32 v[78:79], v[64:65], v[80:81]
	v_mul_f32_e32 v64, v69, v69
	v_mul_f32_e32 v65, v71, v71
	v_pk_add_f32 v[76:77], v[66:67], v[82:83]
	v_fmac_f32_e32 v64, v68, v68
	v_fmac_f32_e32 v65, v70, v70
	v_add_f32_e32 v64, v64, v65
	v_mul_f32_e32 v65, v79, v79
	v_mul_f32_e32 v66, v77, v77
	v_fmac_f32_e32 v65, v78, v78
	v_fmac_f32_e32 v66, v76, v76
	v_add_f32_e32 v65, v65, v66
	v_add_f32_e32 v64, v64, v65
	v_add_f32_e32 v67, v84, v64
	ds_bpermute_b32 v82, v196, v67
	v_lshl_add_u64 v[64:65], s[16:17], 0, v[176:177]
	v_lshl_add_u64 v[80:81], v[168:169], 1, v[64:65]
	global_store_dwordx4 v[80:81], v[72:75], off sc1
	v_cvt_pk_bf16_f32 v66, v68, v69
	s_waitcnt lgkmcnt(0)
	v_add_f32_e32 v64, v67, v82
	ds_bpermute_b32 v65, v197, v64
	v_cvt_pk_bf16_f32 v67, v70, v71
	v_cvt_pk_bf16_f32 v68, v78, v79
	v_cvt_pk_bf16_f32 v69, v76, v77
	global_store_dwordx4 v[80:81], v[66:69], off offset:256 sc1
	s_and_saveexec_b64 s[4:5], s[6:7]
	s_cbranch_execz .LBB0_977
	v_lshlrev_b64 v[66:67], 6, v[174:175]
	v_lshl_add_u64 v[66:67], s[24:25], 0, v[66:67]
	v_lshl_add_u64 v[66:67], s[40:41], 2, v[66:67]
	s_lshl_b32 s10, s49, 2
	v_lshl_add_u64 v[66:67], v[66:67], 0, s[10:11]
	s_waitcnt lgkmcnt(0)
	v_add_f32_e32 v64, v64, v65
	global_store_dword v[66:67], v64, off
.LBB0_977:
	s_or_b64 exec, exec, s[4:5]
	v_add_u32_e32 v100, 0x80, v172
	v_ashrrev_i32_e32 v101, 31, v100
	v_lshlrev_b64 v[110:111], 11, v[100:101]
	s_waitcnt lgkmcnt(0)
	v_lshl_add_u64 v[64:65], v[170:171], 0, v[110:111]
	global_load_dwordx4 v[102:105], v[64:65], off
	global_load_dwordx4 v[106:109], v[64:65], off offset:256
	v_add_u32_e32 v96, 0x90, v172
	v_add_u32_e32 v92, 0xa0, v172
	v_add_u32_e32 v88, 0xb0, v172
	v_ashrrev_i32_e32 v97, 31, v96
	v_ashrrev_i32_e32 v93, 31, v92
	v_ashrrev_i32_e32 v89, 31, v88
	v_lshlrev_b64 v[98:99], 11, v[96:97]
	v_lshlrev_b64 v[94:95], 11, v[92:93]
	v_lshlrev_b64 v[90:91], 11, v[88:89]
	v_lshl_add_u64 v[64:65], v[170:171], 0, v[98:99]
	v_lshl_add_u64 v[66:67], v[170:171], 0, v[94:95]
	v_lshl_add_u64 v[112:113], v[170:171], 0, v[90:91]
	global_load_dwordx4 v[84:87], v[64:65], off
	global_load_dwordx4 v[80:83], v[64:65], off offset:256
	global_load_dwordx4 v[76:79], v[66:67], off
	global_load_dwordx4 v[72:75], v[66:67], off offset:256
	global_load_dwordx4 v[68:71], v[112:113], off
	s_nop 0
	global_load_dwordx4 v[64:67], v[112:113], off offset:256
	s_waitcnt vmcnt(7)
	v_lshlrev_b32_e32 v112, 16, v102
	v_and_b32_e32 v113, 0xffff0000, v102
	v_lshlrev_b32_e32 v102, 16, v103
	v_and_b32_e32 v103, 0xffff0000, v103
	v_lshlrev_b32_e32 v114, 16, v104
	v_and_b32_e32 v115, 0xffff0000, v104
	v_lshlrev_b32_e32 v104, 16, v105
	v_and_b32_e32 v105, 0xffff0000, v105
	s_waitcnt vmcnt(6)
	v_lshlrev_b32_e32 v116, 16, v106
	v_and_b32_e32 v117, 0xffff0000, v106
	v_lshlrev_b32_e32 v106, 16, v107
	v_and_b32_e32 v107, 0xffff0000, v107
	v_lshlrev_b32_e32 v118, 16, v108
	v_and_b32_e32 v119, 0xffff0000, v108
	v_lshlrev_b32_e32 v108, 16, v109
	v_and_b32_e32 v109, 0xffff0000, v109
	v_pk_add_f32 v[62:63], v[62:63], v[102:103]
	v_pk_add_f32 v[60:61], v[60:61], v[112:113]
	v_pk_add_f32 v[58:59], v[58:59], v[104:105]
	v_pk_add_f32 v[56:57], v[56:57], v[114:115]
	v_pk_add_f32 v[54:55], v[54:55], v[106:107]
	v_pk_add_f32 v[52:53], v[52:53], v[116:117]
	v_pk_add_f32 v[102:103], v[50:51], v[108:109]
	v_pk_add_f32 v[104:105], v[48:49], v[118:119]
	v_mul_f32_e32 v106, v61, v61
	v_mul_f32_e32 v107, v63, v63
	v_mul_f32_e32 v108, v57, v57
	v_mul_f32_e32 v109, v59, v59
	v_cvt_pk_bf16_f32 v48, v60, v61
	v_cvt_pk_bf16_f32 v49, v62, v63
	v_cvt_pk_bf16_f32 v50, v56, v57
	v_cvt_pk_bf16_f32 v51, v58, v59
	v_mul_f32_e32 v57, v53, v53
	v_mul_f32_e32 v59, v55, v55
	v_mul_f32_e32 v61, v105, v105
	v_mul_f32_e32 v63, v103, v103
	v_fmac_f32_e32 v106, v60, v60
	v_fmac_f32_e32 v107, v62, v62
	v_fmac_f32_e32 v108, v56, v56
	v_fmac_f32_e32 v109, v58, v58
	v_fmac_f32_e32 v57, v52, v52
	v_fmac_f32_e32 v59, v54, v54
	v_fmac_f32_e32 v61, v104, v104
	v_fmac_f32_e32 v63, v102, v102
	v_add_f32_e32 v56, v106, v107
	v_add_f32_e32 v58, v108, v109
	v_add_f32_e32 v57, v57, v59
	v_add_f32_e32 v59, v61, v63
	v_add_f32_e32 v56, v56, v58
	v_add_f32_e32 v57, v57, v59
	v_add_f32_e32 v58, v56, v57
	ds_bpermute_b32 v59, v196, v58
	v_lshl_add_u64 v[56:57], s[16:17], 0, v[110:111]
	v_lshl_add_u64 v[56:57], v[168:169], 1, v[56:57]
	global_store_dwordx4 v[56:57], v[48:51], off sc1
	s_waitcnt lgkmcnt(0)
	s_nop 0
	v_add_f32_e32 v48, v58, v59
	ds_bpermute_b32 v49, v197, v48
	v_cvt_pk_bf16_f32 v50, v52, v53
	v_cvt_pk_bf16_f32 v51, v54, v55
	v_cvt_pk_bf16_f32 v52, v104, v105
	v_cvt_pk_bf16_f32 v53, v102, v103
	global_store_dwordx4 v[56:57], v[50:53], off offset:256 sc1
	s_and_saveexec_b64 s[4:5], s[6:7]
	s_cbranch_execz .LBB0_979
	v_lshlrev_b64 v[50:51], 6, v[100:101]
	v_lshl_add_u64 v[50:51], s[24:25], 0, v[50:51]
	v_lshl_add_u64 v[50:51], s[40:41], 2, v[50:51]
	s_lshl_b32 s10, s49, 2
	v_lshl_add_u64 v[50:51], v[50:51], 0, s[10:11]
	s_waitcnt lgkmcnt(0)
	v_add_f32_e32 v48, v48, v49
	global_store_dword v[50:51], v48, off
.LBB0_979:
	s_or_b64 exec, exec, s[4:5]
	s_waitcnt vmcnt(7)
	v_lshlrev_b32_e32 v48, 16, v84
	s_waitcnt lgkmcnt(0)
	v_and_b32_e32 v49, 0xffff0000, v84
	v_lshlrev_b32_e32 v50, 16, v85
	v_and_b32_e32 v51, 0xffff0000, v85
	v_lshlrev_b32_e32 v52, 16, v86
	v_and_b32_e32 v53, 0xffff0000, v86
	v_lshlrev_b32_e32 v54, 16, v87
	v_and_b32_e32 v55, 0xffff0000, v87
	v_pk_add_f32 v[46:47], v[46:47], v[50:51]
	v_pk_add_f32 v[44:45], v[44:45], v[48:49]
	v_pk_add_f32 v[48:49], v[42:43], v[54:55]
	v_pk_add_f32 v[42:43], v[40:41], v[52:53]
	v_mul_f32_e32 v40, v45, v45
	v_mul_f32_e32 v41, v47, v47
	v_fmac_f32_e32 v40, v44, v44
	v_fmac_f32_e32 v41, v46, v46
	v_add_f32_e32 v40, v40, v41
	v_mul_f32_e32 v41, v43, v43
	v_mul_f32_e32 v50, v49, v49
	v_fmac_f32_e32 v41, v42, v42
	v_fmac_f32_e32 v50, v48, v48
	v_add_f32_e32 v41, v41, v50
	v_add_f32_e32 v52, v40, v41
	v_cvt_pk_bf16_f32 v40, v44, v45
	v_cvt_pk_bf16_f32 v41, v46, v47
	s_waitcnt vmcnt(6)
	v_lshlrev_b32_e32 v44, 16, v80
	v_and_b32_e32 v45, 0xffff0000, v80
	v_lshlrev_b32_e32 v46, 16, v81
	v_and_b32_e32 v47, 0xffff0000, v81
	v_cvt_pk_bf16_f32 v42, v42, v43
	v_cvt_pk_bf16_f32 v43, v48, v49
	v_lshlrev_b32_e32 v48, 16, v82
	v_and_b32_e32 v49, 0xffff0000, v82
	v_pk_add_f32 v[38:39], v[38:39], v[46:47]
	v_pk_add_f32 v[36:37], v[36:37], v[44:45]
	v_lshlrev_b32_e32 v50, 16, v83
	v_and_b32_e32 v51, 0xffff0000, v83
	v_pk_add_f32 v[46:47], v[32:33], v[48:49]
	v_mul_f32_e32 v32, v37, v37
	v_mul_f32_e32 v33, v39, v39
	v_pk_add_f32 v[44:45], v[34:35], v[50:51]
	v_fmac_f32_e32 v32, v36, v36
	v_fmac_f32_e32 v33, v38, v38
	v_add_f32_e32 v32, v32, v33
	v_mul_f32_e32 v33, v47, v47
	v_mul_f32_e32 v34, v45, v45
	v_fmac_f32_e32 v33, v46, v46
	v_fmac_f32_e32 v34, v44, v44
	v_add_f32_e32 v33, v33, v34
	v_add_f32_e32 v32, v32, v33
	v_add_f32_e32 v35, v52, v32
	ds_bpermute_b32 v50, v196, v35
	v_lshl_add_u64 v[32:33], s[16:17], 0, v[98:99]
	v_lshl_add_u64 v[48:49], v[168:169], 1, v[32:33]
	global_store_dwordx4 v[48:49], v[40:43], off sc1
	v_cvt_pk_bf16_f32 v34, v36, v37
	s_waitcnt lgkmcnt(0)
	v_add_f32_e32 v32, v35, v50
	ds_bpermute_b32 v33, v197, v32
	v_cvt_pk_bf16_f32 v35, v38, v39
	v_cvt_pk_bf16_f32 v36, v46, v47
	v_cvt_pk_bf16_f32 v37, v44, v45
	global_store_dwordx4 v[48:49], v[34:37], off offset:256 sc1
	s_and_saveexec_b64 s[4:5], s[6:7]
	s_cbranch_execz .LBB0_981
	v_lshlrev_b64 v[34:35], 6, v[96:97]
	v_lshl_add_u64 v[34:35], s[24:25], 0, v[34:35]
	v_lshl_add_u64 v[34:35], s[40:41], 2, v[34:35]
	s_lshl_b32 s10, s49, 2
	v_lshl_add_u64 v[34:35], v[34:35], 0, s[10:11]
	s_waitcnt lgkmcnt(0)
	v_add_f32_e32 v32, v32, v33
	global_store_dword v[34:35], v32, off
.LBB0_981:
	s_or_b64 exec, exec, s[4:5]
	s_waitcnt vmcnt(7)
	v_lshlrev_b32_e32 v32, 16, v76
	s_waitcnt lgkmcnt(0)
	v_and_b32_e32 v33, 0xffff0000, v76
	v_lshlrev_b32_e32 v34, 16, v77
	v_and_b32_e32 v35, 0xffff0000, v77
	v_lshlrev_b32_e32 v36, 16, v78
	v_and_b32_e32 v37, 0xffff0000, v78
	v_lshlrev_b32_e32 v38, 16, v79
	v_and_b32_e32 v39, 0xffff0000, v79
	v_pk_add_f32 v[30:31], v[30:31], v[34:35]
	v_pk_add_f32 v[28:29], v[28:29], v[32:33]
	v_pk_add_f32 v[32:33], v[26:27], v[38:39]
	v_pk_add_f32 v[26:27], v[24:25], v[36:37]
	v_mul_f32_e32 v24, v29, v29
	v_mul_f32_e32 v25, v31, v31
	v_fmac_f32_e32 v24, v28, v28
	v_fmac_f32_e32 v25, v30, v30
	v_add_f32_e32 v24, v24, v25
	v_mul_f32_e32 v25, v27, v27
	v_mul_f32_e32 v34, v33, v33
	v_fmac_f32_e32 v25, v26, v26
	v_fmac_f32_e32 v34, v32, v32
	v_add_f32_e32 v25, v25, v34
	v_add_f32_e32 v36, v24, v25
	v_cvt_pk_bf16_f32 v24, v28, v29
	v_cvt_pk_bf16_f32 v25, v30, v31
	s_waitcnt vmcnt(6)
	v_lshlrev_b32_e32 v28, 16, v72
	v_and_b32_e32 v29, 0xffff0000, v72
	v_lshlrev_b32_e32 v30, 16, v73
	v_and_b32_e32 v31, 0xffff0000, v73
	v_cvt_pk_bf16_f32 v26, v26, v27
	v_cvt_pk_bf16_f32 v27, v32, v33
	v_lshlrev_b32_e32 v32, 16, v74
	v_and_b32_e32 v33, 0xffff0000, v74
	v_pk_add_f32 v[22:23], v[22:23], v[30:31]
	v_pk_add_f32 v[20:21], v[20:21], v[28:29]
	v_lshlrev_b32_e32 v34, 16, v75
	v_and_b32_e32 v35, 0xffff0000, v75
	v_pk_add_f32 v[30:31], v[16:17], v[32:33]
	v_mul_f32_e32 v16, v21, v21
	v_mul_f32_e32 v17, v23, v23
	v_pk_add_f32 v[28:29], v[18:19], v[34:35]
	v_fmac_f32_e32 v16, v20, v20
	v_fmac_f32_e32 v17, v22, v22
	v_add_f32_e32 v16, v16, v17
	v_mul_f32_e32 v17, v31, v31
	v_mul_f32_e32 v18, v29, v29
	v_fmac_f32_e32 v17, v30, v30
	v_fmac_f32_e32 v18, v28, v28
	v_add_f32_e32 v17, v17, v18
	v_add_f32_e32 v16, v16, v17
	v_add_f32_e32 v19, v36, v16
	ds_bpermute_b32 v34, v196, v19
	v_lshl_add_u64 v[16:17], s[16:17], 0, v[94:95]
	v_lshl_add_u64 v[32:33], v[168:169], 1, v[16:17]
	global_store_dwordx4 v[32:33], v[24:27], off sc1
	v_cvt_pk_bf16_f32 v18, v20, v21
	s_waitcnt lgkmcnt(0)
	v_add_f32_e32 v16, v19, v34
	ds_bpermute_b32 v17, v197, v16
	v_cvt_pk_bf16_f32 v19, v22, v23
	v_cvt_pk_bf16_f32 v20, v30, v31
	v_cvt_pk_bf16_f32 v21, v28, v29
	global_store_dwordx4 v[32:33], v[18:21], off offset:256 sc1
	s_and_saveexec_b64 s[4:5], s[6:7]
	s_cbranch_execz .LBB0_983
	v_lshlrev_b64 v[18:19], 6, v[92:93]
	v_lshl_add_u64 v[18:19], s[24:25], 0, v[18:19]
	v_lshl_add_u64 v[18:19], s[40:41], 2, v[18:19]
	s_lshl_b32 s10, s49, 2
	v_lshl_add_u64 v[18:19], v[18:19], 0, s[10:11]
	s_waitcnt lgkmcnt(0)
	v_add_f32_e32 v16, v16, v17
	global_store_dword v[18:19], v16, off
.LBB0_983:
	s_or_b64 exec, exec, s[4:5]
	s_waitcnt vmcnt(7)
	v_lshlrev_b32_e32 v16, 16, v68
	s_waitcnt lgkmcnt(0)
	v_and_b32_e32 v17, 0xffff0000, v68
	v_lshlrev_b32_e32 v18, 16, v69
	v_and_b32_e32 v19, 0xffff0000, v69
	v_lshlrev_b32_e32 v20, 16, v70
	v_and_b32_e32 v21, 0xffff0000, v70
	v_lshlrev_b32_e32 v22, 16, v71
	v_and_b32_e32 v23, 0xffff0000, v71
	v_pk_add_f32 v[14:15], v[14:15], v[18:19]
	v_pk_add_f32 v[12:13], v[12:13], v[16:17]
	v_pk_add_f32 v[16:17], v[10:11], v[22:23]
	v_pk_add_f32 v[10:11], v[8:9], v[20:21]
	v_mul_f32_e32 v8, v13, v13
	v_mul_f32_e32 v9, v15, v15
	v_fmac_f32_e32 v8, v12, v12
	v_fmac_f32_e32 v9, v14, v14
	v_add_f32_e32 v8, v8, v9
	v_mul_f32_e32 v9, v11, v11
	v_mul_f32_e32 v18, v17, v17
	v_fmac_f32_e32 v9, v10, v10
	v_fmac_f32_e32 v18, v16, v16
	v_add_f32_e32 v9, v9, v18
	v_add_f32_e32 v20, v8, v9
	v_cvt_pk_bf16_f32 v8, v12, v13
	v_cvt_pk_bf16_f32 v9, v14, v15
	s_waitcnt vmcnt(6)
	v_lshlrev_b32_e32 v12, 16, v64
	v_and_b32_e32 v13, 0xffff0000, v64
	v_lshlrev_b32_e32 v14, 16, v65
	v_and_b32_e32 v15, 0xffff0000, v65
	v_cvt_pk_bf16_f32 v10, v10, v11
	v_cvt_pk_bf16_f32 v11, v16, v17
	v_lshlrev_b32_e32 v16, 16, v66
	v_and_b32_e32 v17, 0xffff0000, v66
	v_pk_add_f32 v[6:7], v[6:7], v[14:15]
	v_pk_add_f32 v[4:5], v[4:5], v[12:13]
	v_lshlrev_b32_e32 v18, 16, v67
	v_and_b32_e32 v19, 0xffff0000, v67
	v_pk_add_f32 v[14:15], v[0:1], v[16:17]
	v_mul_f32_e32 v0, v5, v5
	v_mul_f32_e32 v1, v7, v7
	v_pk_add_f32 v[12:13], v[2:3], v[18:19]
	v_fmac_f32_e32 v0, v4, v4
	v_fmac_f32_e32 v1, v6, v6
	v_add_f32_e32 v0, v0, v1
	v_mul_f32_e32 v1, v15, v15
	v_mul_f32_e32 v2, v13, v13
	v_fmac_f32_e32 v1, v14, v14
	v_fmac_f32_e32 v2, v12, v12
	v_add_f32_e32 v1, v1, v2
	v_add_f32_e32 v0, v0, v1
	v_add_f32_e32 v3, v20, v0
	ds_bpermute_b32 v18, v196, v3
	v_lshl_add_u64 v[0:1], s[16:17], 0, v[90:91]
	v_lshl_add_u64 v[16:17], v[168:169], 1, v[0:1]
	global_store_dwordx4 v[16:17], v[8:11], off sc1
	v_cvt_pk_bf16_f32 v2, v4, v5
	s_waitcnt lgkmcnt(0)
	v_add_f32_e32 v0, v3, v18
	ds_bpermute_b32 v1, v197, v0
	v_cvt_pk_bf16_f32 v3, v6, v7
	v_cvt_pk_bf16_f32 v4, v14, v15
	v_cvt_pk_bf16_f32 v5, v12, v13
	global_store_dwordx4 v[16:17], v[2:5], off offset:256 sc1
	s_and_saveexec_b64 s[4:5], s[6:7]
	s_cbranch_execz .LBB0_985
	v_lshlrev_b64 v[2:3], 6, v[88:89]
	v_lshl_add_u64 v[2:3], s[24:25], 0, v[2:3]
	v_lshl_add_u64 v[2:3], s[40:41], 2, v[2:3]
	s_lshl_b32 s10, s49, 2
	v_lshl_add_u64 v[2:3], v[2:3], 0, s[10:11]
	s_waitcnt lgkmcnt(0)
	v_add_f32_e32 v0, v0, v1
	global_store_dword v[2:3], v0, off

.LBB0_1051:
	v_lshl_add_u32 v162, s8, 8, v159
	s_mov_b64 s[60:61], 0x2000
	v_lshlrev_b32_e32 v204, 6, v162
	v_mov_b32_e32 v205, 0
	v_mbcnt_lo_u32_b32 v248, -1, 0
	v_mbcnt_hi_u32_b32 v248, -1, v248
	v_xor_b32_e32 v248, 16, v248
	v_lshl_add_u64 v[204:205], v[136:137], 0, v[204:205]
	v_lshlrev_b32_e32 v248, 2, v248
	v_lshl_add_u64 v[206:207], v[204:205], 0, s[60:61]
	global_load_dwordx4 v[208:211], v[204:205], off
	global_load_dwordx4 v[212:215], v[204:205], off offset:1024
	global_load_dwordx4 v[216:219], v[204:205], off offset:2048
	global_load_dwordx4 v[220:223], v[204:205], off offset:3072
	global_load_dwordx4 v[224:227], v[206:207], off
	global_load_dwordx4 v[228:231], v[206:207], off offset:1024
	global_load_dwordx4 v[232:235], v[206:207], off offset:2048
	global_load_dwordx4 v[236:239], v[206:207], off offset:3072
	s_waitcnt vmcnt(0)
	v_add_f32_e32 v208, v208, v209
	v_add_f32_e32 v210, v210, v211
	v_add_f32_e32 v212, v212, v213
	v_add_f32_e32 v214, v214, v215
	v_add_f32_e32 v216, v216, v217
	v_add_f32_e32 v218, v218, v219
	v_add_f32_e32 v220, v220, v221
	v_add_f32_e32 v222, v222, v223
	v_add_f32_e32 v224, v224, v225
	v_add_f32_e32 v226, v226, v227
	v_add_f32_e32 v228, v228, v229
	v_add_f32_e32 v230, v230, v231
	v_add_f32_e32 v232, v232, v233
	v_add_f32_e32 v234, v234, v235
	v_add_f32_e32 v236, v236, v237
	v_add_f32_e32 v238, v238, v239
	v_add_f32_e32 v208, v208, v210
	v_add_f32_e32 v212, v212, v214
	v_add_f32_e32 v216, v216, v218
	v_add_f32_e32 v220, v220, v222
	v_add_f32_e32 v224, v224, v226
	v_add_f32_e32 v228, v228, v230
	v_add_f32_e32 v232, v232, v234
	v_add_f32_e32 v236, v236, v238
	ds_bpermute_b32 v209, v248, v208
	ds_bpermute_b32 v213, v248, v212
	ds_bpermute_b32 v217, v248, v216
	ds_bpermute_b32 v221, v248, v220
	ds_bpermute_b32 v225, v248, v224
	ds_bpermute_b32 v229, v248, v228
	ds_bpermute_b32 v233, v248, v232
	ds_bpermute_b32 v237, v248, v236
	s_waitcnt lgkmcnt(0)
	v_add_f32_e32 v208, v208, v209
	v_add_f32_e32 v212, v212, v213
	v_add_f32_e32 v216, v216, v217
	v_add_f32_e32 v220, v220, v221
	v_add_f32_e32 v224, v224, v225
	v_add_f32_e32 v228, v228, v229
	v_add_f32_e32 v232, v232, v233
	v_add_f32_e32 v236, v236, v237
	v_mov_b32_e32 v209, v208
	v_mov_b32_e32 v213, v212
	v_mov_b32_e32 v217, v216
	v_mov_b32_e32 v221, v220
	v_mov_b32_e32 v225, v224
	v_mov_b32_e32 v229, v228
	v_mov_b32_e32 v233, v232
	v_mov_b32_e32 v237, v236
	s_nop 1
	v_permlane32_swap_b32_e32 v208, v209
	v_permlane32_swap_b32_e32 v212, v213
	v_permlane32_swap_b32_e32 v216, v217
	v_permlane32_swap_b32_e32 v220, v221
	v_permlane32_swap_b32_e32 v224, v225
	v_permlane32_swap_b32_e32 v228, v229
	v_permlane32_swap_b32_e32 v232, v233
	v_permlane32_swap_b32_e32 v236, v237
	v_add_f32_e32 v208, v208, v209
	v_add_f32_e32 v212, v212, v213
	v_add_f32_e32 v216, v216, v217
	v_add_f32_e32 v220, v220, v221
	v_add_f32_e32 v224, v224, v225
	v_add_f32_e32 v228, v228, v229
	v_add_f32_e32 v232, v232, v233
	v_add_f32_e32 v236, v236, v237
	v_fmamk_f32 v208, v208, 0x3a800000, v175
	v_fmamk_f32 v212, v212, 0x3a800000, v175
	v_fmamk_f32 v216, v216, 0x3a800000, v175
	v_fmamk_f32 v220, v220, 0x3a800000, v175
	v_fmamk_f32 v224, v224, 0x3a800000, v175
	v_fmamk_f32 v228, v228, 0x3a800000, v175
	v_fmamk_f32 v232, v232, 0x3a800000, v175
	v_fmamk_f32 v236, v236, 0x3a800000, v175
	v_rsq_f32_e32 v176, v208
	v_rsq_f32_e32 v174, v212
	v_rsq_f32_e32 v172, v216
	v_rsq_f32_e32 v170, v220
	v_rsq_f32_e32 v168, v224
	v_rsq_f32_e32 v166, v228
	v_rsq_f32_e32 v164, v232
	v_rsq_f32_e32 v158, v236
	s_nop 0
	v_or_b32_e32 v160, 16, v162
	v_or_b32_e32 v156, 32, v162
	v_or_b32_e32 v154, 48, v162
	v_add_u32_e32 v148, 0x80, v162
	s_waitcnt vmcnt(0)
	s_waitcnt lgkmcnt(2)
	s_waitcnt lgkmcnt(2)
	s_waitcnt lgkmcnt(1)
	s_waitcnt lgkmcnt(2)
	s_waitcnt lgkmcnt(1)
	s_waitcnt lgkmcnt(0)
	s_nop 0
	v_add_u32_e32 v152, 0x90, v162
	s_waitcnt lgkmcnt(0)
	s_waitcnt lgkmcnt(0)
	s_waitcnt vmcnt(0)
	v_add_u32_e32 v150, 0xa0, v162
	s_waitcnt lgkmcnt(0)
	s_waitcnt lgkmcnt(0)
	s_nop 0
	s_nop 1
	v_add_u32_e32 v146, 0xb0, v162
	s_waitcnt lgkmcnt(0)
	s_waitcnt lgkmcnt(0)
	s_waitcnt vmcnt(1)
	s_waitcnt lgkmcnt(0)
	s_waitcnt lgkmcnt(0)
	s_waitcnt vmcnt(0)
	v_mov_b32_e32 v178, v120
	s_waitcnt lgkmcnt(0)
	s_waitcnt lgkmcnt(0)
	v_mov_b32_e32 v179, v124
	v_pk_mul_f32 v[178:179], v[178:179], v[176:177] op_sel_hi:[1,0]
	v_mov_b32_e32 v124, v121
	v_mul_f32_e32 v120, 0xbfb8aa3b, v179
	v_exp_f32_e32 v147, v120
	v_pk_mul_f32 v[120:121], v[124:125], v[176:177] op_sel_hi:[1,0]
	s_andn2_b64 vcc, exec, s[6:7]
	v_mul_f32_e32 v124, 0xbfb8aa3b, v121
	v_exp_f32_e32 v125, v124
	v_add_f32_e32 v147, 1.0, v147
	v_rcp_f32_e32 v147, v147
	v_lshl_or_b32 v124, s33, 7, v167
	v_add_f32_e32 v125, 1.0, v125
	v_rcp_f32_e32 v149, v125
	v_mul_f32_e32 v147, v179, v147
	v_mul_f32_e32 v147, v178, v147
	v_mov_b32_e32 v178, v122
	v_mov_b32_e32 v179, v126
	v_pk_mul_f32 v[178:179], v[178:179], v[176:177] op_sel_hi:[1,0]
	v_mov_b32_e32 v126, v123
	v_mul_f32_e32 v122, 0xbfb8aa3b, v179
	v_mul_f32_e32 v121, v121, v149
	v_exp_f32_e32 v149, v122
	v_pk_mul_f32 v[122:123], v[126:127], v[176:177] op_sel_hi:[1,0]
	v_mul_f32_e32 v127, v120, v121
	v_mul_f32_e32 v126, 0xbfb8aa3b, v123
	v_exp_f32_e32 v126, v126
	v_add_f32_e32 v120, 1.0, v149
	v_rcp_f32_e32 v149, v120
	v_mov_b32_e32 v121, v116
	v_add_f32_e32 v120, 1.0, v126
	v_rcp_f32_e32 v126, v120
	v_mov_b32_e32 v120, v112
	v_pk_mul_f32 v[120:121], v[120:121], v[176:177] op_sel_hi:[1,0]
	v_mul_f32_e32 v116, v179, v149
	v_mul_f32_e32 v112, 0xbfb8aa3b, v121
	v_exp_f32_e32 v112, v112
	v_mul_f32_e32 v149, v178, v116
	v_mov_b32_e32 v116, v113
	v_mul_f32_e32 v123, v123, v126
	v_add_f32_e32 v112, 1.0, v112
	v_rcp_f32_e32 v126, v112
	v_pk_mul_f32 v[112:113], v[116:117], v[176:177] op_sel_hi:[1,0]
	v_mul_f32_e32 v122, v122, v123
	v_mul_f32_e32 v116, 0xbfb8aa3b, v113
	v_exp_f32_e32 v116, v116
	v_mul_f32_e32 v117, v121, v126
	v_mul_f32_e32 v120, v120, v117
	v_mov_b32_e32 v117, v118
	v_add_f32_e32 v116, 1.0, v116
	v_rcp_f32_e32 v121, v116
	v_mov_b32_e32 v116, v114
	v_pk_mul_f32 v[116:117], v[116:117], v[176:177] op_sel_hi:[1,0]
	v_mov_b32_e32 v118, v115
	v_mul_f32_e32 v114, 0xbfb8aa3b, v117
	v_exp_f32_e32 v123, v114
	v_pk_mul_f32 v[114:115], v[118:119], v[176:177] op_sel_hi:[1,0]
	v_mul_f32_e32 v113, v113, v121
	v_mul_f32_e32 v118, 0xbfb8aa3b, v115
	v_exp_f32_e32 v118, v118
	v_add_f32_e32 v119, 1.0, v123
	v_rcp_f32_e32 v119, v119
	v_mul_f32_e32 v112, v112, v113
	v_add_f32_e32 v118, 1.0, v118
	v_rcp_f32_e32 v118, v118
	v_mul_f32_e32 v113, v117, v119
	v_mul_f32_e32 v113, v116, v113
	v_cvt_pk_bf16_f32 v116, v147, v127
	v_cvt_pk_bf16_f32 v117, v149, v122
	v_mov_b32_e32 v122, v104
	v_mov_b32_e32 v123, v108
	v_mul_f32_e32 v115, v115, v118
	v_pk_mul_f32 v[122:123], v[122:123], v[174:175] op_sel_hi:[1,0]
	v_ashrrev_i32_e32 v125, 31, v124
	v_mul_f32_e32 v114, v114, v115
	v_mul_f32_e32 v104, 0xbfb8aa3b, v123
	v_cvt_pk_bf16_f32 v118, v120, v112
	v_cvt_pk_bf16_f32 v119, v113, v114
	v_lshlrev_b64 v[114:115], 1, v[124:125]
	v_exp_f32_e32 v124, v104
	v_mov_b32_e32 v108, v105
	v_mov_b64_e32 v[112:113], s[22:23]
	v_pk_mul_f32 v[104:105], v[108:109], v[174:175] op_sel_hi:[1,0]
	v_mad_i64_i32 v[120:121], s[4:5], v162, s51, v[112:113]
	v_mul_f32_e32 v108, 0xbfb8aa3b, v105
	v_exp_f32_e32 v125, v108
	v_lshl_add_u64 v[108:109], v[120:121], 0, v[114:115]
	v_add_f32_e32 v120, 1.0, v124
	v_rcp_f32_e32 v120, v120
	global_store_dwordx4 v[108:109], v[116:119], off sc1
	v_mov_b32_e32 v109, v110
	v_add_f32_e32 v121, 1.0, v125
	v_mul_f32_e32 v108, v123, v120
	v_mul_f32_e32 v116, v122, v108
	v_mov_b32_e32 v108, v106
	v_pk_mul_f32 v[108:109], v[108:109], v[174:175] op_sel_hi:[1,0]
	v_mov_b32_e32 v110, v107
	v_mul_f32_e32 v106, 0xbfb8aa3b, v109
	v_rcp_f32_e32 v121, v121
	v_exp_f32_e32 v117, v106
	v_pk_mul_f32 v[106:107], v[110:111], v[174:175] op_sel_hi:[1,0]
	v_mul_f32_e32 v105, v105, v121
	v_mul_f32_e32 v110, 0xbfb8aa3b, v107
	v_exp_f32_e32 v110, v110
	v_mul_f32_e32 v111, v104, v105
	v_add_f32_e32 v104, 1.0, v117
	v_rcp_f32_e32 v117, v104
	v_add_f32_e32 v104, 1.0, v110
	v_rcp_f32_e32 v110, v104
	v_mov_b32_e32 v104, v96
	v_mov_b32_e32 v105, v100
	v_pk_mul_f32 v[104:105], v[104:105], v[174:175] op_sel_hi:[1,0]
	v_mul_f32_e32 v100, v109, v117
	v_mul_f32_e32 v96, 0xbfb8aa3b, v105
	v_exp_f32_e32 v96, v96
	v_mul_f32_e32 v108, v108, v100
	v_mov_b32_e32 v100, v97
	v_mul_f32_e32 v107, v107, v110
	v_add_f32_e32 v96, 1.0, v96
	v_rcp_f32_e32 v109, v96
	v_pk_mul_f32 v[96:97], v[100:101], v[174:175] op_sel_hi:[1,0]
	v_mul_f32_e32 v106, v106, v107
	v_mul_f32_e32 v100, 0xbfb8aa3b, v97
	v_exp_f32_e32 v100, v100
	v_mul_f32_e32 v101, v105, v109
	v_mul_f32_e32 v104, v104, v101
	v_mov_b32_e32 v101, v102
	v_add_f32_e32 v100, 1.0, v100
	v_rcp_f32_e32 v105, v100
	v_mov_b32_e32 v100, v98
	v_pk_mul_f32 v[100:101], v[100:101], v[174:175] op_sel_hi:[1,0]
	v_mov_b32_e32 v102, v99
	v_mul_f32_e32 v98, 0xbfb8aa3b, v101
	v_exp_f32_e32 v107, v98
	v_pk_mul_f32 v[98:99], v[102:103], v[174:175] op_sel_hi:[1,0]
	v_mul_f32_e32 v97, v97, v105
	v_mul_f32_e32 v102, 0xbfb8aa3b, v99
	v_exp_f32_e32 v102, v102
	v_add_f32_e32 v103, 1.0, v107
	v_rcp_f32_e32 v103, v103
	v_mul_f32_e32 v105, v96, v97
	v_add_f32_e32 v102, 1.0, v102
	v_rcp_f32_e32 v102, v102
	v_mul_f32_e32 v96, v101, v103
	v_mul_f32_e32 v100, v100, v96
	v_mov_b32_e32 v103, v92
	v_mul_f32_e32 v96, v99, v102
	v_mov_b32_e32 v102, v88
	v_pk_mul_f32 v[102:103], v[102:103], v[172:173] op_sel_hi:[1,0]
	v_mul_f32_e32 v99, v98, v96
	v_mul_f32_e32 v88, 0xbfb8aa3b, v103
	v_cvt_pk_bf16_f32 v96, v116, v111
	v_cvt_pk_bf16_f32 v97, v108, v106
	v_cvt_pk_bf16_f32 v98, v104, v105
	v_exp_f32_e32 v104, v88
	v_mov_b32_e32 v92, v89
	v_pk_mul_f32 v[88:89], v[92:93], v[172:173] op_sel_hi:[1,0]
	v_cvt_pk_bf16_f32 v99, v100, v99
	v_mad_i64_i32 v[100:101], s[4:5], v160, s51, v[112:113]
	v_mul_f32_e32 v92, 0xbfb8aa3b, v89
	v_exp_f32_e32 v105, v92
	v_lshl_add_u64 v[92:93], v[100:101], 0, v[114:115]
	v_add_f32_e32 v100, 1.0, v104
	v_rcp_f32_e32 v100, v100
	global_store_dwordx4 v[92:93], v[96:99], off sc1
	v_mov_b32_e32 v93, v94
	v_add_f32_e32 v101, 1.0, v105
	v_mul_f32_e32 v92, v103, v100
	v_mul_f32_e32 v96, v102, v92
	v_mov_b32_e32 v92, v90
	v_pk_mul_f32 v[92:93], v[92:93], v[172:173] op_sel_hi:[1,0]
	v_mov_b32_e32 v94, v91
	v_mul_f32_e32 v90, 0xbfb8aa3b, v93
	v_rcp_f32_e32 v101, v101
	v_exp_f32_e32 v97, v90
	v_pk_mul_f32 v[90:91], v[94:95], v[172:173] op_sel_hi:[1,0]
	v_mul_f32_e32 v89, v89, v101
	v_mul_f32_e32 v94, 0xbfb8aa3b, v91
	v_exp_f32_e32 v94, v94
	v_mul_f32_e32 v95, v88, v89
	v_add_f32_e32 v88, 1.0, v97
	v_rcp_f32_e32 v97, v88
	v_add_f32_e32 v88, 1.0, v94
	v_rcp_f32_e32 v94, v88
	v_mov_b32_e32 v88, v80
	v_mov_b32_e32 v89, v84
	v_pk_mul_f32 v[88:89], v[88:89], v[172:173] op_sel_hi:[1,0]
	v_mul_f32_e32 v84, v93, v97
	v_mul_f32_e32 v80, 0xbfb8aa3b, v89
	v_exp_f32_e32 v80, v80
	v_mul_f32_e32 v92, v92, v84
	v_mov_b32_e32 v84, v81
	v_mul_f32_e32 v91, v91, v94
	v_add_f32_e32 v80, 1.0, v80
	v_rcp_f32_e32 v93, v80
	v_pk_mul_f32 v[80:81], v[84:85], v[172:173] op_sel_hi:[1,0]
	v_mul_f32_e32 v90, v90, v91
	v_mul_f32_e32 v84, 0xbfb8aa3b, v81
	v_exp_f32_e32 v84, v84
	v_mul_f32_e32 v85, v89, v93
	v_mul_f32_e32 v88, v88, v85
	v_mov_b32_e32 v85, v86
	v_add_f32_e32 v84, 1.0, v84
	v_rcp_f32_e32 v89, v84
	v_mov_b32_e32 v84, v82
	v_pk_mul_f32 v[84:85], v[84:85], v[172:173] op_sel_hi:[1,0]
	v_mov_b32_e32 v86, v83
	v_mul_f32_e32 v82, 0xbfb8aa3b, v85
	v_exp_f32_e32 v91, v82
	v_pk_mul_f32 v[82:83], v[86:87], v[172:173] op_sel_hi:[1,0]
	v_mul_f32_e32 v81, v81, v89
	v_mul_f32_e32 v86, 0xbfb8aa3b, v83
	v_exp_f32_e32 v86, v86
	v_add_f32_e32 v87, 1.0, v91
	v_rcp_f32_e32 v87, v87
	v_mul_f32_e32 v89, v80, v81
	v_add_f32_e32 v86, 1.0, v86
	v_rcp_f32_e32 v86, v86
	v_mul_f32_e32 v80, v85, v87
	v_mul_f32_e32 v84, v84, v80
	v_mov_b32_e32 v87, v76
	v_mul_f32_e32 v80, v83, v86
	v_mov_b32_e32 v86, v72
	v_pk_mul_f32 v[86:87], v[86:87], v[170:171] op_sel_hi:[1,0]
	v_mul_f32_e32 v83, v82, v80
	v_mul_f32_e32 v72, 0xbfb8aa3b, v87
	v_cvt_pk_bf16_f32 v80, v96, v95
	v_cvt_pk_bf16_f32 v81, v92, v90
	v_cvt_pk_bf16_f32 v82, v88, v89
	v_exp_f32_e32 v88, v72
	v_mov_b32_e32 v76, v73
	v_pk_mul_f32 v[72:73], v[76:77], v[170:171] op_sel_hi:[1,0]
	v_cvt_pk_bf16_f32 v83, v84, v83
	v_mad_i64_i32 v[84:85], s[4:5], v156, s51, v[112:113]
	v_mul_f32_e32 v76, 0xbfb8aa3b, v73
	v_exp_f32_e32 v89, v76
	v_lshl_add_u64 v[76:77], v[84:85], 0, v[114:115]
	v_add_f32_e32 v84, 1.0, v88
	v_rcp_f32_e32 v84, v84
	global_store_dwordx4 v[76:77], v[80:83], off sc1
	v_mov_b32_e32 v77, v78
	v_add_f32_e32 v85, 1.0, v89
	v_mul_f32_e32 v76, v87, v84
	v_mul_f32_e32 v80, v86, v76
	v_mov_b32_e32 v76, v74
	v_pk_mul_f32 v[76:77], v[76:77], v[170:171] op_sel_hi:[1,0]
	v_mov_b32_e32 v78, v75
	v_mul_f32_e32 v74, 0xbfb8aa3b, v77
	v_rcp_f32_e32 v85, v85
	v_exp_f32_e32 v81, v74
	v_pk_mul_f32 v[74:75], v[78:79], v[170:171] op_sel_hi:[1,0]
	v_mul_f32_e32 v73, v73, v85
	v_mul_f32_e32 v78, 0xbfb8aa3b, v75
	v_exp_f32_e32 v78, v78
	v_mul_f32_e32 v79, v72, v73
	v_add_f32_e32 v72, 1.0, v81
	v_rcp_f32_e32 v81, v72
	v_add_f32_e32 v72, 1.0, v78
	v_rcp_f32_e32 v78, v72
	v_mov_b32_e32 v72, v64
	v_mov_b32_e32 v73, v68
	v_pk_mul_f32 v[72:73], v[72:73], v[170:171] op_sel_hi:[1,0]
	v_mul_f32_e32 v68, v77, v81
	v_mul_f32_e32 v64, 0xbfb8aa3b, v73
	v_exp_f32_e32 v64, v64
	v_mul_f32_e32 v76, v76, v68
	v_mov_b32_e32 v68, v65
	v_mul_f32_e32 v75, v75, v78
	v_add_f32_e32 v64, 1.0, v64
	v_rcp_f32_e32 v77, v64
	v_pk_mul_f32 v[64:65], v[68:69], v[170:171] op_sel_hi:[1,0]
	v_mul_f32_e32 v74, v74, v75
	v_mul_f32_e32 v68, 0xbfb8aa3b, v65
	v_exp_f32_e32 v68, v68
	v_mul_f32_e32 v69, v73, v77
	v_mul_f32_e32 v72, v72, v69
	v_mov_b32_e32 v69, v70
	v_add_f32_e32 v68, 1.0, v68
	v_rcp_f32_e32 v73, v68
	v_mov_b32_e32 v68, v66
	v_pk_mul_f32 v[68:69], v[68:69], v[170:171] op_sel_hi:[1,0]
	v_mov_b32_e32 v70, v67
	v_mul_f32_e32 v66, 0xbfb8aa3b, v69
	v_exp_f32_e32 v75, v66
	v_pk_mul_f32 v[66:67], v[70:71], v[170:171] op_sel_hi:[1,0]
	v_mul_f32_e32 v65, v65, v73
	v_mul_f32_e32 v70, 0xbfb8aa3b, v67
	v_exp_f32_e32 v70, v70
	v_add_f32_e32 v71, 1.0, v75
	v_rcp_f32_e32 v71, v71
	v_mul_f32_e32 v73, v64, v65
	v_add_f32_e32 v70, 1.0, v70
	v_rcp_f32_e32 v70, v70
	v_mul_f32_e32 v64, v69, v71
	v_mul_f32_e32 v68, v68, v64
	v_mov_b32_e32 v71, v60
	v_mul_f32_e32 v64, v67, v70
	v_mov_b32_e32 v70, v56
	v_pk_mul_f32 v[70:71], v[70:71], v[168:169] op_sel_hi:[1,0]
	v_mul_f32_e32 v67, v66, v64
	v_mul_f32_e32 v56, 0xbfb8aa3b, v71
	v_cvt_pk_bf16_f32 v64, v80, v79
	v_cvt_pk_bf16_f32 v65, v76, v74
	v_cvt_pk_bf16_f32 v66, v72, v73
	v_exp_f32_e32 v72, v56
	v_mov_b32_e32 v60, v57
	v_pk_mul_f32 v[56:57], v[60:61], v[168:169] op_sel_hi:[1,0]
	v_cvt_pk_bf16_f32 v67, v68, v67
	v_mad_i64_i32 v[68:69], s[4:5], v154, s51, v[112:113]
	v_mul_f32_e32 v60, 0xbfb8aa3b, v57
	v_exp_f32_e32 v73, v60
	v_lshl_add_u64 v[60:61], v[68:69], 0, v[114:115]
	v_add_f32_e32 v68, 1.0, v72
	v_rcp_f32_e32 v68, v68
	global_store_dwordx4 v[60:61], v[64:67], off sc1
	v_mov_b32_e32 v61, v62
	v_add_f32_e32 v69, 1.0, v73
	v_mul_f32_e32 v60, v71, v68
	v_mul_f32_e32 v64, v70, v60
	v_mov_b32_e32 v60, v58
	v_pk_mul_f32 v[60:61], v[60:61], v[168:169] op_sel_hi:[1,0]
	v_mov_b32_e32 v62, v59
	v_mul_f32_e32 v58, 0xbfb8aa3b, v61
	v_rcp_f32_e32 v69, v69
	v_exp_f32_e32 v65, v58
	v_pk_mul_f32 v[58:59], v[62:63], v[168:169] op_sel_hi:[1,0]
	v_mul_f32_e32 v57, v57, v69
	v_mul_f32_e32 v62, 0xbfb8aa3b, v59
	v_exp_f32_e32 v62, v62
	v_mul_f32_e32 v63, v56, v57
	v_add_f32_e32 v56, 1.0, v65
	v_rcp_f32_e32 v65, v56
	v_add_f32_e32 v56, 1.0, v62
	v_rcp_f32_e32 v62, v56
	v_mov_b32_e32 v56, v48
	v_mov_b32_e32 v57, v52
	v_pk_mul_f32 v[56:57], v[56:57], v[168:169] op_sel_hi:[1,0]
	v_mul_f32_e32 v52, v61, v65
	v_mul_f32_e32 v48, 0xbfb8aa3b, v57
	v_exp_f32_e32 v48, v48
	v_mul_f32_e32 v60, v60, v52
	v_mov_b32_e32 v52, v49
	v_mul_f32_e32 v59, v59, v62
	v_add_f32_e32 v48, 1.0, v48
	v_rcp_f32_e32 v61, v48
	v_pk_mul_f32 v[48:49], v[52:53], v[168:169] op_sel_hi:[1,0]
	v_mul_f32_e32 v58, v58, v59
	v_mul_f32_e32 v52, 0xbfb8aa3b, v49
	v_exp_f32_e32 v52, v52
	v_mul_f32_e32 v53, v57, v61
	v_mul_f32_e32 v56, v56, v53
	v_mov_b32_e32 v53, v54
	v_add_f32_e32 v52, 1.0, v52
	v_rcp_f32_e32 v57, v52
	v_mov_b32_e32 v52, v50
	v_pk_mul_f32 v[52:53], v[52:53], v[168:169] op_sel_hi:[1,0]
	v_mov_b32_e32 v54, v51
	v_mul_f32_e32 v50, 0xbfb8aa3b, v53
	v_exp_f32_e32 v59, v50
	v_pk_mul_f32 v[50:51], v[54:55], v[168:169] op_sel_hi:[1,0]
	v_mul_f32_e32 v49, v49, v57
	v_mul_f32_e32 v54, 0xbfb8aa3b, v51
	v_exp_f32_e32 v54, v54
	v_add_f32_e32 v55, 1.0, v59
	v_rcp_f32_e32 v55, v55
	v_mul_f32_e32 v57, v48, v49
	v_add_f32_e32 v54, 1.0, v54
	v_rcp_f32_e32 v54, v54
	v_mul_f32_e32 v48, v53, v55
	v_mul_f32_e32 v52, v52, v48
	v_mov_b32_e32 v55, v44
	v_mul_f32_e32 v48, v51, v54
	v_mov_b32_e32 v54, v40
	v_pk_mul_f32 v[54:55], v[54:55], v[166:167] op_sel_hi:[1,0]
	v_mul_f32_e32 v51, v50, v48
	v_mul_f32_e32 v40, 0xbfb8aa3b, v55
	v_cvt_pk_bf16_f32 v48, v64, v63
	v_cvt_pk_bf16_f32 v49, v60, v58
	v_cvt_pk_bf16_f32 v50, v56, v57
	v_exp_f32_e32 v56, v40
	v_mov_b32_e32 v44, v41
	v_pk_mul_f32 v[40:41], v[44:45], v[166:167] op_sel_hi:[1,0]
	v_cvt_pk_bf16_f32 v51, v52, v51
	v_mad_i64_i32 v[52:53], s[4:5], v148, s51, v[112:113]
	v_mul_f32_e32 v44, 0xbfb8aa3b, v41
	v_exp_f32_e32 v57, v44
	v_lshl_add_u64 v[44:45], v[52:53], 0, v[114:115]
	v_add_f32_e32 v52, 1.0, v56
	v_rcp_f32_e32 v52, v52
	global_store_dwordx4 v[44:45], v[48:51], off sc1
	v_mov_b32_e32 v45, v46
	v_add_f32_e32 v53, 1.0, v57
	v_mul_f32_e32 v44, v55, v52
	v_mul_f32_e32 v48, v54, v44
	v_mov_b32_e32 v44, v42
	v_pk_mul_f32 v[44:45], v[44:45], v[166:167] op_sel_hi:[1,0]
	v_mov_b32_e32 v46, v43
	v_mul_f32_e32 v42, 0xbfb8aa3b, v45
	v_rcp_f32_e32 v53, v53
	v_exp_f32_e32 v49, v42
	v_pk_mul_f32 v[42:43], v[46:47], v[166:167] op_sel_hi:[1,0]
	v_mul_f32_e32 v41, v41, v53
	v_mul_f32_e32 v46, 0xbfb8aa3b, v43
	v_exp_f32_e32 v46, v46
	v_mul_f32_e32 v47, v40, v41
	v_add_f32_e32 v40, 1.0, v49
	v_rcp_f32_e32 v49, v40
	v_add_f32_e32 v40, 1.0, v46
	v_rcp_f32_e32 v46, v40
	v_mov_b32_e32 v40, v32
	v_mov_b32_e32 v41, v36
	v_pk_mul_f32 v[40:41], v[40:41], v[166:167] op_sel_hi:[1,0]
	v_mul_f32_e32 v36, v45, v49
	v_mul_f32_e32 v32, 0xbfb8aa3b, v41
	v_exp_f32_e32 v32, v32
	v_mul_f32_e32 v44, v44, v36
	v_mov_b32_e32 v36, v33
	v_mul_f32_e32 v43, v43, v46
	v_add_f32_e32 v32, 1.0, v32
	v_rcp_f32_e32 v45, v32
	v_pk_mul_f32 v[32:33], v[36:37], v[166:167] op_sel_hi:[1,0]
	v_mul_f32_e32 v42, v42, v43
	v_mul_f32_e32 v36, 0xbfb8aa3b, v33
	v_exp_f32_e32 v36, v36
	v_mul_f32_e32 v37, v41, v45
	v_mul_f32_e32 v40, v40, v37
	v_mov_b32_e32 v37, v38
	v_add_f32_e32 v36, 1.0, v36
	v_rcp_f32_e32 v41, v36
	v_mov_b32_e32 v36, v34
	v_pk_mul_f32 v[36:37], v[36:37], v[166:167] op_sel_hi:[1,0]
	v_mov_b32_e32 v38, v35
	v_mul_f32_e32 v34, 0xbfb8aa3b, v37
	v_exp_f32_e32 v43, v34
	v_pk_mul_f32 v[34:35], v[38:39], v[166:167] op_sel_hi:[1,0]
	v_mul_f32_e32 v33, v33, v41
	v_mul_f32_e32 v38, 0xbfb8aa3b, v35
	v_exp_f32_e32 v38, v38
	v_add_f32_e32 v39, 1.0, v43
	v_rcp_f32_e32 v39, v39
	v_mul_f32_e32 v41, v32, v33
	v_add_f32_e32 v38, 1.0, v38
	v_rcp_f32_e32 v38, v38
	v_mul_f32_e32 v32, v37, v39
	v_mul_f32_e32 v36, v36, v32
	v_mov_b32_e32 v39, v28
	v_mul_f32_e32 v32, v35, v38
	v_mov_b32_e32 v38, v24
	v_pk_mul_f32 v[38:39], v[38:39], v[164:165] op_sel_hi:[1,0]
	v_mul_f32_e32 v35, v34, v32
	v_mul_f32_e32 v24, 0xbfb8aa3b, v39
	v_cvt_pk_bf16_f32 v32, v48, v47
	v_cvt_pk_bf16_f32 v33, v44, v42
	v_cvt_pk_bf16_f32 v34, v40, v41
	v_exp_f32_e32 v40, v24
	v_mov_b32_e32 v28, v25
	v_pk_mul_f32 v[24:25], v[28:29], v[164:165] op_sel_hi:[1,0]
	v_cvt_pk_bf16_f32 v35, v36, v35
	v_mad_i64_i32 v[36:37], s[4:5], v152, s51, v[112:113]
	v_mul_f32_e32 v28, 0xbfb8aa3b, v25
	v_exp_f32_e32 v41, v28
	v_lshl_add_u64 v[28:29], v[36:37], 0, v[114:115]
	v_add_f32_e32 v36, 1.0, v40
	v_rcp_f32_e32 v36, v36
	global_store_dwordx4 v[28:29], v[32:35], off sc1
	v_mov_b32_e32 v29, v30
	v_add_f32_e32 v37, 1.0, v41
	v_mul_f32_e32 v28, v39, v36
	v_mul_f32_e32 v32, v38, v28
	v_mov_b32_e32 v28, v26
	v_pk_mul_f32 v[28:29], v[28:29], v[164:165] op_sel_hi:[1,0]
	v_mov_b32_e32 v30, v27
	v_mul_f32_e32 v26, 0xbfb8aa3b, v29
	v_rcp_f32_e32 v37, v37
	v_exp_f32_e32 v33, v26
	v_pk_mul_f32 v[26:27], v[30:31], v[164:165] op_sel_hi:[1,0]
	v_mul_f32_e32 v25, v25, v37
	v_mul_f32_e32 v30, 0xbfb8aa3b, v27
	v_exp_f32_e32 v30, v30
	v_mul_f32_e32 v31, v24, v25
	v_add_f32_e32 v24, 1.0, v33
	v_rcp_f32_e32 v33, v24
	v_add_f32_e32 v24, 1.0, v30
	v_rcp_f32_e32 v30, v24
	v_mov_b32_e32 v24, v16
	v_mov_b32_e32 v25, v20
	v_pk_mul_f32 v[24:25], v[24:25], v[164:165] op_sel_hi:[1,0]
	v_mul_f32_e32 v20, v29, v33
	v_mul_f32_e32 v16, 0xbfb8aa3b, v25
	v_exp_f32_e32 v16, v16
	v_mul_f32_e32 v28, v28, v20
	v_mov_b32_e32 v20, v17
	v_mul_f32_e32 v27, v27, v30
	v_add_f32_e32 v16, 1.0, v16
	v_rcp_f32_e32 v29, v16
	v_pk_mul_f32 v[16:17], v[20:21], v[164:165] op_sel_hi:[1,0]
	v_mul_f32_e32 v26, v26, v27
	v_mul_f32_e32 v20, 0xbfb8aa3b, v17
	v_exp_f32_e32 v20, v20
	v_mul_f32_e32 v21, v25, v29
	v_mul_f32_e32 v24, v24, v21
	v_mov_b32_e32 v21, v22
	v_add_f32_e32 v20, 1.0, v20
	v_rcp_f32_e32 v25, v20
	v_mov_b32_e32 v20, v18
	v_pk_mul_f32 v[20:21], v[20:21], v[164:165] op_sel_hi:[1,0]
	v_mov_b32_e32 v22, v19
	v_mul_f32_e32 v18, 0xbfb8aa3b, v21
	v_exp_f32_e32 v27, v18
	v_pk_mul_f32 v[18:19], v[22:23], v[164:165] op_sel_hi:[1,0]
	v_mul_f32_e32 v17, v17, v25
	v_mul_f32_e32 v22, 0xbfb8aa3b, v19
	v_exp_f32_e32 v22, v22
	v_add_f32_e32 v23, 1.0, v27
	v_rcp_f32_e32 v23, v23
	v_mul_f32_e32 v25, v16, v17
	v_add_f32_e32 v22, 1.0, v22
	v_rcp_f32_e32 v22, v22
	v_mul_f32_e32 v16, v21, v23
	v_mul_f32_e32 v20, v20, v16
	v_mov_b32_e32 v23, v12
	v_mul_f32_e32 v16, v19, v22
	v_mov_b32_e32 v22, v8
	v_pk_mul_f32 v[22:23], v[22:23], v[158:159] op_sel_hi:[1,0]
	v_mul_f32_e32 v19, v18, v16
	v_mul_f32_e32 v8, 0xbfb8aa3b, v23
	v_cvt_pk_bf16_f32 v16, v32, v31
	v_cvt_pk_bf16_f32 v17, v28, v26
	v_cvt_pk_bf16_f32 v18, v24, v25
	v_exp_f32_e32 v24, v8
	v_mov_b32_e32 v12, v9
	v_pk_mul_f32 v[8:9], v[12:13], v[158:159] op_sel_hi:[1,0]
	v_cvt_pk_bf16_f32 v19, v20, v19
	v_mad_i64_i32 v[20:21], s[4:5], v150, s51, v[112:113]
	v_mul_f32_e32 v12, 0xbfb8aa3b, v9
	v_exp_f32_e32 v25, v12
	v_lshl_add_u64 v[12:13], v[20:21], 0, v[114:115]
	v_add_f32_e32 v20, 1.0, v24
	v_rcp_f32_e32 v20, v20
	global_store_dwordx4 v[12:13], v[16:19], off sc1
	v_mov_b32_e32 v13, v14
	v_add_f32_e32 v21, 1.0, v25
	v_mul_f32_e32 v12, v23, v20
	v_mul_f32_e32 v16, v22, v12
	v_mov_b32_e32 v12, v10
	v_pk_mul_f32 v[12:13], v[12:13], v[158:159] op_sel_hi:[1,0]
	v_mov_b32_e32 v14, v11
	v_mul_f32_e32 v10, 0xbfb8aa3b, v13
	v_rcp_f32_e32 v21, v21
	v_exp_f32_e32 v17, v10
	v_pk_mul_f32 v[10:11], v[14:15], v[158:159] op_sel_hi:[1,0]
	v_mul_f32_e32 v9, v9, v21
	v_mul_f32_e32 v14, 0xbfb8aa3b, v11
	v_exp_f32_e32 v14, v14
	v_mul_f32_e32 v15, v8, v9
	v_add_f32_e32 v8, 1.0, v17
	v_rcp_f32_e32 v17, v8
	v_add_f32_e32 v8, 1.0, v14
	v_rcp_f32_e32 v14, v8
	v_mov_b32_e32 v8, v0
	v_mov_b32_e32 v9, v4
	v_pk_mul_f32 v[8:9], v[8:9], v[158:159] op_sel_hi:[1,0]
	v_mul_f32_e32 v4, v13, v17
	v_mul_f32_e32 v0, 0xbfb8aa3b, v9
	v_exp_f32_e32 v0, v0
	v_mul_f32_e32 v12, v12, v4
	v_mov_b32_e32 v4, v1
	v_mul_f32_e32 v11, v11, v14
	v_add_f32_e32 v0, 1.0, v0
	v_rcp_f32_e32 v13, v0
	v_pk_mul_f32 v[0:1], v[4:5], v[158:159] op_sel_hi:[1,0]
	v_mul_f32_e32 v10, v10, v11
	v_mul_f32_e32 v4, 0xbfb8aa3b, v1
	v_exp_f32_e32 v4, v4
	v_mul_f32_e32 v5, v9, v13
	v_mul_f32_e32 v8, v8, v5
	v_mov_b32_e32 v5, v6
	v_add_f32_e32 v4, 1.0, v4
	v_rcp_f32_e32 v9, v4
	v_mov_b32_e32 v4, v2
	v_pk_mul_f32 v[4:5], v[4:5], v[158:159] op_sel_hi:[1,0]
	v_mov_b32_e32 v6, v3
	v_mul_f32_e32 v2, 0xbfb8aa3b, v5
	v_exp_f32_e32 v11, v2
	v_pk_mul_f32 v[2:3], v[6:7], v[158:159] op_sel_hi:[1,0]
	v_mul_f32_e32 v1, v1, v9
	v_mul_f32_e32 v6, 0xbfb8aa3b, v3
	v_exp_f32_e32 v6, v6
	v_add_f32_e32 v7, 1.0, v11
	v_rcp_f32_e32 v7, v7
	v_mul_f32_e32 v9, v0, v1
	v_add_f32_e32 v6, 1.0, v6
	v_rcp_f32_e32 v6, v6
	v_mul_f32_e32 v0, v5, v7
	v_mul_f32_e32 v4, v4, v0
	v_mul_f32_e32 v0, v3, v6
	v_mul_f32_e32 v3, v2, v0
	v_cvt_pk_bf16_f32 v0, v16, v15
	v_cvt_pk_bf16_f32 v1, v12, v10
	v_cvt_pk_bf16_f32 v2, v8, v9
	v_cvt_pk_bf16_f32 v3, v4, v3
	v_mad_i64_i32 v[4:5], s[4:5], v146, s51, v[112:113]
	v_lshl_add_u64 v[4:5], v[4:5], 0, v[114:115]
	s_mov_b64 s[4:5], -1
	global_store_dwordx4 v[4:5], v[0:3], off sc1
	s_cbranch_vccnz .LBB0_1044
	s_andn2_b64 vcc, exec, s[16:17]
	s_cbranch_vccnz .LBB0_1043
	s_barrier
	s_branch .LBB0_1043

.LBB0_1127:
	v_lshl_or_b32 v168, s10, 8, v188
	v_lshl_add_u32 v172, s53, 8, v186
	v_ashrrev_i32_e32 v169, 31, v168
	v_lshlrev_b64 v[204:205], 1, v[168:169]
	v_ashrrev_i32_e32 v173, 31, v172
	v_lshl_add_u64 v[170:171], s[16:17], 0, v[204:205]
	v_lshlrev_b64 v[206:207], 11, v[172:173]
	v_lshl_add_u64 v[128:129], v[170:171], 0, v[206:207]
	global_load_dwordx4 v[192:195], v[128:129], off
	global_load_dwordx4 v[198:201], v[128:129], off offset:256
	v_or_b32_e32 v182, 16, v172
	v_or_b32_e32 v178, 32, v172
	v_or_b32_e32 v174, 48, v172
	v_ashrrev_i32_e32 v183, 31, v182
	v_ashrrev_i32_e32 v179, 31, v178
	v_ashrrev_i32_e32 v175, 31, v174
	v_lshlrev_b64 v[184:185], 11, v[182:183]
	v_lshlrev_b64 v[180:181], 11, v[178:179]
	v_lshlrev_b64 v[176:177], 11, v[174:175]
	v_lshl_add_u64 v[128:129], v[170:171], 0, v[184:185]
	v_lshl_add_u64 v[130:131], v[170:171], 0, v[180:181]
	v_lshl_add_u64 v[208:209], v[170:171], 0, v[176:177]
	global_load_dwordx4 v[148:151], v[128:129], off
	global_load_dwordx4 v[144:147], v[128:129], off offset:256
	global_load_dwordx4 v[140:143], v[130:131], off
	global_load_dwordx4 v[136:139], v[130:131], off offset:256
	global_load_dwordx4 v[132:135], v[208:209], off
	s_nop 0
	global_load_dwordx4 v[128:131], v[208:209], off offset:256
	s_lshl_b32 s30, s10, 2
	s_ashr_i32 s31, s30, 31
	s_waitcnt vmcnt(0)
	v_lshlrev_b32_e32 v208, 16, v192
	v_and_b32_e32 v209, 0xffff0000, v192
	v_lshlrev_b32_e32 v192, 16, v193
	v_and_b32_e32 v193, 0xffff0000, v193
	v_lshlrev_b32_e32 v210, 16, v194
	v_and_b32_e32 v211, 0xffff0000, v194
	v_lshlrev_b32_e32 v194, 16, v195
	v_and_b32_e32 v195, 0xffff0000, v195
	v_lshlrev_b32_e32 v212, 16, v198
	v_and_b32_e32 v213, 0xffff0000, v198
	v_lshlrev_b32_e32 v198, 16, v199
	v_and_b32_e32 v199, 0xffff0000, v199
	v_lshlrev_b32_e32 v214, 16, v200
	v_and_b32_e32 v215, 0xffff0000, v200
	v_lshlrev_b32_e32 v200, 16, v201
	v_and_b32_e32 v201, 0xffff0000, v201
	v_pk_add_f32 v[126:127], v[126:127], v[192:193]
	v_pk_add_f32 v[124:125], v[124:125], v[208:209]
	v_pk_add_f32 v[122:123], v[122:123], v[194:195]
	v_pk_add_f32 v[120:121], v[120:121], v[210:211]
	v_pk_add_f32 v[118:119], v[118:119], v[198:199]
	v_pk_add_f32 v[116:117], v[116:117], v[212:213]
	v_pk_add_f32 v[192:193], v[114:115], v[200:201]
	v_pk_add_f32 v[194:195], v[112:113], v[214:215]
	v_mul_f32_e32 v198, v125, v125
	v_mul_f32_e32 v199, v127, v127
	v_mul_f32_e32 v200, v121, v121
	v_mul_f32_e32 v201, v123, v123
	v_cvt_pk_bf16_f32 v112, v124, v125
	v_cvt_pk_bf16_f32 v113, v126, v127
	v_cvt_pk_bf16_f32 v114, v120, v121
	v_cvt_pk_bf16_f32 v115, v122, v123
	v_mul_f32_e32 v121, v117, v117
	v_mul_f32_e32 v123, v119, v119
	v_mul_f32_e32 v125, v195, v195
	v_mul_f32_e32 v127, v193, v193
	v_fmac_f32_e32 v198, v124, v124
	v_fmac_f32_e32 v199, v126, v126
	v_fmac_f32_e32 v200, v120, v120
	v_fmac_f32_e32 v201, v122, v122
	v_fmac_f32_e32 v121, v116, v116
	v_fmac_f32_e32 v123, v118, v118
	v_fmac_f32_e32 v125, v194, v194
	v_fmac_f32_e32 v127, v192, v192
	v_add_f32_e32 v120, v198, v199
	v_add_f32_e32 v122, v200, v201
	v_add_f32_e32 v121, v121, v123
	v_add_f32_e32 v123, v125, v127
	v_add_f32_e32 v120, v120, v122
	v_add_f32_e32 v121, v121, v123
	v_add_f32_e32 v122, v120, v121
	ds_bpermute_b32 v123, v196, v122
	v_lshl_add_u64 v[120:121], s[16:17], 0, v[206:207]
	v_lshl_add_u64 v[120:121], v[120:121], 0, v[204:205]
	global_store_dwordx4 v[120:121], v[112:115], off sc1
	s_waitcnt lgkmcnt(0)
	s_nop 0
	v_add_f32_e32 v112, v122, v123
	ds_bpermute_b32 v113, v197, v112
	v_cvt_pk_bf16_f32 v114, v116, v117
	v_cvt_pk_bf16_f32 v115, v118, v119
	v_cvt_pk_bf16_f32 v116, v194, v195
	v_cvt_pk_bf16_f32 v117, v192, v193
	global_store_dwordx4 v[120:121], v[114:117], off offset:256 sc1
	s_and_saveexec_b64 s[34:35], s[4:5]
	s_cbranch_execz .LBB0_1129
	v_lshlrev_b64 v[114:115], 6, v[172:173]
	v_lshl_add_u64 v[114:115], s[22:23], 0, v[114:115]
	v_lshl_add_u64 v[114:115], s[30:31], 2, v[114:115]
	s_lshl_b32 s10, s45, 2
	v_lshl_add_u64 v[114:115], v[114:115], 0, s[10:11]
	s_waitcnt lgkmcnt(0)
	v_add_f32_e32 v112, v112, v113
	global_store_dword v[114:115], v112, off
.LBB0_1129:
	s_or_b64 exec, exec, s[34:35]
	v_lshlrev_b32_e32 v112, 16, v148
	s_waitcnt lgkmcnt(0)
	v_and_b32_e32 v113, 0xffff0000, v148
	v_lshlrev_b32_e32 v114, 16, v149
	v_and_b32_e32 v115, 0xffff0000, v149
	v_lshlrev_b32_e32 v116, 16, v150
	v_and_b32_e32 v117, 0xffff0000, v150
	v_lshlrev_b32_e32 v118, 16, v151
	v_and_b32_e32 v119, 0xffff0000, v151
	v_pk_add_f32 v[110:111], v[110:111], v[114:115]
	v_pk_add_f32 v[108:109], v[108:109], v[112:113]
	v_pk_add_f32 v[112:113], v[106:107], v[118:119]
	v_pk_add_f32 v[106:107], v[104:105], v[116:117]
	v_mul_f32_e32 v104, v109, v109
	v_mul_f32_e32 v105, v111, v111
	v_fmac_f32_e32 v104, v108, v108
	v_fmac_f32_e32 v105, v110, v110
	v_add_f32_e32 v104, v104, v105
	v_mul_f32_e32 v105, v107, v107
	v_mul_f32_e32 v114, v113, v113
	v_fmac_f32_e32 v105, v106, v106
	v_fmac_f32_e32 v114, v112, v112
	v_add_f32_e32 v105, v105, v114
	v_add_f32_e32 v116, v104, v105
	v_cvt_pk_bf16_f32 v104, v108, v109
	v_cvt_pk_bf16_f32 v105, v110, v111
	v_lshlrev_b32_e32 v108, 16, v144
	v_and_b32_e32 v109, 0xffff0000, v144
	v_lshlrev_b32_e32 v110, 16, v145
	v_and_b32_e32 v111, 0xffff0000, v145
	v_cvt_pk_bf16_f32 v106, v106, v107
	v_cvt_pk_bf16_f32 v107, v112, v113
	v_lshlrev_b32_e32 v112, 16, v146
	v_and_b32_e32 v113, 0xffff0000, v146
	v_pk_add_f32 v[102:103], v[102:103], v[110:111]
	v_pk_add_f32 v[100:101], v[100:101], v[108:109]
	v_lshlrev_b32_e32 v114, 16, v147
	v_and_b32_e32 v115, 0xffff0000, v147
	v_pk_add_f32 v[110:111], v[96:97], v[112:113]
	v_mul_f32_e32 v96, v101, v101
	v_mul_f32_e32 v97, v103, v103
	v_pk_add_f32 v[108:109], v[98:99], v[114:115]
	v_fmac_f32_e32 v96, v100, v100
	v_fmac_f32_e32 v97, v102, v102
	v_add_f32_e32 v96, v96, v97
	v_mul_f32_e32 v97, v111, v111
	v_mul_f32_e32 v98, v109, v109
	v_fmac_f32_e32 v97, v110, v110
	v_fmac_f32_e32 v98, v108, v108
	v_add_f32_e32 v97, v97, v98
	v_add_f32_e32 v96, v96, v97
	v_add_f32_e32 v99, v116, v96
	ds_bpermute_b32 v114, v196, v99
	v_lshl_add_u64 v[96:97], s[16:17], 0, v[184:185]
	v_lshl_add_u64 v[112:113], v[168:169], 1, v[96:97]
	global_store_dwordx4 v[112:113], v[104:107], off sc1
	v_cvt_pk_bf16_f32 v98, v100, v101
	s_waitcnt lgkmcnt(0)
	v_add_f32_e32 v96, v99, v114
	ds_bpermute_b32 v97, v197, v96
	v_cvt_pk_bf16_f32 v99, v102, v103
	v_cvt_pk_bf16_f32 v100, v110, v111
	v_cvt_pk_bf16_f32 v101, v108, v109
	global_store_dwordx4 v[112:113], v[98:101], off offset:256 sc1
	s_and_saveexec_b64 s[34:35], s[4:5]
	s_cbranch_execz .LBB0_1131
	v_lshlrev_b64 v[98:99], 6, v[182:183]
	v_lshl_add_u64 v[98:99], s[22:23], 0, v[98:99]
	v_lshl_add_u64 v[98:99], s[30:31], 2, v[98:99]
	s_lshl_b32 s10, s45, 2
	v_lshl_add_u64 v[98:99], v[98:99], 0, s[10:11]
	s_waitcnt lgkmcnt(0)
	v_add_f32_e32 v96, v96, v97
	global_store_dword v[98:99], v96, off
.LBB0_1131:
	s_or_b64 exec, exec, s[34:35]
	v_lshlrev_b32_e32 v96, 16, v140
	s_waitcnt lgkmcnt(0)
	v_and_b32_e32 v97, 0xffff0000, v140
	v_lshlrev_b32_e32 v98, 16, v141
	v_and_b32_e32 v99, 0xffff0000, v141
	v_lshlrev_b32_e32 v100, 16, v142
	v_and_b32_e32 v101, 0xffff0000, v142
	v_lshlrev_b32_e32 v102, 16, v143
	v_and_b32_e32 v103, 0xffff0000, v143
	v_pk_add_f32 v[94:95], v[94:95], v[98:99]
	v_pk_add_f32 v[92:93], v[92:93], v[96:97]
	v_pk_add_f32 v[96:97], v[90:91], v[102:103]
	v_pk_add_f32 v[90:91], v[88:89], v[100:101]
	v_mul_f32_e32 v88, v93, v93
	v_mul_f32_e32 v89, v95, v95
	v_fmac_f32_e32 v88, v92, v92
	v_fmac_f32_e32 v89, v94, v94
	v_add_f32_e32 v88, v88, v89
	v_mul_f32_e32 v89, v91, v91
	v_mul_f32_e32 v98, v97, v97
	v_fmac_f32_e32 v89, v90, v90
	v_fmac_f32_e32 v98, v96, v96
	v_add_f32_e32 v89, v89, v98
	v_add_f32_e32 v100, v88, v89
	v_cvt_pk_bf16_f32 v88, v92, v93
	v_cvt_pk_bf16_f32 v89, v94, v95
	v_lshlrev_b32_e32 v92, 16, v136
	v_and_b32_e32 v93, 0xffff0000, v136
	v_lshlrev_b32_e32 v94, 16, v137
	v_and_b32_e32 v95, 0xffff0000, v137
	v_cvt_pk_bf16_f32 v90, v90, v91
	v_cvt_pk_bf16_f32 v91, v96, v97
	v_lshlrev_b32_e32 v96, 16, v138
	v_and_b32_e32 v97, 0xffff0000, v138
	v_pk_add_f32 v[86:87], v[86:87], v[94:95]
	v_pk_add_f32 v[84:85], v[84:85], v[92:93]
	v_lshlrev_b32_e32 v98, 16, v139
	v_and_b32_e32 v99, 0xffff0000, v139
	v_pk_add_f32 v[94:95], v[80:81], v[96:97]
	v_mul_f32_e32 v80, v85, v85
	v_mul_f32_e32 v81, v87, v87
	v_pk_add_f32 v[92:93], v[82:83], v[98:99]
	v_fmac_f32_e32 v80, v84, v84
	v_fmac_f32_e32 v81, v86, v86
	v_add_f32_e32 v80, v80, v81
	v_mul_f32_e32 v81, v95, v95
	v_mul_f32_e32 v82, v93, v93
	v_fmac_f32_e32 v81, v94, v94
	v_fmac_f32_e32 v82, v92, v92
	v_add_f32_e32 v81, v81, v82
	v_add_f32_e32 v80, v80, v81
	v_add_f32_e32 v83, v100, v80
	ds_bpermute_b32 v98, v196, v83
	v_lshl_add_u64 v[80:81], s[16:17], 0, v[180:181]
	v_lshl_add_u64 v[96:97], v[168:169], 1, v[80:81]
	global_store_dwordx4 v[96:97], v[88:91], off sc1
	v_cvt_pk_bf16_f32 v82, v84, v85
	s_waitcnt lgkmcnt(0)
	v_add_f32_e32 v80, v83, v98
	ds_bpermute_b32 v81, v197, v80
	v_cvt_pk_bf16_f32 v83, v86, v87
	v_cvt_pk_bf16_f32 v84, v94, v95
	v_cvt_pk_bf16_f32 v85, v92, v93
	global_store_dwordx4 v[96:97], v[82:85], off offset:256 sc1
	s_and_saveexec_b64 s[34:35], s[4:5]
	s_cbranch_execz .LBB0_1133
	v_lshlrev_b64 v[82:83], 6, v[178:179]
	v_lshl_add_u64 v[82:83], s[22:23], 0, v[82:83]
	v_lshl_add_u64 v[82:83], s[30:31], 2, v[82:83]
	s_lshl_b32 s10, s45, 2
	v_lshl_add_u64 v[82:83], v[82:83], 0, s[10:11]
	s_waitcnt lgkmcnt(0)
	v_add_f32_e32 v80, v80, v81
	global_store_dword v[82:83], v80, off
.LBB0_1133:
	s_or_b64 exec, exec, s[34:35]
	v_lshlrev_b32_e32 v80, 16, v132
	s_waitcnt lgkmcnt(0)
	v_and_b32_e32 v81, 0xffff0000, v132
	v_lshlrev_b32_e32 v82, 16, v133
	v_and_b32_e32 v83, 0xffff0000, v133
	v_lshlrev_b32_e32 v84, 16, v134
	v_and_b32_e32 v85, 0xffff0000, v134
	v_lshlrev_b32_e32 v86, 16, v135
	v_and_b32_e32 v87, 0xffff0000, v135
	v_pk_add_f32 v[78:79], v[78:79], v[82:83]
	v_pk_add_f32 v[76:77], v[76:77], v[80:81]
	v_pk_add_f32 v[80:81], v[74:75], v[86:87]
	v_pk_add_f32 v[74:75], v[72:73], v[84:85]
	v_mul_f32_e32 v72, v77, v77
	v_mul_f32_e32 v73, v79, v79
	v_fmac_f32_e32 v72, v76, v76
	v_fmac_f32_e32 v73, v78, v78
	v_add_f32_e32 v72, v72, v73
	v_mul_f32_e32 v73, v75, v75
	v_mul_f32_e32 v82, v81, v81
	v_fmac_f32_e32 v73, v74, v74
	v_fmac_f32_e32 v82, v80, v80
	v_add_f32_e32 v73, v73, v82
	v_add_f32_e32 v84, v72, v73
	v_cvt_pk_bf16_f32 v72, v76, v77
	v_cvt_pk_bf16_f32 v73, v78, v79
	v_lshlrev_b32_e32 v76, 16, v128
	v_and_b32_e32 v77, 0xffff0000, v128
	v_lshlrev_b32_e32 v78, 16, v129
	v_and_b32_e32 v79, 0xffff0000, v129
	v_cvt_pk_bf16_f32 v74, v74, v75
	v_cvt_pk_bf16_f32 v75, v80, v81
	v_lshlrev_b32_e32 v80, 16, v130
	v_and_b32_e32 v81, 0xffff0000, v130
	v_pk_add_f32 v[70:71], v[70:71], v[78:79]
	v_pk_add_f32 v[68:69], v[68:69], v[76:77]
	v_lshlrev_b32_e32 v82, 16, v131
	v_and_b32_e32 v83, 0xffff0000, v131
	v_pk_add_f32 v[78:79], v[64:65], v[80:81]
	v_mul_f32_e32 v64, v69, v69
	v_mul_f32_e32 v65, v71, v71
	v_pk_add_f32 v[76:77], v[66:67], v[82:83]
	v_fmac_f32_e32 v64, v68, v68
	v_fmac_f32_e32 v65, v70, v70
	v_add_f32_e32 v64, v64, v65
	v_mul_f32_e32 v65, v79, v79
	v_mul_f32_e32 v66, v77, v77
	v_fmac_f32_e32 v65, v78, v78
	v_fmac_f32_e32 v66, v76, v76
	v_add_f32_e32 v65, v65, v66
	v_add_f32_e32 v64, v64, v65
	v_add_f32_e32 v67, v84, v64
	ds_bpermute_b32 v82, v196, v67
	v_lshl_add_u64 v[64:65], s[16:17], 0, v[176:177]
	v_lshl_add_u64 v[80:81], v[168:169], 1, v[64:65]
	global_store_dwordx4 v[80:81], v[72:75], off sc1
	v_cvt_pk_bf16_f32 v66, v68, v69
	s_waitcnt lgkmcnt(0)
	v_add_f32_e32 v64, v67, v82
	ds_bpermute_b32 v65, v197, v64
	v_cvt_pk_bf16_f32 v67, v70, v71
	v_cvt_pk_bf16_f32 v68, v78, v79
	v_cvt_pk_bf16_f32 v69, v76, v77
	global_store_dwordx4 v[80:81], v[66:69], off offset:256 sc1
	s_and_saveexec_b64 s[34:35], s[4:5]
	s_cbranch_execz .LBB0_1135
	v_lshlrev_b64 v[66:67], 6, v[174:175]
	v_lshl_add_u64 v[66:67], s[22:23], 0, v[66:67]
	v_lshl_add_u64 v[66:67], s[30:31], 2, v[66:67]
	s_lshl_b32 s10, s45, 2
	v_lshl_add_u64 v[66:67], v[66:67], 0, s[10:11]
	s_waitcnt lgkmcnt(0)
	v_add_f32_e32 v64, v64, v65
	global_store_dword v[66:67], v64, off
.LBB0_1135:
	s_or_b64 exec, exec, s[34:35]
	v_add_u32_e32 v100, 0x80, v172
	v_ashrrev_i32_e32 v101, 31, v100
	v_lshlrev_b64 v[110:111], 11, v[100:101]
	s_waitcnt lgkmcnt(0)
	v_lshl_add_u64 v[64:65], v[170:171], 0, v[110:111]
	global_load_dwordx4 v[102:105], v[64:65], off
	global_load_dwordx4 v[106:109], v[64:65], off offset:256
	v_add_u32_e32 v96, 0x90, v172
	v_add_u32_e32 v92, 0xa0, v172
	v_add_u32_e32 v88, 0xb0, v172
	v_ashrrev_i32_e32 v97, 31, v96
	v_ashrrev_i32_e32 v93, 31, v92
	v_ashrrev_i32_e32 v89, 31, v88
	v_lshlrev_b64 v[98:99], 11, v[96:97]
	v_lshlrev_b64 v[94:95], 11, v[92:93]
	v_lshlrev_b64 v[90:91], 11, v[88:89]
	v_lshl_add_u64 v[64:65], v[170:171], 0, v[98:99]
	v_lshl_add_u64 v[66:67], v[170:171], 0, v[94:95]
	v_lshl_add_u64 v[112:113], v[170:171], 0, v[90:91]
	global_load_dwordx4 v[84:87], v[64:65], off
	global_load_dwordx4 v[80:83], v[64:65], off offset:256
	global_load_dwordx4 v[76:79], v[66:67], off
	global_load_dwordx4 v[72:75], v[66:67], off offset:256
	global_load_dwordx4 v[68:71], v[112:113], off
	s_nop 0
	global_load_dwordx4 v[64:67], v[112:113], off offset:256
	s_waitcnt vmcnt(7)
	v_lshlrev_b32_e32 v112, 16, v102
	v_and_b32_e32 v113, 0xffff0000, v102
	v_lshlrev_b32_e32 v102, 16, v103
	v_and_b32_e32 v103, 0xffff0000, v103
	v_lshlrev_b32_e32 v114, 16, v104
	v_and_b32_e32 v115, 0xffff0000, v104
	v_lshlrev_b32_e32 v104, 16, v105
	v_and_b32_e32 v105, 0xffff0000, v105
	s_waitcnt vmcnt(6)
	v_lshlrev_b32_e32 v116, 16, v106
	v_and_b32_e32 v117, 0xffff0000, v106
	v_lshlrev_b32_e32 v106, 16, v107
	v_and_b32_e32 v107, 0xffff0000, v107
	v_lshlrev_b32_e32 v118, 16, v108
	v_and_b32_e32 v119, 0xffff0000, v108
	v_lshlrev_b32_e32 v108, 16, v109
	v_and_b32_e32 v109, 0xffff0000, v109
	v_pk_add_f32 v[62:63], v[62:63], v[102:103]
	v_pk_add_f32 v[60:61], v[60:61], v[112:113]
	v_pk_add_f32 v[58:59], v[58:59], v[104:105]
	v_pk_add_f32 v[56:57], v[56:57], v[114:115]
	v_pk_add_f32 v[54:55], v[54:55], v[106:107]
	v_pk_add_f32 v[52:53], v[52:53], v[116:117]
	v_pk_add_f32 v[102:103], v[50:51], v[108:109]
	v_pk_add_f32 v[104:105], v[48:49], v[118:119]
	v_mul_f32_e32 v106, v61, v61
	v_mul_f32_e32 v107, v63, v63
	v_mul_f32_e32 v108, v57, v57
	v_mul_f32_e32 v109, v59, v59
	v_cvt_pk_bf16_f32 v48, v60, v61
	v_cvt_pk_bf16_f32 v49, v62, v63
	v_cvt_pk_bf16_f32 v50, v56, v57
	v_cvt_pk_bf16_f32 v51, v58, v59
	v_mul_f32_e32 v57, v53, v53
	v_mul_f32_e32 v59, v55, v55
	v_mul_f32_e32 v61, v105, v105
	v_mul_f32_e32 v63, v103, v103
	v_fmac_f32_e32 v106, v60, v60
	v_fmac_f32_e32 v107, v62, v62
	v_fmac_f32_e32 v108, v56, v56
	v_fmac_f32_e32 v109, v58, v58
	v_fmac_f32_e32 v57, v52, v52
	v_fmac_f32_e32 v59, v54, v54
	v_fmac_f32_e32 v61, v104, v104
	v_fmac_f32_e32 v63, v102, v102
	v_add_f32_e32 v56, v106, v107
	v_add_f32_e32 v58, v108, v109
	v_add_f32_e32 v57, v57, v59
	v_add_f32_e32 v59, v61, v63
	v_add_f32_e32 v56, v56, v58
	v_add_f32_e32 v57, v57, v59
	v_add_f32_e32 v58, v56, v57
	ds_bpermute_b32 v59, v196, v58
	v_lshl_add_u64 v[56:57], s[16:17], 0, v[110:111]
	v_lshl_add_u64 v[56:57], v[168:169], 1, v[56:57]
	global_store_dwordx4 v[56:57], v[48:51], off sc1
	s_waitcnt lgkmcnt(0)
	s_nop 0
	v_add_f32_e32 v48, v58, v59
	ds_bpermute_b32 v49, v197, v48
	v_cvt_pk_bf16_f32 v50, v52, v53
	v_cvt_pk_bf16_f32 v51, v54, v55
	v_cvt_pk_bf16_f32 v52, v104, v105
	v_cvt_pk_bf16_f32 v53, v102, v103
	global_store_dwordx4 v[56:57], v[50:53], off offset:256 sc1
	s_and_saveexec_b64 s[34:35], s[4:5]
	s_cbranch_execz .LBB0_1137
	v_lshlrev_b64 v[50:51], 6, v[100:101]
	v_lshl_add_u64 v[50:51], s[22:23], 0, v[50:51]
	v_lshl_add_u64 v[50:51], s[30:31], 2, v[50:51]
	s_lshl_b32 s10, s45, 2
	v_lshl_add_u64 v[50:51], v[50:51], 0, s[10:11]
	s_waitcnt lgkmcnt(0)
	v_add_f32_e32 v48, v48, v49
	global_store_dword v[50:51], v48, off
.LBB0_1137:
	s_or_b64 exec, exec, s[34:35]
	s_waitcnt vmcnt(7)
	v_lshlrev_b32_e32 v48, 16, v84
	s_waitcnt lgkmcnt(0)
	v_and_b32_e32 v49, 0xffff0000, v84
	v_lshlrev_b32_e32 v50, 16, v85
	v_and_b32_e32 v51, 0xffff0000, v85
	v_lshlrev_b32_e32 v52, 16, v86
	v_and_b32_e32 v53, 0xffff0000, v86
	v_lshlrev_b32_e32 v54, 16, v87
	v_and_b32_e32 v55, 0xffff0000, v87
	v_pk_add_f32 v[46:47], v[46:47], v[50:51]
	v_pk_add_f32 v[44:45], v[44:45], v[48:49]
	v_pk_add_f32 v[48:49], v[42:43], v[54:55]
	v_pk_add_f32 v[42:43], v[40:41], v[52:53]
	v_mul_f32_e32 v40, v45, v45
	v_mul_f32_e32 v41, v47, v47
	v_fmac_f32_e32 v40, v44, v44
	v_fmac_f32_e32 v41, v46, v46
	v_add_f32_e32 v40, v40, v41
	v_mul_f32_e32 v41, v43, v43
	v_mul_f32_e32 v50, v49, v49
	v_fmac_f32_e32 v41, v42, v42
	v_fmac_f32_e32 v50, v48, v48
	v_add_f32_e32 v41, v41, v50
	v_add_f32_e32 v52, v40, v41
	v_cvt_pk_bf16_f32 v40, v44, v45
	v_cvt_pk_bf16_f32 v41, v46, v47
	s_waitcnt vmcnt(6)
	v_lshlrev_b32_e32 v44, 16, v80
	v_and_b32_e32 v45, 0xffff0000, v80
	v_lshlrev_b32_e32 v46, 16, v81
	v_and_b32_e32 v47, 0xffff0000, v81
	v_cvt_pk_bf16_f32 v42, v42, v43
	v_cvt_pk_bf16_f32 v43, v48, v49
	v_lshlrev_b32_e32 v48, 16, v82
	v_and_b32_e32 v49, 0xffff0000, v82
	v_pk_add_f32 v[38:39], v[38:39], v[46:47]
	v_pk_add_f32 v[36:37], v[36:37], v[44:45]
	v_lshlrev_b32_e32 v50, 16, v83
	v_and_b32_e32 v51, 0xffff0000, v83
	v_pk_add_f32 v[46:47], v[32:33], v[48:49]
	v_mul_f32_e32 v32, v37, v37
	v_mul_f32_e32 v33, v39, v39
	v_pk_add_f32 v[44:45], v[34:35], v[50:51]
	v_fmac_f32_e32 v32, v36, v36
	v_fmac_f32_e32 v33, v38, v38
	v_add_f32_e32 v32, v32, v33
	v_mul_f32_e32 v33, v47, v47
	v_mul_f32_e32 v34, v45, v45
	v_fmac_f32_e32 v33, v46, v46
	v_fmac_f32_e32 v34, v44, v44
	v_add_f32_e32 v33, v33, v34
	v_add_f32_e32 v32, v32, v33
	v_add_f32_e32 v35, v52, v32
	ds_bpermute_b32 v50, v196, v35
	v_lshl_add_u64 v[32:33], s[16:17], 0, v[98:99]
	v_lshl_add_u64 v[48:49], v[168:169], 1, v[32:33]
	global_store_dwordx4 v[48:49], v[40:43], off sc1
	v_cvt_pk_bf16_f32 v34, v36, v37
	s_waitcnt lgkmcnt(0)
	v_add_f32_e32 v32, v35, v50
	ds_bpermute_b32 v33, v197, v32
	v_cvt_pk_bf16_f32 v35, v38, v39
	v_cvt_pk_bf16_f32 v36, v46, v47
	v_cvt_pk_bf16_f32 v37, v44, v45
	global_store_dwordx4 v[48:49], v[34:37], off offset:256 sc1
	s_and_saveexec_b64 s[34:35], s[4:5]
	s_cbranch_execz .LBB0_1139
	v_lshlrev_b64 v[34:35], 6, v[96:97]
	v_lshl_add_u64 v[34:35], s[22:23], 0, v[34:35]
	v_lshl_add_u64 v[34:35], s[30:31], 2, v[34:35]
	s_lshl_b32 s10, s45, 2
	v_lshl_add_u64 v[34:35], v[34:35], 0, s[10:11]
	s_waitcnt lgkmcnt(0)
	v_add_f32_e32 v32, v32, v33
	global_store_dword v[34:35], v32, off
.LBB0_1139:
	s_or_b64 exec, exec, s[34:35]
	s_waitcnt vmcnt(7)
	v_lshlrev_b32_e32 v32, 16, v76
	s_waitcnt lgkmcnt(0)
	v_and_b32_e32 v33, 0xffff0000, v76
	v_lshlrev_b32_e32 v34, 16, v77
	v_and_b32_e32 v35, 0xffff0000, v77
	v_lshlrev_b32_e32 v36, 16, v78
	v_and_b32_e32 v37, 0xffff0000, v78
	v_lshlrev_b32_e32 v38, 16, v79
	v_and_b32_e32 v39, 0xffff0000, v79
	v_pk_add_f32 v[30:31], v[30:31], v[34:35]
	v_pk_add_f32 v[28:29], v[28:29], v[32:33]
	v_pk_add_f32 v[32:33], v[26:27], v[38:39]
	v_pk_add_f32 v[26:27], v[24:25], v[36:37]
	v_mul_f32_e32 v24, v29, v29
	v_mul_f32_e32 v25, v31, v31
	v_fmac_f32_e32 v24, v28, v28
	v_fmac_f32_e32 v25, v30, v30
	v_add_f32_e32 v24, v24, v25
	v_mul_f32_e32 v25, v27, v27
	v_mul_f32_e32 v34, v33, v33
	v_fmac_f32_e32 v25, v26, v26
	v_fmac_f32_e32 v34, v32, v32
	v_add_f32_e32 v25, v25, v34
	v_add_f32_e32 v36, v24, v25
	v_cvt_pk_bf16_f32 v24, v28, v29
	v_cvt_pk_bf16_f32 v25, v30, v31
	s_waitcnt vmcnt(6)
	v_lshlrev_b32_e32 v28, 16, v72
	v_and_b32_e32 v29, 0xffff0000, v72
	v_lshlrev_b32_e32 v30, 16, v73
	v_and_b32_e32 v31, 0xffff0000, v73
	v_cvt_pk_bf16_f32 v26, v26, v27
	v_cvt_pk_bf16_f32 v27, v32, v33
	v_lshlrev_b32_e32 v32, 16, v74
	v_and_b32_e32 v33, 0xffff0000, v74
	v_pk_add_f32 v[22:23], v[22:23], v[30:31]
	v_pk_add_f32 v[20:21], v[20:21], v[28:29]
	v_lshlrev_b32_e32 v34, 16, v75
	v_and_b32_e32 v35, 0xffff0000, v75
	v_pk_add_f32 v[30:31], v[16:17], v[32:33]
	v_mul_f32_e32 v16, v21, v21
	v_mul_f32_e32 v17, v23, v23
	v_pk_add_f32 v[28:29], v[18:19], v[34:35]
	v_fmac_f32_e32 v16, v20, v20
	v_fmac_f32_e32 v17, v22, v22
	v_add_f32_e32 v16, v16, v17
	v_mul_f32_e32 v17, v31, v31
	v_mul_f32_e32 v18, v29, v29
	v_fmac_f32_e32 v17, v30, v30
	v_fmac_f32_e32 v18, v28, v28
	v_add_f32_e32 v17, v17, v18
	v_add_f32_e32 v16, v16, v17
	v_add_f32_e32 v19, v36, v16
	ds_bpermute_b32 v34, v196, v19
	v_lshl_add_u64 v[16:17], s[16:17], 0, v[94:95]
	v_lshl_add_u64 v[32:33], v[168:169], 1, v[16:17]
	global_store_dwordx4 v[32:33], v[24:27], off sc1
	v_cvt_pk_bf16_f32 v18, v20, v21
	s_waitcnt lgkmcnt(0)
	v_add_f32_e32 v16, v19, v34
	ds_bpermute_b32 v17, v197, v16
	v_cvt_pk_bf16_f32 v19, v22, v23
	v_cvt_pk_bf16_f32 v20, v30, v31
	v_cvt_pk_bf16_f32 v21, v28, v29
	global_store_dwordx4 v[32:33], v[18:21], off offset:256 sc1
	s_and_saveexec_b64 s[34:35], s[4:5]
	s_cbranch_execz .LBB0_1141
	v_lshlrev_b64 v[18:19], 6, v[92:93]
	v_lshl_add_u64 v[18:19], s[22:23], 0, v[18:19]
	v_lshl_add_u64 v[18:19], s[30:31], 2, v[18:19]
	s_lshl_b32 s10, s45, 2
	v_lshl_add_u64 v[18:19], v[18:19], 0, s[10:11]
	s_waitcnt lgkmcnt(0)
	v_add_f32_e32 v16, v16, v17
	global_store_dword v[18:19], v16, off
.LBB0_1141:
	s_or_b64 exec, exec, s[34:35]
	s_waitcnt vmcnt(7)
	v_lshlrev_b32_e32 v16, 16, v68
	s_waitcnt lgkmcnt(0)
	v_and_b32_e32 v17, 0xffff0000, v68
	v_lshlrev_b32_e32 v18, 16, v69
	v_and_b32_e32 v19, 0xffff0000, v69
	v_lshlrev_b32_e32 v20, 16, v70
	v_and_b32_e32 v21, 0xffff0000, v70
	v_lshlrev_b32_e32 v22, 16, v71
	v_and_b32_e32 v23, 0xffff0000, v71
	v_pk_add_f32 v[14:15], v[14:15], v[18:19]
	v_pk_add_f32 v[12:13], v[12:13], v[16:17]
	v_pk_add_f32 v[16:17], v[10:11], v[22:23]
	v_pk_add_f32 v[10:11], v[8:9], v[20:21]
	v_mul_f32_e32 v8, v13, v13
	v_mul_f32_e32 v9, v15, v15
	v_fmac_f32_e32 v8, v12, v12
	v_fmac_f32_e32 v9, v14, v14
	v_add_f32_e32 v8, v8, v9
	v_mul_f32_e32 v9, v11, v11
	v_mul_f32_e32 v18, v17, v17
	v_fmac_f32_e32 v9, v10, v10
	v_fmac_f32_e32 v18, v16, v16
	v_add_f32_e32 v9, v9, v18
	v_add_f32_e32 v20, v8, v9
	v_cvt_pk_bf16_f32 v8, v12, v13
	v_cvt_pk_bf16_f32 v9, v14, v15
	s_waitcnt vmcnt(6)
	v_lshlrev_b32_e32 v12, 16, v64
	v_and_b32_e32 v13, 0xffff0000, v64
	v_lshlrev_b32_e32 v14, 16, v65
	v_and_b32_e32 v15, 0xffff0000, v65
	v_cvt_pk_bf16_f32 v10, v10, v11
	v_cvt_pk_bf16_f32 v11, v16, v17
	v_lshlrev_b32_e32 v16, 16, v66
	v_and_b32_e32 v17, 0xffff0000, v66
	v_pk_add_f32 v[6:7], v[6:7], v[14:15]
	v_pk_add_f32 v[4:5], v[4:5], v[12:13]
	v_lshlrev_b32_e32 v18, 16, v67
	v_and_b32_e32 v19, 0xffff0000, v67
	v_pk_add_f32 v[14:15], v[0:1], v[16:17]
	v_mul_f32_e32 v0, v5, v5
	v_mul_f32_e32 v1, v7, v7
	v_pk_add_f32 v[12:13], v[2:3], v[18:19]
	v_fmac_f32_e32 v0, v4, v4
	v_fmac_f32_e32 v1, v6, v6
	v_add_f32_e32 v0, v0, v1
	v_mul_f32_e32 v1, v15, v15
	v_mul_f32_e32 v2, v13, v13
	v_fmac_f32_e32 v1, v14, v14
	v_fmac_f32_e32 v2, v12, v12
	v_add_f32_e32 v1, v1, v2
	v_add_f32_e32 v0, v0, v1
	v_add_f32_e32 v3, v20, v0
	ds_bpermute_b32 v18, v196, v3
	v_lshl_add_u64 v[0:1], s[16:17], 0, v[90:91]
	v_lshl_add_u64 v[16:17], v[168:169], 1, v[0:1]
	global_store_dwordx4 v[16:17], v[8:11], off sc1
	v_cvt_pk_bf16_f32 v2, v4, v5
	s_waitcnt lgkmcnt(0)
	v_add_f32_e32 v0, v3, v18
	ds_bpermute_b32 v1, v197, v0
	v_cvt_pk_bf16_f32 v3, v6, v7
	v_cvt_pk_bf16_f32 v4, v14, v15
	v_cvt_pk_bf16_f32 v5, v12, v13
	global_store_dwordx4 v[16:17], v[2:5], off offset:256 sc1
	s_and_saveexec_b64 s[34:35], s[4:5]
	s_cbranch_execz .LBB0_1143
	v_lshlrev_b64 v[2:3], 6, v[88:89]
	v_lshl_add_u64 v[2:3], s[22:23], 0, v[2:3]
	v_lshl_add_u64 v[2:3], s[30:31], 2, v[2:3]
	s_lshl_b32 s10, s45, 2
	v_lshl_add_u64 v[2:3], v[2:3], 0, s[10:11]
	s_waitcnt lgkmcnt(0)
	v_add_f32_e32 v0, v0, v1
	global_store_dword v[2:3], v0, off
